# GEMM unit epilogues un-aligned (template's ALIGN_EPI=false form): per-unit realign/restore barriers dropped in 8 phases
# baseline (speedup 1.0000x reference)
; #define PG8_STAGE(bufoff, gbase, voff) do { _Pragma("unroll") for (int _i = 0; _i < 2; ++_i) \
;         __builtin_amdgcn_global_load_lds((const unsigned*)((const char*)(gbase) + (voff)[_i]), (PG8_LAS unsigned*)(lds + (bufoff) + ldsw + _i * 8192), 16, 0, 0); } while (0)
; #define PG8_LDA(dst, b, h) do { _Pragma("unroll") for (int m = 0; m < 4; ++m) _Pragma("unroll") for (int k = 0; k < 2; ++k) dst[m][k] = *(const PG8_LAS bf16x8*)(lds + PG8_SA(b, h) + aoff + m * 2048 + k * 1024); } while (0)
; #define PG8_LDB(dst, b, h) do { _Pragma("unroll") for (int n = 0; n < 2; ++n) _Pragma("unroll") for (int k = 0; k < 2; ++k) dst[n][k] = *(const PG8_LAS bf16x8*)(lds + PG8_SB(b, h) + boff + n * 2048 + k * 1024); } while (0)
; #define PG8_MMA(ai, bj, At, Bt) do { __builtin_amdgcn_s_setprio(1); _Pragma("unroll") for (int m = 0; m < 4; ++m) _Pragma("unroll") for (int n = 0; n < 2; ++n) _Pragma("unroll") for (int k = 0; k < 2; ++k) \
;         acc[ai][bj][m][n] = __builtin_amdgcn_mfma_f32_16x16x32_bf16(Bt[n][k], At[m][k], acc[ai][bj][m][n], 0, 0, 0); __builtin_amdgcn_s_setprio(0); } while (0)
; #define PG8_WAIT_V(n) asm volatile("s_waitcnt vmcnt(" #n ")" ::: "memory")
; #define PG8_BAR __builtin_amdgcn_s_barrier()
; template <class Epi, class Sched, bool ALIGN_EPI = false, bool SP2 = false>
; __device__ __forceinline__ void gemm_phase(PG8_LAS unsigned char* lds, const Gemm g, const Sched& S, const Epi& E) {
;     ...
;         for (int t = 0; t < nt; t += 2) {
;             const bool last = (t == nt - 2);
;             const char* a1 = cA + (size_t)(t + 1) * kstep;
;             const char* a2 = last ? nA : cA + (size_t)(t + 2) * kstep; const char* b2 = last ? nB : cB + (size_t)(t + 2) * kstep;
;             const char* a3 = a2 + kstep; const char* b3 = b2 + kstep;
;             if (last && has_next) S.a_ready(nxt);
;             if constexpr (SP2) {
;             PG8_LDB(B0, 0, 0); PG8_LDB(B1, 0, 1); PG8_SCHED; PG8_LDA(At, 0, 0); PG8_STAGE(PG8_SA(1, 1), a1 + hstep, voffA);
;             PG8_WAIT_V(8); PG8_WAIT_L(0); PG8_BAR; PG8_MMA(0, 0, At, B0); PG8_MMA(0, 1, At, B1); PG8_BAR; PG8_SCHED;
;             PG8_LDA(At, 0, 1); PG8_STAGE(PG8_SB(0, 0), b2, voffB); PG8_STAGE(PG8_SB(0, 1), b2 + hstep, voffB); PG8_STAGE(PG8_SA(0, 0), a2, voffA);
;             PG8_WAIT_V(8); PG8_WAIT_L(0); PG8_BAR; PG8_MMA(1, 0, At, B0); PG8_MMA(1, 1, At, B1); PG8_BAR; PG8_SCHED;
.LBB0_491:
	ds_read_b128 v[156:159], v151
	ds_read_b128 v[160:163], v151 offset:1024
	ds_read_b128 v[164:167], v151 offset:2048
	ds_read_b128 v[168:171], v151 offset:3072
	ds_read_b128 v[174:177], v152
	ds_read_b128 v[178:181], v152 offset:1024
	ds_read_b128 v[182:185], v152 offset:2048
	ds_read_b128 v[186:189], v152 offset:3072
	s_add_u32 s20, s18, 0xfffc0080
	s_addc_u32 s21, s19, -1
	s_cmp_eq_u32 s60, 12
	s_cselect_b32 s23, s11, s21
	s_cselect_b32 s22, s52, s20
	s_cselect_b32 s21, s9, s57
	s_cselect_b32 s20, s53, s56
	v_lshl_add_u64 v[222:223], s[18:19], 0, v[142:143]
	s_add_i32 m0, s31, 0xc000
	ds_read_b128 v[190:193], v153
	ds_read_b128 v[194:197], v153 offset:1024
	ds_read_b128 v[198:201], v153 offset:2048
	ds_read_b128 v[202:205], v153 offset:3072
	ds_read_b128 v[206:209], v153 offset:4096
	ds_read_b128 v[210:213], v153 offset:5120
	ds_read_b128 v[214:217], v153 offset:6144
	ds_read_b128 v[218:221], v153 offset:7168
	global_load_lds_dwordx4 v[222:223], off
	v_lshl_add_u64 v[222:223], s[18:19], 0, v[144:145]
	s_add_i32 m0, s31, 0xe000
	s_nop 0
	global_load_lds_dwordx4 v[222:223], off
	s_waitcnt vmcnt(8)
	s_waitcnt lgkmcnt(0)
	s_barrier
	s_waitcnt lgkmcnt(0)
	v_mfma_f32_16x16x32_bf16 v[126:129], v[156:159], v[190:193], v[126:129]
	v_mfma_f32_16x16x32_bf16 v[122:125], v[164:167], v[190:193], v[122:125]
	v_mfma_f32_16x16x32_bf16 v[114:117], v[156:159], v[198:201], v[114:117]
	v_mfma_f32_16x16x32_bf16 v[106:109], v[164:167], v[198:201], v[106:109]
	v_mfma_f32_16x16x32_bf16 v[98:101], v[156:159], v[206:209], v[98:101]
	v_mfma_f32_16x16x32_bf16 v[90:93], v[164:167], v[206:209], v[90:93]
	v_mfma_f32_16x16x32_bf16 v[82:85], v[156:159], v[214:217], v[82:85]
	v_mfma_f32_16x16x32_bf16 v[74:77], v[164:167], v[214:217], v[74:77]
	v_mfma_f32_16x16x32_bf16 v[126:129], v[160:163], v[194:197], v[126:129]
	v_mfma_f32_16x16x32_bf16 v[122:125], v[168:171], v[194:197], v[122:125]
	v_mfma_f32_16x16x32_bf16 v[114:117], v[160:163], v[202:205], v[114:117]
	v_mfma_f32_16x16x32_bf16 v[106:109], v[168:171], v[202:205], v[106:109]
	v_mfma_f32_16x16x32_bf16 v[98:101], v[160:163], v[210:213], v[98:101]
	v_mfma_f32_16x16x32_bf16 v[90:93], v[168:171], v[210:213], v[90:93]
	v_mfma_f32_16x16x32_bf16 v[82:85], v[160:163], v[218:221], v[82:85]
	v_mfma_f32_16x16x32_bf16 v[74:77], v[168:171], v[218:221], v[74:77]
	v_mfma_f32_16x16x32_bf16 v[118:121], v[174:177], v[190:193], v[118:121]
	v_mfma_f32_16x16x32_bf16 v[110:113], v[182:185], v[190:193], v[110:113]
	v_mfma_f32_16x16x32_bf16 v[102:105], v[174:177], v[198:201], v[102:105]
	v_mfma_f32_16x16x32_bf16 v[94:97], v[182:185], v[198:201], v[94:97]
	v_mfma_f32_16x16x32_bf16 v[86:89], v[174:177], v[206:209], v[86:89]
	v_mfma_f32_16x16x32_bf16 v[78:81], v[182:185], v[206:209], v[78:81]
	v_mfma_f32_16x16x32_bf16 v[70:73], v[174:177], v[214:217], v[70:73]
	v_mfma_f32_16x16x32_bf16 v[66:69], v[182:185], v[214:217], v[66:69]
	v_mfma_f32_16x16x32_bf16 v[118:121], v[178:181], v[194:197], v[118:121]
	v_mfma_f32_16x16x32_bf16 v[110:113], v[186:189], v[194:197], v[110:113]
	v_mfma_f32_16x16x32_bf16 v[102:105], v[178:181], v[202:205], v[102:105]
	v_mfma_f32_16x16x32_bf16 v[94:97], v[186:189], v[202:205], v[94:97]
	v_mfma_f32_16x16x32_bf16 v[86:89], v[178:181], v[210:213], v[86:89]
	v_mfma_f32_16x16x32_bf16 v[78:81], v[186:189], v[210:213], v[78:81]
	v_mfma_f32_16x16x32_bf16 v[70:73], v[178:181], v[218:221], v[70:73]
	v_mfma_f32_16x16x32_bf16 v[66:69], v[186:189], v[218:221], v[66:69]
	s_barrier
	s_add_i32 s61, s44, s28
	v_lshl_add_u64 v[222:223], s[20:21], 0, v[134:135]
	s_mov_b32 m0, s61
	ds_read_b128 v[190:193], v153 offset:16384
	ds_read_b128 v[194:197], v153 offset:17408
	ds_read_b128 v[198:201], v153 offset:18432
	ds_read_b128 v[202:205], v153 offset:19456
	ds_read_b128 v[206:209], v153 offset:20480
	ds_read_b128 v[210:213], v153 offset:21504
	ds_read_b128 v[214:217], v153 offset:22528
	ds_read_b128 v[218:221], v153 offset:23552
	global_load_lds_dwordx4 v[222:223], off
	s_add_i32 m0, s61, 0x2000
	s_add_u32 s62, s20, 0x40000
	v_lshl_add_u64 v[224:225], s[20:21], 0, v[130:131]
	s_addc_u32 s63, s21, 0
	s_add_i32 s61, s45, s28
	global_load_lds_dwordx4 v[224:225], off
	v_lshl_add_u64 v[226:227], s[62:63], 0, v[134:135]
	s_mov_b32 m0, s61
	v_lshl_add_u64 v[228:229], s[22:23], 0, v[132:133]
	global_load_lds_dwordx4 v[226:227], off
	v_lshl_add_u64 v[226:227], s[62:63], 0, v[130:131]
	s_add_i32 m0, s61, 0x2000
	s_nop 0
	global_load_lds_dwordx4 v[226:227], off
	v_lshl_add_u64 v[226:227], s[22:23], 0, v[136:137]
	s_mov_b32 m0, s31
	s_nop 0
	global_load_lds_dwordx4 v[226:227], off
	s_mov_b32 m0, s33
	s_nop 0
	global_load_lds_dwordx4 v[228:229], off
	s_waitcnt vmcnt(8)
	s_waitcnt lgkmcnt(0)
	s_barrier
; #define PG8_STAGE(bufoff, gbase, voff) do { _Pragma("unroll") for (int _i = 0; _i < 2; ++_i) \
;         __builtin_amdgcn_global_load_lds((const unsigned*)((const char*)(gbase) + (voff)[_i]), (PG8_LAS unsigned*)(lds + (bufoff) + ldsw + _i * 8192), 16, 0, 0); } while (0)
; #define PG8_LDA(dst, b, h) do { _Pragma("unroll") for (int m = 0; m < 4; ++m) _Pragma("unroll") for (int k = 0; k < 2; ++k) dst[m][k] = *(const PG8_LAS bf16x8*)(lds + PG8_SA(b, h) + aoff + m * 2048 + k * 1024); } while (0)
; #define PG8_LDB(dst, b, h) do { _Pragma("unroll") for (int n = 0; n < 2; ++n) _Pragma("unroll") for (int k = 0; k < 2; ++k) dst[n][k] = *(const PG8_LAS bf16x8*)(lds + PG8_SB(b, h) + boff + n * 2048 + k * 1024); } while (0)
; #define PG8_MMA(ai, bj, At, Bt) do { __builtin_amdgcn_s_setprio(1); _Pragma("unroll") for (int m = 0; m < 4; ++m) _Pragma("unroll") for (int n = 0; n < 2; ++n) _Pragma("unroll") for (int k = 0; k < 2; ++k) \
;         acc[ai][bj][m][n] = __builtin_amdgcn_mfma_f32_16x16x32_bf16(Bt[n][k], At[m][k], acc[ai][bj][m][n], 0, 0, 0); __builtin_amdgcn_s_setprio(0); } while (0)
; #define PG8_WAIT_V(n) asm volatile("s_waitcnt vmcnt(" #n ")" ::: "memory")
; #define PG8_WAIT_L(n) asm volatile("s_waitcnt lgkmcnt(" #n ")" ::: "memory")
; #define PG8_BAR __builtin_amdgcn_s_barrier()
; #define PG8_SCHED __builtin_amdgcn_sched_barrier(0)
; template <class Epi, class Sched, bool ALIGN_EPI = false, bool SP2 = false>
; __device__ __forceinline__ void gemm_phase(PG8_LAS unsigned char* lds, const Gemm g, const Sched& S, const Epi& E) {
;     ...
;             PG8_WAIT_V(8); PG8_WAIT_L(0); PG8_BAR; PG8_MMA(1, 0, At, B0); PG8_MMA(1, 1, At, B1); PG8_BAR; PG8_SCHED;
;             PG8_LDB(B0, 1, 0); PG8_LDB(B1, 1, 1); PG8_SCHED; PG8_LDA(At, 1, 0); PG8_STAGE(PG8_SA(0, 1), a2 + hstep, voffA);
;             PG8_WAIT_V(8); PG8_WAIT_L(0); PG8_BAR; PG8_MMA(0, 0, At, B0); PG8_MMA(0, 1, At, B1); PG8_BAR; PG8_SCHED;
	s_waitcnt lgkmcnt(0)
	v_mfma_f32_16x16x32_bf16 v[62:65], v[156:159], v[190:193], v[62:65]
	v_mfma_f32_16x16x32_bf16 v[58:61], v[164:167], v[190:193], v[58:61]
	v_mfma_f32_16x16x32_bf16 v[50:53], v[156:159], v[198:201], v[50:53]
	v_mfma_f32_16x16x32_bf16 v[42:45], v[164:167], v[198:201], v[42:45]
	v_mfma_f32_16x16x32_bf16 v[34:37], v[156:159], v[206:209], v[34:37]
	v_mfma_f32_16x16x32_bf16 v[26:29], v[164:167], v[206:209], v[26:29]
	v_mfma_f32_16x16x32_bf16 v[18:21], v[156:159], v[214:217], v[18:21]
	v_mfma_f32_16x16x32_bf16 v[10:13], v[164:167], v[214:217], v[10:13]
	v_mfma_f32_16x16x32_bf16 v[62:65], v[160:163], v[194:197], v[62:65]
	v_mfma_f32_16x16x32_bf16 v[58:61], v[168:171], v[194:197], v[58:61]
	v_mfma_f32_16x16x32_bf16 v[50:53], v[160:163], v[202:205], v[50:53]
	v_mfma_f32_16x16x32_bf16 v[42:45], v[168:171], v[202:205], v[42:45]
	v_mfma_f32_16x16x32_bf16 v[34:37], v[160:163], v[210:213], v[34:37]
	v_mfma_f32_16x16x32_bf16 v[26:29], v[168:171], v[210:213], v[26:29]
	v_mfma_f32_16x16x32_bf16 v[18:21], v[160:163], v[218:221], v[18:21]
	v_mfma_f32_16x16x32_bf16 v[10:13], v[168:171], v[218:221], v[10:13]
	v_mfma_f32_16x16x32_bf16 v[54:57], v[174:177], v[190:193], v[54:57]
	v_mfma_f32_16x16x32_bf16 v[46:49], v[182:185], v[190:193], v[46:49]
	v_mfma_f32_16x16x32_bf16 v[38:41], v[174:177], v[198:201], v[38:41]
	v_mfma_f32_16x16x32_bf16 v[30:33], v[182:185], v[198:201], v[30:33]
	v_mfma_f32_16x16x32_bf16 v[22:25], v[174:177], v[206:209], v[22:25]
	v_mfma_f32_16x16x32_bf16 v[14:17], v[182:185], v[206:209], v[14:17]
	v_mfma_f32_16x16x32_bf16 v[6:9], v[174:177], v[214:217], v[6:9]
	v_mfma_f32_16x16x32_bf16 v[2:5], v[182:185], v[214:217], v[2:5]
	v_mfma_f32_16x16x32_bf16 v[54:57], v[178:181], v[194:197], v[54:57]
	v_mfma_f32_16x16x32_bf16 v[46:49], v[186:189], v[194:197], v[46:49]
	v_mfma_f32_16x16x32_bf16 v[38:41], v[178:181], v[202:205], v[38:41]
	v_mfma_f32_16x16x32_bf16 v[30:33], v[186:189], v[202:205], v[30:33]
	v_mfma_f32_16x16x32_bf16 v[22:25], v[178:181], v[210:213], v[22:25]
	v_mfma_f32_16x16x32_bf16 v[14:17], v[186:189], v[210:213], v[14:17]
	v_mfma_f32_16x16x32_bf16 v[6:9], v[178:181], v[218:221], v[6:9]
	v_mfma_f32_16x16x32_bf16 v[2:5], v[186:189], v[218:221], v[2:5]
	s_barrier
	s_add_i32 s61, 0, 0x18000
	v_add_u32_e32 v138, s61, v150
	s_add_i32 s62, 0, 0x1c000
	ds_read_b128 v[156:159], v138
	ds_read_b128 v[160:163], v138 offset:1024
	ds_read_b128 v[164:167], v138 offset:2048
	ds_read_b128 v[168:171], v138 offset:3072
	v_add_u32_e32 v138, s62, v150
	ds_read_b128 v[174:177], v138
	ds_read_b128 v[178:181], v138 offset:1024
	ds_read_b128 v[182:185], v138 offset:2048
	ds_read_b128 v[186:189], v138 offset:3072
	s_add_u32 s22, s22, 0x40000
	s_addc_u32 s23, s23, 0
	s_mov_b32 m0, s34
	v_lshl_add_u64 v[230:231], s[22:23], 0, v[136:137]
	ds_read_b128 v[190:193], v153 offset:32768
	ds_read_b128 v[194:197], v153 offset:33792
	ds_read_b128 v[198:201], v153 offset:34816
	ds_read_b128 v[202:205], v153 offset:35840
	ds_read_b128 v[206:209], v153 offset:36864
	ds_read_b128 v[210:213], v153 offset:37888
	ds_read_b128 v[214:217], v153 offset:38912
	ds_read_b128 v[218:221], v153 offset:39936
	global_load_lds_dwordx4 v[230:231], off
	v_lshl_add_u64 v[230:231], s[22:23], 0, v[132:133]
	s_mov_b32 m0, s35
	s_nop 0
	global_load_lds_dwordx4 v[230:231], off
	s_waitcnt vmcnt(8)
	s_waitcnt lgkmcnt(0)
	s_barrier
	s_waitcnt lgkmcnt(0)
	v_mfma_f32_16x16x32_bf16 v[126:129], v[156:159], v[190:193], v[126:129]
	v_mfma_f32_16x16x32_bf16 v[122:125], v[164:167], v[190:193], v[122:125]
	v_mfma_f32_16x16x32_bf16 v[114:117], v[156:159], v[198:201], v[114:117]
	v_mfma_f32_16x16x32_bf16 v[106:109], v[164:167], v[198:201], v[106:109]
	v_mfma_f32_16x16x32_bf16 v[98:101], v[156:159], v[206:209], v[98:101]
	v_mfma_f32_16x16x32_bf16 v[90:93], v[164:167], v[206:209], v[90:93]
	v_mfma_f32_16x16x32_bf16 v[82:85], v[156:159], v[214:217], v[82:85]
	v_mfma_f32_16x16x32_bf16 v[74:77], v[164:167], v[214:217], v[74:77]
	v_mfma_f32_16x16x32_bf16 v[126:129], v[160:163], v[194:197], v[126:129]
	v_mfma_f32_16x16x32_bf16 v[122:125], v[168:171], v[194:197], v[122:125]
	v_mfma_f32_16x16x32_bf16 v[114:117], v[160:163], v[202:205], v[114:117]
	v_mfma_f32_16x16x32_bf16 v[106:109], v[168:171], v[202:205], v[106:109]
	v_mfma_f32_16x16x32_bf16 v[98:101], v[160:163], v[210:213], v[98:101]
	v_mfma_f32_16x16x32_bf16 v[90:93], v[168:171], v[210:213], v[90:93]
	v_mfma_f32_16x16x32_bf16 v[82:85], v[160:163], v[218:221], v[82:85]
	v_mfma_f32_16x16x32_bf16 v[74:77], v[168:171], v[218:221], v[74:77]
	v_mfma_f32_16x16x32_bf16 v[118:121], v[174:177], v[190:193], v[118:121]
	v_mfma_f32_16x16x32_bf16 v[110:113], v[182:185], v[190:193], v[110:113]
	v_mfma_f32_16x16x32_bf16 v[102:105], v[174:177], v[198:201], v[102:105]
	v_mfma_f32_16x16x32_bf16 v[94:97], v[182:185], v[198:201], v[94:97]
	v_mfma_f32_16x16x32_bf16 v[86:89], v[174:177], v[206:209], v[86:89]
	v_mfma_f32_16x16x32_bf16 v[78:81], v[182:185], v[206:209], v[78:81]
	v_mfma_f32_16x16x32_bf16 v[70:73], v[174:177], v[214:217], v[70:73]
	v_mfma_f32_16x16x32_bf16 v[66:69], v[182:185], v[214:217], v[66:69]
	v_mfma_f32_16x16x32_bf16 v[118:121], v[178:181], v[194:197], v[118:121]
	v_mfma_f32_16x16x32_bf16 v[110:113], v[186:189], v[194:197], v[110:113]
	v_mfma_f32_16x16x32_bf16 v[102:105], v[178:181], v[202:205], v[102:105]
	v_mfma_f32_16x16x32_bf16 v[94:97], v[186:189], v[202:205], v[94:97]
	v_mfma_f32_16x16x32_bf16 v[86:89], v[178:181], v[210:213], v[86:89]
	v_mfma_f32_16x16x32_bf16 v[78:81], v[186:189], v[210:213], v[78:81]
	v_mfma_f32_16x16x32_bf16 v[70:73], v[178:181], v[218:221], v[70:73]
	v_mfma_f32_16x16x32_bf16 v[66:69], v[186:189], v[218:221], v[66:69]
	s_barrier
; #define PG8_WAIT_V(n) asm volatile("s_waitcnt vmcnt(" #n ")" ::: "memory")
; template <class Epi, class Sched, bool ALIGN_EPI = false, bool SP2 = false>
; __device__ __forceinline__ void gemm_phase(PG8_LAS unsigned char* lds, const Gemm g, const Sched& S, const Epi& E) {
;     ...
;             PG8_LDA(At, 1, 1); PG8_STAGE(PG8_SB(1, 0), b3, voffB); PG8_STAGE(PG8_SB(1, 1), b3 + hstep, voffB); PG8_STAGE(PG8_SA(1, 0), a3, voffA);
;             PG8_WAIT_V(8); PG8_WAIT_L(0); PG8_BAR; PG8_MMA(1, 0, At, B0); PG8_MMA(1, 1, At, B1); PG8_BAR; PG8_SCHED;
;             } else {
;             PG8_LDB(B0, 0, 0); PG8_SCHED; PG8_LDA(At, 0, 0); PG8_STAGE(PG8_SA(1, 1), a1 + hstep, voffA);
;             PG8_WAIT_L(8); PG8_BAR; PG8_WAIT_L(0); PG8_MMA(0, 0, At, B0); PG8_BAR; PG8_SCHED;
;             PG8_LDB(B1, 0, 1); PG8_STAGE(PG8_SB(0, 0), b2, voffB);
;             PG8_BAR; PG8_WAIT_L(0); PG8_MMA(0, 1, At, B1); PG8_BAR;
;             PG8_LDA(At, 0, 1); PG8_STAGE(PG8_SA(0, 0), a2, voffA);
;             PG8_BAR; PG8_WAIT_L(0); PG8_MMA(1, 0, At, B0); PG8_BAR; PG8_SCHED;
;             PG8_STAGE(PG8_SB(0, 1), b2 + hstep, voffB);
;             PG8_WAIT_V(6); PG8_BAR; PG8_MMA(1, 1, At, B1); PG8_BAR;
;             PG8_LDB(B0, 1, 0); PG8_SCHED; PG8_LDA(At, 1, 0); PG8_STAGE(PG8_SA(0, 1), a2 + hstep, voffA);
;             PG8_WAIT_L(8); PG8_BAR; PG8_WAIT_L(0); PG8_MMA(0, 0, At, B0); PG8_BAR; PG8_SCHED;
;             PG8_LDB(B1, 1, 1); PG8_STAGE(PG8_SB(1, 0), b3, voffB);
;             PG8_BAR; PG8_WAIT_L(0); PG8_MMA(0, 1, At, B1); PG8_BAR;
;             PG8_LDA(At, 1, 1); PG8_STAGE(PG8_SA(1, 0), a3, voffA);
;             PG8_BAR; PG8_WAIT_L(0); PG8_MMA(1, 0, At, B0); PG8_BAR; PG8_SCHED;
;             PG8_STAGE(PG8_SB(1, 1), b3 + hstep, voffB);
;             PG8_WAIT_V(6); PG8_BAR; PG8_MMA(1, 1, At, B1); PG8_BAR;
;             }
;         }
;         if constexpr (ALIGN_EPI) { if (wr == 0) PG8_BAR; }
;     __device__ __forceinline__ void operator()(const f32x4 (&acc)[2][2][4][2], const pg8::Unit& u, int wr, int wc, int fr, int fq) const {
;         const int row0 = u.pm * 256 + wr * 64 + fr, cin = wc * 32 + 8 * fq;
; #pragma unroll
;         for (int ai = 0; ai < 2; ++ai)
; #pragma unroll
;             for (int m = 0; m < 4; ++m) {
;                 const size_t row = (size_t)(row0 + ai * 128 + m * 16);
;                 if constexpr (MODE == EP_SWIGLU) {
	s_add_i32 s22, s61, s28
	v_lshl_add_u64 v[222:223], v[222:223], 0, s[4:5]
	s_mov_b32 m0, s22
	ds_read_b128 v[190:193], v153 offset:49152
	ds_read_b128 v[194:197], v153 offset:50176
	ds_read_b128 v[198:201], v153 offset:51200
	ds_read_b128 v[202:205], v153 offset:52224
	ds_read_b128 v[206:209], v153 offset:53248
	ds_read_b128 v[210:213], v153 offset:54272
	ds_read_b128 v[214:217], v153 offset:55296
	ds_read_b128 v[218:221], v153 offset:56320
	global_load_lds_dwordx4 v[222:223], off
	s_add_i32 m0, s22, 0x2000
	s_add_u32 s20, s20, 0x40080
	v_lshl_add_u64 v[222:223], v[224:225], 0, s[4:5]
	s_addc_u32 s21, s21, 0
	s_add_i32 s22, s62, s28
	global_load_lds_dwordx4 v[222:223], off
	v_lshl_add_u64 v[222:223], s[20:21], 0, v[134:135]
	s_mov_b32 m0, s22
	s_nop 0
	global_load_lds_dwordx4 v[222:223], off
	v_lshl_add_u64 v[222:223], s[20:21], 0, v[130:131]
	s_add_i32 m0, s22, 0x2000
	s_nop 0
	global_load_lds_dwordx4 v[222:223], off
	v_lshl_add_u64 v[222:223], v[226:227], 0, s[4:5]
	s_mov_b32 m0, s39
	s_nop 0
	global_load_lds_dwordx4 v[222:223], off
	v_lshl_add_u64 v[222:223], v[228:229], 0, s[4:5]
	s_mov_b32 m0, s40
	s_nop 0
	global_load_lds_dwordx4 v[222:223], off
	s_waitcnt vmcnt(8)
	s_waitcnt lgkmcnt(0)
	s_barrier
	s_waitcnt lgkmcnt(0)
	v_mfma_f32_16x16x32_bf16 v[62:65], v[156:159], v[190:193], v[62:65]
	v_mfma_f32_16x16x32_bf16 v[58:61], v[164:167], v[190:193], v[58:61]
	v_mfma_f32_16x16x32_bf16 v[50:53], v[156:159], v[198:201], v[50:53]
	v_mfma_f32_16x16x32_bf16 v[42:45], v[164:167], v[198:201], v[42:45]
	v_mfma_f32_16x16x32_bf16 v[34:37], v[156:159], v[206:209], v[34:37]
	v_mfma_f32_16x16x32_bf16 v[26:29], v[164:167], v[206:209], v[26:29]
	v_mfma_f32_16x16x32_bf16 v[18:21], v[156:159], v[214:217], v[18:21]
	v_mfma_f32_16x16x32_bf16 v[10:13], v[164:167], v[214:217], v[10:13]
	v_mfma_f32_16x16x32_bf16 v[62:65], v[160:163], v[194:197], v[62:65]
	v_mfma_f32_16x16x32_bf16 v[58:61], v[168:171], v[194:197], v[58:61]
	v_mfma_f32_16x16x32_bf16 v[50:53], v[160:163], v[202:205], v[50:53]
	v_mfma_f32_16x16x32_bf16 v[42:45], v[168:171], v[202:205], v[42:45]
	v_mfma_f32_16x16x32_bf16 v[34:37], v[160:163], v[210:213], v[34:37]
	v_mfma_f32_16x16x32_bf16 v[26:29], v[168:171], v[210:213], v[26:29]
	v_mfma_f32_16x16x32_bf16 v[18:21], v[160:163], v[218:221], v[18:21]
	v_mfma_f32_16x16x32_bf16 v[10:13], v[168:171], v[218:221], v[10:13]
	v_mfma_f32_16x16x32_bf16 v[54:57], v[174:177], v[190:193], v[54:57]
	v_mfma_f32_16x16x32_bf16 v[46:49], v[182:185], v[190:193], v[46:49]
	v_mfma_f32_16x16x32_bf16 v[38:41], v[174:177], v[198:201], v[38:41]
	v_mfma_f32_16x16x32_bf16 v[30:33], v[182:185], v[198:201], v[30:33]
	v_mfma_f32_16x16x32_bf16 v[22:25], v[174:177], v[206:209], v[22:25]
	v_mfma_f32_16x16x32_bf16 v[14:17], v[182:185], v[206:209], v[14:17]
	v_mfma_f32_16x16x32_bf16 v[6:9], v[174:177], v[214:217], v[6:9]
	v_mfma_f32_16x16x32_bf16 v[2:5], v[182:185], v[214:217], v[2:5]
	v_mfma_f32_16x16x32_bf16 v[54:57], v[178:181], v[194:197], v[54:57]
	v_mfma_f32_16x16x32_bf16 v[46:49], v[186:189], v[194:197], v[46:49]
	v_mfma_f32_16x16x32_bf16 v[38:41], v[178:181], v[202:205], v[38:41]
	v_mfma_f32_16x16x32_bf16 v[30:33], v[186:189], v[202:205], v[30:33]
	v_mfma_f32_16x16x32_bf16 v[22:25], v[178:181], v[210:213], v[22:25]
	v_mfma_f32_16x16x32_bf16 v[14:17], v[186:189], v[210:213], v[14:17]
	v_mfma_f32_16x16x32_bf16 v[6:9], v[178:181], v[218:221], v[6:9]
	v_mfma_f32_16x16x32_bf16 v[2:5], v[186:189], v[218:221], v[2:5]
	s_barrier
	s_add_i32 s60, s60, 2
	s_add_u32 s18, s18, 0x100
	s_addc_u32 s19, s19, 0
	s_add_u32 s56, s56, 0x100
	s_addc_u32 s57, s57, 0
	s_cmp_gt_u32 s60, 13
	s_cbranch_scc0 .LBB0_491
	s_andn2_b64 vcc, s[6:7], s[2:3]
	s_cbranch_vccz .LBB0_494
	s_barrier
.LBB0_494:
	v_lshl_add_u32 v155, s16, 8, v1
	s_ashr_i32 s16, s17, 1
	s_mul_hi_i32 s9, s16, 0x55555556
	s_lshr_b32 s11, s9, 31
	s_add_i32 s9, s9, s11
	s_mul_i32 s9, s9, 3
	s_sub_i32 s9, s16, s9
	s_lshl_b32 s11, s17, 2
	v_ashrrev_i32_e32 v156, 13, v155
	s_and_b32 s17, s11, 4
	s_lshl_b32 s9, s9, 1
	s_lshl_b32 s16, s16, 3
	v_and_b32_e32 v162, 0x1fcf, v155
	v_ashrrev_i32_e32 v157, 31, v156
	s_lshl_b32 s11, -1, s9
	s_or_b32 s16, s17, s16
	v_lshlrev_b64 v[156:157], 13, v[156:157]
	v_bitop3_b32 v138, v155, s11, v154 bitop3:0x20
	v_lshrrev_b32_e32 v158, s9, v162
	s_or_b32 s18, s16, s41
	s_lshr_b32 s20, 0x2000, s9
	s_ashr_i32 s19, s18, 31
	v_mul_u32_u24_e32 v138, s20, v138
	v_or_b32_e32 v158, v156, v158
	v_mov_b32_e32 v159, v157
	s_lshl_b64 s[16:17], s[18:19], 15
	v_lshl_add_u64 v[158:159], v[158:159], 0, v[138:139]
	v_lshl_add_u64 v[160:161], v[158:159], 0, s[16:17]
	s_or_b32 s18, s18, 2
	v_lshlrev_b64 v[160:161], 7, v[160:161]
	s_ashr_i32 s19, s18, 31
	v_lshl_add_u64 v[160:161], v[140:141], 0, v[160:161]
	s_lshl_b64 s[18:19], s[18:19], 15
	v_cvt_pk_bf16_f32 v126, v126, v127
	v_cvt_pk_bf16_f32 v127, v128, v129
	v_cvt_pk_bf16_f32 v128, v122, v123
	v_cvt_pk_bf16_f32 v129, v124, v125
	global_store_dwordx4 v[160:161], v[126:129], off
	v_lshl_add_u64 v[122:123], v[158:159], 0, s[18:19]
	v_cvt_pk_bf16_f32 v118, v118, v119
	v_cvt_pk_bf16_f32 v119, v120, v121
	v_cvt_pk_bf16_f32 v120, v110, v111
	v_or_b32_e32 v110, 16, v162
	v_lshlrev_b64 v[122:123], 7, v[122:123]
	v_bitop3_b32 v111, v162, s11, 16 bitop3:0x32
	v_lshrrev_b32_e32 v110, s9, v110
	v_lshl_add_u64 v[122:123], v[140:141], 0, v[122:123]
	v_mul_u32_u24_e32 v138, s20, v111
	v_or_b32_e32 v110, v156, v110
	v_mov_b32_e32 v111, v157
	v_cvt_pk_bf16_f32 v121, v112, v113
	global_store_dwordx4 v[122:123], v[118:121], off
	s_andn2_b64 vcc, exec, s[2:3]
	s_mov_b64 s[2:3], -1
	v_lshl_add_u64 v[118:119], v[110:111], 0, v[138:139]
	v_lshl_add_u64 v[110:111], v[118:119], 0, s[16:17]
; template <class Epi, class Sched, bool ALIGN_EPI = false, bool SP2 = false>
; __device__ __forceinline__ void gemm_phase(PG8_LAS unsigned char* lds, const Gemm g, const Sched& S, const Epi& E) {
;     ...
;         if (!has_next) break;
; #pragma unroll
;         for (int a = 0; a < 2; ++a)
; #pragma unroll
;             for (int b = 0; b < 2; ++b)
; #pragma unroll
;                 for (int m = 0; m < 4; ++m)
; #pragma unroll
;                     for (int n = 0; n < 2; ++n) acc[a][b][m][n] = (f32x4){0.f, 0.f, 0.f, 0.f};
;         cur = nxt; cA = nA; cB = nB; ++ui;
;     __device__ __forceinline__ void operator()(const f32x4 (&acc)[2][2][4][2], const pg8::Unit& u, int wr, int wc, int fr, int fq) const {
;     ...
;                 const size_t row = (size_t)(row0 + ai * 128 + m * 16);
;                 if constexpr (MODE == EP_SWIGLU) {
;                     const f32x4 g0 = acc[ai][0][m][0], g1 = acc[ai][0][m][1], u0 = acc[ai][1][m][0], u1 = acc[ai][1][m][1];
;                     float r[8];
; #pragma unroll
;                     for (int j = 0; j < 4; ++j) { r[j] = g0[j] * sigmoidf_(g0[j]) * u0[j]; r[4 + j] = g1[j] * sigmoidf_(g1[j]) * u1[j]; }
;                     u32x4 w; w.x = cvt_pk_bf16(r[0], r[1]); w.y = cvt_pk_bf16(r[2], r[3]); w.z = cvt_pk_bf16(r[4], r[5]); w.w = cvt_pk_bf16(r[6], r[7]);
;                     *(u32x4*)(O + row * ldc + u.pn * 128 + cin) = w;
;                 } else {
; #pragma unroll
;                     for (int bj = 0; bj < 2; ++bj) {
;                         const int col = u.pn * 256 + bj * 128 + cin;
;                         const f32x4 a0 = acc[ai][bj][m][0], a1 = acc[ai][bj][m][1];
;                         float r[8] = {a0[0], a0[1], a0[2], a0[3], a1[0], a1[1], a1[2], a1[3]};
;                         bf16_t* dst = O + row * ldc + col;
;                         if constexpr (MODE == EP_SPLIT) { if (col >= 3072) dst = O2 + row * 768 + (col - 3072); }
;                         if constexpr (MODE == EP_QKV) {
;                             const int sg = u.pn >> 1, g = sg % 3, hh = (u.pn & 1) * 4 + ((bj * 128 + cin) >> 6), dd = cin & 63;
;                             const int bb = (int)(row >> 13), t = (int)row & (T - 1), dsh = 2 * g, r = t & ((1 << dsh) - 1), uu = t >> dsh;
;                             dst = O + ((((size_t)(sg * 8 + hh) * 4 + bb) * T + (size_t)r * (T >> dsh) + uu) << 6) + dd;
;                         }
	v_lshlrev_b64 v[110:111], 7, v[110:111]
	v_lshl_add_u64 v[120:121], v[140:141], 0, v[110:111]
	v_cvt_pk_bf16_f32 v110, v114, v115
	v_cvt_pk_bf16_f32 v111, v116, v117
	v_cvt_pk_bf16_f32 v112, v106, v107
	v_cvt_pk_bf16_f32 v113, v108, v109
	global_store_dwordx4 v[120:121], v[110:113], off
	v_lshl_add_u64 v[106:107], v[118:119], 0, s[18:19]
	v_cvt_pk_bf16_f32 v102, v102, v103
	v_cvt_pk_bf16_f32 v103, v104, v105
	v_cvt_pk_bf16_f32 v104, v94, v95
	v_or_b32_e32 v94, 32, v162
	v_lshlrev_b64 v[106:107], 7, v[106:107]
	v_bitop3_b32 v95, v162, s11, 32 bitop3:0x32
	v_lshrrev_b32_e32 v94, s9, v94
	v_lshl_add_u64 v[106:107], v[140:141], 0, v[106:107]
	v_mul_u32_u24_e32 v138, s20, v95
	v_or_b32_e32 v94, v156, v94
	v_mov_b32_e32 v95, v157
	v_cvt_pk_bf16_f32 v105, v96, v97
	global_store_dwordx4 v[106:107], v[102:105], off
	s_nop 1
	v_lshl_add_u64 v[102:103], v[94:95], 0, v[138:139]
	v_lshl_add_u64 v[94:95], v[102:103], 0, s[16:17]
	v_lshlrev_b64 v[94:95], 7, v[94:95]
	v_lshl_add_u64 v[104:105], v[140:141], 0, v[94:95]
	v_cvt_pk_bf16_f32 v94, v98, v99
	v_cvt_pk_bf16_f32 v95, v100, v101
	v_cvt_pk_bf16_f32 v96, v90, v91
	v_cvt_pk_bf16_f32 v97, v92, v93
	global_store_dwordx4 v[104:105], v[94:97], off
	v_lshl_add_u64 v[90:91], v[102:103], 0, s[18:19]
	v_cvt_pk_bf16_f32 v86, v86, v87
	v_cvt_pk_bf16_f32 v87, v88, v89
	v_cvt_pk_bf16_f32 v88, v78, v79
	v_or_b32_e32 v78, 48, v162
	v_lshlrev_b64 v[90:91], 7, v[90:91]
	v_bitop3_b32 v79, v162, s11, 48 bitop3:0x32
	v_lshrrev_b32_e32 v78, s9, v78
	v_lshl_add_u64 v[90:91], v[140:141], 0, v[90:91]
	v_mul_u32_u24_e32 v138, s20, v79
	v_or_b32_e32 v156, v156, v78
	v_cvt_pk_bf16_f32 v89, v80, v81
	global_store_dwordx4 v[90:91], v[86:89], off
	s_nop 1
	v_lshl_add_u64 v[86:87], v[156:157], 0, v[138:139]
	v_lshl_add_u64 v[78:79], v[86:87], 0, s[16:17]
	v_lshlrev_b64 v[78:79], 7, v[78:79]
	v_lshl_add_u64 v[88:89], v[140:141], 0, v[78:79]
	v_cvt_pk_bf16_f32 v78, v82, v83
	v_cvt_pk_bf16_f32 v79, v84, v85
	v_cvt_pk_bf16_f32 v80, v74, v75
	v_lshl_add_u64 v[74:75], v[86:87], 0, s[18:19]
	v_cvt_pk_bf16_f32 v81, v76, v77
	global_store_dwordx4 v[88:89], v[78:81], off
	v_lshlrev_b64 v[74:75], 7, v[74:75]
	v_cvt_pk_bf16_f32 v70, v70, v71
	v_cvt_pk_bf16_f32 v71, v72, v73
	v_cvt_pk_bf16_f32 v72, v66, v67
	v_cvt_pk_bf16_f32 v73, v68, v69
	v_add_u32_e32 v68, 0x80, v155
	v_lshl_add_u64 v[74:75], v[140:141], 0, v[74:75]
	v_ashrrev_i32_e32 v66, 13, v68
	global_store_dwordx4 v[74:75], v[70:73], off
	v_ashrrev_i32_e32 v67, 31, v66
	v_lshlrev_b64 v[66:67], 13, v[66:67]
	v_and_b32_e32 v72, 0x1fcf, v68
	v_bitop3_b32 v68, v68, s11, v154 bitop3:0x20
	v_lshrrev_b32_e32 v69, s9, v72
	v_mul_u32_u24_e32 v138, s20, v68
	v_or_b32_e32 v68, v66, v69
	v_mov_b32_e32 v69, v67
	v_lshl_add_u64 v[68:69], v[68:69], 0, v[138:139]
	v_lshl_add_u64 v[70:71], v[68:69], 0, s[16:17]
	v_lshlrev_b64 v[70:71], 7, v[70:71]
	v_lshl_add_u64 v[70:71], v[140:141], 0, v[70:71]
	v_cvt_pk_bf16_f32 v62, v62, v63
	v_cvt_pk_bf16_f32 v63, v64, v65
	v_cvt_pk_bf16_f32 v64, v58, v59
	v_cvt_pk_bf16_f32 v65, v60, v61
	global_store_dwordx4 v[70:71], v[62:65], off
	v_lshl_add_u64 v[58:59], v[68:69], 0, s[18:19]
	v_cvt_pk_bf16_f32 v54, v54, v55
	v_cvt_pk_bf16_f32 v55, v56, v57
	v_cvt_pk_bf16_f32 v56, v46, v47
	v_or_b32_e32 v46, 16, v72
	v_lshlrev_b64 v[58:59], 7, v[58:59]
	v_bitop3_b32 v47, v72, s11, 16 bitop3:0x32
	v_lshrrev_b32_e32 v46, s9, v46
	v_lshl_add_u64 v[58:59], v[140:141], 0, v[58:59]
	v_mul_u32_u24_e32 v138, s20, v47
	v_or_b32_e32 v46, v66, v46
	v_mov_b32_e32 v47, v67
	v_cvt_pk_bf16_f32 v57, v48, v49
	global_store_dwordx4 v[58:59], v[54:57], off
	s_nop 1
	v_lshl_add_u64 v[54:55], v[46:47], 0, v[138:139]
	v_lshl_add_u64 v[46:47], v[54:55], 0, s[16:17]
	v_lshlrev_b64 v[46:47], 7, v[46:47]
	v_lshl_add_u64 v[56:57], v[140:141], 0, v[46:47]
	v_cvt_pk_bf16_f32 v46, v50, v51
	v_cvt_pk_bf16_f32 v47, v52, v53
	v_cvt_pk_bf16_f32 v48, v42, v43
	v_cvt_pk_bf16_f32 v49, v44, v45
	global_store_dwordx4 v[56:57], v[46:49], off
	v_lshl_add_u64 v[42:43], v[54:55], 0, s[18:19]
	v_cvt_pk_bf16_f32 v38, v38, v39
	v_cvt_pk_bf16_f32 v39, v40, v41
	v_cvt_pk_bf16_f32 v40, v30, v31
	v_or_b32_e32 v30, 32, v72
	v_lshlrev_b64 v[42:43], 7, v[42:43]
	v_bitop3_b32 v31, v72, s11, 32 bitop3:0x32
	v_lshrrev_b32_e32 v30, s9, v30
	v_lshl_add_u64 v[42:43], v[140:141], 0, v[42:43]
	v_mul_u32_u24_e32 v138, s20, v31
	v_or_b32_e32 v30, v66, v30
	v_mov_b32_e32 v31, v67
	v_cvt_pk_bf16_f32 v41, v32, v33
	global_store_dwordx4 v[42:43], v[38:41], off
	s_nop 1
	v_lshl_add_u64 v[38:39], v[30:31], 0, v[138:139]
	v_lshl_add_u64 v[30:31], v[38:39], 0, s[16:17]
	v_lshlrev_b64 v[30:31], 7, v[30:31]
	v_lshl_add_u64 v[40:41], v[140:141], 0, v[30:31]
	v_cvt_pk_bf16_f32 v30, v34, v35
	v_cvt_pk_bf16_f32 v31, v36, v37
	v_cvt_pk_bf16_f32 v32, v26, v27
	v_cvt_pk_bf16_f32 v33, v28, v29
	global_store_dwordx4 v[40:41], v[30:33], off
	v_lshl_add_u64 v[26:27], v[38:39], 0, s[18:19]
	v_cvt_pk_bf16_f32 v22, v22, v23
	v_cvt_pk_bf16_f32 v23, v24, v25
	v_cvt_pk_bf16_f32 v24, v14, v15
	v_or_b32_e32 v14, 48, v72
	v_lshlrev_b64 v[26:27], 7, v[26:27]
	v_bitop3_b32 v15, v72, s11, 48 bitop3:0x32
	v_lshrrev_b32_e32 v14, s9, v14
	v_lshl_add_u64 v[26:27], v[140:141], 0, v[26:27]
	v_mul_u32_u24_e32 v138, s20, v15
	v_or_b32_e32 v66, v66, v14
	v_cvt_pk_bf16_f32 v25, v16, v17
	global_store_dwordx4 v[26:27], v[22:25], off
	s_nop 1
	v_lshl_add_u64 v[22:23], v[66:67], 0, v[138:139]
	v_lshl_add_u64 v[14:15], v[22:23], 0, s[16:17]
	v_lshlrev_b64 v[14:15], 7, v[14:15]
	v_lshl_add_u64 v[24:25], v[140:141], 0, v[14:15]
	v_cvt_pk_bf16_f32 v14, v18, v19
	v_cvt_pk_bf16_f32 v15, v20, v21
	v_cvt_pk_bf16_f32 v16, v10, v11
	v_lshl_add_u64 v[10:11], v[22:23], 0, s[18:19]
	v_lshlrev_b64 v[10:11], 7, v[10:11]
	v_lshl_add_u64 v[10:11], v[140:141], 0, v[10:11]
	v_cvt_pk_bf16_f32 v17, v12, v13
	global_store_dwordx4 v[24:25], v[14:17], off
	v_cvt_pk_bf16_f32 v6, v6, v7
	v_cvt_pk_bf16_f32 v7, v8, v9
	v_cvt_pk_bf16_f32 v8, v2, v3
	v_cvt_pk_bf16_f32 v9, v4, v5
	global_store_dwordx4 v[10:11], v[6:9], off
	s_cbranch_vccnz .LBB0_487
	s_andn2_b64 vcc, exec, s[0:1]
	s_cbranch_vccnz .LBB0_486
	s_branch .LBB0_486

; #define PG8_STAGE(bufoff, gbase, voff) do { _Pragma("unroll") for (int _i = 0; _i < 2; ++_i) \
;         __builtin_amdgcn_global_load_lds((const unsigned*)((const char*)(gbase) + (voff)[_i]), (PG8_LAS unsigned*)(lds + (bufoff) + ldsw + _i * 8192), 16, 0, 0); } while (0)
; #define PG8_LDA(dst, b, h) do { _Pragma("unroll") for (int m = 0; m < 4; ++m) _Pragma("unroll") for (int k = 0; k < 2; ++k) dst[m][k] = *(const PG8_LAS bf16x8*)(lds + PG8_SA(b, h) + aoff + m * 2048 + k * 1024); } while (0)
; #define PG8_LDB(dst, b, h) do { _Pragma("unroll") for (int n = 0; n < 2; ++n) _Pragma("unroll") for (int k = 0; k < 2; ++k) dst[n][k] = *(const PG8_LAS bf16x8*)(lds + PG8_SB(b, h) + boff + n * 2048 + k * 1024); } while (0)
; #define PG8_MMA(ai, bj, At, Bt) do { __builtin_amdgcn_s_setprio(1); _Pragma("unroll") for (int m = 0; m < 4; ++m) _Pragma("unroll") for (int n = 0; n < 2; ++n) _Pragma("unroll") for (int k = 0; k < 2; ++k) \
;         acc[ai][bj][m][n] = __builtin_amdgcn_mfma_f32_16x16x32_bf16(Bt[n][k], At[m][k], acc[ai][bj][m][n], 0, 0, 0); __builtin_amdgcn_s_setprio(0); } while (0)
; #define PG8_WAIT_V(n) asm volatile("s_waitcnt vmcnt(" #n ")" ::: "memory")
; #define PG8_WAIT_L(n) asm volatile("s_waitcnt lgkmcnt(" #n ")" ::: "memory")
; template <class Epi, class Sched, bool ALIGN_EPI = false, bool SP2 = false>
; __device__ __forceinline__ void gemm_phase(PG8_LAS unsigned char* lds, const Gemm g, const Sched& S, const Epi& E) {
;     ...
;             const bool last = (t == nt - 2);
;             const char* a1 = cA + (size_t)(t + 1) * kstep;
;             const char* a2 = last ? nA : cA + (size_t)(t + 2) * kstep; const char* b2 = last ? nB : cB + (size_t)(t + 2) * kstep;
;             const char* a3 = a2 + kstep; const char* b3 = b2 + kstep;
;             if (last && has_next) S.a_ready(nxt);
;             if constexpr (SP2) {
;             PG8_LDB(B0, 0, 0); PG8_LDB(B1, 0, 1); PG8_SCHED; PG8_LDA(At, 0, 0); PG8_STAGE(PG8_SA(1, 1), a1 + hstep, voffA);
;             PG8_WAIT_V(8); PG8_WAIT_L(0); PG8_BAR; PG8_MMA(0, 0, At, B0); PG8_MMA(0, 1, At, B1); PG8_BAR; PG8_SCHED;
;             PG8_LDA(At, 0, 1); PG8_STAGE(PG8_SB(0, 0), b2, voffB); PG8_STAGE(PG8_SB(0, 1), b2 + hstep, voffB); PG8_STAGE(PG8_SA(0, 0), a2, voffA);
;             PG8_WAIT_V(8); PG8_WAIT_L(0); PG8_BAR; PG8_MMA(1, 0, At, B0); PG8_MMA(1, 1, At, B1); PG8_BAR; PG8_SCHED;
.LBB0_689:
	ds_read_b128 v[148:151], v157
	ds_read_b128 v[152:155], v157 offset:1024
	ds_read_b128 v[160:163], v157 offset:2048
	ds_read_b128 v[164:167], v157 offset:3072
	ds_read_b128 v[168:171], v158
	ds_read_b128 v[174:177], v158 offset:1024
	ds_read_b128 v[178:181], v158 offset:2048
	ds_read_b128 v[182:185], v158 offset:3072
	s_add_u32 s30, s28, 0xfffc0080
	s_addc_u32 s31, s29, -1
	s_cmp_eq_u32 s74, 12
	s_cselect_b32 s35, s23, s31
	s_cselect_b32 s34, s70, s30
	s_cselect_b32 s31, s21, s73
	s_cselect_b32 s30, s71, s72
	v_lshl_add_u64 v[218:219], s[28:29], 0, v[140:141]
	s_add_i32 m0, s44, 0xc000
	ds_read_b128 v[186:189], v159
	ds_read_b128 v[190:193], v159 offset:1024
	ds_read_b128 v[194:197], v159 offset:2048
	ds_read_b128 v[198:201], v159 offset:3072
	ds_read_b128 v[202:205], v159 offset:4096
	ds_read_b128 v[206:209], v159 offset:5120
	ds_read_b128 v[210:213], v159 offset:6144
	ds_read_b128 v[214:217], v159 offset:7168
	global_load_lds_dwordx4 v[218:219], off
	v_lshl_add_u64 v[218:219], s[28:29], 0, v[142:143]
	s_add_i32 m0, s44, 0xe000
	s_nop 0
	global_load_lds_dwordx4 v[218:219], off
	s_waitcnt vmcnt(8)
	s_waitcnt lgkmcnt(0)
	s_barrier
	s_waitcnt lgkmcnt(0)
	v_mfma_f32_16x16x32_bf16 v[126:129], v[148:151], v[186:189], v[126:129]
	v_mfma_f32_16x16x32_bf16 v[122:125], v[160:163], v[186:189], v[122:125]
	v_mfma_f32_16x16x32_bf16 v[114:117], v[148:151], v[194:197], v[114:117]
	v_mfma_f32_16x16x32_bf16 v[106:109], v[160:163], v[194:197], v[106:109]
	v_mfma_f32_16x16x32_bf16 v[98:101], v[148:151], v[202:205], v[98:101]
	v_mfma_f32_16x16x32_bf16 v[90:93], v[160:163], v[202:205], v[90:93]
	v_mfma_f32_16x16x32_bf16 v[82:85], v[148:151], v[210:213], v[82:85]
	v_mfma_f32_16x16x32_bf16 v[74:77], v[160:163], v[210:213], v[74:77]
	v_mfma_f32_16x16x32_bf16 v[126:129], v[152:155], v[190:193], v[126:129]
	v_mfma_f32_16x16x32_bf16 v[122:125], v[164:167], v[190:193], v[122:125]
	v_mfma_f32_16x16x32_bf16 v[114:117], v[152:155], v[198:201], v[114:117]
	v_mfma_f32_16x16x32_bf16 v[106:109], v[164:167], v[198:201], v[106:109]
	v_mfma_f32_16x16x32_bf16 v[98:101], v[152:155], v[206:209], v[98:101]
	v_mfma_f32_16x16x32_bf16 v[90:93], v[164:167], v[206:209], v[90:93]
	v_mfma_f32_16x16x32_bf16 v[82:85], v[152:155], v[214:217], v[82:85]
	v_mfma_f32_16x16x32_bf16 v[74:77], v[164:167], v[214:217], v[74:77]
	v_mfma_f32_16x16x32_bf16 v[118:121], v[168:171], v[186:189], v[118:121]
	v_mfma_f32_16x16x32_bf16 v[110:113], v[178:181], v[186:189], v[110:113]
	v_mfma_f32_16x16x32_bf16 v[102:105], v[168:171], v[194:197], v[102:105]
	v_mfma_f32_16x16x32_bf16 v[94:97], v[178:181], v[194:197], v[94:97]
	v_mfma_f32_16x16x32_bf16 v[86:89], v[168:171], v[202:205], v[86:89]
	v_mfma_f32_16x16x32_bf16 v[78:81], v[178:181], v[202:205], v[78:81]
	v_mfma_f32_16x16x32_bf16 v[70:73], v[168:171], v[210:213], v[70:73]
	v_mfma_f32_16x16x32_bf16 v[66:69], v[178:181], v[210:213], v[66:69]
	v_mfma_f32_16x16x32_bf16 v[118:121], v[174:177], v[190:193], v[118:121]
	v_mfma_f32_16x16x32_bf16 v[110:113], v[182:185], v[190:193], v[110:113]
	v_mfma_f32_16x16x32_bf16 v[102:105], v[174:177], v[198:201], v[102:105]
	v_mfma_f32_16x16x32_bf16 v[94:97], v[182:185], v[198:201], v[94:97]
	v_mfma_f32_16x16x32_bf16 v[86:89], v[174:177], v[206:209], v[86:89]
	v_mfma_f32_16x16x32_bf16 v[78:81], v[182:185], v[206:209], v[78:81]
	v_mfma_f32_16x16x32_bf16 v[70:73], v[174:177], v[214:217], v[70:73]
	v_mfma_f32_16x16x32_bf16 v[66:69], v[182:185], v[214:217], v[66:69]
	s_barrier
	s_add_i32 s75, s63, s41
	v_lshl_add_u64 v[218:219], s[30:31], 0, v[136:137]
	s_mov_b32 m0, s75
	ds_read_b128 v[186:189], v159 offset:16384
	ds_read_b128 v[190:193], v159 offset:17408
	ds_read_b128 v[194:197], v159 offset:18432
	ds_read_b128 v[198:201], v159 offset:19456
	ds_read_b128 v[202:205], v159 offset:20480
	ds_read_b128 v[206:209], v159 offset:21504
	ds_read_b128 v[210:213], v159 offset:22528
	ds_read_b128 v[214:217], v159 offset:23552
	global_load_lds_dwordx4 v[218:219], off
	s_add_i32 m0, s75, 0x2000
	s_add_u32 s76, s30, 0x40000
	v_lshl_add_u64 v[220:221], s[30:31], 0, v[132:133]
	s_addc_u32 s77, s31, 0
	s_add_i32 s75, s66, s41
	global_load_lds_dwordx4 v[220:221], off
	v_lshl_add_u64 v[222:223], s[76:77], 0, v[136:137]
	s_mov_b32 m0, s75
	v_lshl_add_u64 v[224:225], s[34:35], 0, v[134:135]
	global_load_lds_dwordx4 v[222:223], off
	v_lshl_add_u64 v[222:223], s[76:77], 0, v[132:133]
	s_add_i32 m0, s75, 0x2000
	s_nop 0
	global_load_lds_dwordx4 v[222:223], off
	v_lshl_add_u64 v[222:223], s[34:35], 0, v[138:139]
	s_mov_b32 m0, s44
	s_nop 0
	global_load_lds_dwordx4 v[222:223], off
	s_mov_b32 m0, s45
	s_nop 0
	global_load_lds_dwordx4 v[224:225], off
	s_waitcnt vmcnt(8)
	s_waitcnt lgkmcnt(0)
	s_barrier
; #define PG8_STAGE(bufoff, gbase, voff) do { _Pragma("unroll") for (int _i = 0; _i < 2; ++_i) \
;         __builtin_amdgcn_global_load_lds((const unsigned*)((const char*)(gbase) + (voff)[_i]), (PG8_LAS unsigned*)(lds + (bufoff) + ldsw + _i * 8192), 16, 0, 0); } while (0)
; #define PG8_LDA(dst, b, h) do { _Pragma("unroll") for (int m = 0; m < 4; ++m) _Pragma("unroll") for (int k = 0; k < 2; ++k) dst[m][k] = *(const PG8_LAS bf16x8*)(lds + PG8_SA(b, h) + aoff + m * 2048 + k * 1024); } while (0)
; #define PG8_LDB(dst, b, h) do { _Pragma("unroll") for (int n = 0; n < 2; ++n) _Pragma("unroll") for (int k = 0; k < 2; ++k) dst[n][k] = *(const PG8_LAS bf16x8*)(lds + PG8_SB(b, h) + boff + n * 2048 + k * 1024); } while (0)
; #define PG8_MMA(ai, bj, At, Bt) do { __builtin_amdgcn_s_setprio(1); _Pragma("unroll") for (int m = 0; m < 4; ++m) _Pragma("unroll") for (int n = 0; n < 2; ++n) _Pragma("unroll") for (int k = 0; k < 2; ++k) \
;         acc[ai][bj][m][n] = __builtin_amdgcn_mfma_f32_16x16x32_bf16(Bt[n][k], At[m][k], acc[ai][bj][m][n], 0, 0, 0); __builtin_amdgcn_s_setprio(0); } while (0)
; #define PG8_WAIT_V(n) asm volatile("s_waitcnt vmcnt(" #n ")" ::: "memory")
; #define PG8_WAIT_L(n) asm volatile("s_waitcnt lgkmcnt(" #n ")" ::: "memory")
; #define PG8_BAR __builtin_amdgcn_s_barrier()
; #define PG8_SCHED __builtin_amdgcn_sched_barrier(0)
; template <class Epi, class Sched, bool ALIGN_EPI = false, bool SP2 = false>
; __device__ __forceinline__ void gemm_phase(PG8_LAS unsigned char* lds, const Gemm g, const Sched& S, const Epi& E) {
;     ...
;             PG8_WAIT_V(8); PG8_WAIT_L(0); PG8_BAR; PG8_MMA(1, 0, At, B0); PG8_MMA(1, 1, At, B1); PG8_BAR; PG8_SCHED;
;             PG8_LDB(B0, 1, 0); PG8_LDB(B1, 1, 1); PG8_SCHED; PG8_LDA(At, 1, 0); PG8_STAGE(PG8_SA(0, 1), a2 + hstep, voffA);
;             PG8_WAIT_V(8); PG8_WAIT_L(0); PG8_BAR; PG8_MMA(0, 0, At, B0); PG8_MMA(0, 1, At, B1); PG8_BAR; PG8_SCHED;
	s_waitcnt lgkmcnt(0)
	v_mfma_f32_16x16x32_bf16 v[62:65], v[148:151], v[186:189], v[62:65]
	v_mfma_f32_16x16x32_bf16 v[58:61], v[160:163], v[186:189], v[58:61]
	v_mfma_f32_16x16x32_bf16 v[50:53], v[148:151], v[194:197], v[50:53]
	v_mfma_f32_16x16x32_bf16 v[42:45], v[160:163], v[194:197], v[42:45]
	v_mfma_f32_16x16x32_bf16 v[34:37], v[148:151], v[202:205], v[34:37]
	v_mfma_f32_16x16x32_bf16 v[26:29], v[160:163], v[202:205], v[26:29]
	v_mfma_f32_16x16x32_bf16 v[18:21], v[148:151], v[210:213], v[18:21]
	v_mfma_f32_16x16x32_bf16 v[10:13], v[160:163], v[210:213], v[10:13]
	v_mfma_f32_16x16x32_bf16 v[62:65], v[152:155], v[190:193], v[62:65]
	v_mfma_f32_16x16x32_bf16 v[58:61], v[164:167], v[190:193], v[58:61]
	v_mfma_f32_16x16x32_bf16 v[50:53], v[152:155], v[198:201], v[50:53]
	v_mfma_f32_16x16x32_bf16 v[42:45], v[164:167], v[198:201], v[42:45]
	v_mfma_f32_16x16x32_bf16 v[34:37], v[152:155], v[206:209], v[34:37]
	v_mfma_f32_16x16x32_bf16 v[26:29], v[164:167], v[206:209], v[26:29]
	v_mfma_f32_16x16x32_bf16 v[18:21], v[152:155], v[214:217], v[18:21]
	v_mfma_f32_16x16x32_bf16 v[10:13], v[164:167], v[214:217], v[10:13]
	v_mfma_f32_16x16x32_bf16 v[54:57], v[168:171], v[186:189], v[54:57]
	v_mfma_f32_16x16x32_bf16 v[46:49], v[178:181], v[186:189], v[46:49]
	v_mfma_f32_16x16x32_bf16 v[38:41], v[168:171], v[194:197], v[38:41]
	v_mfma_f32_16x16x32_bf16 v[30:33], v[178:181], v[194:197], v[30:33]
	v_mfma_f32_16x16x32_bf16 v[22:25], v[168:171], v[202:205], v[22:25]
	v_mfma_f32_16x16x32_bf16 v[14:17], v[178:181], v[202:205], v[14:17]
	v_mfma_f32_16x16x32_bf16 v[6:9], v[168:171], v[210:213], v[6:9]
	v_mfma_f32_16x16x32_bf16 v[2:5], v[178:181], v[210:213], v[2:5]
	v_mfma_f32_16x16x32_bf16 v[54:57], v[174:177], v[190:193], v[54:57]
	v_mfma_f32_16x16x32_bf16 v[46:49], v[182:185], v[190:193], v[46:49]
	v_mfma_f32_16x16x32_bf16 v[38:41], v[174:177], v[198:201], v[38:41]
	v_mfma_f32_16x16x32_bf16 v[30:33], v[182:185], v[198:201], v[30:33]
	v_mfma_f32_16x16x32_bf16 v[22:25], v[174:177], v[206:209], v[22:25]
	v_mfma_f32_16x16x32_bf16 v[14:17], v[182:185], v[206:209], v[14:17]
	v_mfma_f32_16x16x32_bf16 v[6:9], v[174:177], v[214:217], v[6:9]
	v_mfma_f32_16x16x32_bf16 v[2:5], v[182:185], v[214:217], v[2:5]
	s_barrier
	s_add_i32 s75, 0, 0x18000
	s_add_i32 s76, 0, 0x1c000
	v_add_u32_e32 v164, s75, v131
	v_add_u32_e32 v182, s76, v131
	ds_read_b128 v[148:151], v164
	ds_read_b128 v[152:155], v164 offset:1024
	ds_read_b128 v[160:163], v164 offset:2048
	ds_read_b128 v[164:167], v164 offset:3072
	ds_read_b128 v[168:171], v182
	ds_read_b128 v[174:177], v182 offset:1024
	ds_read_b128 v[178:181], v182 offset:2048
	ds_read_b128 v[182:185], v182 offset:3072
	s_add_u32 s34, s34, 0x40000
	s_addc_u32 s35, s35, 0
	s_mov_b32 m0, s52
	v_lshl_add_u64 v[226:227], s[34:35], 0, v[138:139]
	ds_read_b128 v[186:189], v159 offset:32768
	ds_read_b128 v[190:193], v159 offset:33792
	ds_read_b128 v[194:197], v159 offset:34816
	ds_read_b128 v[198:201], v159 offset:35840
	ds_read_b128 v[202:205], v159 offset:36864
	ds_read_b128 v[206:209], v159 offset:37888
	ds_read_b128 v[210:213], v159 offset:38912
	ds_read_b128 v[214:217], v159 offset:39936
	global_load_lds_dwordx4 v[226:227], off
	v_lshl_add_u64 v[226:227], s[34:35], 0, v[134:135]
	s_mov_b32 m0, s53
	s_nop 0
	global_load_lds_dwordx4 v[226:227], off
	s_waitcnt vmcnt(8)
	s_waitcnt lgkmcnt(0)
	s_barrier
	s_waitcnt lgkmcnt(0)
	v_mfma_f32_16x16x32_bf16 v[126:129], v[148:151], v[186:189], v[126:129]
	v_mfma_f32_16x16x32_bf16 v[122:125], v[160:163], v[186:189], v[122:125]
	v_mfma_f32_16x16x32_bf16 v[114:117], v[148:151], v[194:197], v[114:117]
	v_mfma_f32_16x16x32_bf16 v[106:109], v[160:163], v[194:197], v[106:109]
	v_mfma_f32_16x16x32_bf16 v[98:101], v[148:151], v[202:205], v[98:101]
	v_mfma_f32_16x16x32_bf16 v[90:93], v[160:163], v[202:205], v[90:93]
	v_mfma_f32_16x16x32_bf16 v[82:85], v[148:151], v[210:213], v[82:85]
	v_mfma_f32_16x16x32_bf16 v[74:77], v[160:163], v[210:213], v[74:77]
	v_mfma_f32_16x16x32_bf16 v[126:129], v[152:155], v[190:193], v[126:129]
	v_mfma_f32_16x16x32_bf16 v[122:125], v[164:167], v[190:193], v[122:125]
	v_mfma_f32_16x16x32_bf16 v[114:117], v[152:155], v[198:201], v[114:117]
	v_mfma_f32_16x16x32_bf16 v[106:109], v[164:167], v[198:201], v[106:109]
	v_mfma_f32_16x16x32_bf16 v[98:101], v[152:155], v[206:209], v[98:101]
	v_mfma_f32_16x16x32_bf16 v[90:93], v[164:167], v[206:209], v[90:93]
	v_mfma_f32_16x16x32_bf16 v[82:85], v[152:155], v[214:217], v[82:85]
	v_mfma_f32_16x16x32_bf16 v[74:77], v[164:167], v[214:217], v[74:77]
	v_mfma_f32_16x16x32_bf16 v[118:121], v[168:171], v[186:189], v[118:121]
	v_mfma_f32_16x16x32_bf16 v[110:113], v[178:181], v[186:189], v[110:113]
	v_mfma_f32_16x16x32_bf16 v[102:105], v[168:171], v[194:197], v[102:105]
	v_mfma_f32_16x16x32_bf16 v[94:97], v[178:181], v[194:197], v[94:97]
	v_mfma_f32_16x16x32_bf16 v[86:89], v[168:171], v[202:205], v[86:89]
	v_mfma_f32_16x16x32_bf16 v[78:81], v[178:181], v[202:205], v[78:81]
	v_mfma_f32_16x16x32_bf16 v[70:73], v[168:171], v[210:213], v[70:73]
	v_mfma_f32_16x16x32_bf16 v[66:69], v[178:181], v[210:213], v[66:69]
	v_mfma_f32_16x16x32_bf16 v[118:121], v[174:177], v[190:193], v[118:121]
	v_mfma_f32_16x16x32_bf16 v[110:113], v[182:185], v[190:193], v[110:113]
	v_mfma_f32_16x16x32_bf16 v[102:105], v[174:177], v[198:201], v[102:105]
	v_mfma_f32_16x16x32_bf16 v[94:97], v[182:185], v[198:201], v[94:97]
	v_mfma_f32_16x16x32_bf16 v[86:89], v[174:177], v[206:209], v[86:89]
	v_mfma_f32_16x16x32_bf16 v[78:81], v[182:185], v[206:209], v[78:81]
	v_mfma_f32_16x16x32_bf16 v[70:73], v[174:177], v[214:217], v[70:73]
	v_mfma_f32_16x16x32_bf16 v[66:69], v[182:185], v[214:217], v[66:69]
	s_barrier
; #define PG8_BAR __builtin_amdgcn_s_barrier()
; template <class Epi, class Sched, bool ALIGN_EPI = false, bool SP2 = false>
; __device__ __forceinline__ void gemm_phase(PG8_LAS unsigned char* lds, const Gemm g, const Sched& S, const Epi& E) {
;     ...
;             PG8_LDA(At, 1, 1); PG8_STAGE(PG8_SB(1, 0), b3, voffB); PG8_STAGE(PG8_SB(1, 1), b3 + hstep, voffB); PG8_STAGE(PG8_SA(1, 0), a3, voffA);
;             PG8_WAIT_V(8); PG8_WAIT_L(0); PG8_BAR; PG8_MMA(1, 0, At, B0); PG8_MMA(1, 1, At, B1); PG8_BAR; PG8_SCHED;
;             } else {
;             PG8_LDB(B0, 0, 0); PG8_SCHED; PG8_LDA(At, 0, 0); PG8_STAGE(PG8_SA(1, 1), a1 + hstep, voffA);
;             PG8_WAIT_L(8); PG8_BAR; PG8_WAIT_L(0); PG8_MMA(0, 0, At, B0); PG8_BAR; PG8_SCHED;
;             PG8_LDB(B1, 0, 1); PG8_STAGE(PG8_SB(0, 0), b2, voffB);
;             PG8_BAR; PG8_WAIT_L(0); PG8_MMA(0, 1, At, B1); PG8_BAR;
;             PG8_LDA(At, 0, 1); PG8_STAGE(PG8_SA(0, 0), a2, voffA);
;             PG8_BAR; PG8_WAIT_L(0); PG8_MMA(1, 0, At, B0); PG8_BAR; PG8_SCHED;
;             PG8_STAGE(PG8_SB(0, 1), b2 + hstep, voffB);
;             PG8_WAIT_V(6); PG8_BAR; PG8_MMA(1, 1, At, B1); PG8_BAR;
;             PG8_LDB(B0, 1, 0); PG8_SCHED; PG8_LDA(At, 1, 0); PG8_STAGE(PG8_SA(0, 1), a2 + hstep, voffA);
;             PG8_WAIT_L(8); PG8_BAR; PG8_WAIT_L(0); PG8_MMA(0, 0, At, B0); PG8_BAR; PG8_SCHED;
;             PG8_LDB(B1, 1, 1); PG8_STAGE(PG8_SB(1, 0), b3, voffB);
;             PG8_BAR; PG8_WAIT_L(0); PG8_MMA(0, 1, At, B1); PG8_BAR;
;             PG8_LDA(At, 1, 1); PG8_STAGE(PG8_SA(1, 0), a3, voffA);
;             PG8_BAR; PG8_WAIT_L(0); PG8_MMA(1, 0, At, B0); PG8_BAR; PG8_SCHED;
;             PG8_STAGE(PG8_SB(1, 1), b3 + hstep, voffB);
;             PG8_WAIT_V(6); PG8_BAR; PG8_MMA(1, 1, At, B1); PG8_BAR;
;             }
;         }
;         if constexpr (ALIGN_EPI) { if (wr == 0) PG8_BAR; }
;     __device__ __forceinline__ void operator()(const f32x4 (&acc)[2][2][4][2], const pg8::Unit& u, int wr, int wc, int fr, int fq) const {
;     ...
; #pragma unroll
;                     for (int bj = 0; bj < 2; ++bj) {
;                         const int col = u.pn * 256 + bj * 128 + cin;
;                         const f32x4 a0 = acc[ai][bj][m][0], a1 = acc[ai][bj][m][1];
;                         float r[8] = {a0[0], a0[1], a0[2], a0[3], a1[0], a1[1], a1[2], a1[3]};
;                         bf16_t* dst = O + row * ldc + col;
	s_add_i32 s34, s75, s41
	v_lshl_add_u64 v[218:219], v[218:219], 0, s[10:11]
	s_mov_b32 m0, s34
	ds_read_b128 v[186:189], v159 offset:49152
	ds_read_b128 v[190:193], v159 offset:50176
	ds_read_b128 v[194:197], v159 offset:51200
	ds_read_b128 v[198:201], v159 offset:52224
	ds_read_b128 v[202:205], v159 offset:53248
	ds_read_b128 v[206:209], v159 offset:54272
	ds_read_b128 v[210:213], v159 offset:55296
	ds_read_b128 v[214:217], v159 offset:56320
	global_load_lds_dwordx4 v[218:219], off
	s_add_i32 m0, s34, 0x2000
	s_add_u32 s30, s30, 0x40080
	v_lshl_add_u64 v[218:219], v[220:221], 0, s[10:11]
	s_addc_u32 s31, s31, 0
	s_add_i32 s34, s76, s41
	global_load_lds_dwordx4 v[218:219], off
	v_lshl_add_u64 v[218:219], s[30:31], 0, v[136:137]
	s_mov_b32 m0, s34
	s_nop 0
	global_load_lds_dwordx4 v[218:219], off
	v_lshl_add_u64 v[218:219], s[30:31], 0, v[132:133]
	s_add_i32 m0, s34, 0x2000
	s_nop 0
	global_load_lds_dwordx4 v[218:219], off
	v_lshl_add_u64 v[218:219], v[222:223], 0, s[10:11]
	s_mov_b32 m0, s57
	s_nop 0
	global_load_lds_dwordx4 v[218:219], off
	v_lshl_add_u64 v[218:219], v[224:225], 0, s[10:11]
	s_mov_b32 m0, s60
	s_nop 0
	global_load_lds_dwordx4 v[218:219], off
	s_waitcnt vmcnt(8)
	s_waitcnt lgkmcnt(0)
	s_barrier
	s_waitcnt lgkmcnt(0)
	v_mfma_f32_16x16x32_bf16 v[62:65], v[148:151], v[186:189], v[62:65]
	v_mfma_f32_16x16x32_bf16 v[58:61], v[160:163], v[186:189], v[58:61]
	v_mfma_f32_16x16x32_bf16 v[50:53], v[148:151], v[194:197], v[50:53]
	v_mfma_f32_16x16x32_bf16 v[42:45], v[160:163], v[194:197], v[42:45]
	v_mfma_f32_16x16x32_bf16 v[34:37], v[148:151], v[202:205], v[34:37]
	v_mfma_f32_16x16x32_bf16 v[26:29], v[160:163], v[202:205], v[26:29]
	v_mfma_f32_16x16x32_bf16 v[18:21], v[148:151], v[210:213], v[18:21]
	v_mfma_f32_16x16x32_bf16 v[10:13], v[160:163], v[210:213], v[10:13]
	v_mfma_f32_16x16x32_bf16 v[62:65], v[152:155], v[190:193], v[62:65]
	v_mfma_f32_16x16x32_bf16 v[58:61], v[164:167], v[190:193], v[58:61]
	v_mfma_f32_16x16x32_bf16 v[50:53], v[152:155], v[198:201], v[50:53]
	v_mfma_f32_16x16x32_bf16 v[42:45], v[164:167], v[198:201], v[42:45]
	v_mfma_f32_16x16x32_bf16 v[34:37], v[152:155], v[206:209], v[34:37]
	v_mfma_f32_16x16x32_bf16 v[26:29], v[164:167], v[206:209], v[26:29]
	v_mfma_f32_16x16x32_bf16 v[18:21], v[152:155], v[214:217], v[18:21]
	v_mfma_f32_16x16x32_bf16 v[10:13], v[164:167], v[214:217], v[10:13]
	v_mfma_f32_16x16x32_bf16 v[54:57], v[168:171], v[186:189], v[54:57]
	v_mfma_f32_16x16x32_bf16 v[46:49], v[178:181], v[186:189], v[46:49]
	v_mfma_f32_16x16x32_bf16 v[38:41], v[168:171], v[194:197], v[38:41]
	v_mfma_f32_16x16x32_bf16 v[30:33], v[178:181], v[194:197], v[30:33]
	v_mfma_f32_16x16x32_bf16 v[22:25], v[168:171], v[202:205], v[22:25]
	v_mfma_f32_16x16x32_bf16 v[14:17], v[178:181], v[202:205], v[14:17]
	v_mfma_f32_16x16x32_bf16 v[6:9], v[168:171], v[210:213], v[6:9]
	v_mfma_f32_16x16x32_bf16 v[2:5], v[178:181], v[210:213], v[2:5]
	v_mfma_f32_16x16x32_bf16 v[54:57], v[174:177], v[190:193], v[54:57]
	v_mfma_f32_16x16x32_bf16 v[46:49], v[182:185], v[190:193], v[46:49]
	v_mfma_f32_16x16x32_bf16 v[38:41], v[174:177], v[198:201], v[38:41]
	v_mfma_f32_16x16x32_bf16 v[30:33], v[182:185], v[198:201], v[30:33]
	v_mfma_f32_16x16x32_bf16 v[22:25], v[174:177], v[206:209], v[22:25]
	v_mfma_f32_16x16x32_bf16 v[14:17], v[182:185], v[206:209], v[14:17]
	v_mfma_f32_16x16x32_bf16 v[6:9], v[174:177], v[214:217], v[6:9]
	v_mfma_f32_16x16x32_bf16 v[2:5], v[182:185], v[214:217], v[2:5]
	s_barrier
	s_add_i32 s74, s74, 2
	s_add_u32 s28, s28, 0x100
	s_addc_u32 s29, s29, 0
	s_add_u32 s72, s72, 0x100
	s_addc_u32 s73, s73, 0
	s_cmp_gt_u32 s74, 13
	s_cbranch_scc0 .LBB0_689
	s_andn2_b64 vcc, s[12:13], s[2:3]
	s_cbranch_vccz .LBB0_692
	s_barrier
.LBB0_692:
	v_lshl_or_b32 v160, s5, 8, v156
	v_lshl_add_u32 v168, s4, 8, v1
	v_mov_b64_e32 v[148:149], s[6:7]
	v_ashrrev_i32_e32 v161, 31, v160
	v_mad_i64_i32 v[152:153], s[4:5], v168, s67, v[148:149]
	v_lshlrev_b64 v[150:151], 1, v[160:161]
	v_lshl_add_u64 v[162:163], v[152:153], 0, v[150:151]
	v_mov_b64_e32 v[152:153], s[8:9]
	v_mov_b32_e32 v161, v137
	v_mad_i64_i32 v[164:165], s[4:5], v168, s69, v[152:153]
	v_lshlrev_b64 v[154:155], 1, v[160:161]
	v_lshl_add_u64 v[164:165], v[164:165], 0, v[154:155]
	v_lshl_add_u64 v[166:167], v[164:165], 0, s[16:17]
	v_cmp_lt_i32_e32 vcc, s68, v160
	v_cvt_pk_bf16_f32 v126, v126, v127
	v_cvt_pk_bf16_f32 v127, v128, v129
	v_cvt_pk_bf16_f32 v128, v122, v123
	v_cvt_pk_bf16_f32 v129, v124, v125
	v_lshl_add_u64 v[122:123], v[162:163], 0, s[14:15]
	s_nop 0
	v_cndmask_b32_e32 v167, v163, v167, vcc
	v_cndmask_b32_e32 v166, v162, v166, vcc
	global_store_dwordx4 v[166:167], v[126:129], off
	v_lshl_add_u64 v[124:125], v[164:165], 0, s[18:19]
	v_cvt_pk_bf16_f32 v118, v118, v119
	v_cvt_pk_bf16_f32 v119, v120, v121
	v_cvt_pk_bf16_f32 v120, v110, v111
	v_cvt_pk_bf16_f32 v121, v112, v113
	s_nop 0
	v_or_b32_e32 v126, 0x80, v160
	v_cmp_lt_i32_e64 s[4:5], s68, v126
	v_or_b32_e32 v112, 16, v168
	v_mad_i64_i32 v[110:111], s[28:29], v112, s67, v[148:149]
	v_cndmask_b32_e64 v123, v123, v125, s[4:5]
	v_cndmask_b32_e64 v122, v122, v124, s[4:5]
	global_store_dwordx4 v[122:123], v[118:121], off
	s_nop 1
	v_lshl_add_u64 v[118:119], v[110:111], 0, v[150:151]
	v_mad_i64_i32 v[110:111], s[28:29], v112, s69, v[152:153]
	v_lshl_add_u64 v[120:121], v[110:111], 0, v[154:155]
	v_lshl_add_u64 v[110:111], v[120:121], 0, s[16:17]
	v_cndmask_b32_e32 v123, v119, v111, vcc
	v_cndmask_b32_e32 v122, v118, v110, vcc
	v_cvt_pk_bf16_f32 v110, v114, v115
	v_cvt_pk_bf16_f32 v111, v116, v117
	v_cvt_pk_bf16_f32 v112, v106, v107
	v_cvt_pk_bf16_f32 v113, v108, v109
	global_store_dwordx4 v[122:123], v[110:113], off
; #define PG8_BAR __builtin_amdgcn_s_barrier()
; template <class Epi, class Sched, bool ALIGN_EPI = false, bool SP2 = false>
; __device__ __forceinline__ void gemm_phase(PG8_LAS unsigned char* lds, const Gemm g, const Sched& S, const Epi& E) {
;     ...
;         if (!has_next) break;
; #pragma unroll
;         for (int a = 0; a < 2; ++a)
; #pragma unroll
;             for (int b = 0; b < 2; ++b)
; #pragma unroll
;                 for (int m = 0; m < 4; ++m)
; #pragma unroll
;                     for (int n = 0; n < 2; ++n) acc[a][b][m][n] = (f32x4){0.f, 0.f, 0.f, 0.f};
;         cur = nxt; cA = nA; cB = nB; ++ui;
;         if constexpr (ALIGN_EPI) { if (wr == 1) PG8_BAR; }
;     __device__ __forceinline__ void operator()(const f32x4 (&acc)[2][2][4][2], const pg8::Unit& u, int wr, int wc, int fr, int fq) const {
;     ...
; #pragma unroll
;                     for (int bj = 0; bj < 2; ++bj) {
;                         const int col = u.pn * 256 + bj * 128 + cin;
;                         const f32x4 a0 = acc[ai][bj][m][0], a1 = acc[ai][bj][m][1];
;                         float r[8] = {a0[0], a0[1], a0[2], a0[3], a1[0], a1[1], a1[2], a1[3]};
;                         bf16_t* dst = O + row * ldc + col;
;                         if constexpr (MODE == EP_SPLIT) { if (col >= 3072) dst = O2 + row * 768 + (col - 3072); }
	v_lshl_add_u64 v[106:107], v[118:119], 0, s[14:15]
	v_lshl_add_u64 v[108:109], v[120:121], 0, s[18:19]
	v_cvt_pk_bf16_f32 v102, v102, v103
	v_cvt_pk_bf16_f32 v103, v104, v105
	v_cvt_pk_bf16_f32 v104, v94, v95
	v_cvt_pk_bf16_f32 v105, v96, v97
	v_or_b32_e32 v96, 32, v168
	v_cndmask_b32_e64 v107, v107, v109, s[4:5]
	v_cndmask_b32_e64 v106, v106, v108, s[4:5]
	v_mad_i64_i32 v[94:95], s[28:29], v96, s67, v[148:149]
	global_store_dwordx4 v[106:107], v[102:105], off
	s_nop 1
	v_lshl_add_u64 v[102:103], v[94:95], 0, v[150:151]
	v_mad_i64_i32 v[94:95], s[28:29], v96, s69, v[152:153]
	v_lshl_add_u64 v[104:105], v[94:95], 0, v[154:155]
	v_lshl_add_u64 v[94:95], v[104:105], 0, s[16:17]
	v_cndmask_b32_e32 v107, v103, v95, vcc
	v_cndmask_b32_e32 v106, v102, v94, vcc
	v_cvt_pk_bf16_f32 v94, v98, v99
	v_cvt_pk_bf16_f32 v95, v100, v101
	v_cvt_pk_bf16_f32 v96, v90, v91
	v_cvt_pk_bf16_f32 v97, v92, v93
	global_store_dwordx4 v[106:107], v[94:97], off
	v_lshl_add_u64 v[90:91], v[102:103], 0, s[14:15]
	v_lshl_add_u64 v[92:93], v[104:105], 0, s[18:19]
	v_cvt_pk_bf16_f32 v86, v86, v87
	v_cvt_pk_bf16_f32 v87, v88, v89
	v_cvt_pk_bf16_f32 v88, v78, v79
	v_cvt_pk_bf16_f32 v89, v80, v81
	v_or_b32_e32 v80, 48, v168
	v_cndmask_b32_e64 v91, v91, v93, s[4:5]
	v_cndmask_b32_e64 v90, v90, v92, s[4:5]
	v_mad_i64_i32 v[78:79], s[28:29], v80, s67, v[148:149]
	global_store_dwordx4 v[90:91], v[86:89], off
	s_nop 1
	v_lshl_add_u64 v[86:87], v[78:79], 0, v[150:151]
	v_mad_i64_i32 v[78:79], s[28:29], v80, s69, v[152:153]
	v_lshl_add_u64 v[88:89], v[78:79], 0, v[154:155]
	v_lshl_add_u64 v[78:79], v[88:89], 0, s[16:17]
	v_cndmask_b32_e32 v91, v87, v79, vcc
	v_cndmask_b32_e32 v90, v86, v78, vcc
	v_cvt_pk_bf16_f32 v78, v82, v83
	v_cvt_pk_bf16_f32 v79, v84, v85
	v_cvt_pk_bf16_f32 v80, v74, v75
	v_cvt_pk_bf16_f32 v81, v76, v77
	global_store_dwordx4 v[90:91], v[78:81], off
	v_cvt_pk_bf16_f32 v70, v70, v71
	v_cvt_pk_bf16_f32 v71, v72, v73
	v_cvt_pk_bf16_f32 v72, v66, v67
	v_cvt_pk_bf16_f32 v73, v68, v69
	v_add_u32_e32 v68, 0x80, v168
	v_lshl_add_u64 v[74:75], v[86:87], 0, s[14:15]
	v_lshl_add_u64 v[76:77], v[88:89], 0, s[18:19]
	v_mad_i64_i32 v[66:67], s[28:29], v68, s67, v[148:149]
	v_mad_i64_i32 v[68:69], s[28:29], v68, s69, v[152:153]
	v_cndmask_b32_e64 v75, v75, v77, s[4:5]
	v_cndmask_b32_e64 v74, v74, v76, s[4:5]
	v_lshl_add_u64 v[68:69], v[68:69], 0, v[154:155]
	global_store_dwordx4 v[74:75], v[70:73], off
	v_lshl_add_u64 v[66:67], v[66:67], 0, v[150:151]
	v_cvt_pk_bf16_f32 v62, v62, v63
	v_cvt_pk_bf16_f32 v63, v64, v65
	v_cvt_pk_bf16_f32 v64, v58, v59
	v_cvt_pk_bf16_f32 v65, v60, v61
	s_nop 0
	v_lshl_add_u64 v[70:71], v[68:69], 0, s[16:17]
	v_cndmask_b32_e32 v71, v67, v71, vcc
	v_cndmask_b32_e32 v70, v66, v70, vcc
	global_store_dwordx4 v[70:71], v[62:65], off
	v_lshl_add_u64 v[58:59], v[66:67], 0, s[14:15]
	v_lshl_add_u64 v[60:61], v[68:69], 0, s[18:19]
	v_cvt_pk_bf16_f32 v54, v54, v55
	v_cvt_pk_bf16_f32 v55, v56, v57
	v_cvt_pk_bf16_f32 v56, v46, v47
	v_cvt_pk_bf16_f32 v57, v48, v49
	v_add_u32_e32 v48, 0x90, v168
	v_cndmask_b32_e64 v59, v59, v61, s[4:5]
	v_cndmask_b32_e64 v58, v58, v60, s[4:5]
	v_mad_i64_i32 v[46:47], s[28:29], v48, s67, v[148:149]
	global_store_dwordx4 v[58:59], v[54:57], off
	s_nop 1
	v_lshl_add_u64 v[54:55], v[46:47], 0, v[150:151]
	v_mad_i64_i32 v[46:47], s[28:29], v48, s69, v[152:153]
	v_lshl_add_u64 v[56:57], v[46:47], 0, v[154:155]
	v_lshl_add_u64 v[46:47], v[56:57], 0, s[16:17]
	v_cndmask_b32_e32 v59, v55, v47, vcc
	v_cndmask_b32_e32 v58, v54, v46, vcc
	v_cvt_pk_bf16_f32 v46, v50, v51
	v_cvt_pk_bf16_f32 v47, v52, v53
	v_cvt_pk_bf16_f32 v48, v42, v43
	v_cvt_pk_bf16_f32 v49, v44, v45
	global_store_dwordx4 v[58:59], v[46:49], off
	v_lshl_add_u64 v[42:43], v[54:55], 0, s[14:15]
	v_lshl_add_u64 v[44:45], v[56:57], 0, s[18:19]
	v_cvt_pk_bf16_f32 v38, v38, v39
	v_cvt_pk_bf16_f32 v39, v40, v41
	v_cvt_pk_bf16_f32 v40, v30, v31
	v_cvt_pk_bf16_f32 v41, v32, v33
	v_add_u32_e32 v32, 0xa0, v168
	v_cndmask_b32_e64 v43, v43, v45, s[4:5]
	v_cndmask_b32_e64 v42, v42, v44, s[4:5]
	v_mad_i64_i32 v[30:31], s[28:29], v32, s67, v[148:149]
	global_store_dwordx4 v[42:43], v[38:41], off
	s_nop 1
	v_lshl_add_u64 v[38:39], v[30:31], 0, v[150:151]
	v_mad_i64_i32 v[30:31], s[28:29], v32, s69, v[152:153]
	v_lshl_add_u64 v[40:41], v[30:31], 0, v[154:155]
	v_lshl_add_u64 v[30:31], v[40:41], 0, s[16:17]
	v_cndmask_b32_e32 v43, v39, v31, vcc
	v_cndmask_b32_e32 v42, v38, v30, vcc
	v_cvt_pk_bf16_f32 v30, v34, v35
	v_cvt_pk_bf16_f32 v31, v36, v37
	v_cvt_pk_bf16_f32 v32, v26, v27
	v_cvt_pk_bf16_f32 v33, v28, v29
	global_store_dwordx4 v[42:43], v[30:33], off
	v_lshl_add_u64 v[26:27], v[38:39], 0, s[14:15]
	v_lshl_add_u64 v[28:29], v[40:41], 0, s[18:19]
	v_cvt_pk_bf16_f32 v22, v22, v23
	v_cvt_pk_bf16_f32 v23, v24, v25
	v_cvt_pk_bf16_f32 v24, v14, v15
	v_cvt_pk_bf16_f32 v25, v16, v17
	v_add_u32_e32 v16, 0xb0, v168
	v_cndmask_b32_e64 v27, v27, v29, s[4:5]
	v_cndmask_b32_e64 v26, v26, v28, s[4:5]
	v_mad_i64_i32 v[14:15], s[28:29], v16, s67, v[148:149]
	global_store_dwordx4 v[26:27], v[22:25], off
	s_nop 1
	v_lshl_add_u64 v[22:23], v[14:15], 0, v[150:151]
	v_mad_i64_i32 v[14:15], s[28:29], v16, s69, v[152:153]
	v_lshl_add_u64 v[24:25], v[14:15], 0, v[154:155]
	v_lshl_add_u64 v[14:15], v[24:25], 0, s[16:17]
	v_cndmask_b32_e32 v27, v23, v15, vcc
	v_cndmask_b32_e32 v26, v22, v14, vcc
	v_cvt_pk_bf16_f32 v14, v18, v19
	v_cvt_pk_bf16_f32 v15, v20, v21
	v_cvt_pk_bf16_f32 v16, v10, v11
	v_cvt_pk_bf16_f32 v17, v12, v13
	v_lshl_add_u64 v[10:11], v[22:23], 0, s[14:15]
	v_lshl_add_u64 v[12:13], v[24:25], 0, s[18:19]
	v_cndmask_b32_e64 v11, v11, v13, s[4:5]
	v_cndmask_b32_e64 v10, v10, v12, s[4:5]
	s_andn2_b64 vcc, exec, s[2:3]
	s_mov_b64 s[2:3], -1
	global_store_dwordx4 v[26:27], v[14:17], off
	v_cvt_pk_bf16_f32 v6, v6, v7
	v_cvt_pk_bf16_f32 v7, v8, v9
	v_cvt_pk_bf16_f32 v8, v2, v3
	v_cvt_pk_bf16_f32 v9, v4, v5
	global_store_dwordx4 v[10:11], v[6:9], off
	s_cbranch_vccnz .LBB0_685
	s_andn2_b64 vcc, exec, s[0:1]
	s_cbranch_vccnz .LBB0_684
	s_branch .LBB0_684

; #define PG8_STAGE(bufoff, gbase, voff) do { _Pragma("unroll") for (int _i = 0; _i < 2; ++_i) \
;         __builtin_amdgcn_global_load_lds((const unsigned*)((const char*)(gbase) + (voff)[_i]), (PG8_LAS unsigned*)(lds + (bufoff) + ldsw + _i * 8192), 16, 0, 0); } while (0)
; #define PG8_LDA(dst, b, h) do { _Pragma("unroll") for (int m = 0; m < 4; ++m) _Pragma("unroll") for (int k = 0; k < 2; ++k) dst[m][k] = *(const PG8_LAS bf16x8*)(lds + PG8_SA(b, h) + aoff + m * 2048 + k * 1024); } while (0)
; #define PG8_LDB(dst, b, h) do { _Pragma("unroll") for (int n = 0; n < 2; ++n) _Pragma("unroll") for (int k = 0; k < 2; ++k) dst[n][k] = *(const PG8_LAS bf16x8*)(lds + PG8_SB(b, h) + boff + n * 2048 + k * 1024); } while (0)
; #define PG8_MMA(ai, bj, At, Bt) do { __builtin_amdgcn_s_setprio(1); _Pragma("unroll") for (int m = 0; m < 4; ++m) _Pragma("unroll") for (int n = 0; n < 2; ++n) _Pragma("unroll") for (int k = 0; k < 2; ++k) \
;         acc[ai][bj][m][n] = __builtin_amdgcn_mfma_f32_16x16x32_bf16(Bt[n][k], At[m][k], acc[ai][bj][m][n], 0, 0, 0); __builtin_amdgcn_s_setprio(0); } while (0)
; #define PG8_WAIT_V(n) asm volatile("s_waitcnt vmcnt(" #n ")" ::: "memory")
; #define PG8_WAIT_L(n) asm volatile("s_waitcnt lgkmcnt(" #n ")" ::: "memory")
; template <class Epi, class Sched, bool ALIGN_EPI = false, bool SP2 = false>
; __device__ __forceinline__ void gemm_phase(PG8_LAS unsigned char* lds, const Gemm g, const Sched& S, const Epi& E) {
;     ...
;             const bool last = (t == nt - 2);
;             const char* a1 = cA + (size_t)(t + 1) * kstep;
;             const char* a2 = last ? nA : cA + (size_t)(t + 2) * kstep; const char* b2 = last ? nB : cB + (size_t)(t + 2) * kstep;
;             const char* a3 = a2 + kstep; const char* b3 = b2 + kstep;
;             if (last && has_next) S.a_ready(nxt);
;             if constexpr (SP2) {
;             PG8_LDB(B0, 0, 0); PG8_LDB(B1, 0, 1); PG8_SCHED; PG8_LDA(At, 0, 0); PG8_STAGE(PG8_SA(1, 1), a1 + hstep, voffA);
;             PG8_WAIT_V(8); PG8_WAIT_L(0); PG8_BAR; PG8_MMA(0, 0, At, B0); PG8_MMA(0, 1, At, B1); PG8_BAR; PG8_SCHED;
;             PG8_LDA(At, 0, 1); PG8_STAGE(PG8_SB(0, 0), b2, voffB); PG8_STAGE(PG8_SB(0, 1), b2 + hstep, voffB); PG8_STAGE(PG8_SA(0, 0), a2, voffA);
;             PG8_WAIT_V(8); PG8_WAIT_L(0); PG8_BAR; PG8_MMA(1, 0, At, B0); PG8_MMA(1, 1, At, B1); PG8_BAR; PG8_SCHED;
.LBB0_1221:
	ds_read_b128 v[154:157], v150
	ds_read_b128 v[158:161], v150 offset:1024
	ds_read_b128 v[162:165], v150 offset:2048
	ds_read_b128 v[166:169], v150 offset:3072
	ds_read_b128 v[174:177], v151
	ds_read_b128 v[178:181], v151 offset:1024
	ds_read_b128 v[182:185], v151 offset:2048
	ds_read_b128 v[186:189], v151 offset:3072
	s_add_u32 s40, s38, 0xfffc0080
	s_addc_u32 s41, s39, -1
	s_cmp_eq_u32 s71, 12
	s_cselect_b32 s43, s29, s41
	s_cselect_b32 s42, s67, s40
	s_cselect_b32 s41, s27, s70
	s_cselect_b32 s40, s68, s69
	v_lshl_add_u64 v[146:147], s[38:39], 0, v[138:139]
	s_add_i32 m0, s55, 0xc000
	ds_read_b128 v[190:193], v152
	ds_read_b128 v[194:197], v152 offset:1024
	ds_read_b128 v[198:201], v152 offset:2048
	ds_read_b128 v[202:205], v152 offset:3072
	ds_read_b128 v[206:209], v152 offset:4096
	ds_read_b128 v[210:213], v152 offset:5120
	ds_read_b128 v[214:217], v152 offset:6144
	ds_read_b128 v[218:221], v152 offset:7168
	global_load_lds_dwordx4 v[146:147], off
	v_lshl_add_u64 v[146:147], s[38:39], 0, v[140:141]
	s_add_i32 m0, s55, 0xe000
	s_nop 0
	global_load_lds_dwordx4 v[146:147], off
	s_waitcnt vmcnt(8)
	s_waitcnt lgkmcnt(0)
	s_barrier
	s_waitcnt lgkmcnt(0)
	v_mfma_f32_16x16x32_bf16 v[126:129], v[154:157], v[190:193], v[126:129]
	v_mfma_f32_16x16x32_bf16 v[122:125], v[162:165], v[190:193], v[122:125]
	v_mfma_f32_16x16x32_bf16 v[110:113], v[154:157], v[198:201], v[110:113]
	v_mfma_f32_16x16x32_bf16 v[106:109], v[162:165], v[198:201], v[106:109]
	v_mfma_f32_16x16x32_bf16 v[94:97], v[154:157], v[206:209], v[94:97]
	v_mfma_f32_16x16x32_bf16 v[90:93], v[162:165], v[206:209], v[90:93]
	v_mfma_f32_16x16x32_bf16 v[78:81], v[154:157], v[214:217], v[78:81]
	v_mfma_f32_16x16x32_bf16 v[74:77], v[162:165], v[214:217], v[74:77]
	v_mfma_f32_16x16x32_bf16 v[126:129], v[158:161], v[194:197], v[126:129]
	v_mfma_f32_16x16x32_bf16 v[122:125], v[166:169], v[194:197], v[122:125]
	v_mfma_f32_16x16x32_bf16 v[110:113], v[158:161], v[202:205], v[110:113]
	v_mfma_f32_16x16x32_bf16 v[106:109], v[166:169], v[202:205], v[106:109]
	v_mfma_f32_16x16x32_bf16 v[94:97], v[158:161], v[210:213], v[94:97]
	v_mfma_f32_16x16x32_bf16 v[90:93], v[166:169], v[210:213], v[90:93]
	v_mfma_f32_16x16x32_bf16 v[78:81], v[158:161], v[218:221], v[78:81]
	v_mfma_f32_16x16x32_bf16 v[74:77], v[166:169], v[218:221], v[74:77]
	v_mfma_f32_16x16x32_bf16 v[118:121], v[174:177], v[190:193], v[118:121]
	v_mfma_f32_16x16x32_bf16 v[114:117], v[182:185], v[190:193], v[114:117]
	v_mfma_f32_16x16x32_bf16 v[102:105], v[174:177], v[198:201], v[102:105]
	v_mfma_f32_16x16x32_bf16 v[98:101], v[182:185], v[198:201], v[98:101]
	v_mfma_f32_16x16x32_bf16 v[86:89], v[174:177], v[206:209], v[86:89]
	v_mfma_f32_16x16x32_bf16 v[82:85], v[182:185], v[206:209], v[82:85]
	v_mfma_f32_16x16x32_bf16 v[70:73], v[174:177], v[214:217], v[70:73]
	v_mfma_f32_16x16x32_bf16 v[66:69], v[182:185], v[214:217], v[66:69]
	v_mfma_f32_16x16x32_bf16 v[118:121], v[178:181], v[194:197], v[118:121]
	v_mfma_f32_16x16x32_bf16 v[114:117], v[186:189], v[194:197], v[114:117]
	v_mfma_f32_16x16x32_bf16 v[102:105], v[178:181], v[202:205], v[102:105]
	v_mfma_f32_16x16x32_bf16 v[98:101], v[186:189], v[202:205], v[98:101]
	v_mfma_f32_16x16x32_bf16 v[86:89], v[178:181], v[210:213], v[86:89]
	v_mfma_f32_16x16x32_bf16 v[82:85], v[186:189], v[210:213], v[82:85]
	v_mfma_f32_16x16x32_bf16 v[70:73], v[178:181], v[218:221], v[70:73]
	v_mfma_f32_16x16x32_bf16 v[66:69], v[186:189], v[218:221], v[66:69]
	s_barrier
	s_add_i32 s72, s64, s54
	v_lshl_add_u64 v[146:147], s[40:41], 0, v[132:133]
	s_mov_b32 m0, s72
	ds_read_b128 v[190:193], v152 offset:16384
	ds_read_b128 v[194:197], v152 offset:17408
	ds_read_b128 v[198:201], v152 offset:18432
	ds_read_b128 v[202:205], v152 offset:19456
	ds_read_b128 v[206:209], v152 offset:20480
	ds_read_b128 v[210:213], v152 offset:21504
	ds_read_b128 v[214:217], v152 offset:22528
	ds_read_b128 v[218:221], v152 offset:23552
	global_load_lds_dwordx4 v[146:147], off
	s_add_i32 m0, s72, 0x2000
	s_add_u32 s72, s40, 0x40000
	v_lshl_add_u64 v[170:171], s[40:41], 0, v[136:137]
	s_addc_u32 s73, s41, 0
	s_add_i32 s74, s65, s54
	global_load_lds_dwordx4 v[170:171], off
	v_lshl_add_u64 v[222:223], s[72:73], 0, v[132:133]
	s_mov_b32 m0, s74
	v_lshl_add_u64 v[224:225], s[42:43], 0, v[134:135]
	global_load_lds_dwordx4 v[222:223], off
	v_lshl_add_u64 v[222:223], s[72:73], 0, v[136:137]
	s_add_i32 m0, s74, 0x2000
	s_nop 0
	global_load_lds_dwordx4 v[222:223], off
	v_lshl_add_u64 v[222:223], s[42:43], 0, v[130:131]
	s_mov_b32 m0, s55
	s_nop 0
	global_load_lds_dwordx4 v[222:223], off
	s_mov_b32 m0, s56
	s_nop 0
	global_load_lds_dwordx4 v[224:225], off
	s_waitcnt vmcnt(8)
	s_waitcnt lgkmcnt(0)
	s_barrier
; #define PG8_STAGE(bufoff, gbase, voff) do { _Pragma("unroll") for (int _i = 0; _i < 2; ++_i) \
;         __builtin_amdgcn_global_load_lds((const unsigned*)((const char*)(gbase) + (voff)[_i]), (PG8_LAS unsigned*)(lds + (bufoff) + ldsw + _i * 8192), 16, 0, 0); } while (0)
; #define PG8_LDA(dst, b, h) do { _Pragma("unroll") for (int m = 0; m < 4; ++m) _Pragma("unroll") for (int k = 0; k < 2; ++k) dst[m][k] = *(const PG8_LAS bf16x8*)(lds + PG8_SA(b, h) + aoff + m * 2048 + k * 1024); } while (0)
; #define PG8_LDB(dst, b, h) do { _Pragma("unroll") for (int n = 0; n < 2; ++n) _Pragma("unroll") for (int k = 0; k < 2; ++k) dst[n][k] = *(const PG8_LAS bf16x8*)(lds + PG8_SB(b, h) + boff + n * 2048 + k * 1024); } while (0)
; #define PG8_MMA(ai, bj, At, Bt) do { __builtin_amdgcn_s_setprio(1); _Pragma("unroll") for (int m = 0; m < 4; ++m) _Pragma("unroll") for (int n = 0; n < 2; ++n) _Pragma("unroll") for (int k = 0; k < 2; ++k) \
;         acc[ai][bj][m][n] = __builtin_amdgcn_mfma_f32_16x16x32_bf16(Bt[n][k], At[m][k], acc[ai][bj][m][n], 0, 0, 0); __builtin_amdgcn_s_setprio(0); } while (0)
; #define PG8_WAIT_V(n) asm volatile("s_waitcnt vmcnt(" #n ")" ::: "memory")
; #define PG8_WAIT_L(n) asm volatile("s_waitcnt lgkmcnt(" #n ")" ::: "memory")
; #define PG8_BAR __builtin_amdgcn_s_barrier()
; #define PG8_SCHED __builtin_amdgcn_sched_barrier(0)
; template <class Epi, class Sched, bool ALIGN_EPI = false, bool SP2 = false>
; __device__ __forceinline__ void gemm_phase(PG8_LAS unsigned char* lds, const Gemm g, const Sched& S, const Epi& E) {
;     ...
;             PG8_WAIT_V(8); PG8_WAIT_L(0); PG8_BAR; PG8_MMA(1, 0, At, B0); PG8_MMA(1, 1, At, B1); PG8_BAR; PG8_SCHED;
;             PG8_LDB(B0, 1, 0); PG8_LDB(B1, 1, 1); PG8_SCHED; PG8_LDA(At, 1, 0); PG8_STAGE(PG8_SA(0, 1), a2 + hstep, voffA);
;             PG8_WAIT_V(8); PG8_WAIT_L(0); PG8_BAR; PG8_MMA(0, 0, At, B0); PG8_MMA(0, 1, At, B1); PG8_BAR; PG8_SCHED;
	s_waitcnt lgkmcnt(0)
	v_mfma_f32_16x16x32_bf16 v[62:65], v[154:157], v[190:193], v[62:65]
	v_mfma_f32_16x16x32_bf16 v[58:61], v[162:165], v[190:193], v[58:61]
	v_mfma_f32_16x16x32_bf16 v[46:49], v[154:157], v[198:201], v[46:49]
	v_mfma_f32_16x16x32_bf16 v[42:45], v[162:165], v[198:201], v[42:45]
	v_mfma_f32_16x16x32_bf16 v[30:33], v[154:157], v[206:209], v[30:33]
	v_mfma_f32_16x16x32_bf16 v[26:29], v[162:165], v[206:209], v[26:29]
	v_mfma_f32_16x16x32_bf16 v[14:17], v[154:157], v[214:217], v[14:17]
	v_mfma_f32_16x16x32_bf16 v[10:13], v[162:165], v[214:217], v[10:13]
	v_mfma_f32_16x16x32_bf16 v[62:65], v[158:161], v[194:197], v[62:65]
	v_mfma_f32_16x16x32_bf16 v[58:61], v[166:169], v[194:197], v[58:61]
	v_mfma_f32_16x16x32_bf16 v[46:49], v[158:161], v[202:205], v[46:49]
	v_mfma_f32_16x16x32_bf16 v[42:45], v[166:169], v[202:205], v[42:45]
	v_mfma_f32_16x16x32_bf16 v[30:33], v[158:161], v[210:213], v[30:33]
	v_mfma_f32_16x16x32_bf16 v[26:29], v[166:169], v[210:213], v[26:29]
	v_mfma_f32_16x16x32_bf16 v[14:17], v[158:161], v[218:221], v[14:17]
	v_mfma_f32_16x16x32_bf16 v[10:13], v[166:169], v[218:221], v[10:13]
	v_mfma_f32_16x16x32_bf16 v[54:57], v[174:177], v[190:193], v[54:57]
	v_mfma_f32_16x16x32_bf16 v[50:53], v[182:185], v[190:193], v[50:53]
	v_mfma_f32_16x16x32_bf16 v[38:41], v[174:177], v[198:201], v[38:41]
	v_mfma_f32_16x16x32_bf16 v[34:37], v[182:185], v[198:201], v[34:37]
	v_mfma_f32_16x16x32_bf16 v[22:25], v[174:177], v[206:209], v[22:25]
	v_mfma_f32_16x16x32_bf16 v[18:21], v[182:185], v[206:209], v[18:21]
	v_mfma_f32_16x16x32_bf16 v[6:9], v[174:177], v[214:217], v[6:9]
	v_mfma_f32_16x16x32_bf16 v[2:5], v[182:185], v[214:217], v[2:5]
	v_mfma_f32_16x16x32_bf16 v[54:57], v[178:181], v[194:197], v[54:57]
	v_mfma_f32_16x16x32_bf16 v[50:53], v[186:189], v[194:197], v[50:53]
	v_mfma_f32_16x16x32_bf16 v[38:41], v[178:181], v[202:205], v[38:41]
	v_mfma_f32_16x16x32_bf16 v[34:37], v[186:189], v[202:205], v[34:37]
	v_mfma_f32_16x16x32_bf16 v[22:25], v[178:181], v[210:213], v[22:25]
	v_mfma_f32_16x16x32_bf16 v[18:21], v[186:189], v[210:213], v[18:21]
	v_mfma_f32_16x16x32_bf16 v[6:9], v[178:181], v[218:221], v[6:9]
	v_mfma_f32_16x16x32_bf16 v[2:5], v[186:189], v[218:221], v[2:5]
	s_barrier
	s_add_i32 s72, 0, 0x18000
	v_add_u32_e32 v153, s72, v148
	s_add_i32 s73, 0, 0x1c000
	ds_read_b128 v[154:157], v153
	ds_read_b128 v[158:161], v153 offset:1024
	ds_read_b128 v[162:165], v153 offset:2048
	ds_read_b128 v[166:169], v153 offset:3072
	v_add_u32_e32 v153, s73, v148
	ds_read_b128 v[174:177], v153
	ds_read_b128 v[178:181], v153 offset:1024
	ds_read_b128 v[182:185], v153 offset:2048
	ds_read_b128 v[186:189], v153 offset:3072
	s_add_u32 s42, s42, 0x40000
	s_addc_u32 s43, s43, 0
	s_mov_b32 m0, s57
	v_lshl_add_u64 v[226:227], s[42:43], 0, v[130:131]
	ds_read_b128 v[190:193], v152 offset:32768
	ds_read_b128 v[194:197], v152 offset:33792
	ds_read_b128 v[198:201], v152 offset:34816
	ds_read_b128 v[202:205], v152 offset:35840
	ds_read_b128 v[206:209], v152 offset:36864
	ds_read_b128 v[210:213], v152 offset:37888
	ds_read_b128 v[214:217], v152 offset:38912
	ds_read_b128 v[218:221], v152 offset:39936
	global_load_lds_dwordx4 v[226:227], off
	v_lshl_add_u64 v[226:227], s[42:43], 0, v[134:135]
	s_mov_b32 m0, s58
	s_nop 0
	global_load_lds_dwordx4 v[226:227], off
	s_waitcnt vmcnt(8)
	s_waitcnt lgkmcnt(0)
	s_barrier
	s_waitcnt lgkmcnt(0)
	v_mfma_f32_16x16x32_bf16 v[126:129], v[154:157], v[190:193], v[126:129]
	v_mfma_f32_16x16x32_bf16 v[122:125], v[162:165], v[190:193], v[122:125]
	v_mfma_f32_16x16x32_bf16 v[110:113], v[154:157], v[198:201], v[110:113]
	v_mfma_f32_16x16x32_bf16 v[106:109], v[162:165], v[198:201], v[106:109]
	v_mfma_f32_16x16x32_bf16 v[94:97], v[154:157], v[206:209], v[94:97]
	v_mfma_f32_16x16x32_bf16 v[90:93], v[162:165], v[206:209], v[90:93]
	v_mfma_f32_16x16x32_bf16 v[78:81], v[154:157], v[214:217], v[78:81]
	v_mfma_f32_16x16x32_bf16 v[74:77], v[162:165], v[214:217], v[74:77]
	v_mfma_f32_16x16x32_bf16 v[126:129], v[158:161], v[194:197], v[126:129]
	v_mfma_f32_16x16x32_bf16 v[122:125], v[166:169], v[194:197], v[122:125]
	v_mfma_f32_16x16x32_bf16 v[110:113], v[158:161], v[202:205], v[110:113]
	v_mfma_f32_16x16x32_bf16 v[106:109], v[166:169], v[202:205], v[106:109]
	v_mfma_f32_16x16x32_bf16 v[94:97], v[158:161], v[210:213], v[94:97]
	v_mfma_f32_16x16x32_bf16 v[90:93], v[166:169], v[210:213], v[90:93]
	v_mfma_f32_16x16x32_bf16 v[78:81], v[158:161], v[218:221], v[78:81]
	v_mfma_f32_16x16x32_bf16 v[74:77], v[166:169], v[218:221], v[74:77]
	v_mfma_f32_16x16x32_bf16 v[118:121], v[174:177], v[190:193], v[118:121]
	v_mfma_f32_16x16x32_bf16 v[114:117], v[182:185], v[190:193], v[114:117]
	v_mfma_f32_16x16x32_bf16 v[102:105], v[174:177], v[198:201], v[102:105]
	v_mfma_f32_16x16x32_bf16 v[98:101], v[182:185], v[198:201], v[98:101]
	v_mfma_f32_16x16x32_bf16 v[86:89], v[174:177], v[206:209], v[86:89]
	v_mfma_f32_16x16x32_bf16 v[82:85], v[182:185], v[206:209], v[82:85]
	v_mfma_f32_16x16x32_bf16 v[70:73], v[174:177], v[214:217], v[70:73]
	v_mfma_f32_16x16x32_bf16 v[66:69], v[182:185], v[214:217], v[66:69]
	v_mfma_f32_16x16x32_bf16 v[118:121], v[178:181], v[194:197], v[118:121]
	v_mfma_f32_16x16x32_bf16 v[114:117], v[186:189], v[194:197], v[114:117]
	v_mfma_f32_16x16x32_bf16 v[102:105], v[178:181], v[202:205], v[102:105]
	v_mfma_f32_16x16x32_bf16 v[98:101], v[186:189], v[202:205], v[98:101]
	v_mfma_f32_16x16x32_bf16 v[86:89], v[178:181], v[210:213], v[86:89]
	v_mfma_f32_16x16x32_bf16 v[82:85], v[186:189], v[210:213], v[82:85]
	v_mfma_f32_16x16x32_bf16 v[70:73], v[178:181], v[218:221], v[70:73]
	v_mfma_f32_16x16x32_bf16 v[66:69], v[186:189], v[218:221], v[66:69]
	s_barrier
; #define PG8_WAIT_V(n) asm volatile("s_waitcnt vmcnt(" #n ")" ::: "memory")
; #define PG8_BAR __builtin_amdgcn_s_barrier()
; template <class Epi, class Sched, bool ALIGN_EPI = false, bool SP2 = false>
; __device__ __forceinline__ void gemm_phase(PG8_LAS unsigned char* lds, const Gemm g, const Sched& S, const Epi& E) {
;     ...
;             PG8_LDA(At, 1, 1); PG8_STAGE(PG8_SB(1, 0), b3, voffB); PG8_STAGE(PG8_SB(1, 1), b3 + hstep, voffB); PG8_STAGE(PG8_SA(1, 0), a3, voffA);
;             PG8_WAIT_V(8); PG8_WAIT_L(0); PG8_BAR; PG8_MMA(1, 0, At, B0); PG8_MMA(1, 1, At, B1); PG8_BAR; PG8_SCHED;
;             } else {
;             PG8_LDB(B0, 0, 0); PG8_SCHED; PG8_LDA(At, 0, 0); PG8_STAGE(PG8_SA(1, 1), a1 + hstep, voffA);
;             PG8_WAIT_L(8); PG8_BAR; PG8_WAIT_L(0); PG8_MMA(0, 0, At, B0); PG8_BAR; PG8_SCHED;
;             PG8_LDB(B1, 0, 1); PG8_STAGE(PG8_SB(0, 0), b2, voffB);
;             PG8_BAR; PG8_WAIT_L(0); PG8_MMA(0, 1, At, B1); PG8_BAR;
;             PG8_LDA(At, 0, 1); PG8_STAGE(PG8_SA(0, 0), a2, voffA);
;             PG8_BAR; PG8_WAIT_L(0); PG8_MMA(1, 0, At, B0); PG8_BAR; PG8_SCHED;
;             PG8_STAGE(PG8_SB(0, 1), b2 + hstep, voffB);
;             PG8_WAIT_V(6); PG8_BAR; PG8_MMA(1, 1, At, B1); PG8_BAR;
;             PG8_LDB(B0, 1, 0); PG8_SCHED; PG8_LDA(At, 1, 0); PG8_STAGE(PG8_SA(0, 1), a2 + hstep, voffA);
;             PG8_WAIT_L(8); PG8_BAR; PG8_WAIT_L(0); PG8_MMA(0, 0, At, B0); PG8_BAR; PG8_SCHED;
;             PG8_LDB(B1, 1, 1); PG8_STAGE(PG8_SB(1, 0), b3, voffB);
;             PG8_BAR; PG8_WAIT_L(0); PG8_MMA(0, 1, At, B1); PG8_BAR;
;             PG8_LDA(At, 1, 1); PG8_STAGE(PG8_SA(1, 0), a3, voffA);
;             PG8_BAR; PG8_WAIT_L(0); PG8_MMA(1, 0, At, B0); PG8_BAR; PG8_SCHED;
;             PG8_STAGE(PG8_SB(1, 1), b3 + hstep, voffB);
;             PG8_WAIT_V(6); PG8_BAR; PG8_MMA(1, 1, At, B1); PG8_BAR;
;             }
;         }
;         if constexpr (ALIGN_EPI) { if (wr == 0) PG8_BAR; }
;     __device__ __forceinline__ void operator()(const f32x4 (&acc)[2][2][4][2], const pg8::Unit& u, int wr, int wc, int fr, int fq) const {
;     ...
;                         if constexpr (MODE == EP_SIG) {
; #pragma unroll
;                             for (int j = 0; j < 8; ++j) r[j] = sigmoidf_(r[j]);
;                             dst = (col < 1024) ? (O + row * 1024 + col) : (O2 + row * 1024 + (col - 1024));
;                         }
	s_add_i32 s42, s72, s54
	v_lshl_add_u64 v[146:147], v[146:147], 0, s[10:11]
	s_mov_b32 m0, s42
	ds_read_b128 v[190:193], v152 offset:49152
	ds_read_b128 v[194:197], v152 offset:50176
	ds_read_b128 v[198:201], v152 offset:51200
	ds_read_b128 v[202:205], v152 offset:52224
	ds_read_b128 v[206:209], v152 offset:53248
	ds_read_b128 v[210:213], v152 offset:54272
	ds_read_b128 v[214:217], v152 offset:55296
	ds_read_b128 v[218:221], v152 offset:56320
	global_load_lds_dwordx4 v[146:147], off
	s_add_i32 m0, s42, 0x2000
	s_add_u32 s40, s40, 0x40080
	v_lshl_add_u64 v[146:147], v[170:171], 0, s[10:11]
	s_addc_u32 s41, s41, 0
	s_add_i32 s42, s73, s54
	global_load_lds_dwordx4 v[146:147], off
	v_lshl_add_u64 v[146:147], s[40:41], 0, v[132:133]
	s_mov_b32 m0, s42
	s_nop 0
	global_load_lds_dwordx4 v[146:147], off
	v_lshl_add_u64 v[146:147], s[40:41], 0, v[136:137]
	s_add_i32 m0, s42, 0x2000
	s_nop 0
	global_load_lds_dwordx4 v[146:147], off
	v_lshl_add_u64 v[146:147], v[222:223], 0, s[10:11]
	s_mov_b32 m0, s60
	s_nop 0
	global_load_lds_dwordx4 v[146:147], off
	v_lshl_add_u64 v[146:147], v[224:225], 0, s[10:11]
	s_mov_b32 m0, s61
	s_nop 0
	global_load_lds_dwordx4 v[146:147], off
	s_waitcnt vmcnt(8)
	s_waitcnt lgkmcnt(0)
	s_barrier
	s_waitcnt lgkmcnt(0)
	v_mfma_f32_16x16x32_bf16 v[62:65], v[154:157], v[190:193], v[62:65]
	v_mfma_f32_16x16x32_bf16 v[58:61], v[162:165], v[190:193], v[58:61]
	v_mfma_f32_16x16x32_bf16 v[46:49], v[154:157], v[198:201], v[46:49]
	v_mfma_f32_16x16x32_bf16 v[42:45], v[162:165], v[198:201], v[42:45]
	v_mfma_f32_16x16x32_bf16 v[30:33], v[154:157], v[206:209], v[30:33]
	v_mfma_f32_16x16x32_bf16 v[26:29], v[162:165], v[206:209], v[26:29]
	v_mfma_f32_16x16x32_bf16 v[14:17], v[154:157], v[214:217], v[14:17]
	v_mfma_f32_16x16x32_bf16 v[10:13], v[162:165], v[214:217], v[10:13]
	v_mfma_f32_16x16x32_bf16 v[62:65], v[158:161], v[194:197], v[62:65]
	v_mfma_f32_16x16x32_bf16 v[58:61], v[166:169], v[194:197], v[58:61]
	v_mfma_f32_16x16x32_bf16 v[46:49], v[158:161], v[202:205], v[46:49]
	v_mfma_f32_16x16x32_bf16 v[42:45], v[166:169], v[202:205], v[42:45]
	v_mfma_f32_16x16x32_bf16 v[30:33], v[158:161], v[210:213], v[30:33]
	v_mfma_f32_16x16x32_bf16 v[26:29], v[166:169], v[210:213], v[26:29]
	v_mfma_f32_16x16x32_bf16 v[14:17], v[158:161], v[218:221], v[14:17]
	v_mfma_f32_16x16x32_bf16 v[10:13], v[166:169], v[218:221], v[10:13]
	v_mfma_f32_16x16x32_bf16 v[54:57], v[174:177], v[190:193], v[54:57]
	v_mfma_f32_16x16x32_bf16 v[50:53], v[182:185], v[190:193], v[50:53]
	v_mfma_f32_16x16x32_bf16 v[38:41], v[174:177], v[198:201], v[38:41]
	v_mfma_f32_16x16x32_bf16 v[34:37], v[182:185], v[198:201], v[34:37]
	v_mfma_f32_16x16x32_bf16 v[22:25], v[174:177], v[206:209], v[22:25]
	v_mfma_f32_16x16x32_bf16 v[18:21], v[182:185], v[206:209], v[18:21]
	v_mfma_f32_16x16x32_bf16 v[6:9], v[174:177], v[214:217], v[6:9]
	v_mfma_f32_16x16x32_bf16 v[2:5], v[182:185], v[214:217], v[2:5]
	v_mfma_f32_16x16x32_bf16 v[54:57], v[178:181], v[194:197], v[54:57]
	v_mfma_f32_16x16x32_bf16 v[50:53], v[186:189], v[194:197], v[50:53]
	v_mfma_f32_16x16x32_bf16 v[38:41], v[178:181], v[202:205], v[38:41]
	v_mfma_f32_16x16x32_bf16 v[34:37], v[186:189], v[202:205], v[34:37]
	v_mfma_f32_16x16x32_bf16 v[22:25], v[178:181], v[210:213], v[22:25]
	v_mfma_f32_16x16x32_bf16 v[18:21], v[186:189], v[210:213], v[18:21]
	v_mfma_f32_16x16x32_bf16 v[6:9], v[178:181], v[218:221], v[6:9]
	v_mfma_f32_16x16x32_bf16 v[2:5], v[186:189], v[218:221], v[2:5]
	s_barrier
	s_add_i32 s71, s71, 2
	s_add_u32 s38, s38, 0x100
	s_addc_u32 s39, s39, 0
	s_add_u32 s69, s69, 0x100
	s_addc_u32 s70, s70, 0
	s_cmp_gt_u32 s71, 13
	s_cbranch_scc0 .LBB0_1221
	s_andn2_b64 vcc, s[12:13], s[2:3]
	s_cbranch_vccz .LBB0_1224
	s_barrier
.LBB0_1224:
	v_mul_f32_e32 v122, 0xbfb8aa3b, v122
	v_exp_f32_e32 v122, v122
	v_mul_f32_e32 v123, 0xbfb8aa3b, v123
	v_exp_f32_e32 v123, v123
	v_mul_f32_e32 v128, 0xbfb8aa3b, v128
	v_add_f32_e32 v122, 1.0, v122
	v_rcp_f32_e32 v164, v122
	v_add_f32_e32 v122, 1.0, v123
	v_mul_f32_e32 v123, 0xbfb8aa3b, v124
	v_exp_f32_e32 v123, v123
	v_mul_f32_e32 v124, 0xbfb8aa3b, v125
	v_mul_f32_e32 v126, 0xbfb8aa3b, v126
	v_exp_f32_e32 v128, v128
	v_mul_f32_e32 v129, 0xbfb8aa3b, v129
	v_exp_f32_e32 v124, v124
	v_exp_f32_e32 v153, v126
	v_mul_f32_e32 v126, 0xbfb8aa3b, v127
	v_exp_f32_e32 v129, v129
	v_lshl_add_u32 v146, s4, 8, v1
	v_exp_f32_e32 v154, v126
	v_lshl_or_b32 v158, s5, 8, v149
	v_ashrrev_i32_e32 v147, 31, v146
	v_rcp_f32_e32 v165, v122
	v_add_f32_e32 v122, 1.0, v123
	v_mul_f32_e32 v118, 0xbfb8aa3b, v118
	v_lshlrev_b64 v[126:127], 11, v[146:147]
	v_add_f32_e32 v128, 1.0, v128
	v_rcp_f32_e32 v166, v122
	v_add_f32_e32 v122, 1.0, v124
	v_ashrrev_i32_e32 v159, 31, v158
	v_exp_f32_e32 v118, v118
	v_mul_f32_e32 v119, 0xbfb8aa3b, v119
	v_mul_f32_e32 v114, 0xbfb8aa3b, v114
	v_rcp_f32_e32 v156, v128
	v_add_f32_e32 v128, 1.0, v129
	v_rcp_f32_e32 v167, v122
	v_lshl_add_u64 v[124:125], s[90:91], 0, v[126:127]
	v_lshlrev_b64 v[122:123], 1, v[158:159]
	v_mov_b32_e32 v159, v133
	v_exp_f32_e32 v119, v119
	v_exp_f32_e32 v114, v114
	v_mul_f32_e32 v115, 0xbfb8aa3b, v115
	v_add_f32_e32 v147, 1.0, v153
	v_add_f32_e32 v153, 1.0, v154
	v_rcp_f32_e32 v157, v128
	v_lshl_add_u64 v[128:129], v[124:125], 0, v[122:123]
	v_lshl_add_u64 v[154:155], s[8:9], 0, v[126:127]
	v_lshlrev_b64 v[124:125], 1, v[158:159]
	v_exp_f32_e32 v115, v115
	v_lshl_add_u64 v[160:161], v[154:155], 0, v[124:125]
	v_rcp_f32_e32 v147, v147
	v_lshl_add_u64 v[154:155], v[160:161], 0, s[16:17]
	v_cmp_gt_i32_e32 vcc, s66, v158
	v_add_f32_e32 v118, 1.0, v118
	v_rcp_f32_e32 v153, v153
	v_cndmask_b32_e32 v163, v155, v129, vcc
	v_cndmask_b32_e32 v162, v154, v128, vcc
; __device__ __forceinline__ unsigned cvt_pk_bf16(float lo, float hi) { unsigned r; asm volatile("v_cvt_pk_bf16_f32 %0, %1, %2" : "=v"(r) : "v"(lo), "v"(hi)); return r; }
; __device__ __forceinline__ float sigmoidf_(float x) { return __builtin_amdgcn_rcpf(1.0f + __expf(-x)); }
;     __device__ __forceinline__ void operator()(const f32x4 (&acc)[2][2][4][2], const pg8::Unit& u, int wr, int wc, int fr, int fq) const {
;     ...
;                         if constexpr (MODE == EP_SIG) {
; #pragma unroll
;                             for (int j = 0; j < 8; ++j) r[j] = sigmoidf_(r[j]);
;                             dst = (col < 1024) ? (O + row * 1024 + col) : (O2 + row * 1024 + (col - 1024));
;     ...
;                         u32x4 w; w.x = cvt_pk_bf16(r[0], r[1]); w.y = cvt_pk_bf16(r[2], r[3]); w.z = cvt_pk_bf16(r[4], r[5]); w.w = cvt_pk_bf16(r[6], r[7]);
;                         *(u32x4*)dst = w;
	v_cvt_pk_bf16_f32 v154, v147, v153
	v_rcp_f32_e32 v147, v118
	v_add_f32_e32 v118, 1.0, v119
	v_mul_f32_e32 v119, 0xbfb8aa3b, v120
	v_add_f32_e32 v114, 1.0, v114
	v_cvt_pk_bf16_f32 v155, v156, v157
	v_cvt_pk_bf16_f32 v156, v164, v165
	v_cvt_pk_bf16_f32 v157, v166, v167
	global_store_dwordx4 v[162:163], v[154:157], off
	v_exp_f32_e32 v119, v119
	v_mul_f32_e32 v120, 0xbfb8aa3b, v121
	v_rcp_f32_e32 v154, v114
	v_add_f32_e32 v114, 1.0, v115
	v_mul_f32_e32 v115, 0xbfb8aa3b, v116
	v_exp_f32_e32 v120, v120
	v_exp_f32_e32 v115, v115
	v_mul_f32_e32 v116, 0xbfb8aa3b, v117
	v_exp_f32_e32 v116, v116
	v_mul_f32_e32 v106, 0xbfb8aa3b, v106
	v_exp_f32_e32 v106, v106
	v_mul_f32_e32 v107, 0xbfb8aa3b, v107
	v_rcp_f32_e32 v121, v118
	v_add_f32_e32 v118, 1.0, v119
	v_exp_f32_e32 v107, v107
	v_rcp_f32_e32 v153, v118
	v_add_f32_e32 v118, 1.0, v120
	v_rcp_f32_e32 v155, v114
	v_add_f32_e32 v114, 1.0, v115
	v_rcp_f32_e32 v120, v118
	v_rcp_f32_e32 v156, v114
	v_add_f32_e32 v114, 1.0, v116
	v_or_b32_e32 v118, 0x80, v158
	v_rcp_f32_e32 v157, v114
	v_lshl_add_u64 v[114:115], v[128:129], 0, s[14:15]
	v_lshl_add_u64 v[116:117], v[160:161], 0, s[18:19]
	v_cmp_gt_i32_e64 s[4:5], s66, v118
	v_add_f32_e32 v106, 1.0, v106
	v_mul_f32_e32 v112, 0xbfb8aa3b, v112
	v_cndmask_b32_e64 v119, v117, v115, s[4:5]
	v_cndmask_b32_e64 v118, v116, v114, s[4:5]
	v_cvt_pk_bf16_f32 v114, v147, v121
	v_cvt_pk_bf16_f32 v115, v153, v120
	v_rcp_f32_e32 v120, v106
	v_add_f32_e32 v106, 1.0, v107
	v_mul_f32_e32 v107, 0xbfb8aa3b, v108
	v_exp_f32_e32 v107, v107
	v_mul_f32_e32 v108, 0xbfb8aa3b, v109
	v_exp_f32_e32 v112, v112
	v_mul_f32_e32 v113, 0xbfb8aa3b, v113
	v_exp_f32_e32 v108, v108
	v_exp_f32_e32 v113, v113
	v_cvt_pk_bf16_f32 v116, v154, v155
	v_cvt_pk_bf16_f32 v117, v156, v157
	global_store_dwordx4 v[118:119], v[114:117], off
	v_mul_f32_e32 v110, 0xbfb8aa3b, v110
	v_rcp_f32_e32 v109, v106
	v_or_b32_e32 v114, 16, v146
	v_ashrrev_i32_e32 v115, 31, v114
	v_exp_f32_e32 v116, v110
	v_mul_f32_e32 v110, 0xbfb8aa3b, v111
	v_add_f32_e32 v106, 1.0, v107
	v_exp_f32_e32 v117, v110
	v_lshlrev_b64 v[110:111], 11, v[114:115]
	v_add_f32_e32 v112, 1.0, v112
	v_rcp_f32_e32 v121, v106
	v_add_f32_e32 v106, 1.0, v108
	v_mul_f32_e32 v102, 0xbfb8aa3b, v102
	v_mul_f32_e32 v98, 0xbfb8aa3b, v98
	v_rcp_f32_e32 v118, v112
	v_add_f32_e32 v112, 1.0, v113
	v_rcp_f32_e32 v128, v106
	v_lshl_add_u64 v[106:107], s[90:91], 0, v[110:111]
	v_exp_f32_e32 v102, v102
	v_mul_f32_e32 v103, 0xbfb8aa3b, v103
	v_exp_f32_e32 v98, v98
	v_mul_f32_e32 v99, 0xbfb8aa3b, v99
	v_rcp_f32_e32 v119, v112
	v_lshl_add_u64 v[112:113], v[106:107], 0, v[122:123]
	v_lshl_add_u64 v[106:107], s[8:9], 0, v[110:111]
	v_exp_f32_e32 v103, v103
	v_exp_f32_e32 v99, v99
	v_add_f32_e32 v114, 1.0, v116
	v_lshl_add_u64 v[110:111], v[106:107], 0, v[124:125]
	v_rcp_f32_e32 v116, v114
	v_add_f32_e32 v114, 1.0, v117
	v_lshl_add_u64 v[106:107], v[110:111], 0, s[16:17]
	v_rcp_f32_e32 v117, v114
	v_cndmask_b32_e32 v115, v107, v113, vcc
	v_cndmask_b32_e32 v114, v106, v112, vcc
	v_cvt_pk_bf16_f32 v106, v116, v117
	v_cvt_pk_bf16_f32 v107, v118, v119
	v_cvt_pk_bf16_f32 v108, v120, v109
	v_add_f32_e32 v102, 1.0, v102
	v_add_f32_e32 v98, 1.0, v98
	v_cvt_pk_bf16_f32 v109, v121, v128
	global_store_dwordx4 v[114:115], v[106:109], off
	v_mul_f32_e32 v90, 0xbfb8aa3b, v90
	v_exp_f32_e32 v90, v90
	v_rcp_f32_e32 v106, v102
	v_add_f32_e32 v102, 1.0, v103
	v_mul_f32_e32 v103, 0xbfb8aa3b, v104
	v_rcp_f32_e32 v108, v98
	v_add_f32_e32 v98, 1.0, v99
	v_mul_f32_e32 v99, 0xbfb8aa3b, v100
	v_exp_f32_e32 v103, v103
	v_mul_f32_e32 v104, 0xbfb8aa3b, v105
	v_exp_f32_e32 v99, v99
	v_mul_f32_e32 v100, 0xbfb8aa3b, v101
	v_exp_f32_e32 v104, v104
	v_exp_f32_e32 v100, v100
	v_mul_f32_e32 v91, 0xbfb8aa3b, v91
	v_exp_f32_e32 v91, v91
	v_rcp_f32_e32 v105, v102
	v_add_f32_e32 v102, 1.0, v103
	v_rcp_f32_e32 v109, v98
	v_add_f32_e32 v98, 1.0, v99
	v_rcp_f32_e32 v107, v102
	v_add_f32_e32 v102, 1.0, v104
	v_rcp_f32_e32 v114, v98
	v_add_f32_e32 v98, 1.0, v100
	v_rcp_f32_e32 v104, v102
	v_rcp_f32_e32 v115, v98
	v_lshl_add_u64 v[98:99], v[112:113], 0, s[14:15]
	v_lshl_add_u64 v[100:101], v[110:111], 0, s[18:19]
	v_add_f32_e32 v90, 1.0, v90
	v_cndmask_b32_e64 v103, v101, v99, s[4:5]
	v_cndmask_b32_e64 v102, v100, v98, s[4:5]
	v_cvt_pk_bf16_f32 v98, v106, v105
	v_cvt_pk_bf16_f32 v99, v107, v104
	v_rcp_f32_e32 v104, v90
	v_add_f32_e32 v90, 1.0, v91
	v_mul_f32_e32 v91, 0xbfb8aa3b, v92
	v_mul_f32_e32 v96, 0xbfb8aa3b, v96
	v_exp_f32_e32 v91, v91
	v_mul_f32_e32 v92, 0xbfb8aa3b, v93
	v_exp_f32_e32 v96, v96
	v_mul_f32_e32 v97, 0xbfb8aa3b, v97
	v_exp_f32_e32 v92, v92
	v_exp_f32_e32 v97, v97
	v_cvt_pk_bf16_f32 v100, v108, v109
	v_cvt_pk_bf16_f32 v101, v114, v115
	global_store_dwordx4 v[102:103], v[98:101], off
	v_mul_f32_e32 v94, 0xbfb8aa3b, v94
	v_rcp_f32_e32 v93, v90
	v_or_b32_e32 v98, 32, v146
	v_ashrrev_i32_e32 v99, 31, v98
	v_exp_f32_e32 v100, v94
	v_mul_f32_e32 v94, 0xbfb8aa3b, v95
	v_add_f32_e32 v90, 1.0, v91
	v_exp_f32_e32 v101, v94
	v_lshlrev_b64 v[94:95], 11, v[98:99]
	v_add_f32_e32 v96, 1.0, v96
	v_rcp_f32_e32 v105, v90
	v_add_f32_e32 v90, 1.0, v92
	v_mul_f32_e32 v86, 0xbfb8aa3b, v86
	v_mul_f32_e32 v82, 0xbfb8aa3b, v82
	v_rcp_f32_e32 v102, v96
	v_add_f32_e32 v96, 1.0, v97
	v_rcp_f32_e32 v106, v90
	v_lshl_add_u64 v[90:91], s[90:91], 0, v[94:95]
	v_exp_f32_e32 v86, v86
	v_mul_f32_e32 v87, 0xbfb8aa3b, v87
	v_exp_f32_e32 v82, v82
	v_mul_f32_e32 v83, 0xbfb8aa3b, v83
	v_rcp_f32_e32 v103, v96
	v_lshl_add_u64 v[96:97], v[90:91], 0, v[122:123]
	v_lshl_add_u64 v[90:91], s[8:9], 0, v[94:95]
	v_exp_f32_e32 v87, v87
	v_exp_f32_e32 v83, v83
	v_add_f32_e32 v98, 1.0, v100
	v_lshl_add_u64 v[94:95], v[90:91], 0, v[124:125]
; __device__ __forceinline__ unsigned cvt_pk_bf16(float lo, float hi) { unsigned r; asm volatile("v_cvt_pk_bf16_f32 %0, %1, %2" : "=v"(r) : "v"(lo), "v"(hi)); return r; }
; __device__ __forceinline__ float sigmoidf_(float x) { return __builtin_amdgcn_rcpf(1.0f + __expf(-x)); }
;     __device__ __forceinline__ void operator()(const f32x4 (&acc)[2][2][4][2], const pg8::Unit& u, int wr, int wc, int fr, int fq) const {
;     ...
;                         if constexpr (MODE == EP_SIG) {
; #pragma unroll
;                             for (int j = 0; j < 8; ++j) r[j] = sigmoidf_(r[j]);
;                             dst = (col < 1024) ? (O + row * 1024 + col) : (O2 + row * 1024 + (col - 1024));
;     ...
;                         u32x4 w; w.x = cvt_pk_bf16(r[0], r[1]); w.y = cvt_pk_bf16(r[2], r[3]); w.z = cvt_pk_bf16(r[4], r[5]); w.w = cvt_pk_bf16(r[6], r[7]);
;                         *(u32x4*)dst = w;
	v_rcp_f32_e32 v100, v98
	v_add_f32_e32 v98, 1.0, v101
	v_lshl_add_u64 v[90:91], v[94:95], 0, s[16:17]
	v_rcp_f32_e32 v101, v98
	v_cndmask_b32_e32 v99, v91, v97, vcc
	v_cndmask_b32_e32 v98, v90, v96, vcc
	v_cvt_pk_bf16_f32 v90, v100, v101
	v_cvt_pk_bf16_f32 v91, v102, v103
	v_cvt_pk_bf16_f32 v92, v104, v93
	v_add_f32_e32 v86, 1.0, v86
	v_add_f32_e32 v82, 1.0, v82
	v_cvt_pk_bf16_f32 v93, v105, v106
	global_store_dwordx4 v[98:99], v[90:93], off
	v_mul_f32_e32 v74, 0xbfb8aa3b, v74
	v_exp_f32_e32 v74, v74
	v_rcp_f32_e32 v90, v86
	v_add_f32_e32 v86, 1.0, v87
	v_mul_f32_e32 v87, 0xbfb8aa3b, v88
	v_rcp_f32_e32 v92, v82
	v_add_f32_e32 v82, 1.0, v83
	v_mul_f32_e32 v83, 0xbfb8aa3b, v84
	v_exp_f32_e32 v87, v87
	v_mul_f32_e32 v88, 0xbfb8aa3b, v89
	v_exp_f32_e32 v83, v83
	v_mul_f32_e32 v84, 0xbfb8aa3b, v85
	v_exp_f32_e32 v88, v88
	v_exp_f32_e32 v84, v84
	v_mul_f32_e32 v75, 0xbfb8aa3b, v75
	v_exp_f32_e32 v75, v75
	v_rcp_f32_e32 v89, v86
	v_add_f32_e32 v86, 1.0, v87
	v_rcp_f32_e32 v93, v82
	v_add_f32_e32 v82, 1.0, v83
	v_rcp_f32_e32 v91, v86
	v_add_f32_e32 v86, 1.0, v88
	v_rcp_f32_e32 v98, v82
	v_add_f32_e32 v82, 1.0, v84
	v_rcp_f32_e32 v88, v86
	v_rcp_f32_e32 v99, v82
	v_lshl_add_u64 v[82:83], v[96:97], 0, s[14:15]
	v_lshl_add_u64 v[84:85], v[94:95], 0, s[18:19]
	v_add_f32_e32 v74, 1.0, v74
	v_cndmask_b32_e64 v87, v85, v83, s[4:5]
	v_cndmask_b32_e64 v86, v84, v82, s[4:5]
	v_cvt_pk_bf16_f32 v82, v90, v89
	v_cvt_pk_bf16_f32 v83, v91, v88
	v_rcp_f32_e32 v88, v74
	v_add_f32_e32 v74, 1.0, v75
	v_mul_f32_e32 v75, 0xbfb8aa3b, v76
	v_mul_f32_e32 v80, 0xbfb8aa3b, v80
	v_exp_f32_e32 v75, v75
	v_mul_f32_e32 v76, 0xbfb8aa3b, v77
	v_exp_f32_e32 v80, v80
	v_mul_f32_e32 v81, 0xbfb8aa3b, v81
	v_exp_f32_e32 v76, v76
	v_exp_f32_e32 v81, v81
	v_cvt_pk_bf16_f32 v84, v92, v93
	v_cvt_pk_bf16_f32 v85, v98, v99
	global_store_dwordx4 v[86:87], v[82:85], off
	v_mul_f32_e32 v78, 0xbfb8aa3b, v78
	v_rcp_f32_e32 v77, v74
	v_or_b32_e32 v82, 48, v146
	v_ashrrev_i32_e32 v83, 31, v82
	v_exp_f32_e32 v84, v78
	v_mul_f32_e32 v78, 0xbfb8aa3b, v79
	v_add_f32_e32 v74, 1.0, v75
	v_exp_f32_e32 v85, v78
	v_lshlrev_b64 v[78:79], 11, v[82:83]
	v_add_f32_e32 v80, 1.0, v80
	v_rcp_f32_e32 v89, v74
	v_add_f32_e32 v74, 1.0, v76
	v_mul_f32_e32 v70, 0xbfb8aa3b, v70
	v_mul_f32_e32 v66, 0xbfb8aa3b, v66
	v_rcp_f32_e32 v86, v80
	v_add_f32_e32 v80, 1.0, v81
	v_rcp_f32_e32 v90, v74
	v_lshl_add_u64 v[74:75], s[90:91], 0, v[78:79]
	v_exp_f32_e32 v70, v70
	v_mul_f32_e32 v71, 0xbfb8aa3b, v71
	v_exp_f32_e32 v66, v66
	v_mul_f32_e32 v67, 0xbfb8aa3b, v67
	v_rcp_f32_e32 v87, v80
	v_lshl_add_u64 v[80:81], v[74:75], 0, v[122:123]
	v_lshl_add_u64 v[74:75], s[8:9], 0, v[78:79]
	v_exp_f32_e32 v71, v71
	v_exp_f32_e32 v67, v67
	v_add_f32_e32 v82, 1.0, v84
	v_lshl_add_u64 v[78:79], v[74:75], 0, v[124:125]
	v_rcp_f32_e32 v84, v82
	v_add_f32_e32 v82, 1.0, v85
	v_lshl_add_u64 v[74:75], v[78:79], 0, s[16:17]
	v_rcp_f32_e32 v85, v82
	v_cndmask_b32_e32 v83, v75, v81, vcc
	v_cndmask_b32_e32 v82, v74, v80, vcc
	v_cvt_pk_bf16_f32 v74, v84, v85
	v_cvt_pk_bf16_f32 v75, v86, v87
	v_cvt_pk_bf16_f32 v76, v88, v77
	v_add_f32_e32 v70, 1.0, v70
	v_add_f32_e32 v66, 1.0, v66
	v_cvt_pk_bf16_f32 v77, v89, v90
	global_store_dwordx4 v[82:83], v[74:77], off
	v_mul_f32_e32 v58, 0xbfb8aa3b, v58
	v_exp_f32_e32 v58, v58
	v_rcp_f32_e32 v74, v70
	v_add_f32_e32 v70, 1.0, v71
	v_mul_f32_e32 v71, 0xbfb8aa3b, v72
	v_rcp_f32_e32 v76, v66
	v_add_f32_e32 v66, 1.0, v67
	v_mul_f32_e32 v67, 0xbfb8aa3b, v68
	v_exp_f32_e32 v71, v71
	v_mul_f32_e32 v72, 0xbfb8aa3b, v73
	v_exp_f32_e32 v67, v67
	v_mul_f32_e32 v68, 0xbfb8aa3b, v69
	v_exp_f32_e32 v72, v72
	v_exp_f32_e32 v68, v68
	v_mul_f32_e32 v59, 0xbfb8aa3b, v59
	v_exp_f32_e32 v59, v59
	v_rcp_f32_e32 v73, v70
	v_add_f32_e32 v70, 1.0, v71
	v_rcp_f32_e32 v77, v66
	v_add_f32_e32 v66, 1.0, v67
	v_rcp_f32_e32 v75, v70
	v_add_f32_e32 v70, 1.0, v72
	v_rcp_f32_e32 v82, v66
	v_add_f32_e32 v66, 1.0, v68
	v_rcp_f32_e32 v72, v70
	v_rcp_f32_e32 v83, v66
	v_lshl_add_u64 v[66:67], v[80:81], 0, s[14:15]
	v_lshl_add_u64 v[68:69], v[78:79], 0, s[18:19]
	v_add_f32_e32 v58, 1.0, v58
	v_cndmask_b32_e64 v71, v69, v67, s[4:5]
	v_cndmask_b32_e64 v70, v68, v66, s[4:5]
	v_cvt_pk_bf16_f32 v66, v74, v73
	v_cvt_pk_bf16_f32 v67, v75, v72
	v_rcp_f32_e32 v72, v58
	v_add_f32_e32 v58, 1.0, v59
	v_mul_f32_e32 v59, 0xbfb8aa3b, v60
	v_mul_f32_e32 v64, 0xbfb8aa3b, v64
	v_exp_f32_e32 v59, v59
	v_mul_f32_e32 v60, 0xbfb8aa3b, v61
	v_exp_f32_e32 v64, v64
	v_mul_f32_e32 v65, 0xbfb8aa3b, v65
	v_exp_f32_e32 v60, v60
	v_exp_f32_e32 v65, v65
	v_mul_f32_e32 v62, 0xbfb8aa3b, v62
	v_cvt_pk_bf16_f32 v68, v76, v77
	v_cvt_pk_bf16_f32 v69, v82, v83
	global_store_dwordx4 v[70:71], v[66:69], off
	v_rcp_f32_e32 v61, v58
	v_add_f32_e32 v58, 1.0, v59
	v_exp_f32_e32 v66, v62
	v_mul_f32_e32 v62, 0xbfb8aa3b, v63
	v_exp_f32_e32 v67, v62
	v_lshl_add_u64 v[62:63], v[126:127], 0, s[0:1]
	v_add_f32_e32 v64, 1.0, v64
	v_rcp_f32_e32 v73, v58
	v_add_f32_e32 v58, 1.0, v60
	v_mul_f32_e32 v54, 0xbfb8aa3b, v54
	v_mul_f32_e32 v50, 0xbfb8aa3b, v50
	v_rcp_f32_e32 v70, v64
	v_add_f32_e32 v64, 1.0, v65
	v_rcp_f32_e32 v74, v58
	v_lshl_add_u64 v[58:59], s[90:91], 0, v[62:63]
	v_exp_f32_e32 v54, v54
	v_mul_f32_e32 v55, 0xbfb8aa3b, v55
	v_exp_f32_e32 v50, v50
	v_mul_f32_e32 v51, 0xbfb8aa3b, v51
	v_rcp_f32_e32 v71, v64
	v_lshl_add_u64 v[64:65], v[58:59], 0, v[122:123]
	v_lshl_add_u64 v[58:59], s[8:9], 0, v[62:63]
	v_exp_f32_e32 v55, v55
	v_exp_f32_e32 v51, v51
	v_add_f32_e32 v66, 1.0, v66
	v_lshl_add_u64 v[62:63], v[58:59], 0, v[124:125]
	v_rcp_f32_e32 v68, v66
	v_add_f32_e32 v66, 1.0, v67
	v_lshl_add_u64 v[58:59], v[62:63], 0, s[16:17]
	v_rcp_f32_e32 v69, v66
	v_cndmask_b32_e32 v67, v59, v65, vcc
; __device__ __forceinline__ unsigned cvt_pk_bf16(float lo, float hi) { unsigned r; asm volatile("v_cvt_pk_bf16_f32 %0, %1, %2" : "=v"(r) : "v"(lo), "v"(hi)); return r; }
; __device__ __forceinline__ float sigmoidf_(float x) { return __builtin_amdgcn_rcpf(1.0f + __expf(-x)); }
;     __device__ __forceinline__ void operator()(const f32x4 (&acc)[2][2][4][2], const pg8::Unit& u, int wr, int wc, int fr, int fq) const {
;     ...
;                         if constexpr (MODE == EP_SIG) {
; #pragma unroll
;                             for (int j = 0; j < 8; ++j) r[j] = sigmoidf_(r[j]);
;                             dst = (col < 1024) ? (O + row * 1024 + col) : (O2 + row * 1024 + (col - 1024));
;     ...
;                         u32x4 w; w.x = cvt_pk_bf16(r[0], r[1]); w.y = cvt_pk_bf16(r[2], r[3]); w.z = cvt_pk_bf16(r[4], r[5]); w.w = cvt_pk_bf16(r[6], r[7]);
;                         *(u32x4*)dst = w;
	v_cndmask_b32_e32 v66, v58, v64, vcc
	v_cvt_pk_bf16_f32 v58, v68, v69
	v_cvt_pk_bf16_f32 v59, v70, v71
	v_cvt_pk_bf16_f32 v60, v72, v61
	v_add_f32_e32 v54, 1.0, v54
	v_add_f32_e32 v50, 1.0, v50
	v_cvt_pk_bf16_f32 v61, v73, v74
	global_store_dwordx4 v[66:67], v[58:61], off
	v_mul_f32_e32 v42, 0xbfb8aa3b, v42
	v_exp_f32_e32 v42, v42
	v_rcp_f32_e32 v58, v54
	v_add_f32_e32 v54, 1.0, v55
	v_mul_f32_e32 v55, 0xbfb8aa3b, v56
	v_rcp_f32_e32 v60, v50
	v_add_f32_e32 v50, 1.0, v51
	v_mul_f32_e32 v51, 0xbfb8aa3b, v52
	v_exp_f32_e32 v55, v55
	v_mul_f32_e32 v56, 0xbfb8aa3b, v57
	v_exp_f32_e32 v51, v51
	v_mul_f32_e32 v52, 0xbfb8aa3b, v53
	v_exp_f32_e32 v56, v56
	v_exp_f32_e32 v52, v52
	v_mul_f32_e32 v43, 0xbfb8aa3b, v43
	v_exp_f32_e32 v43, v43
	v_rcp_f32_e32 v57, v54
	v_add_f32_e32 v54, 1.0, v55
	v_rcp_f32_e32 v61, v50
	v_add_f32_e32 v50, 1.0, v51
	v_rcp_f32_e32 v59, v54
	v_add_f32_e32 v54, 1.0, v56
	v_rcp_f32_e32 v66, v50
	v_add_f32_e32 v50, 1.0, v52
	v_rcp_f32_e32 v56, v54
	v_rcp_f32_e32 v67, v50
	v_lshl_add_u64 v[50:51], v[64:65], 0, s[14:15]
	v_lshl_add_u64 v[52:53], v[62:63], 0, s[18:19]
	v_add_f32_e32 v42, 1.0, v42
	v_cndmask_b32_e64 v55, v53, v51, s[4:5]
	v_cndmask_b32_e64 v54, v52, v50, s[4:5]
	v_cvt_pk_bf16_f32 v50, v58, v57
	v_cvt_pk_bf16_f32 v51, v59, v56
	v_rcp_f32_e32 v56, v42
	v_add_f32_e32 v42, 1.0, v43
	v_mul_f32_e32 v43, 0xbfb8aa3b, v44
	v_mul_f32_e32 v48, 0xbfb8aa3b, v48
	v_exp_f32_e32 v43, v43
	v_mul_f32_e32 v44, 0xbfb8aa3b, v45
	v_exp_f32_e32 v48, v48
	v_mul_f32_e32 v49, 0xbfb8aa3b, v49
	v_exp_f32_e32 v44, v44
	v_exp_f32_e32 v49, v49
	v_mul_f32_e32 v46, 0xbfb8aa3b, v46
	v_cvt_pk_bf16_f32 v52, v60, v61
	v_cvt_pk_bf16_f32 v53, v66, v67
	global_store_dwordx4 v[54:55], v[50:53], off
	v_rcp_f32_e32 v45, v42
	v_add_f32_e32 v42, 1.0, v43
	v_exp_f32_e32 v50, v46
	v_mul_f32_e32 v46, 0xbfb8aa3b, v47
	v_exp_f32_e32 v51, v46
	v_lshl_add_u64 v[46:47], v[126:127], 0, s[20:21]
	v_add_f32_e32 v48, 1.0, v48
	v_rcp_f32_e32 v57, v42
	v_add_f32_e32 v42, 1.0, v44
	v_mul_f32_e32 v38, 0xbfb8aa3b, v38
	v_mul_f32_e32 v34, 0xbfb8aa3b, v34
	v_rcp_f32_e32 v54, v48
	v_add_f32_e32 v48, 1.0, v49
	v_rcp_f32_e32 v58, v42
	v_lshl_add_u64 v[42:43], s[90:91], 0, v[46:47]
	v_exp_f32_e32 v38, v38
	v_mul_f32_e32 v39, 0xbfb8aa3b, v39
	v_exp_f32_e32 v34, v34
	v_mul_f32_e32 v35, 0xbfb8aa3b, v35
	v_rcp_f32_e32 v55, v48
	v_lshl_add_u64 v[48:49], v[42:43], 0, v[122:123]
	v_lshl_add_u64 v[42:43], s[8:9], 0, v[46:47]
	v_exp_f32_e32 v39, v39
	v_exp_f32_e32 v35, v35
	v_add_f32_e32 v50, 1.0, v50
	v_lshl_add_u64 v[46:47], v[42:43], 0, v[124:125]
	v_rcp_f32_e32 v52, v50
	v_add_f32_e32 v50, 1.0, v51
	v_lshl_add_u64 v[42:43], v[46:47], 0, s[16:17]
	v_rcp_f32_e32 v53, v50
	v_cndmask_b32_e32 v51, v43, v49, vcc
	v_cndmask_b32_e32 v50, v42, v48, vcc
	v_cvt_pk_bf16_f32 v42, v52, v53
	v_cvt_pk_bf16_f32 v43, v54, v55
	v_cvt_pk_bf16_f32 v44, v56, v45
	v_add_f32_e32 v38, 1.0, v38
	v_add_f32_e32 v34, 1.0, v34
	v_cvt_pk_bf16_f32 v45, v57, v58
	global_store_dwordx4 v[50:51], v[42:45], off
	v_mul_f32_e32 v26, 0xbfb8aa3b, v26
	v_exp_f32_e32 v26, v26
	v_rcp_f32_e32 v42, v38
	v_add_f32_e32 v38, 1.0, v39
	v_mul_f32_e32 v39, 0xbfb8aa3b, v40
	v_rcp_f32_e32 v44, v34
	v_add_f32_e32 v34, 1.0, v35
	v_mul_f32_e32 v35, 0xbfb8aa3b, v36
	v_exp_f32_e32 v39, v39
	v_mul_f32_e32 v40, 0xbfb8aa3b, v41
	v_exp_f32_e32 v35, v35
	v_mul_f32_e32 v36, 0xbfb8aa3b, v37
	v_exp_f32_e32 v40, v40
	v_exp_f32_e32 v36, v36
	v_mul_f32_e32 v27, 0xbfb8aa3b, v27
	v_exp_f32_e32 v27, v27
	v_rcp_f32_e32 v41, v38
	v_add_f32_e32 v38, 1.0, v39
	v_rcp_f32_e32 v45, v34
	v_add_f32_e32 v34, 1.0, v35
	v_rcp_f32_e32 v43, v38
	v_add_f32_e32 v38, 1.0, v40
	v_rcp_f32_e32 v50, v34
	v_add_f32_e32 v34, 1.0, v36
	v_rcp_f32_e32 v40, v38
	v_rcp_f32_e32 v51, v34
	v_lshl_add_u64 v[34:35], v[48:49], 0, s[14:15]
	v_lshl_add_u64 v[36:37], v[46:47], 0, s[18:19]
	v_add_f32_e32 v26, 1.0, v26
	v_cndmask_b32_e64 v39, v37, v35, s[4:5]
	v_cndmask_b32_e64 v38, v36, v34, s[4:5]
	v_cvt_pk_bf16_f32 v34, v42, v41
	v_cvt_pk_bf16_f32 v35, v43, v40
	v_rcp_f32_e32 v40, v26
	v_add_f32_e32 v26, 1.0, v27
	v_mul_f32_e32 v27, 0xbfb8aa3b, v28
	v_mul_f32_e32 v32, 0xbfb8aa3b, v32
	v_exp_f32_e32 v27, v27
	v_mul_f32_e32 v28, 0xbfb8aa3b, v29
	v_exp_f32_e32 v32, v32
	v_mul_f32_e32 v33, 0xbfb8aa3b, v33
	v_exp_f32_e32 v28, v28
	v_exp_f32_e32 v33, v33
	v_mul_f32_e32 v30, 0xbfb8aa3b, v30
	v_cvt_pk_bf16_f32 v36, v44, v45
	v_cvt_pk_bf16_f32 v37, v50, v51
	global_store_dwordx4 v[38:39], v[34:37], off
	v_rcp_f32_e32 v29, v26
	v_add_f32_e32 v26, 1.0, v27
	v_exp_f32_e32 v34, v30
	v_mul_f32_e32 v30, 0xbfb8aa3b, v31
	v_exp_f32_e32 v35, v30
	v_lshl_add_u64 v[30:31], v[126:127], 0, s[22:23]
	v_add_f32_e32 v32, 1.0, v32
	v_rcp_f32_e32 v41, v26
	v_add_f32_e32 v26, 1.0, v28
	v_mul_f32_e32 v22, 0xbfb8aa3b, v22
; #define PG8_BAR __builtin_amdgcn_s_barrier()
; __device__ __forceinline__ float sigmoidf_(float x) { return __builtin_amdgcn_rcpf(1.0f + __expf(-x)); }
; template <class Epi, class Sched, bool ALIGN_EPI = false, bool SP2 = false>
; __device__ __forceinline__ void gemm_phase(PG8_LAS unsigned char* lds, const Gemm g, const Sched& S, const Epi& E) {
;     ...
;         if (!has_next) break;
; #pragma unroll
;         for (int a = 0; a < 2; ++a)
; #pragma unroll
;             for (int b = 0; b < 2; ++b)
; #pragma unroll
;                 for (int m = 0; m < 4; ++m)
; #pragma unroll
;                     for (int n = 0; n < 2; ++n) acc[a][b][m][n] = (f32x4){0.f, 0.f, 0.f, 0.f};
;         cur = nxt; cA = nA; cB = nB; ++ui;
;         if constexpr (ALIGN_EPI) { if (wr == 1) PG8_BAR; }
;     __device__ __forceinline__ void operator()(const f32x4 (&acc)[2][2][4][2], const pg8::Unit& u, int wr, int wc, int fr, int fq) const {
;     ...
;                         if constexpr (MODE == EP_SIG) {
; #pragma unroll
;                             for (int j = 0; j < 8; ++j) r[j] = sigmoidf_(r[j]);
;                             dst = (col < 1024) ? (O + row * 1024 + col) : (O2 + row * 1024 + (col - 1024));
	v_mul_f32_e32 v18, 0xbfb8aa3b, v18
	v_rcp_f32_e32 v38, v32
	v_add_f32_e32 v32, 1.0, v33
	v_rcp_f32_e32 v42, v26
	v_lshl_add_u64 v[26:27], s[90:91], 0, v[30:31]
	v_exp_f32_e32 v22, v22
	v_mul_f32_e32 v23, 0xbfb8aa3b, v23
	v_exp_f32_e32 v18, v18
	v_mul_f32_e32 v19, 0xbfb8aa3b, v19
	v_rcp_f32_e32 v39, v32
	v_lshl_add_u64 v[32:33], v[26:27], 0, v[122:123]
	v_lshl_add_u64 v[26:27], s[8:9], 0, v[30:31]
	v_exp_f32_e32 v23, v23
	v_exp_f32_e32 v19, v19
	v_add_f32_e32 v34, 1.0, v34
	v_lshl_add_u64 v[30:31], v[26:27], 0, v[124:125]
	v_rcp_f32_e32 v36, v34
	v_add_f32_e32 v34, 1.0, v35
	v_lshl_add_u64 v[26:27], v[30:31], 0, s[16:17]
	v_rcp_f32_e32 v37, v34
	v_cndmask_b32_e32 v35, v27, v33, vcc
	v_cndmask_b32_e32 v34, v26, v32, vcc
	v_cvt_pk_bf16_f32 v26, v36, v37
	v_cvt_pk_bf16_f32 v27, v38, v39
	v_cvt_pk_bf16_f32 v28, v40, v29
	v_add_f32_e32 v22, 1.0, v22
	v_add_f32_e32 v18, 1.0, v18
	v_cvt_pk_bf16_f32 v29, v41, v42
	global_store_dwordx4 v[34:35], v[26:29], off
	v_mul_f32_e32 v10, 0xbfb8aa3b, v10
	v_exp_f32_e32 v10, v10
	v_rcp_f32_e32 v26, v22
	v_add_f32_e32 v22, 1.0, v23
	v_mul_f32_e32 v23, 0xbfb8aa3b, v24
	v_rcp_f32_e32 v28, v18
	v_add_f32_e32 v18, 1.0, v19
	v_mul_f32_e32 v19, 0xbfb8aa3b, v20
	v_exp_f32_e32 v23, v23
	v_mul_f32_e32 v24, 0xbfb8aa3b, v25
	v_exp_f32_e32 v19, v19
	v_mul_f32_e32 v20, 0xbfb8aa3b, v21
	v_exp_f32_e32 v24, v24
	v_exp_f32_e32 v20, v20
	v_mul_f32_e32 v11, 0xbfb8aa3b, v11
	v_exp_f32_e32 v11, v11
	v_rcp_f32_e32 v25, v22
	v_add_f32_e32 v22, 1.0, v23
	v_rcp_f32_e32 v29, v18
	v_add_f32_e32 v18, 1.0, v19
	v_rcp_f32_e32 v27, v22
	v_add_f32_e32 v22, 1.0, v24
	v_rcp_f32_e32 v34, v18
	v_add_f32_e32 v18, 1.0, v20
	v_rcp_f32_e32 v24, v22
	v_rcp_f32_e32 v35, v18
	v_lshl_add_u64 v[18:19], v[32:33], 0, s[14:15]
	v_lshl_add_u64 v[20:21], v[30:31], 0, s[18:19]
	v_add_f32_e32 v10, 1.0, v10
	v_cndmask_b32_e64 v23, v21, v19, s[4:5]
	v_cndmask_b32_e64 v22, v20, v18, s[4:5]
	v_cvt_pk_bf16_f32 v18, v26, v25
	v_cvt_pk_bf16_f32 v19, v27, v24
	v_rcp_f32_e32 v24, v10
	v_add_f32_e32 v10, 1.0, v11
	v_mul_f32_e32 v11, 0xbfb8aa3b, v12
	v_mul_f32_e32 v16, 0xbfb8aa3b, v16
	v_exp_f32_e32 v11, v11
	v_mul_f32_e32 v12, 0xbfb8aa3b, v13
	v_exp_f32_e32 v16, v16
	v_mul_f32_e32 v17, 0xbfb8aa3b, v17
	v_exp_f32_e32 v12, v12
	v_exp_f32_e32 v17, v17
	v_mul_f32_e32 v14, 0xbfb8aa3b, v14
	v_cvt_pk_bf16_f32 v20, v28, v29
	v_cvt_pk_bf16_f32 v21, v34, v35
	global_store_dwordx4 v[22:23], v[18:21], off
	v_rcp_f32_e32 v13, v10
	v_add_f32_e32 v10, 1.0, v11
	v_exp_f32_e32 v18, v14
	v_mul_f32_e32 v14, 0xbfb8aa3b, v15
	v_exp_f32_e32 v19, v14
	v_lshl_add_u64 v[14:15], v[126:127], 0, s[24:25]
	v_add_f32_e32 v16, 1.0, v16
	v_rcp_f32_e32 v25, v10
	v_add_f32_e32 v10, 1.0, v12
	v_rcp_f32_e32 v22, v16
	v_add_f32_e32 v16, 1.0, v17
	v_rcp_f32_e32 v26, v10
	v_lshl_add_u64 v[10:11], s[90:91], 0, v[14:15]
	v_mul_f32_e32 v2, 0xbfb8aa3b, v2
	v_rcp_f32_e32 v23, v16
	v_lshl_add_u64 v[16:17], v[10:11], 0, v[122:123]
	v_lshl_add_u64 v[10:11], s[8:9], 0, v[14:15]
	v_mul_f32_e32 v5, 0xbfb8aa3b, v5
	v_exp_f32_e32 v2, v2
	v_mul_f32_e32 v3, 0xbfb8aa3b, v3
	v_add_f32_e32 v18, 1.0, v18
	v_lshl_add_u64 v[14:15], v[10:11], 0, v[124:125]
	v_exp_f32_e32 v5, v5
	v_mul_f32_e32 v6, 0xbfb8aa3b, v6
	v_mul_f32_e32 v7, 0xbfb8aa3b, v7
	v_mul_f32_e32 v8, 0xbfb8aa3b, v8
	v_mul_f32_e32 v9, 0xbfb8aa3b, v9
	v_exp_f32_e32 v3, v3
	v_mul_f32_e32 v4, 0xbfb8aa3b, v4
	v_rcp_f32_e32 v20, v18
	v_add_f32_e32 v18, 1.0, v19
	v_lshl_add_u64 v[10:11], v[14:15], 0, s[16:17]
	v_exp_f32_e32 v6, v6
	v_exp_f32_e32 v7, v7
	v_exp_f32_e32 v8, v8
	v_exp_f32_e32 v9, v9
	v_exp_f32_e32 v4, v4
	v_rcp_f32_e32 v21, v18
	v_cndmask_b32_e32 v19, v11, v17, vcc
	v_cndmask_b32_e32 v18, v10, v16, vcc
	v_cvt_pk_bf16_f32 v10, v20, v21
	v_cvt_pk_bf16_f32 v11, v22, v23
	v_cvt_pk_bf16_f32 v12, v24, v13
	v_cvt_pk_bf16_f32 v13, v25, v26
	global_store_dwordx4 v[18:19], v[10:13], off
	v_add_f32_e32 v2, 1.0, v2
	v_add_f32_e32 v5, 1.0, v5
	v_lshl_add_u64 v[10:11], v[16:17], 0, s[14:15]
	v_lshl_add_u64 v[12:13], v[14:15], 0, s[18:19]
	v_cndmask_b32_e64 v10, v12, v10, s[4:5]
	v_rcp_f32_e32 v12, v2
	v_add_f32_e32 v2, 1.0, v3
	v_cndmask_b32_e64 v11, v13, v11, s[4:5]
	v_rcp_f32_e32 v5, v5
	v_add_f32_e32 v6, 1.0, v6
	v_add_f32_e32 v7, 1.0, v7
	v_add_f32_e32 v8, 1.0, v8
	v_add_f32_e32 v9, 1.0, v9
	v_rcp_f32_e32 v13, v2
	v_add_f32_e32 v2, 1.0, v4
	s_andn2_b64 vcc, exec, s[2:3]
	s_mov_b64 s[2:3], -1
	v_rcp_f32_e32 v6, v6
	v_rcp_f32_e32 v7, v7
	v_rcp_f32_e32 v8, v8
	v_rcp_f32_e32 v9, v9
	v_rcp_f32_e32 v14, v2
	v_cvt_pk_bf16_f32 v2, v6, v7
	v_cvt_pk_bf16_f32 v3, v8, v9
	v_cvt_pk_bf16_f32 v4, v12, v13
	v_cvt_pk_bf16_f32 v5, v14, v5
	global_store_dwordx4 v[10:11], v[2:5], off
	s_cbranch_vccnz .LBB0_1213
	s_andn2_b64 vcc, exec, s[6:7]
	s_cbranch_vccnz .LBB0_1212
	s_branch .LBB0_1212

; #define PG8_STAGE(bufoff, gbase, voff) do { _Pragma("unroll") for (int _i = 0; _i < 2; ++_i) \
;         __builtin_amdgcn_global_load_lds((const unsigned*)((const char*)(gbase) + (voff)[_i]), (PG8_LAS unsigned*)(lds + (bufoff) + ldsw + _i * 8192), 16, 0, 0); } while (0)
; #define PG8_LDA(dst, b, h) do { _Pragma("unroll") for (int m = 0; m < 4; ++m) _Pragma("unroll") for (int k = 0; k < 2; ++k) dst[m][k] = *(const PG8_LAS bf16x8*)(lds + PG8_SA(b, h) + aoff + m * 2048 + k * 1024); } while (0)
; #define PG8_LDB(dst, b, h) do { _Pragma("unroll") for (int n = 0; n < 2; ++n) _Pragma("unroll") for (int k = 0; k < 2; ++k) dst[n][k] = *(const PG8_LAS bf16x8*)(lds + PG8_SB(b, h) + boff + n * 2048 + k * 1024); } while (0)
; #define PG8_MMA(ai, bj, At, Bt) do { __builtin_amdgcn_s_setprio(1); _Pragma("unroll") for (int m = 0; m < 4; ++m) _Pragma("unroll") for (int n = 0; n < 2; ++n) _Pragma("unroll") for (int k = 0; k < 2; ++k) \
;         acc[ai][bj][m][n] = __builtin_amdgcn_mfma_f32_16x16x32_bf16(Bt[n][k], At[m][k], acc[ai][bj][m][n], 0, 0, 0); __builtin_amdgcn_s_setprio(0); } while (0)
; #define PG8_WAIT_V(n) asm volatile("s_waitcnt vmcnt(" #n ")" ::: "memory")
; #define PG8_WAIT_L(n) asm volatile("s_waitcnt lgkmcnt(" #n ")" ::: "memory")
; template <class Epi, class Sched, bool ALIGN_EPI = false, bool SP2 = false>
; __device__ __forceinline__ void gemm_phase(PG8_LAS unsigned char* lds, const Gemm g, const Sched& S, const Epi& E) {
;     ...
;             const bool last = (t == nt - 2);
;             const char* a1 = cA + (size_t)(t + 1) * kstep;
;             const char* a2 = last ? nA : cA + (size_t)(t + 2) * kstep; const char* b2 = last ? nB : cB + (size_t)(t + 2) * kstep;
;             const char* a3 = a2 + kstep; const char* b3 = b2 + kstep;
;             if (last && has_next) S.a_ready(nxt);
;             if constexpr (SP2) {
;             PG8_LDB(B0, 0, 0); PG8_LDB(B1, 0, 1); PG8_SCHED; PG8_LDA(At, 0, 0); PG8_STAGE(PG8_SA(1, 1), a1 + hstep, voffA);
;             PG8_WAIT_V(8); PG8_WAIT_L(0); PG8_BAR; PG8_MMA(0, 0, At, B0); PG8_MMA(0, 1, At, B1); PG8_BAR; PG8_SCHED;
;             PG8_LDA(At, 0, 1); PG8_STAGE(PG8_SB(0, 0), b2, voffB); PG8_STAGE(PG8_SB(0, 1), b2 + hstep, voffB); PG8_STAGE(PG8_SA(0, 0), a2, voffA);
;             PG8_WAIT_V(8); PG8_WAIT_L(0); PG8_BAR; PG8_MMA(1, 0, At, B0); PG8_MMA(1, 1, At, B1); PG8_BAR; PG8_SCHED;
.LBB0_1314:
	ds_read_b128 v[146:149], v154
	ds_read_b128 v[158:161], v154 offset:1024
	ds_read_b128 v[162:165], v154 offset:2048
	ds_read_b128 v[166:169], v154 offset:3072
	ds_read_b128 v[174:177], v155
	ds_read_b128 v[178:181], v155 offset:1024
	ds_read_b128 v[182:185], v155 offset:2048
	ds_read_b128 v[186:189], v155 offset:3072
	s_add_u32 s30, s28, 0xfffc0080
	s_addc_u32 s31, s29, -1
	s_cmp_eq_u32 s64, 12
	s_cselect_b32 s35, s21, s31
	s_cselect_b32 s34, s60, s30
	s_cselect_b32 s31, s19, s63
	s_cselect_b32 s30, s61, s62
	v_lshl_add_u64 v[150:151], s[28:29], 0, v[138:139]
	s_add_i32 m0, s27, 0xc000
	ds_read_b128 v[190:193], v156
	ds_read_b128 v[194:197], v156 offset:1024
	ds_read_b128 v[198:201], v156 offset:2048
	ds_read_b128 v[202:205], v156 offset:3072
	ds_read_b128 v[206:209], v156 offset:4096
	ds_read_b128 v[210:213], v156 offset:5120
	ds_read_b128 v[214:217], v156 offset:6144
	ds_read_b128 v[218:221], v156 offset:7168
	global_load_lds_dwordx4 v[150:151], off
	v_lshl_add_u64 v[150:151], s[28:29], 0, v[140:141]
	s_add_i32 m0, s27, 0xe000
	s_nop 0
	global_load_lds_dwordx4 v[150:151], off
	s_waitcnt vmcnt(8)
	s_waitcnt lgkmcnt(0)
	s_barrier
	s_waitcnt lgkmcnt(0)
	v_mfma_f32_16x16x32_bf16 v[126:129], v[146:149], v[190:193], v[126:129]
	v_mfma_f32_16x16x32_bf16 v[122:125], v[162:165], v[190:193], v[122:125]
	v_mfma_f32_16x16x32_bf16 v[114:117], v[146:149], v[198:201], v[114:117]
	v_mfma_f32_16x16x32_bf16 v[106:109], v[162:165], v[198:201], v[106:109]
	v_mfma_f32_16x16x32_bf16 v[98:101], v[146:149], v[206:209], v[98:101]
	v_mfma_f32_16x16x32_bf16 v[90:93], v[162:165], v[206:209], v[90:93]
	v_mfma_f32_16x16x32_bf16 v[82:85], v[146:149], v[214:217], v[82:85]
	v_mfma_f32_16x16x32_bf16 v[74:77], v[162:165], v[214:217], v[74:77]
	v_mfma_f32_16x16x32_bf16 v[126:129], v[158:161], v[194:197], v[126:129]
	v_mfma_f32_16x16x32_bf16 v[122:125], v[166:169], v[194:197], v[122:125]
	v_mfma_f32_16x16x32_bf16 v[114:117], v[158:161], v[202:205], v[114:117]
	v_mfma_f32_16x16x32_bf16 v[106:109], v[166:169], v[202:205], v[106:109]
	v_mfma_f32_16x16x32_bf16 v[98:101], v[158:161], v[210:213], v[98:101]
	v_mfma_f32_16x16x32_bf16 v[90:93], v[166:169], v[210:213], v[90:93]
	v_mfma_f32_16x16x32_bf16 v[82:85], v[158:161], v[218:221], v[82:85]
	v_mfma_f32_16x16x32_bf16 v[74:77], v[166:169], v[218:221], v[74:77]
	v_mfma_f32_16x16x32_bf16 v[118:121], v[174:177], v[190:193], v[118:121]
	v_mfma_f32_16x16x32_bf16 v[110:113], v[182:185], v[190:193], v[110:113]
	v_mfma_f32_16x16x32_bf16 v[102:105], v[174:177], v[198:201], v[102:105]
	v_mfma_f32_16x16x32_bf16 v[94:97], v[182:185], v[198:201], v[94:97]
	v_mfma_f32_16x16x32_bf16 v[86:89], v[174:177], v[206:209], v[86:89]
	v_mfma_f32_16x16x32_bf16 v[78:81], v[182:185], v[206:209], v[78:81]
	v_mfma_f32_16x16x32_bf16 v[70:73], v[174:177], v[214:217], v[70:73]
	v_mfma_f32_16x16x32_bf16 v[66:69], v[182:185], v[214:217], v[66:69]
	v_mfma_f32_16x16x32_bf16 v[118:121], v[178:181], v[194:197], v[118:121]
	v_mfma_f32_16x16x32_bf16 v[110:113], v[186:189], v[194:197], v[110:113]
	v_mfma_f32_16x16x32_bf16 v[102:105], v[178:181], v[202:205], v[102:105]
	v_mfma_f32_16x16x32_bf16 v[94:97], v[186:189], v[202:205], v[94:97]
	v_mfma_f32_16x16x32_bf16 v[86:89], v[178:181], v[210:213], v[86:89]
	v_mfma_f32_16x16x32_bf16 v[78:81], v[186:189], v[210:213], v[78:81]
	v_mfma_f32_16x16x32_bf16 v[70:73], v[178:181], v[218:221], v[70:73]
	v_mfma_f32_16x16x32_bf16 v[66:69], v[186:189], v[218:221], v[66:69]
	s_barrier
	s_add_i32 s65, s57, s42
	v_lshl_add_u64 v[150:151], s[30:31], 0, v[132:133]
	s_mov_b32 m0, s65
	ds_read_b128 v[190:193], v156 offset:16384
	ds_read_b128 v[194:197], v156 offset:17408
	ds_read_b128 v[198:201], v156 offset:18432
	ds_read_b128 v[202:205], v156 offset:19456
	ds_read_b128 v[206:209], v156 offset:20480
	ds_read_b128 v[210:213], v156 offset:21504
	ds_read_b128 v[214:217], v156 offset:22528
	ds_read_b128 v[218:221], v156 offset:23552
	global_load_lds_dwordx4 v[150:151], off
	s_add_i32 m0, s65, 0x2000
	s_add_u32 s66, s30, 0x40000
	v_lshl_add_u64 v[170:171], s[30:31], 0, v[136:137]
	s_addc_u32 s67, s31, 0
	s_add_i32 s65, s58, s42
	global_load_lds_dwordx4 v[170:171], off
	v_lshl_add_u64 v[222:223], s[66:67], 0, v[132:133]
	s_mov_b32 m0, s65
	v_lshl_add_u64 v[224:225], s[34:35], 0, v[134:135]
	global_load_lds_dwordx4 v[222:223], off
	v_lshl_add_u64 v[222:223], s[66:67], 0, v[136:137]
	s_add_i32 m0, s65, 0x2000
	s_nop 0
	global_load_lds_dwordx4 v[222:223], off
	v_lshl_add_u64 v[222:223], s[34:35], 0, v[130:131]
	s_mov_b32 m0, s27
	s_nop 0
	global_load_lds_dwordx4 v[222:223], off
	s_mov_b32 m0, s43
	s_nop 0
	global_load_lds_dwordx4 v[224:225], off
	s_waitcnt vmcnt(8)
	s_waitcnt lgkmcnt(0)
	s_barrier
; #define PG8_STAGE(bufoff, gbase, voff) do { _Pragma("unroll") for (int _i = 0; _i < 2; ++_i) \
;         __builtin_amdgcn_global_load_lds((const unsigned*)((const char*)(gbase) + (voff)[_i]), (PG8_LAS unsigned*)(lds + (bufoff) + ldsw + _i * 8192), 16, 0, 0); } while (0)
; #define PG8_LDA(dst, b, h) do { _Pragma("unroll") for (int m = 0; m < 4; ++m) _Pragma("unroll") for (int k = 0; k < 2; ++k) dst[m][k] = *(const PG8_LAS bf16x8*)(lds + PG8_SA(b, h) + aoff + m * 2048 + k * 1024); } while (0)
; #define PG8_LDB(dst, b, h) do { _Pragma("unroll") for (int n = 0; n < 2; ++n) _Pragma("unroll") for (int k = 0; k < 2; ++k) dst[n][k] = *(const PG8_LAS bf16x8*)(lds + PG8_SB(b, h) + boff + n * 2048 + k * 1024); } while (0)
; #define PG8_MMA(ai, bj, At, Bt) do { __builtin_amdgcn_s_setprio(1); _Pragma("unroll") for (int m = 0; m < 4; ++m) _Pragma("unroll") for (int n = 0; n < 2; ++n) _Pragma("unroll") for (int k = 0; k < 2; ++k) \
;         acc[ai][bj][m][n] = __builtin_amdgcn_mfma_f32_16x16x32_bf16(Bt[n][k], At[m][k], acc[ai][bj][m][n], 0, 0, 0); __builtin_amdgcn_s_setprio(0); } while (0)
; #define PG8_WAIT_V(n) asm volatile("s_waitcnt vmcnt(" #n ")" ::: "memory")
; #define PG8_WAIT_L(n) asm volatile("s_waitcnt lgkmcnt(" #n ")" ::: "memory")
; #define PG8_BAR __builtin_amdgcn_s_barrier()
; #define PG8_SCHED __builtin_amdgcn_sched_barrier(0)
; template <class Epi, class Sched, bool ALIGN_EPI = false, bool SP2 = false>
; __device__ __forceinline__ void gemm_phase(PG8_LAS unsigned char* lds, const Gemm g, const Sched& S, const Epi& E) {
;     ...
;             PG8_WAIT_V(8); PG8_WAIT_L(0); PG8_BAR; PG8_MMA(1, 0, At, B0); PG8_MMA(1, 1, At, B1); PG8_BAR; PG8_SCHED;
;             PG8_LDB(B0, 1, 0); PG8_LDB(B1, 1, 1); PG8_SCHED; PG8_LDA(At, 1, 0); PG8_STAGE(PG8_SA(0, 1), a2 + hstep, voffA);
;             PG8_WAIT_V(8); PG8_WAIT_L(0); PG8_BAR; PG8_MMA(0, 0, At, B0); PG8_MMA(0, 1, At, B1); PG8_BAR; PG8_SCHED;
	s_waitcnt lgkmcnt(0)
	v_mfma_f32_16x16x32_bf16 v[62:65], v[146:149], v[190:193], v[62:65]
	v_mfma_f32_16x16x32_bf16 v[58:61], v[162:165], v[190:193], v[58:61]
	v_mfma_f32_16x16x32_bf16 v[50:53], v[146:149], v[198:201], v[50:53]
	v_mfma_f32_16x16x32_bf16 v[42:45], v[162:165], v[198:201], v[42:45]
	v_mfma_f32_16x16x32_bf16 v[34:37], v[146:149], v[206:209], v[34:37]
	v_mfma_f32_16x16x32_bf16 v[26:29], v[162:165], v[206:209], v[26:29]
	v_mfma_f32_16x16x32_bf16 v[18:21], v[146:149], v[214:217], v[18:21]
	v_mfma_f32_16x16x32_bf16 v[10:13], v[162:165], v[214:217], v[10:13]
	v_mfma_f32_16x16x32_bf16 v[62:65], v[158:161], v[194:197], v[62:65]
	v_mfma_f32_16x16x32_bf16 v[58:61], v[166:169], v[194:197], v[58:61]
	v_mfma_f32_16x16x32_bf16 v[50:53], v[158:161], v[202:205], v[50:53]
	v_mfma_f32_16x16x32_bf16 v[42:45], v[166:169], v[202:205], v[42:45]
	v_mfma_f32_16x16x32_bf16 v[34:37], v[158:161], v[210:213], v[34:37]
	v_mfma_f32_16x16x32_bf16 v[26:29], v[166:169], v[210:213], v[26:29]
	v_mfma_f32_16x16x32_bf16 v[18:21], v[158:161], v[218:221], v[18:21]
	v_mfma_f32_16x16x32_bf16 v[10:13], v[166:169], v[218:221], v[10:13]
	v_mfma_f32_16x16x32_bf16 v[54:57], v[174:177], v[190:193], v[54:57]
	v_mfma_f32_16x16x32_bf16 v[46:49], v[182:185], v[190:193], v[46:49]
	v_mfma_f32_16x16x32_bf16 v[38:41], v[174:177], v[198:201], v[38:41]
	v_mfma_f32_16x16x32_bf16 v[30:33], v[182:185], v[198:201], v[30:33]
	v_mfma_f32_16x16x32_bf16 v[22:25], v[174:177], v[206:209], v[22:25]
	v_mfma_f32_16x16x32_bf16 v[14:17], v[182:185], v[206:209], v[14:17]
	v_mfma_f32_16x16x32_bf16 v[6:9], v[174:177], v[214:217], v[6:9]
	v_mfma_f32_16x16x32_bf16 v[2:5], v[182:185], v[214:217], v[2:5]
	v_mfma_f32_16x16x32_bf16 v[54:57], v[178:181], v[194:197], v[54:57]
	v_mfma_f32_16x16x32_bf16 v[46:49], v[186:189], v[194:197], v[46:49]
	v_mfma_f32_16x16x32_bf16 v[38:41], v[178:181], v[202:205], v[38:41]
	v_mfma_f32_16x16x32_bf16 v[30:33], v[186:189], v[202:205], v[30:33]
	v_mfma_f32_16x16x32_bf16 v[22:25], v[178:181], v[210:213], v[22:25]
	v_mfma_f32_16x16x32_bf16 v[14:17], v[186:189], v[210:213], v[14:17]
	v_mfma_f32_16x16x32_bf16 v[6:9], v[178:181], v[218:221], v[6:9]
	v_mfma_f32_16x16x32_bf16 v[2:5], v[186:189], v[218:221], v[2:5]
	s_barrier
	s_add_i32 s65, 0, 0x18000
	v_add_u32_e32 v157, s65, v152
	s_add_i32 s66, 0, 0x1c000
	ds_read_b128 v[146:149], v157
	ds_read_b128 v[158:161], v157 offset:1024
	ds_read_b128 v[162:165], v157 offset:2048
	ds_read_b128 v[166:169], v157 offset:3072
	v_add_u32_e32 v157, s66, v152
	ds_read_b128 v[174:177], v157
	ds_read_b128 v[178:181], v157 offset:1024
	ds_read_b128 v[182:185], v157 offset:2048
	ds_read_b128 v[186:189], v157 offset:3072
	s_add_u32 s34, s34, 0x40000
	s_addc_u32 s35, s35, 0
	s_mov_b32 m0, s44
	v_lshl_add_u64 v[226:227], s[34:35], 0, v[130:131]
	ds_read_b128 v[190:193], v156 offset:32768
	ds_read_b128 v[194:197], v156 offset:33792
	ds_read_b128 v[198:201], v156 offset:34816
	ds_read_b128 v[202:205], v156 offset:35840
	ds_read_b128 v[206:209], v156 offset:36864
	ds_read_b128 v[210:213], v156 offset:37888
	ds_read_b128 v[214:217], v156 offset:38912
	ds_read_b128 v[218:221], v156 offset:39936
	global_load_lds_dwordx4 v[226:227], off
	v_lshl_add_u64 v[226:227], s[34:35], 0, v[134:135]
	s_mov_b32 m0, s45
	s_nop 0
	global_load_lds_dwordx4 v[226:227], off
	s_waitcnt vmcnt(8)
	s_waitcnt lgkmcnt(0)
	s_barrier
	s_waitcnt lgkmcnt(0)
	v_mfma_f32_16x16x32_bf16 v[126:129], v[146:149], v[190:193], v[126:129]
	v_mfma_f32_16x16x32_bf16 v[122:125], v[162:165], v[190:193], v[122:125]
	v_mfma_f32_16x16x32_bf16 v[114:117], v[146:149], v[198:201], v[114:117]
	v_mfma_f32_16x16x32_bf16 v[106:109], v[162:165], v[198:201], v[106:109]
	v_mfma_f32_16x16x32_bf16 v[98:101], v[146:149], v[206:209], v[98:101]
	v_mfma_f32_16x16x32_bf16 v[90:93], v[162:165], v[206:209], v[90:93]
	v_mfma_f32_16x16x32_bf16 v[82:85], v[146:149], v[214:217], v[82:85]
	v_mfma_f32_16x16x32_bf16 v[74:77], v[162:165], v[214:217], v[74:77]
	v_mfma_f32_16x16x32_bf16 v[126:129], v[158:161], v[194:197], v[126:129]
	v_mfma_f32_16x16x32_bf16 v[122:125], v[166:169], v[194:197], v[122:125]
	v_mfma_f32_16x16x32_bf16 v[114:117], v[158:161], v[202:205], v[114:117]
	v_mfma_f32_16x16x32_bf16 v[106:109], v[166:169], v[202:205], v[106:109]
	v_mfma_f32_16x16x32_bf16 v[98:101], v[158:161], v[210:213], v[98:101]
	v_mfma_f32_16x16x32_bf16 v[90:93], v[166:169], v[210:213], v[90:93]
	v_mfma_f32_16x16x32_bf16 v[82:85], v[158:161], v[218:221], v[82:85]
	v_mfma_f32_16x16x32_bf16 v[74:77], v[166:169], v[218:221], v[74:77]
	v_mfma_f32_16x16x32_bf16 v[118:121], v[174:177], v[190:193], v[118:121]
	v_mfma_f32_16x16x32_bf16 v[110:113], v[182:185], v[190:193], v[110:113]
	v_mfma_f32_16x16x32_bf16 v[102:105], v[174:177], v[198:201], v[102:105]
	v_mfma_f32_16x16x32_bf16 v[94:97], v[182:185], v[198:201], v[94:97]
	v_mfma_f32_16x16x32_bf16 v[86:89], v[174:177], v[206:209], v[86:89]
	v_mfma_f32_16x16x32_bf16 v[78:81], v[182:185], v[206:209], v[78:81]
	v_mfma_f32_16x16x32_bf16 v[70:73], v[174:177], v[214:217], v[70:73]
	v_mfma_f32_16x16x32_bf16 v[66:69], v[182:185], v[214:217], v[66:69]
	v_mfma_f32_16x16x32_bf16 v[118:121], v[178:181], v[194:197], v[118:121]
	v_mfma_f32_16x16x32_bf16 v[110:113], v[186:189], v[194:197], v[110:113]
	v_mfma_f32_16x16x32_bf16 v[102:105], v[178:181], v[202:205], v[102:105]
	v_mfma_f32_16x16x32_bf16 v[94:97], v[186:189], v[202:205], v[94:97]
	v_mfma_f32_16x16x32_bf16 v[86:89], v[178:181], v[210:213], v[86:89]
	v_mfma_f32_16x16x32_bf16 v[78:81], v[186:189], v[210:213], v[78:81]
	v_mfma_f32_16x16x32_bf16 v[70:73], v[178:181], v[218:221], v[70:73]
	v_mfma_f32_16x16x32_bf16 v[66:69], v[186:189], v[218:221], v[66:69]
	s_barrier
; #define PG8_BAR __builtin_amdgcn_s_barrier()
; template <class Epi, class Sched, bool ALIGN_EPI = false, bool SP2 = false>
; __device__ __forceinline__ void gemm_phase(PG8_LAS unsigned char* lds, const Gemm g, const Sched& S, const Epi& E) {
;     ...
;             PG8_LDA(At, 1, 1); PG8_STAGE(PG8_SB(1, 0), b3, voffB); PG8_STAGE(PG8_SB(1, 1), b3 + hstep, voffB); PG8_STAGE(PG8_SA(1, 0), a3, voffA);
;             PG8_WAIT_V(8); PG8_WAIT_L(0); PG8_BAR; PG8_MMA(1, 0, At, B0); PG8_MMA(1, 1, At, B1); PG8_BAR; PG8_SCHED;
;             } else {
;             PG8_LDB(B0, 0, 0); PG8_SCHED; PG8_LDA(At, 0, 0); PG8_STAGE(PG8_SA(1, 1), a1 + hstep, voffA);
;             PG8_WAIT_L(8); PG8_BAR; PG8_WAIT_L(0); PG8_MMA(0, 0, At, B0); PG8_BAR; PG8_SCHED;
;             PG8_LDB(B1, 0, 1); PG8_STAGE(PG8_SB(0, 0), b2, voffB);
;             PG8_BAR; PG8_WAIT_L(0); PG8_MMA(0, 1, At, B1); PG8_BAR;
;             PG8_LDA(At, 0, 1); PG8_STAGE(PG8_SA(0, 0), a2, voffA);
;             PG8_BAR; PG8_WAIT_L(0); PG8_MMA(1, 0, At, B0); PG8_BAR; PG8_SCHED;
;             PG8_STAGE(PG8_SB(0, 1), b2 + hstep, voffB);
;             PG8_WAIT_V(6); PG8_BAR; PG8_MMA(1, 1, At, B1); PG8_BAR;
;             PG8_LDB(B0, 1, 0); PG8_SCHED; PG8_LDA(At, 1, 0); PG8_STAGE(PG8_SA(0, 1), a2 + hstep, voffA);
;             PG8_WAIT_L(8); PG8_BAR; PG8_WAIT_L(0); PG8_MMA(0, 0, At, B0); PG8_BAR; PG8_SCHED;
;             PG8_LDB(B1, 1, 1); PG8_STAGE(PG8_SB(1, 0), b3, voffB);
;             PG8_BAR; PG8_WAIT_L(0); PG8_MMA(0, 1, At, B1); PG8_BAR;
;             PG8_LDA(At, 1, 1); PG8_STAGE(PG8_SA(1, 0), a3, voffA);
;             PG8_BAR; PG8_WAIT_L(0); PG8_MMA(1, 0, At, B0); PG8_BAR; PG8_SCHED;
;             PG8_STAGE(PG8_SB(1, 1), b3 + hstep, voffB);
;             PG8_WAIT_V(6); PG8_BAR; PG8_MMA(1, 1, At, B1); PG8_BAR;
;             }
;         }
;         if constexpr (ALIGN_EPI) { if (wr == 0) PG8_BAR; }
;     __device__ __forceinline__ void operator()(const f32x4 (&acc)[2][2][4][2], const pg8::Unit& u, int wr, int wc, int fr, int fq) const {
;     ...
;                         if constexpr (MODE == EP_MULG) {
;                             const u32x4 gv = *(const u32x4*)(G + row * 1024 + col);
;                             r[0] *= lo_bf(gv.x); r[1] *= hi_bf(gv.x); r[2] *= lo_bf(gv.y); r[3] *= hi_bf(gv.y); r[4] *= lo_bf(gv.z); r[5] *= hi_bf(gv.z); r[6] *= lo_bf(gv.w); r[7] *= hi_bf(gv.w);
;                         }
	s_add_i32 s34, s65, s42
	v_lshl_add_u64 v[150:151], v[150:151], 0, s[8:9]
	s_mov_b32 m0, s34
	ds_read_b128 v[190:193], v156 offset:49152
	ds_read_b128 v[194:197], v156 offset:50176
	ds_read_b128 v[198:201], v156 offset:51200
	ds_read_b128 v[202:205], v156 offset:52224
	ds_read_b128 v[206:209], v156 offset:53248
	ds_read_b128 v[210:213], v156 offset:54272
	ds_read_b128 v[214:217], v156 offset:55296
	ds_read_b128 v[218:221], v156 offset:56320
	global_load_lds_dwordx4 v[150:151], off
	s_add_i32 m0, s34, 0x2000
	s_add_u32 s30, s30, 0x40080
	v_lshl_add_u64 v[150:151], v[170:171], 0, s[8:9]
	s_addc_u32 s31, s31, 0
	s_add_i32 s34, s66, s42
	global_load_lds_dwordx4 v[150:151], off
	v_lshl_add_u64 v[150:151], s[30:31], 0, v[132:133]
	s_mov_b32 m0, s34
	s_nop 0
	global_load_lds_dwordx4 v[150:151], off
	v_lshl_add_u64 v[150:151], s[30:31], 0, v[136:137]
	s_add_i32 m0, s34, 0x2000
	s_nop 0
	global_load_lds_dwordx4 v[150:151], off
	v_lshl_add_u64 v[150:151], v[222:223], 0, s[8:9]
	s_mov_b32 m0, s53
	s_nop 0
	global_load_lds_dwordx4 v[150:151], off
	v_lshl_add_u64 v[150:151], v[224:225], 0, s[8:9]
	s_mov_b32 m0, s54
	s_nop 0
	global_load_lds_dwordx4 v[150:151], off
	s_waitcnt vmcnt(8)
	s_waitcnt lgkmcnt(0)
	s_barrier
	s_waitcnt lgkmcnt(0)
	v_mfma_f32_16x16x32_bf16 v[62:65], v[146:149], v[190:193], v[62:65]
	v_mfma_f32_16x16x32_bf16 v[58:61], v[162:165], v[190:193], v[58:61]
	v_mfma_f32_16x16x32_bf16 v[50:53], v[146:149], v[198:201], v[50:53]
	v_mfma_f32_16x16x32_bf16 v[42:45], v[162:165], v[198:201], v[42:45]
	v_mfma_f32_16x16x32_bf16 v[34:37], v[146:149], v[206:209], v[34:37]
	v_mfma_f32_16x16x32_bf16 v[26:29], v[162:165], v[206:209], v[26:29]
	v_mfma_f32_16x16x32_bf16 v[18:21], v[146:149], v[214:217], v[18:21]
	v_mfma_f32_16x16x32_bf16 v[10:13], v[162:165], v[214:217], v[10:13]
	v_mfma_f32_16x16x32_bf16 v[62:65], v[158:161], v[194:197], v[62:65]
	v_mfma_f32_16x16x32_bf16 v[58:61], v[166:169], v[194:197], v[58:61]
	v_mfma_f32_16x16x32_bf16 v[50:53], v[158:161], v[202:205], v[50:53]
	v_mfma_f32_16x16x32_bf16 v[42:45], v[166:169], v[202:205], v[42:45]
	v_mfma_f32_16x16x32_bf16 v[34:37], v[158:161], v[210:213], v[34:37]
	v_mfma_f32_16x16x32_bf16 v[26:29], v[166:169], v[210:213], v[26:29]
	v_mfma_f32_16x16x32_bf16 v[18:21], v[158:161], v[218:221], v[18:21]
	v_mfma_f32_16x16x32_bf16 v[10:13], v[166:169], v[218:221], v[10:13]
	v_mfma_f32_16x16x32_bf16 v[54:57], v[174:177], v[190:193], v[54:57]
	v_mfma_f32_16x16x32_bf16 v[46:49], v[182:185], v[190:193], v[46:49]
	v_mfma_f32_16x16x32_bf16 v[38:41], v[174:177], v[198:201], v[38:41]
	v_mfma_f32_16x16x32_bf16 v[30:33], v[182:185], v[198:201], v[30:33]
	v_mfma_f32_16x16x32_bf16 v[22:25], v[174:177], v[206:209], v[22:25]
	v_mfma_f32_16x16x32_bf16 v[14:17], v[182:185], v[206:209], v[14:17]
	v_mfma_f32_16x16x32_bf16 v[6:9], v[174:177], v[214:217], v[6:9]
	v_mfma_f32_16x16x32_bf16 v[2:5], v[182:185], v[214:217], v[2:5]
	v_mfma_f32_16x16x32_bf16 v[54:57], v[178:181], v[194:197], v[54:57]
	v_mfma_f32_16x16x32_bf16 v[46:49], v[186:189], v[194:197], v[46:49]
	v_mfma_f32_16x16x32_bf16 v[38:41], v[178:181], v[202:205], v[38:41]
	v_mfma_f32_16x16x32_bf16 v[30:33], v[186:189], v[202:205], v[30:33]
	v_mfma_f32_16x16x32_bf16 v[22:25], v[178:181], v[210:213], v[22:25]
	v_mfma_f32_16x16x32_bf16 v[14:17], v[186:189], v[210:213], v[14:17]
	v_mfma_f32_16x16x32_bf16 v[6:9], v[178:181], v[218:221], v[6:9]
	v_mfma_f32_16x16x32_bf16 v[2:5], v[186:189], v[218:221], v[2:5]
	s_barrier
	s_add_i32 s64, s64, 2
	s_add_u32 s28, s28, 0x100
	s_addc_u32 s29, s29, 0
	s_add_u32 s62, s62, 0x100
	s_addc_u32 s63, s63, 0
	s_cmp_gt_u32 s64, 13
	s_cbranch_scc0 .LBB0_1314
	s_andn2_b64 vcc, s[10:11], s[2:3]
	s_cbranch_vccz .LBB0_1317
	s_barrier
.LBB0_1317:
	v_lshl_add_u32 v150, s26, 8, v1
	v_lshl_or_b32 v146, s59, 8, v153
	v_ashrrev_i32_e32 v151, 31, v150
	v_lshlrev_b64 v[148:149], 11, v[150:151]
	v_ashrrev_i32_e32 v147, 31, v146
	v_lshlrev_b64 v[146:147], 1, v[146:147]
	v_lshl_add_u64 v[158:159], s[90:91], 0, v[148:149]
	v_lshl_add_u64 v[162:163], v[158:159], 0, v[146:147]
	global_load_dwordx4 v[158:161], v[162:163], off
	v_lshl_add_u64 v[164:165], s[6:7], 0, v[148:149]
	v_lshl_add_u64 v[164:165], v[164:165], 0, v[146:147]
	s_andn2_b64 vcc, exec, s[2:3]
	s_mov_b64 s[2:3], -1
	s_waitcnt vmcnt(0)
	v_lshlrev_b32_e32 v167, 16, v161
	v_and_b32_e32 v161, 0xffff0000, v161
	v_lshlrev_b32_e32 v151, 16, v158
	v_and_b32_e32 v157, 0xffff0000, v158
	v_lshlrev_b32_e32 v158, 16, v159
	v_and_b32_e32 v159, 0xffff0000, v159
	v_lshlrev_b32_e32 v166, 16, v160
	v_and_b32_e32 v160, 0xffff0000, v160
	v_mul_f32_e32 v125, v125, v161
	v_mul_f32_e32 v126, v126, v151
	v_mul_f32_e32 v127, v127, v157
	v_mul_f32_e32 v128, v128, v158
	v_mul_f32_e32 v129, v129, v159
	v_mul_f32_e32 v151, v122, v166
	v_mul_f32_e32 v157, v123, v160
	v_mul_f32_e32 v158, v124, v167
	v_cvt_pk_bf16_f32 v122, v126, v127
	v_cvt_pk_bf16_f32 v123, v128, v129
	v_cvt_pk_bf16_f32 v124, v151, v157
	v_cvt_pk_bf16_f32 v125, v158, v125
	global_store_dwordx4 v[164:165], v[122:125], off
	global_load_dwordx4 v[122:125], v[162:163], off offset:256
	v_or_b32_e32 v126, 16, v150
	v_ashrrev_i32_e32 v127, 31, v126
	v_lshlrev_b64 v[126:127], 11, v[126:127]
	v_lshl_add_u64 v[128:129], s[90:91], 0, v[126:127]
	v_lshl_add_u64 v[128:129], v[128:129], 0, v[146:147]
	s_waitcnt vmcnt(0)
; __device__ __forceinline__ unsigned cvt_pk_bf16(float lo, float hi) { unsigned r; asm volatile("v_cvt_pk_bf16_f32 %0, %1, %2" : "=v"(r) : "v"(lo), "v"(hi)); return r; }
; __device__ __forceinline__ float lo_bf(unsigned u) { return __uint_as_float(u << 16); }
; __device__ __forceinline__ float hi_bf(unsigned u) { return __uint_as_float(u & 0xffff0000u); }
;     __device__ __forceinline__ void operator()(const f32x4 (&acc)[2][2][4][2], const pg8::Unit& u, int wr, int wc, int fr, int fq) const {
;     ...
;                         if constexpr (MODE == EP_MULG) {
;                             const u32x4 gv = *(const u32x4*)(G + row * 1024 + col);
;                             r[0] *= lo_bf(gv.x); r[1] *= hi_bf(gv.x); r[2] *= lo_bf(gv.y); r[3] *= hi_bf(gv.y); r[4] *= lo_bf(gv.z); r[5] *= hi_bf(gv.z); r[6] *= lo_bf(gv.w); r[7] *= hi_bf(gv.w);
;                         }
;     ...
;                         u32x4 w; w.x = cvt_pk_bf16(r[0], r[1]); w.y = cvt_pk_bf16(r[2], r[3]); w.z = cvt_pk_bf16(r[4], r[5]); w.w = cvt_pk_bf16(r[6], r[7]);
;                         *(u32x4*)dst = w;
	v_lshlrev_b32_e32 v159, 16, v125
	v_and_b32_e32 v125, 0xffff0000, v125
	v_lshlrev_b32_e32 v151, 16, v122
	v_and_b32_e32 v122, 0xffff0000, v122
	v_lshlrev_b32_e32 v157, 16, v123
	v_and_b32_e32 v123, 0xffff0000, v123
	v_lshlrev_b32_e32 v158, 16, v124
	v_and_b32_e32 v124, 0xffff0000, v124
	v_mul_f32_e32 v113, v113, v125
	v_mul_f32_e32 v118, v118, v151
	v_mul_f32_e32 v119, v119, v122
	v_mul_f32_e32 v120, v120, v157
	v_mul_f32_e32 v121, v121, v123
	v_mul_f32_e32 v122, v110, v158
	v_mul_f32_e32 v123, v111, v124
	v_mul_f32_e32 v124, v112, v159
	v_cvt_pk_bf16_f32 v110, v118, v119
	v_cvt_pk_bf16_f32 v111, v120, v121
	v_cvt_pk_bf16_f32 v112, v122, v123
	v_cvt_pk_bf16_f32 v113, v124, v113
	global_store_dwordx4 v[164:165], v[110:113], off offset:256
	global_load_dwordx4 v[110:113], v[128:129], off
	v_lshl_add_u64 v[118:119], s[6:7], 0, v[126:127]
	v_lshl_add_u64 v[118:119], v[118:119], 0, v[146:147]
	s_waitcnt vmcnt(0)
	v_lshlrev_b32_e32 v123, 16, v113
	v_and_b32_e32 v113, 0xffff0000, v113
	v_lshlrev_b32_e32 v120, 16, v110
	v_and_b32_e32 v110, 0xffff0000, v110
	v_lshlrev_b32_e32 v121, 16, v111
	v_and_b32_e32 v111, 0xffff0000, v111
	v_lshlrev_b32_e32 v122, 16, v112
	v_and_b32_e32 v112, 0xffff0000, v112
	v_mul_f32_e32 v109, v109, v113
	v_mul_f32_e32 v114, v114, v120
	v_mul_f32_e32 v110, v115, v110
	v_mul_f32_e32 v115, v116, v121
	v_mul_f32_e32 v111, v117, v111
	v_mul_f32_e32 v116, v106, v122
	v_mul_f32_e32 v112, v107, v112
	v_mul_f32_e32 v117, v108, v123
	v_cvt_pk_bf16_f32 v106, v114, v110
	v_cvt_pk_bf16_f32 v107, v115, v111
	v_cvt_pk_bf16_f32 v108, v116, v112
	v_cvt_pk_bf16_f32 v109, v117, v109
	global_store_dwordx4 v[118:119], v[106:109], off
	global_load_dwordx4 v[106:109], v[128:129], off offset:256
	v_or_b32_e32 v110, 32, v150
	v_ashrrev_i32_e32 v111, 31, v110
	v_lshlrev_b64 v[110:111], 11, v[110:111]
	v_lshl_add_u64 v[112:113], s[90:91], 0, v[110:111]
	v_lshl_add_u64 v[112:113], v[112:113], 0, v[146:147]
	s_waitcnt vmcnt(0)
	v_lshlrev_b32_e32 v117, 16, v109
	v_and_b32_e32 v109, 0xffff0000, v109
	v_lshlrev_b32_e32 v114, 16, v106
	v_and_b32_e32 v106, 0xffff0000, v106
	v_lshlrev_b32_e32 v115, 16, v107
	v_and_b32_e32 v107, 0xffff0000, v107
	v_lshlrev_b32_e32 v116, 16, v108
	v_and_b32_e32 v108, 0xffff0000, v108
	v_mul_f32_e32 v97, v97, v109
	v_mul_f32_e32 v102, v102, v114
	v_mul_f32_e32 v103, v103, v106
	v_mul_f32_e32 v104, v104, v115
	v_mul_f32_e32 v105, v105, v107
	v_mul_f32_e32 v106, v94, v116
	v_mul_f32_e32 v107, v95, v108
	v_mul_f32_e32 v108, v96, v117
	v_cvt_pk_bf16_f32 v94, v102, v103
	v_cvt_pk_bf16_f32 v95, v104, v105
	v_cvt_pk_bf16_f32 v96, v106, v107
	v_cvt_pk_bf16_f32 v97, v108, v97
	global_store_dwordx4 v[118:119], v[94:97], off offset:256
	global_load_dwordx4 v[94:97], v[112:113], off
	v_lshl_add_u64 v[102:103], s[6:7], 0, v[110:111]
	v_lshl_add_u64 v[102:103], v[102:103], 0, v[146:147]
	s_waitcnt vmcnt(0)
	v_lshlrev_b32_e32 v107, 16, v97
	v_and_b32_e32 v97, 0xffff0000, v97
	v_lshlrev_b32_e32 v104, 16, v94
	v_and_b32_e32 v94, 0xffff0000, v94
	v_lshlrev_b32_e32 v105, 16, v95
	v_and_b32_e32 v95, 0xffff0000, v95
	v_lshlrev_b32_e32 v106, 16, v96
	v_and_b32_e32 v96, 0xffff0000, v96
	v_mul_f32_e32 v93, v93, v97
	v_mul_f32_e32 v98, v98, v104
	v_mul_f32_e32 v94, v99, v94
	v_mul_f32_e32 v99, v100, v105
	v_mul_f32_e32 v95, v101, v95
	v_mul_f32_e32 v100, v90, v106
	v_mul_f32_e32 v96, v91, v96
	v_mul_f32_e32 v101, v92, v107
	v_cvt_pk_bf16_f32 v90, v98, v94
	v_cvt_pk_bf16_f32 v91, v99, v95
	v_cvt_pk_bf16_f32 v92, v100, v96
	v_cvt_pk_bf16_f32 v93, v101, v93
	global_store_dwordx4 v[102:103], v[90:93], off
	global_load_dwordx4 v[90:93], v[112:113], off offset:256
	v_or_b32_e32 v94, 48, v150
	v_ashrrev_i32_e32 v95, 31, v94
	v_lshlrev_b64 v[94:95], 11, v[94:95]
	v_lshl_add_u64 v[96:97], s[90:91], 0, v[94:95]
	v_lshl_add_u64 v[96:97], v[96:97], 0, v[146:147]
	s_waitcnt vmcnt(0)
	v_lshlrev_b32_e32 v101, 16, v93
	v_and_b32_e32 v93, 0xffff0000, v93
	v_lshlrev_b32_e32 v98, 16, v90
	v_and_b32_e32 v90, 0xffff0000, v90
	v_lshlrev_b32_e32 v99, 16, v91
	v_and_b32_e32 v91, 0xffff0000, v91
	v_lshlrev_b32_e32 v100, 16, v92
	v_and_b32_e32 v92, 0xffff0000, v92
	v_mul_f32_e32 v81, v81, v93
	v_mul_f32_e32 v86, v86, v98
	v_mul_f32_e32 v87, v87, v90
	v_mul_f32_e32 v88, v88, v99
	v_mul_f32_e32 v89, v89, v91
	v_mul_f32_e32 v90, v78, v100
	v_mul_f32_e32 v91, v79, v92
	v_mul_f32_e32 v92, v80, v101
	v_cvt_pk_bf16_f32 v78, v86, v87
	v_cvt_pk_bf16_f32 v79, v88, v89
	v_cvt_pk_bf16_f32 v80, v90, v91
	v_cvt_pk_bf16_f32 v81, v92, v81
	global_store_dwordx4 v[102:103], v[78:81], off offset:256
	global_load_dwordx4 v[78:81], v[96:97], off
	v_lshl_add_u64 v[86:87], s[6:7], 0, v[94:95]
	v_lshl_add_u64 v[86:87], v[86:87], 0, v[146:147]
	s_waitcnt vmcnt(0)
	v_lshlrev_b32_e32 v91, 16, v81
	v_and_b32_e32 v81, 0xffff0000, v81
	v_lshlrev_b32_e32 v88, 16, v78
	v_and_b32_e32 v78, 0xffff0000, v78
	v_lshlrev_b32_e32 v89, 16, v79
	v_and_b32_e32 v79, 0xffff0000, v79
	v_lshlrev_b32_e32 v90, 16, v80
	v_and_b32_e32 v80, 0xffff0000, v80
	v_mul_f32_e32 v77, v77, v81
	v_mul_f32_e32 v82, v82, v88
	v_mul_f32_e32 v78, v83, v78
	v_mul_f32_e32 v83, v84, v89
	v_mul_f32_e32 v79, v85, v79
	v_mul_f32_e32 v84, v74, v90
	v_mul_f32_e32 v80, v75, v80
	v_mul_f32_e32 v85, v76, v91
	v_cvt_pk_bf16_f32 v74, v82, v78
	v_cvt_pk_bf16_f32 v75, v83, v79
	v_cvt_pk_bf16_f32 v76, v84, v80
	v_cvt_pk_bf16_f32 v77, v85, v77
	global_store_dwordx4 v[86:87], v[74:77], off
	global_load_dwordx4 v[74:77], v[96:97], off offset:256
	v_lshl_add_u64 v[78:79], v[148:149], 0, s[0:1]
	v_lshl_add_u64 v[80:81], s[90:91], 0, v[78:79]
	v_lshl_add_u64 v[80:81], v[80:81], 0, v[146:147]
	s_waitcnt vmcnt(0)
; __device__ __forceinline__ unsigned cvt_pk_bf16(float lo, float hi) { unsigned r; asm volatile("v_cvt_pk_bf16_f32 %0, %1, %2" : "=v"(r) : "v"(lo), "v"(hi)); return r; }
; __device__ __forceinline__ float lo_bf(unsigned u) { return __uint_as_float(u << 16); }
; __device__ __forceinline__ float hi_bf(unsigned u) { return __uint_as_float(u & 0xffff0000u); }
;     __device__ __forceinline__ void operator()(const f32x4 (&acc)[2][2][4][2], const pg8::Unit& u, int wr, int wc, int fr, int fq) const {
;     ...
;                         if constexpr (MODE == EP_MULG) {
;                             const u32x4 gv = *(const u32x4*)(G + row * 1024 + col);
;                             r[0] *= lo_bf(gv.x); r[1] *= hi_bf(gv.x); r[2] *= lo_bf(gv.y); r[3] *= hi_bf(gv.y); r[4] *= lo_bf(gv.z); r[5] *= hi_bf(gv.z); r[6] *= lo_bf(gv.w); r[7] *= hi_bf(gv.w);
;                         }
;     ...
;                         u32x4 w; w.x = cvt_pk_bf16(r[0], r[1]); w.y = cvt_pk_bf16(r[2], r[3]); w.z = cvt_pk_bf16(r[4], r[5]); w.w = cvt_pk_bf16(r[6], r[7]);
;                         *(u32x4*)dst = w;
	v_lshlrev_b32_e32 v85, 16, v77
	v_and_b32_e32 v77, 0xffff0000, v77
	v_lshlrev_b32_e32 v82, 16, v74
	v_and_b32_e32 v74, 0xffff0000, v74
	v_lshlrev_b32_e32 v83, 16, v75
	v_and_b32_e32 v75, 0xffff0000, v75
	v_lshlrev_b32_e32 v84, 16, v76
	v_and_b32_e32 v76, 0xffff0000, v76
	v_mul_f32_e32 v69, v69, v77
	v_mul_f32_e32 v70, v70, v82
	v_mul_f32_e32 v71, v71, v74
	v_mul_f32_e32 v72, v72, v83
	v_mul_f32_e32 v73, v73, v75
	v_mul_f32_e32 v74, v66, v84
	v_mul_f32_e32 v75, v67, v76
	v_mul_f32_e32 v76, v68, v85
	v_cvt_pk_bf16_f32 v66, v70, v71
	v_cvt_pk_bf16_f32 v67, v72, v73
	v_cvt_pk_bf16_f32 v68, v74, v75
	v_cvt_pk_bf16_f32 v69, v76, v69
	global_store_dwordx4 v[86:87], v[66:69], off offset:256
	global_load_dwordx4 v[66:69], v[80:81], off
	v_lshl_add_u64 v[70:71], s[6:7], 0, v[78:79]
	v_lshl_add_u64 v[70:71], v[70:71], 0, v[146:147]
	s_waitcnt vmcnt(0)
	v_lshlrev_b32_e32 v75, 16, v69
	v_and_b32_e32 v69, 0xffff0000, v69
	v_lshlrev_b32_e32 v72, 16, v66
	v_and_b32_e32 v66, 0xffff0000, v66
	v_lshlrev_b32_e32 v73, 16, v67
	v_and_b32_e32 v67, 0xffff0000, v67
	v_lshlrev_b32_e32 v74, 16, v68
	v_and_b32_e32 v68, 0xffff0000, v68
	v_mul_f32_e32 v61, v61, v69
	v_mul_f32_e32 v62, v62, v72
	v_mul_f32_e32 v63, v63, v66
	v_mul_f32_e32 v64, v64, v73
	v_mul_f32_e32 v65, v65, v67
	v_mul_f32_e32 v66, v58, v74
	v_mul_f32_e32 v67, v59, v68
	v_mul_f32_e32 v68, v60, v75
	v_cvt_pk_bf16_f32 v58, v62, v63
	v_cvt_pk_bf16_f32 v59, v64, v65
	v_cvt_pk_bf16_f32 v60, v66, v67
	v_cvt_pk_bf16_f32 v61, v68, v61
	global_store_dwordx4 v[70:71], v[58:61], off
	global_load_dwordx4 v[58:61], v[80:81], off offset:256
	v_lshl_add_u64 v[62:63], v[148:149], 0, s[12:13]
	v_lshl_add_u64 v[64:65], s[90:91], 0, v[62:63]
	v_lshl_add_u64 v[64:65], v[64:65], 0, v[146:147]
	s_waitcnt vmcnt(0)
	v_lshlrev_b32_e32 v69, 16, v61
	v_and_b32_e32 v61, 0xffff0000, v61
	v_lshlrev_b32_e32 v66, 16, v58
	v_and_b32_e32 v58, 0xffff0000, v58
	v_lshlrev_b32_e32 v67, 16, v59
	v_and_b32_e32 v59, 0xffff0000, v59
	v_lshlrev_b32_e32 v68, 16, v60
	v_and_b32_e32 v60, 0xffff0000, v60
	v_mul_f32_e32 v49, v49, v61
	v_mul_f32_e32 v54, v54, v66
	v_mul_f32_e32 v55, v55, v58
	v_mul_f32_e32 v56, v56, v67
	v_mul_f32_e32 v57, v57, v59
	v_mul_f32_e32 v58, v46, v68
	v_mul_f32_e32 v59, v47, v60
	v_mul_f32_e32 v60, v48, v69
	v_cvt_pk_bf16_f32 v46, v54, v55
	v_cvt_pk_bf16_f32 v47, v56, v57
	v_cvt_pk_bf16_f32 v48, v58, v59
	v_cvt_pk_bf16_f32 v49, v60, v49
	global_store_dwordx4 v[70:71], v[46:49], off offset:256
	global_load_dwordx4 v[46:49], v[64:65], off
	v_lshl_add_u64 v[54:55], s[6:7], 0, v[62:63]
	v_lshl_add_u64 v[54:55], v[54:55], 0, v[146:147]
	s_waitcnt vmcnt(0)
	v_lshlrev_b32_e32 v59, 16, v49
	v_and_b32_e32 v49, 0xffff0000, v49
	v_lshlrev_b32_e32 v56, 16, v46
	v_and_b32_e32 v46, 0xffff0000, v46
	v_lshlrev_b32_e32 v57, 16, v47
	v_and_b32_e32 v47, 0xffff0000, v47
	v_lshlrev_b32_e32 v58, 16, v48
	v_and_b32_e32 v48, 0xffff0000, v48
	v_mul_f32_e32 v45, v45, v49
	v_mul_f32_e32 v50, v50, v56
	v_mul_f32_e32 v46, v51, v46
	v_mul_f32_e32 v51, v52, v57
	v_mul_f32_e32 v47, v53, v47
	v_mul_f32_e32 v52, v42, v58
	v_mul_f32_e32 v48, v43, v48
	v_mul_f32_e32 v53, v44, v59
	v_cvt_pk_bf16_f32 v42, v50, v46
	v_cvt_pk_bf16_f32 v43, v51, v47
	v_cvt_pk_bf16_f32 v44, v52, v48
	v_cvt_pk_bf16_f32 v45, v53, v45
	global_store_dwordx4 v[54:55], v[42:45], off
	global_load_dwordx4 v[42:45], v[64:65], off offset:256
	v_lshl_add_u64 v[46:47], v[148:149], 0, s[14:15]
	v_lshl_add_u64 v[48:49], s[90:91], 0, v[46:47]
	v_lshl_add_u64 v[48:49], v[48:49], 0, v[146:147]
	s_waitcnt vmcnt(0)
; #define PG8_BAR __builtin_amdgcn_s_barrier()
; __device__ __forceinline__ float lo_bf(unsigned u) { return __uint_as_float(u << 16); }
; __device__ __forceinline__ float hi_bf(unsigned u) { return __uint_as_float(u & 0xffff0000u); }
; template <class Epi, class Sched, bool ALIGN_EPI = false, bool SP2 = false>
; __device__ __forceinline__ void gemm_phase(PG8_LAS unsigned char* lds, const Gemm g, const Sched& S, const Epi& E) {
;     ...
;         if (!has_next) break;
; #pragma unroll
;         for (int a = 0; a < 2; ++a)
; #pragma unroll
;             for (int b = 0; b < 2; ++b)
; #pragma unroll
;                 for (int m = 0; m < 4; ++m)
; #pragma unroll
;                     for (int n = 0; n < 2; ++n) acc[a][b][m][n] = (f32x4){0.f, 0.f, 0.f, 0.f};
;         cur = nxt; cA = nA; cB = nB; ++ui;
;         if constexpr (ALIGN_EPI) { if (wr == 1) PG8_BAR; }
;     __device__ __forceinline__ void operator()(const f32x4 (&acc)[2][2][4][2], const pg8::Unit& u, int wr, int wc, int fr, int fq) const {
;     ...
;                         if constexpr (MODE == EP_MULG) {
;                             const u32x4 gv = *(const u32x4*)(G + row * 1024 + col);
;                             r[0] *= lo_bf(gv.x); r[1] *= hi_bf(gv.x); r[2] *= lo_bf(gv.y); r[3] *= hi_bf(gv.y); r[4] *= lo_bf(gv.z); r[5] *= hi_bf(gv.z); r[6] *= lo_bf(gv.w); r[7] *= hi_bf(gv.w);
;                         }
	v_lshlrev_b32_e32 v53, 16, v45
	v_and_b32_e32 v45, 0xffff0000, v45
	v_lshlrev_b32_e32 v50, 16, v42
	v_and_b32_e32 v42, 0xffff0000, v42
	v_lshlrev_b32_e32 v51, 16, v43
	v_and_b32_e32 v43, 0xffff0000, v43
	v_lshlrev_b32_e32 v52, 16, v44
	v_and_b32_e32 v44, 0xffff0000, v44
	v_mul_f32_e32 v33, v33, v45
	v_mul_f32_e32 v38, v38, v50
	v_mul_f32_e32 v39, v39, v42
	v_mul_f32_e32 v40, v40, v51
	v_mul_f32_e32 v41, v41, v43
	v_mul_f32_e32 v42, v30, v52
	v_mul_f32_e32 v43, v31, v44
	v_mul_f32_e32 v44, v32, v53
	v_cvt_pk_bf16_f32 v30, v38, v39
	v_cvt_pk_bf16_f32 v31, v40, v41
	v_cvt_pk_bf16_f32 v32, v42, v43
	v_cvt_pk_bf16_f32 v33, v44, v33
	global_store_dwordx4 v[54:55], v[30:33], off offset:256
	global_load_dwordx4 v[30:33], v[48:49], off
	v_lshl_add_u64 v[38:39], s[6:7], 0, v[46:47]
	v_lshl_add_u64 v[38:39], v[38:39], 0, v[146:147]
	s_waitcnt vmcnt(0)
	v_lshlrev_b32_e32 v43, 16, v33
	v_and_b32_e32 v33, 0xffff0000, v33
	v_lshlrev_b32_e32 v40, 16, v30
	v_and_b32_e32 v30, 0xffff0000, v30
	v_lshlrev_b32_e32 v41, 16, v31
	v_and_b32_e32 v31, 0xffff0000, v31
	v_lshlrev_b32_e32 v42, 16, v32
	v_and_b32_e32 v32, 0xffff0000, v32
	v_mul_f32_e32 v29, v29, v33
	v_mul_f32_e32 v34, v34, v40
	v_mul_f32_e32 v30, v35, v30
	v_mul_f32_e32 v35, v36, v41
	v_mul_f32_e32 v31, v37, v31
	v_mul_f32_e32 v36, v26, v42
	v_mul_f32_e32 v32, v27, v32
	v_mul_f32_e32 v37, v28, v43
	v_cvt_pk_bf16_f32 v26, v34, v30
	v_cvt_pk_bf16_f32 v27, v35, v31
	v_cvt_pk_bf16_f32 v28, v36, v32
	v_cvt_pk_bf16_f32 v29, v37, v29
	global_store_dwordx4 v[38:39], v[26:29], off
	global_load_dwordx4 v[26:29], v[48:49], off offset:256
	v_lshl_add_u64 v[30:31], v[148:149], 0, s[16:17]
	v_lshl_add_u64 v[32:33], s[90:91], 0, v[30:31]
	v_lshl_add_u64 v[32:33], v[32:33], 0, v[146:147]
	s_waitcnt vmcnt(0)
	v_lshlrev_b32_e32 v37, 16, v29
	v_and_b32_e32 v29, 0xffff0000, v29
	v_lshlrev_b32_e32 v34, 16, v26
	v_and_b32_e32 v26, 0xffff0000, v26
	v_lshlrev_b32_e32 v35, 16, v27
	v_and_b32_e32 v27, 0xffff0000, v27
	v_lshlrev_b32_e32 v36, 16, v28
	v_and_b32_e32 v28, 0xffff0000, v28
	v_mul_f32_e32 v17, v17, v29
	v_mul_f32_e32 v22, v22, v34
	v_mul_f32_e32 v23, v23, v26
	v_mul_f32_e32 v24, v24, v35
	v_mul_f32_e32 v25, v25, v27
	v_mul_f32_e32 v26, v14, v36
	v_mul_f32_e32 v27, v15, v28
	v_mul_f32_e32 v28, v16, v37
	v_cvt_pk_bf16_f32 v14, v22, v23
	v_cvt_pk_bf16_f32 v15, v24, v25
	v_cvt_pk_bf16_f32 v16, v26, v27
	v_cvt_pk_bf16_f32 v17, v28, v17
	global_store_dwordx4 v[38:39], v[14:17], off offset:256
	global_load_dwordx4 v[14:17], v[32:33], off
	v_lshl_add_u64 v[22:23], s[6:7], 0, v[30:31]
	v_lshl_add_u64 v[22:23], v[22:23], 0, v[146:147]
	s_waitcnt vmcnt(0)
	v_lshlrev_b32_e32 v27, 16, v17
	v_and_b32_e32 v17, 0xffff0000, v17
	v_lshlrev_b32_e32 v24, 16, v14
	v_and_b32_e32 v14, 0xffff0000, v14
	v_lshlrev_b32_e32 v25, 16, v15
	v_and_b32_e32 v15, 0xffff0000, v15
	v_lshlrev_b32_e32 v26, 16, v16
	v_and_b32_e32 v16, 0xffff0000, v16
	v_mul_f32_e32 v13, v13, v17
	v_mul_f32_e32 v18, v18, v24
	v_mul_f32_e32 v14, v19, v14
	v_mul_f32_e32 v19, v20, v25
	v_mul_f32_e32 v15, v21, v15
	v_mul_f32_e32 v20, v10, v26
	v_mul_f32_e32 v16, v11, v16
	v_mul_f32_e32 v21, v12, v27
	v_cvt_pk_bf16_f32 v10, v18, v14
	v_cvt_pk_bf16_f32 v11, v19, v15
	v_cvt_pk_bf16_f32 v12, v20, v16
	v_cvt_pk_bf16_f32 v13, v21, v13
	global_store_dwordx4 v[22:23], v[10:13], off
	global_load_dwordx4 v[10:13], v[32:33], off offset:256
	s_waitcnt vmcnt(0)
	v_lshlrev_b32_e32 v17, 16, v13
	v_and_b32_e32 v13, 0xffff0000, v13
	v_lshlrev_b32_e32 v14, 16, v10
	v_and_b32_e32 v10, 0xffff0000, v10
	v_lshlrev_b32_e32 v15, 16, v11
	v_and_b32_e32 v11, 0xffff0000, v11
	v_lshlrev_b32_e32 v16, 16, v12
	v_and_b32_e32 v12, 0xffff0000, v12
	v_mul_f32_e32 v5, v5, v13
	v_mul_f32_e32 v6, v6, v14
	v_mul_f32_e32 v7, v7, v10
	v_mul_f32_e32 v8, v8, v15
	v_mul_f32_e32 v9, v9, v11
	v_mul_f32_e32 v10, v2, v16
	v_mul_f32_e32 v11, v3, v12
	v_mul_f32_e32 v12, v4, v17
	v_cvt_pk_bf16_f32 v2, v6, v7
	v_cvt_pk_bf16_f32 v3, v8, v9
	v_cvt_pk_bf16_f32 v4, v10, v11
	v_cvt_pk_bf16_f32 v5, v12, v5
	global_store_dwordx4 v[22:23], v[2:5], off offset:256
	s_cbranch_vccnz .LBB0_1306
	s_andn2_b64 vcc, exec, s[4:5]
	s_cbranch_vccnz .LBB0_1305
	s_branch .LBB0_1305

; #define PG8_STAGE(bufoff, gbase, voff) do { _Pragma("unroll") for (int _i = 0; _i < 2; ++_i) \
;         __builtin_amdgcn_global_load_lds((const unsigned*)((const char*)(gbase) + (voff)[_i]), (PG8_LAS unsigned*)(lds + (bufoff) + ldsw + _i * 8192), 16, 0, 0); } while (0)
; #define PG8_LDA(dst, b, h) do { _Pragma("unroll") for (int m = 0; m < 4; ++m) _Pragma("unroll") for (int k = 0; k < 2; ++k) dst[m][k] = *(const PG8_LAS bf16x8*)(lds + PG8_SA(b, h) + aoff + m * 2048 + k * 1024); } while (0)
; #define PG8_LDB(dst, b, h) do { _Pragma("unroll") for (int n = 0; n < 2; ++n) _Pragma("unroll") for (int k = 0; k < 2; ++k) dst[n][k] = *(const PG8_LAS bf16x8*)(lds + PG8_SB(b, h) + boff + n * 2048 + k * 1024); } while (0)
; #define PG8_MMA(ai, bj, At, Bt) do { __builtin_amdgcn_s_setprio(1); _Pragma("unroll") for (int m = 0; m < 4; ++m) _Pragma("unroll") for (int n = 0; n < 2; ++n) _Pragma("unroll") for (int k = 0; k < 2; ++k) \
;         acc[ai][bj][m][n] = __builtin_amdgcn_mfma_f32_16x16x32_bf16(Bt[n][k], At[m][k], acc[ai][bj][m][n], 0, 0, 0); __builtin_amdgcn_s_setprio(0); } while (0)
; #define PG8_WAIT_V(n) asm volatile("s_waitcnt vmcnt(" #n ")" ::: "memory")
; #define PG8_WAIT_L(n) asm volatile("s_waitcnt lgkmcnt(" #n ")" ::: "memory")
; template <class Epi, class Sched, bool ALIGN_EPI = false, bool SP2 = false>
; __device__ __forceinline__ void gemm_phase(PG8_LAS unsigned char* lds, const Gemm g, const Sched& S, const Epi& E) {
;     ...
;             const bool last = (t == nt - 2);
;             const char* a1 = cA + (size_t)(t + 1) * kstep;
;             const char* a2 = last ? nA : cA + (size_t)(t + 2) * kstep; const char* b2 = last ? nB : cB + (size_t)(t + 2) * kstep;
;             const char* a3 = a2 + kstep; const char* b3 = b2 + kstep;
;             if (last && has_next) S.a_ready(nxt);
;             if constexpr (SP2) {
;             PG8_LDB(B0, 0, 0); PG8_LDB(B1, 0, 1); PG8_SCHED; PG8_LDA(At, 0, 0); PG8_STAGE(PG8_SA(1, 1), a1 + hstep, voffA);
;             PG8_WAIT_V(8); PG8_WAIT_L(0); PG8_BAR; PG8_MMA(0, 0, At, B0); PG8_MMA(0, 1, At, B1); PG8_BAR; PG8_SCHED;
;             PG8_LDA(At, 0, 1); PG8_STAGE(PG8_SB(0, 0), b2, voffB); PG8_STAGE(PG8_SB(0, 1), b2 + hstep, voffB); PG8_STAGE(PG8_SA(0, 0), a2, voffA);
;             PG8_WAIT_V(8); PG8_WAIT_L(0); PG8_BAR; PG8_MMA(1, 0, At, B0); PG8_MMA(1, 1, At, B1); PG8_BAR; PG8_SCHED;
.LBB0_1339:
	ds_read_b128 v[146:149], v154
	ds_read_b128 v[158:161], v154 offset:1024
	ds_read_b128 v[162:165], v154 offset:2048
	ds_read_b128 v[166:169], v154 offset:3072
	ds_read_b128 v[174:177], v155
	ds_read_b128 v[178:181], v155 offset:1024
	ds_read_b128 v[182:185], v155 offset:2048
	ds_read_b128 v[186:189], v155 offset:3072
	s_add_u32 s38, s34, 0xfffe0080
	s_addc_u32 s39, s35, -1
	s_cmp_eq_u32 s68, 4
	s_cselect_b32 s41, s25, s39
	s_cselect_b32 s40, s64, s38
	s_cselect_b32 s39, s23, s67
	s_cselect_b32 s38, s65, s66
	v_lshl_add_u64 v[150:151], s[34:35], 0, v[138:139]
	s_add_i32 m0, s31, 0xc000
	ds_read_b128 v[190:193], v156
	ds_read_b128 v[194:197], v156 offset:1024
	ds_read_b128 v[198:201], v156 offset:2048
	ds_read_b128 v[202:205], v156 offset:3072
	ds_read_b128 v[206:209], v156 offset:4096
	ds_read_b128 v[210:213], v156 offset:5120
	ds_read_b128 v[214:217], v156 offset:6144
	ds_read_b128 v[218:221], v156 offset:7168
	global_load_lds_dwordx4 v[150:151], off
	v_lshl_add_u64 v[150:151], s[34:35], 0, v[140:141]
	s_add_i32 m0, s31, 0xe000
	s_nop 0
	global_load_lds_dwordx4 v[150:151], off
	s_waitcnt vmcnt(8)
	s_waitcnt lgkmcnt(0)
	s_barrier
	s_waitcnt lgkmcnt(0)
	v_mfma_f32_16x16x32_bf16 v[126:129], v[146:149], v[190:193], v[126:129]
	v_mfma_f32_16x16x32_bf16 v[122:125], v[162:165], v[190:193], v[122:125]
	v_mfma_f32_16x16x32_bf16 v[110:113], v[146:149], v[198:201], v[110:113]
	v_mfma_f32_16x16x32_bf16 v[106:109], v[162:165], v[198:201], v[106:109]
	v_mfma_f32_16x16x32_bf16 v[94:97], v[146:149], v[206:209], v[94:97]
	v_mfma_f32_16x16x32_bf16 v[90:93], v[162:165], v[206:209], v[90:93]
	v_mfma_f32_16x16x32_bf16 v[78:81], v[146:149], v[214:217], v[78:81]
	v_mfma_f32_16x16x32_bf16 v[74:77], v[162:165], v[214:217], v[74:77]
	v_mfma_f32_16x16x32_bf16 v[126:129], v[158:161], v[194:197], v[126:129]
	v_mfma_f32_16x16x32_bf16 v[122:125], v[166:169], v[194:197], v[122:125]
	v_mfma_f32_16x16x32_bf16 v[110:113], v[158:161], v[202:205], v[110:113]
	v_mfma_f32_16x16x32_bf16 v[106:109], v[166:169], v[202:205], v[106:109]
	v_mfma_f32_16x16x32_bf16 v[94:97], v[158:161], v[210:213], v[94:97]
	v_mfma_f32_16x16x32_bf16 v[90:93], v[166:169], v[210:213], v[90:93]
	v_mfma_f32_16x16x32_bf16 v[78:81], v[158:161], v[218:221], v[78:81]
	v_mfma_f32_16x16x32_bf16 v[74:77], v[166:169], v[218:221], v[74:77]
	v_mfma_f32_16x16x32_bf16 v[118:121], v[174:177], v[190:193], v[118:121]
	v_mfma_f32_16x16x32_bf16 v[114:117], v[182:185], v[190:193], v[114:117]
	v_mfma_f32_16x16x32_bf16 v[102:105], v[174:177], v[198:201], v[102:105]
	v_mfma_f32_16x16x32_bf16 v[98:101], v[182:185], v[198:201], v[98:101]
	v_mfma_f32_16x16x32_bf16 v[86:89], v[174:177], v[206:209], v[86:89]
	v_mfma_f32_16x16x32_bf16 v[82:85], v[182:185], v[206:209], v[82:85]
	v_mfma_f32_16x16x32_bf16 v[70:73], v[174:177], v[214:217], v[70:73]
	v_mfma_f32_16x16x32_bf16 v[66:69], v[182:185], v[214:217], v[66:69]
	v_mfma_f32_16x16x32_bf16 v[118:121], v[178:181], v[194:197], v[118:121]
	v_mfma_f32_16x16x32_bf16 v[114:117], v[186:189], v[194:197], v[114:117]
	v_mfma_f32_16x16x32_bf16 v[102:105], v[178:181], v[202:205], v[102:105]
	v_mfma_f32_16x16x32_bf16 v[98:101], v[186:189], v[202:205], v[98:101]
	v_mfma_f32_16x16x32_bf16 v[86:89], v[178:181], v[210:213], v[86:89]
	v_mfma_f32_16x16x32_bf16 v[82:85], v[186:189], v[210:213], v[82:85]
	v_mfma_f32_16x16x32_bf16 v[70:73], v[178:181], v[218:221], v[70:73]
	v_mfma_f32_16x16x32_bf16 v[66:69], v[186:189], v[218:221], v[66:69]
	s_barrier
	s_add_i32 s69, s61, s52
	v_lshl_add_u64 v[150:151], s[38:39], 0, v[132:133]
	s_mov_b32 m0, s69
	ds_read_b128 v[190:193], v156 offset:16384
	ds_read_b128 v[194:197], v156 offset:17408
	ds_read_b128 v[198:201], v156 offset:18432
	ds_read_b128 v[202:205], v156 offset:19456
	ds_read_b128 v[206:209], v156 offset:20480
	ds_read_b128 v[210:213], v156 offset:21504
	ds_read_b128 v[214:217], v156 offset:22528
	ds_read_b128 v[218:221], v156 offset:23552
	global_load_lds_dwordx4 v[150:151], off
	s_add_i32 m0, s69, 0x2000
	s_add_u32 s70, s38, 0x20000
	v_lshl_add_u64 v[170:171], s[38:39], 0, v[136:137]
	s_addc_u32 s71, s39, 0
	s_add_i32 s69, s62, s52
	global_load_lds_dwordx4 v[170:171], off
	v_lshl_add_u64 v[222:223], s[70:71], 0, v[132:133]
	s_mov_b32 m0, s69
	v_lshl_add_u64 v[224:225], s[40:41], 0, v[134:135]
	global_load_lds_dwordx4 v[222:223], off
	v_lshl_add_u64 v[222:223], s[70:71], 0, v[136:137]
	s_add_i32 m0, s69, 0x2000
	s_nop 0
	global_load_lds_dwordx4 v[222:223], off
	v_lshl_add_u64 v[222:223], s[40:41], 0, v[130:131]
	s_mov_b32 m0, s31
	s_nop 0
	global_load_lds_dwordx4 v[222:223], off
	s_mov_b32 m0, s53
	s_nop 0
	global_load_lds_dwordx4 v[224:225], off
	s_waitcnt vmcnt(8)
	s_waitcnt lgkmcnt(0)
	s_barrier
; #define PG8_STAGE(bufoff, gbase, voff) do { _Pragma("unroll") for (int _i = 0; _i < 2; ++_i) \
;         __builtin_amdgcn_global_load_lds((const unsigned*)((const char*)(gbase) + (voff)[_i]), (PG8_LAS unsigned*)(lds + (bufoff) + ldsw + _i * 8192), 16, 0, 0); } while (0)
; #define PG8_LDA(dst, b, h) do { _Pragma("unroll") for (int m = 0; m < 4; ++m) _Pragma("unroll") for (int k = 0; k < 2; ++k) dst[m][k] = *(const PG8_LAS bf16x8*)(lds + PG8_SA(b, h) + aoff + m * 2048 + k * 1024); } while (0)
; #define PG8_LDB(dst, b, h) do { _Pragma("unroll") for (int n = 0; n < 2; ++n) _Pragma("unroll") for (int k = 0; k < 2; ++k) dst[n][k] = *(const PG8_LAS bf16x8*)(lds + PG8_SB(b, h) + boff + n * 2048 + k * 1024); } while (0)
; #define PG8_MMA(ai, bj, At, Bt) do { __builtin_amdgcn_s_setprio(1); _Pragma("unroll") for (int m = 0; m < 4; ++m) _Pragma("unroll") for (int n = 0; n < 2; ++n) _Pragma("unroll") for (int k = 0; k < 2; ++k) \
;         acc[ai][bj][m][n] = __builtin_amdgcn_mfma_f32_16x16x32_bf16(Bt[n][k], At[m][k], acc[ai][bj][m][n], 0, 0, 0); __builtin_amdgcn_s_setprio(0); } while (0)
; #define PG8_WAIT_V(n) asm volatile("s_waitcnt vmcnt(" #n ")" ::: "memory")
; #define PG8_WAIT_L(n) asm volatile("s_waitcnt lgkmcnt(" #n ")" ::: "memory")
; #define PG8_BAR __builtin_amdgcn_s_barrier()
; #define PG8_SCHED __builtin_amdgcn_sched_barrier(0)
; template <class Epi, class Sched, bool ALIGN_EPI = false, bool SP2 = false>
; __device__ __forceinline__ void gemm_phase(PG8_LAS unsigned char* lds, const Gemm g, const Sched& S, const Epi& E) {
;     ...
;             PG8_WAIT_V(8); PG8_WAIT_L(0); PG8_BAR; PG8_MMA(1, 0, At, B0); PG8_MMA(1, 1, At, B1); PG8_BAR; PG8_SCHED;
;             PG8_LDB(B0, 1, 0); PG8_LDB(B1, 1, 1); PG8_SCHED; PG8_LDA(At, 1, 0); PG8_STAGE(PG8_SA(0, 1), a2 + hstep, voffA);
;             PG8_WAIT_V(8); PG8_WAIT_L(0); PG8_BAR; PG8_MMA(0, 0, At, B0); PG8_MMA(0, 1, At, B1); PG8_BAR; PG8_SCHED;
	s_waitcnt lgkmcnt(0)
	v_mfma_f32_16x16x32_bf16 v[62:65], v[146:149], v[190:193], v[62:65]
	v_mfma_f32_16x16x32_bf16 v[58:61], v[162:165], v[190:193], v[58:61]
	v_mfma_f32_16x16x32_bf16 v[46:49], v[146:149], v[198:201], v[46:49]
	v_mfma_f32_16x16x32_bf16 v[42:45], v[162:165], v[198:201], v[42:45]
	v_mfma_f32_16x16x32_bf16 v[30:33], v[146:149], v[206:209], v[30:33]
	v_mfma_f32_16x16x32_bf16 v[26:29], v[162:165], v[206:209], v[26:29]
	v_mfma_f32_16x16x32_bf16 v[14:17], v[146:149], v[214:217], v[14:17]
	v_mfma_f32_16x16x32_bf16 v[10:13], v[162:165], v[214:217], v[10:13]
	v_mfma_f32_16x16x32_bf16 v[62:65], v[158:161], v[194:197], v[62:65]
	v_mfma_f32_16x16x32_bf16 v[58:61], v[166:169], v[194:197], v[58:61]
	v_mfma_f32_16x16x32_bf16 v[46:49], v[158:161], v[202:205], v[46:49]
	v_mfma_f32_16x16x32_bf16 v[42:45], v[166:169], v[202:205], v[42:45]
	v_mfma_f32_16x16x32_bf16 v[30:33], v[158:161], v[210:213], v[30:33]
	v_mfma_f32_16x16x32_bf16 v[26:29], v[166:169], v[210:213], v[26:29]
	v_mfma_f32_16x16x32_bf16 v[14:17], v[158:161], v[218:221], v[14:17]
	v_mfma_f32_16x16x32_bf16 v[10:13], v[166:169], v[218:221], v[10:13]
	v_mfma_f32_16x16x32_bf16 v[54:57], v[174:177], v[190:193], v[54:57]
	v_mfma_f32_16x16x32_bf16 v[50:53], v[182:185], v[190:193], v[50:53]
	v_mfma_f32_16x16x32_bf16 v[38:41], v[174:177], v[198:201], v[38:41]
	v_mfma_f32_16x16x32_bf16 v[34:37], v[182:185], v[198:201], v[34:37]
	v_mfma_f32_16x16x32_bf16 v[22:25], v[174:177], v[206:209], v[22:25]
	v_mfma_f32_16x16x32_bf16 v[18:21], v[182:185], v[206:209], v[18:21]
	v_mfma_f32_16x16x32_bf16 v[6:9], v[174:177], v[214:217], v[6:9]
	v_mfma_f32_16x16x32_bf16 v[2:5], v[182:185], v[214:217], v[2:5]
	v_mfma_f32_16x16x32_bf16 v[54:57], v[178:181], v[194:197], v[54:57]
	v_mfma_f32_16x16x32_bf16 v[50:53], v[186:189], v[194:197], v[50:53]
	v_mfma_f32_16x16x32_bf16 v[38:41], v[178:181], v[202:205], v[38:41]
	v_mfma_f32_16x16x32_bf16 v[34:37], v[186:189], v[202:205], v[34:37]
	v_mfma_f32_16x16x32_bf16 v[22:25], v[178:181], v[210:213], v[22:25]
	v_mfma_f32_16x16x32_bf16 v[18:21], v[186:189], v[210:213], v[18:21]
	v_mfma_f32_16x16x32_bf16 v[6:9], v[178:181], v[218:221], v[6:9]
	v_mfma_f32_16x16x32_bf16 v[2:5], v[186:189], v[218:221], v[2:5]
	s_barrier
	s_add_i32 s69, 0, 0x18000
	v_add_u32_e32 v157, s69, v152
	s_add_i32 s70, 0, 0x1c000
	ds_read_b128 v[146:149], v157
	ds_read_b128 v[158:161], v157 offset:1024
	ds_read_b128 v[162:165], v157 offset:2048
	ds_read_b128 v[166:169], v157 offset:3072
	v_add_u32_e32 v157, s70, v152
	ds_read_b128 v[174:177], v157
	ds_read_b128 v[178:181], v157 offset:1024
	ds_read_b128 v[182:185], v157 offset:2048
	ds_read_b128 v[186:189], v157 offset:3072
	s_add_u32 s40, s40, 0x20000
	s_addc_u32 s41, s41, 0
	s_mov_b32 m0, s54
	v_lshl_add_u64 v[226:227], s[40:41], 0, v[130:131]
	ds_read_b128 v[190:193], v156 offset:32768
	ds_read_b128 v[194:197], v156 offset:33792
	ds_read_b128 v[198:201], v156 offset:34816
	ds_read_b128 v[202:205], v156 offset:35840
	ds_read_b128 v[206:209], v156 offset:36864
	ds_read_b128 v[210:213], v156 offset:37888
	ds_read_b128 v[214:217], v156 offset:38912
	ds_read_b128 v[218:221], v156 offset:39936
	global_load_lds_dwordx4 v[226:227], off
	v_lshl_add_u64 v[226:227], s[40:41], 0, v[134:135]
	s_mov_b32 m0, s55
	s_nop 0
	global_load_lds_dwordx4 v[226:227], off
	s_waitcnt vmcnt(8)
	s_waitcnt lgkmcnt(0)
	s_barrier
	s_waitcnt lgkmcnt(0)
	v_mfma_f32_16x16x32_bf16 v[126:129], v[146:149], v[190:193], v[126:129]
	v_mfma_f32_16x16x32_bf16 v[122:125], v[162:165], v[190:193], v[122:125]
	v_mfma_f32_16x16x32_bf16 v[110:113], v[146:149], v[198:201], v[110:113]
	v_mfma_f32_16x16x32_bf16 v[106:109], v[162:165], v[198:201], v[106:109]
	v_mfma_f32_16x16x32_bf16 v[94:97], v[146:149], v[206:209], v[94:97]
	v_mfma_f32_16x16x32_bf16 v[90:93], v[162:165], v[206:209], v[90:93]
	v_mfma_f32_16x16x32_bf16 v[78:81], v[146:149], v[214:217], v[78:81]
	v_mfma_f32_16x16x32_bf16 v[74:77], v[162:165], v[214:217], v[74:77]
	v_mfma_f32_16x16x32_bf16 v[126:129], v[158:161], v[194:197], v[126:129]
	v_mfma_f32_16x16x32_bf16 v[122:125], v[166:169], v[194:197], v[122:125]
	v_mfma_f32_16x16x32_bf16 v[110:113], v[158:161], v[202:205], v[110:113]
	v_mfma_f32_16x16x32_bf16 v[106:109], v[166:169], v[202:205], v[106:109]
	v_mfma_f32_16x16x32_bf16 v[94:97], v[158:161], v[210:213], v[94:97]
	v_mfma_f32_16x16x32_bf16 v[90:93], v[166:169], v[210:213], v[90:93]
	v_mfma_f32_16x16x32_bf16 v[78:81], v[158:161], v[218:221], v[78:81]
	v_mfma_f32_16x16x32_bf16 v[74:77], v[166:169], v[218:221], v[74:77]
	v_mfma_f32_16x16x32_bf16 v[118:121], v[174:177], v[190:193], v[118:121]
	v_mfma_f32_16x16x32_bf16 v[114:117], v[182:185], v[190:193], v[114:117]
	v_mfma_f32_16x16x32_bf16 v[102:105], v[174:177], v[198:201], v[102:105]
	v_mfma_f32_16x16x32_bf16 v[98:101], v[182:185], v[198:201], v[98:101]
	v_mfma_f32_16x16x32_bf16 v[86:89], v[174:177], v[206:209], v[86:89]
	v_mfma_f32_16x16x32_bf16 v[82:85], v[182:185], v[206:209], v[82:85]
	v_mfma_f32_16x16x32_bf16 v[70:73], v[174:177], v[214:217], v[70:73]
	v_mfma_f32_16x16x32_bf16 v[66:69], v[182:185], v[214:217], v[66:69]
	v_mfma_f32_16x16x32_bf16 v[118:121], v[178:181], v[194:197], v[118:121]
	v_mfma_f32_16x16x32_bf16 v[114:117], v[186:189], v[194:197], v[114:117]
	v_mfma_f32_16x16x32_bf16 v[102:105], v[178:181], v[202:205], v[102:105]
	v_mfma_f32_16x16x32_bf16 v[98:101], v[186:189], v[202:205], v[98:101]
	v_mfma_f32_16x16x32_bf16 v[86:89], v[178:181], v[210:213], v[86:89]
	v_mfma_f32_16x16x32_bf16 v[82:85], v[186:189], v[210:213], v[82:85]
	v_mfma_f32_16x16x32_bf16 v[70:73], v[178:181], v[218:221], v[70:73]
	v_mfma_f32_16x16x32_bf16 v[66:69], v[186:189], v[218:221], v[66:69]
	s_barrier
; template <class Epi, class Sched, bool ALIGN_EPI = false, bool SP2 = false>
; __device__ __forceinline__ void gemm_phase(PG8_LAS unsigned char* lds, const Gemm g, const Sched& S, const Epi& E) {
;     ...
;             PG8_LDA(At, 1, 1); PG8_STAGE(PG8_SB(1, 0), b3, voffB); PG8_STAGE(PG8_SB(1, 1), b3 + hstep, voffB); PG8_STAGE(PG8_SA(1, 0), a3, voffA);
;             PG8_WAIT_V(8); PG8_WAIT_L(0); PG8_BAR; PG8_MMA(1, 0, At, B0); PG8_MMA(1, 1, At, B1); PG8_BAR; PG8_SCHED;
;             } else {
;             PG8_LDB(B0, 0, 0); PG8_SCHED; PG8_LDA(At, 0, 0); PG8_STAGE(PG8_SA(1, 1), a1 + hstep, voffA);
;             PG8_WAIT_L(8); PG8_BAR; PG8_WAIT_L(0); PG8_MMA(0, 0, At, B0); PG8_BAR; PG8_SCHED;
;             PG8_LDB(B1, 0, 1); PG8_STAGE(PG8_SB(0, 0), b2, voffB);
;             PG8_BAR; PG8_WAIT_L(0); PG8_MMA(0, 1, At, B1); PG8_BAR;
;             PG8_LDA(At, 0, 1); PG8_STAGE(PG8_SA(0, 0), a2, voffA);
;             PG8_BAR; PG8_WAIT_L(0); PG8_MMA(1, 0, At, B0); PG8_BAR; PG8_SCHED;
;             PG8_STAGE(PG8_SB(0, 1), b2 + hstep, voffB);
;             PG8_WAIT_V(6); PG8_BAR; PG8_MMA(1, 1, At, B1); PG8_BAR;
;             PG8_LDB(B0, 1, 0); PG8_SCHED; PG8_LDA(At, 1, 0); PG8_STAGE(PG8_SA(0, 1), a2 + hstep, voffA);
;             PG8_WAIT_L(8); PG8_BAR; PG8_WAIT_L(0); PG8_MMA(0, 0, At, B0); PG8_BAR; PG8_SCHED;
;             PG8_LDB(B1, 1, 1); PG8_STAGE(PG8_SB(1, 0), b3, voffB);
;             PG8_BAR; PG8_WAIT_L(0); PG8_MMA(0, 1, At, B1); PG8_BAR;
;             PG8_LDA(At, 1, 1); PG8_STAGE(PG8_SA(1, 0), a3, voffA);
;             PG8_BAR; PG8_WAIT_L(0); PG8_MMA(1, 0, At, B0); PG8_BAR; PG8_SCHED;
;             PG8_STAGE(PG8_SB(1, 1), b3 + hstep, voffB);
;             PG8_WAIT_V(6); PG8_BAR; PG8_MMA(1, 1, At, B1); PG8_BAR;
;             }
;         }
;         if constexpr (ALIGN_EPI) { if (wr == 0) PG8_BAR; }
;     __device__ __forceinline__ void operator()(const f32x4 (&acc)[2][2][4][2], const pg8::Unit& u, int wr, int wc, int fr, int fq) const {
;     ...
;                         if constexpr (MODE == EP_MIX) {
;                             const u32x4 gv = *(const u32x4*)(G + row * 1024 + col);
;                             const u32x4 tv = *(const u32x4*)(G2 + row * 1024 + col);
;                             r[0] = lo_bf(tv.x) + r[0] * lo_bf(gv.x); r[1] = hi_bf(tv.x) + r[1] * hi_bf(gv.x); r[2] = lo_bf(tv.y) + r[2] * lo_bf(gv.y); r[3] = hi_bf(tv.y) + r[3] * hi_bf(gv.y);
	s_add_i32 s40, s69, s52
	v_lshl_add_u64 v[150:151], v[150:151], 0, s[10:11]
	s_mov_b32 m0, s40
	ds_read_b128 v[190:193], v156 offset:49152
	ds_read_b128 v[194:197], v156 offset:50176
	ds_read_b128 v[198:201], v156 offset:51200
	ds_read_b128 v[202:205], v156 offset:52224
	ds_read_b128 v[206:209], v156 offset:53248
	ds_read_b128 v[210:213], v156 offset:54272
	ds_read_b128 v[214:217], v156 offset:55296
	ds_read_b128 v[218:221], v156 offset:56320
	global_load_lds_dwordx4 v[150:151], off
	s_add_i32 m0, s40, 0x2000
	s_add_u32 s38, s38, 0x20080
	v_lshl_add_u64 v[150:151], v[170:171], 0, s[10:11]
	s_addc_u32 s39, s39, 0
	s_add_i32 s40, s70, s52
	global_load_lds_dwordx4 v[150:151], off
	v_lshl_add_u64 v[150:151], s[38:39], 0, v[132:133]
	s_mov_b32 m0, s40
	s_nop 0
	global_load_lds_dwordx4 v[150:151], off
	v_lshl_add_u64 v[150:151], s[38:39], 0, v[136:137]
	s_add_i32 m0, s40, 0x2000
	s_nop 0
	global_load_lds_dwordx4 v[150:151], off
	v_lshl_add_u64 v[150:151], v[222:223], 0, s[10:11]
	s_mov_b32 m0, s57
	s_nop 0
	global_load_lds_dwordx4 v[150:151], off
	v_lshl_add_u64 v[150:151], v[224:225], 0, s[10:11]
	s_mov_b32 m0, s58
	s_nop 0
	global_load_lds_dwordx4 v[150:151], off
	s_waitcnt vmcnt(8)
	s_waitcnt lgkmcnt(0)
	s_barrier
	s_waitcnt lgkmcnt(0)
	v_mfma_f32_16x16x32_bf16 v[62:65], v[146:149], v[190:193], v[62:65]
	v_mfma_f32_16x16x32_bf16 v[58:61], v[162:165], v[190:193], v[58:61]
	v_mfma_f32_16x16x32_bf16 v[46:49], v[146:149], v[198:201], v[46:49]
	v_mfma_f32_16x16x32_bf16 v[42:45], v[162:165], v[198:201], v[42:45]
	v_mfma_f32_16x16x32_bf16 v[30:33], v[146:149], v[206:209], v[30:33]
	v_mfma_f32_16x16x32_bf16 v[26:29], v[162:165], v[206:209], v[26:29]
	v_mfma_f32_16x16x32_bf16 v[14:17], v[146:149], v[214:217], v[14:17]
	v_mfma_f32_16x16x32_bf16 v[10:13], v[162:165], v[214:217], v[10:13]
	v_mfma_f32_16x16x32_bf16 v[62:65], v[158:161], v[194:197], v[62:65]
	v_mfma_f32_16x16x32_bf16 v[58:61], v[166:169], v[194:197], v[58:61]
	v_mfma_f32_16x16x32_bf16 v[46:49], v[158:161], v[202:205], v[46:49]
	v_mfma_f32_16x16x32_bf16 v[42:45], v[166:169], v[202:205], v[42:45]
	v_mfma_f32_16x16x32_bf16 v[30:33], v[158:161], v[210:213], v[30:33]
	v_mfma_f32_16x16x32_bf16 v[26:29], v[166:169], v[210:213], v[26:29]
	v_mfma_f32_16x16x32_bf16 v[14:17], v[158:161], v[218:221], v[14:17]
	v_mfma_f32_16x16x32_bf16 v[10:13], v[166:169], v[218:221], v[10:13]
	v_mfma_f32_16x16x32_bf16 v[54:57], v[174:177], v[190:193], v[54:57]
	v_mfma_f32_16x16x32_bf16 v[50:53], v[182:185], v[190:193], v[50:53]
	v_mfma_f32_16x16x32_bf16 v[38:41], v[174:177], v[198:201], v[38:41]
	v_mfma_f32_16x16x32_bf16 v[34:37], v[182:185], v[198:201], v[34:37]
	v_mfma_f32_16x16x32_bf16 v[22:25], v[174:177], v[206:209], v[22:25]
	v_mfma_f32_16x16x32_bf16 v[18:21], v[182:185], v[206:209], v[18:21]
	v_mfma_f32_16x16x32_bf16 v[6:9], v[174:177], v[214:217], v[6:9]
	v_mfma_f32_16x16x32_bf16 v[2:5], v[182:185], v[214:217], v[2:5]
	v_mfma_f32_16x16x32_bf16 v[54:57], v[178:181], v[194:197], v[54:57]
	v_mfma_f32_16x16x32_bf16 v[50:53], v[186:189], v[194:197], v[50:53]
	v_mfma_f32_16x16x32_bf16 v[38:41], v[178:181], v[202:205], v[38:41]
	v_mfma_f32_16x16x32_bf16 v[34:37], v[186:189], v[202:205], v[34:37]
	v_mfma_f32_16x16x32_bf16 v[22:25], v[178:181], v[210:213], v[22:25]
	v_mfma_f32_16x16x32_bf16 v[18:21], v[186:189], v[210:213], v[18:21]
	v_mfma_f32_16x16x32_bf16 v[6:9], v[178:181], v[218:221], v[6:9]
	v_mfma_f32_16x16x32_bf16 v[2:5], v[186:189], v[218:221], v[2:5]
	s_barrier
	s_add_i32 s68, s68, 2
	s_add_u32 s34, s34, 0x100
	s_addc_u32 s35, s35, 0
	s_add_u32 s66, s66, 0x100
	s_addc_u32 s67, s67, 0
	s_cmp_gt_u32 s68, 5
	s_cbranch_scc0 .LBB0_1339
	s_andn2_b64 vcc, s[12:13], s[2:3]
	s_cbranch_vccz .LBB0_1342
	s_barrier
.LBB0_1342:
	v_lshl_add_u32 v150, s30, 8, v1
	v_lshl_or_b32 v146, s63, 8, v153
	v_ashrrev_i32_e32 v151, 31, v150
	v_lshlrev_b64 v[148:149], 11, v[150:151]
	v_ashrrev_i32_e32 v147, 31, v146
	v_lshlrev_b64 v[146:147], 1, v[146:147]
	v_lshl_add_u64 v[158:159], s[6:7], 0, v[148:149]
	v_lshl_add_u64 v[166:167], v[158:159], 0, v[146:147]
	v_lshl_add_u64 v[158:159], s[8:9], 0, v[148:149]
	v_lshl_add_u64 v[168:169], v[158:159], 0, v[146:147]
	global_load_dwordx4 v[158:161], v[168:169], off
	global_load_dwordx4 v[162:165], v[166:167], off
	s_andn2_b64 vcc, exec, s[2:3]
	s_mov_b64 s[2:3], -1
	s_waitcnt vmcnt(0)
	v_lshlrev_b32_e32 v151, 16, v158
	v_lshlrev_b32_e32 v157, 16, v162
	v_and_b32_e32 v158, 0xffff0000, v158
	v_and_b32_e32 v162, 0xffff0000, v162
	v_lshlrev_b32_e32 v170, 16, v159
	v_lshlrev_b32_e32 v171, 16, v163
	v_and_b32_e32 v159, 0xffff0000, v159
	v_and_b32_e32 v163, 0xffff0000, v163
	v_lshlrev_b32_e32 v174, 16, v160
	v_lshlrev_b32_e32 v175, 16, v164
	v_and_b32_e32 v160, 0xffff0000, v160
	v_and_b32_e32 v164, 0xffff0000, v164
	v_lshlrev_b32_e32 v176, 16, v161
	v_lshlrev_b32_e32 v177, 16, v165
	v_and_b32_e32 v161, 0xffff0000, v161
	v_and_b32_e32 v165, 0xffff0000, v165
	v_fmac_f32_e32 v158, v127, v162
	v_fmac_f32_e32 v159, v129, v163
	v_fmac_f32_e32 v160, v123, v164
	v_fmac_f32_e32 v161, v125, v165
	v_fmac_f32_e32 v151, v126, v157
	v_fmac_f32_e32 v170, v128, v171
	v_fmac_f32_e32 v174, v122, v175
	v_fmac_f32_e32 v176, v124, v177
	v_cvt_pk_bf16_f32 v122, v151, v158
	v_cvt_pk_bf16_f32 v123, v170, v159
	v_cvt_pk_bf16_f32 v124, v174, v160
	v_cvt_pk_bf16_f32 v125, v176, v161
	global_load_dwordx4 v[126:129], v[168:169], off offset:256
	global_load_dwordx4 v[158:161], v[166:167], off offset:256
	v_or_b32_e32 v162, 16, v150
	v_ashrrev_i32_e32 v163, 31, v162
	v_lshl_add_u64 v[164:165], s[4:5], 0, v[148:149]
	v_lshlrev_b64 v[162:163], 11, v[162:163]
	v_lshl_add_u64 v[164:165], v[164:165], 0, v[146:147]
	v_lshl_add_u64 v[168:169], s[8:9], 0, v[162:163]
	global_store_dwordx4 v[164:165], v[122:125], off
	v_lshl_add_u64 v[166:167], s[6:7], 0, v[162:163]
	v_lshl_add_u64 v[168:169], v[168:169], 0, v[146:147]
	v_lshl_add_u64 v[166:167], v[166:167], 0, v[146:147]
	s_waitcnt vmcnt(2)
; __device__ __forceinline__ unsigned cvt_pk_bf16(float lo, float hi) { unsigned r; asm volatile("v_cvt_pk_bf16_f32 %0, %1, %2" : "=v"(r) : "v"(lo), "v"(hi)); return r; }
; __device__ __forceinline__ float lo_bf(unsigned u) { return __uint_as_float(u << 16); }
; __device__ __forceinline__ float hi_bf(unsigned u) { return __uint_as_float(u & 0xffff0000u); }
;     __device__ __forceinline__ void operator()(const f32x4 (&acc)[2][2][4][2], const pg8::Unit& u, int wr, int wc, int fr, int fq) const {
;     ...
;                         if constexpr (MODE == EP_MIX) {
;                             const u32x4 gv = *(const u32x4*)(G + row * 1024 + col);
;                             const u32x4 tv = *(const u32x4*)(G2 + row * 1024 + col);
;                             r[0] = lo_bf(tv.x) + r[0] * lo_bf(gv.x); r[1] = hi_bf(tv.x) + r[1] * hi_bf(gv.x); r[2] = lo_bf(tv.y) + r[2] * lo_bf(gv.y); r[3] = hi_bf(tv.y) + r[3] * hi_bf(gv.y);
;                             r[4] = lo_bf(tv.z) + r[4] * lo_bf(gv.z); r[5] = hi_bf(tv.z) + r[5] * hi_bf(gv.z); r[6] = lo_bf(tv.w) + r[6] * lo_bf(gv.w); r[7] = hi_bf(tv.w) + r[7] * hi_bf(gv.w);
;     ...
;                         u32x4 w; w.x = cvt_pk_bf16(r[0], r[1]); w.y = cvt_pk_bf16(r[2], r[3]); w.z = cvt_pk_bf16(r[4], r[5]); w.w = cvt_pk_bf16(r[6], r[7]);
;                         *(u32x4*)dst = w;
	v_lshlrev_b32_e32 v122, 16, v126
	s_waitcnt vmcnt(1)
	v_lshlrev_b32_e32 v123, 16, v158
	v_and_b32_e32 v124, 0xffff0000, v126
	v_and_b32_e32 v125, 0xffff0000, v158
	v_lshlrev_b32_e32 v126, 16, v127
	v_lshlrev_b32_e32 v151, 16, v159
	v_and_b32_e32 v127, 0xffff0000, v127
	v_and_b32_e32 v157, 0xffff0000, v159
	v_lshlrev_b32_e32 v158, 16, v128
	v_lshlrev_b32_e32 v159, 16, v160
	v_and_b32_e32 v128, 0xffff0000, v128
	v_and_b32_e32 v160, 0xffff0000, v160
	v_lshlrev_b32_e32 v170, 16, v129
	v_lshlrev_b32_e32 v171, 16, v161
	v_and_b32_e32 v129, 0xffff0000, v129
	v_and_b32_e32 v161, 0xffff0000, v161
	v_fmac_f32_e32 v122, v118, v123
	v_fmac_f32_e32 v124, v119, v125
	v_fmac_f32_e32 v126, v120, v151
	v_fmac_f32_e32 v127, v121, v157
	v_fmac_f32_e32 v158, v114, v159
	v_fmac_f32_e32 v128, v115, v160
	v_fmac_f32_e32 v170, v116, v171
	v_fmac_f32_e32 v129, v117, v161
	v_cvt_pk_bf16_f32 v114, v122, v124
	v_cvt_pk_bf16_f32 v115, v126, v127
	v_cvt_pk_bf16_f32 v116, v158, v128
	v_cvt_pk_bf16_f32 v117, v170, v129
	global_load_dwordx4 v[118:121], v[168:169], off
	global_load_dwordx4 v[122:125], v[166:167], off
	s_waitcnt vmcnt(1)
	v_lshlrev_b32_e32 v126, 16, v120
	global_store_dwordx4 v[164:165], v[114:117], off offset:256
	s_waitcnt vmcnt(1)
	v_lshlrev_b32_e32 v127, 16, v124
	v_and_b32_e32 v120, 0xffff0000, v120
	v_lshlrev_b32_e32 v114, 16, v118
	v_lshlrev_b32_e32 v115, 16, v122
	v_and_b32_e32 v116, 0xffff0000, v118
	v_and_b32_e32 v117, 0xffff0000, v122
	v_lshlrev_b32_e32 v118, 16, v119
	v_lshlrev_b32_e32 v122, 16, v123
	v_and_b32_e32 v119, 0xffff0000, v119
	v_and_b32_e32 v123, 0xffff0000, v123
	v_and_b32_e32 v124, 0xffff0000, v124
	v_lshlrev_b32_e32 v128, 16, v121
	v_lshlrev_b32_e32 v129, 16, v125
	v_and_b32_e32 v121, 0xffff0000, v121
	v_and_b32_e32 v125, 0xffff0000, v125
	v_fmac_f32_e32 v114, v110, v115
	v_fmac_f32_e32 v116, v111, v117
	v_fmac_f32_e32 v118, v112, v122
	v_fmac_f32_e32 v119, v113, v123
	v_fmac_f32_e32 v126, v106, v127
	v_fmac_f32_e32 v120, v107, v124
	v_fmac_f32_e32 v128, v108, v129
	v_fmac_f32_e32 v121, v109, v125
	v_cvt_pk_bf16_f32 v106, v114, v116
	v_cvt_pk_bf16_f32 v107, v118, v119
	v_cvt_pk_bf16_f32 v108, v126, v120
	v_cvt_pk_bf16_f32 v109, v128, v121
	global_load_dwordx4 v[110:113], v[168:169], off offset:256
	global_load_dwordx4 v[114:117], v[166:167], off offset:256
	v_or_b32_e32 v118, 32, v150
	v_ashrrev_i32_e32 v119, 31, v118
	v_lshl_add_u64 v[120:121], s[4:5], 0, v[162:163]
	v_lshlrev_b64 v[118:119], 11, v[118:119]
	v_lshl_add_u64 v[120:121], v[120:121], 0, v[146:147]
	v_lshl_add_u64 v[124:125], s[8:9], 0, v[118:119]
	global_store_dwordx4 v[120:121], v[106:109], off
	v_lshl_add_u64 v[122:123], s[6:7], 0, v[118:119]
	v_lshl_add_u64 v[124:125], v[124:125], 0, v[146:147]
	v_lshl_add_u64 v[122:123], v[122:123], 0, v[146:147]
	s_waitcnt vmcnt(2)
	v_lshlrev_b32_e32 v106, 16, v110
	s_waitcnt vmcnt(1)
	v_lshlrev_b32_e32 v107, 16, v114
	v_and_b32_e32 v108, 0xffff0000, v110
	v_and_b32_e32 v109, 0xffff0000, v114
	v_lshlrev_b32_e32 v110, 16, v111
	v_lshlrev_b32_e32 v114, 16, v115
	v_and_b32_e32 v111, 0xffff0000, v111
	v_and_b32_e32 v115, 0xffff0000, v115
	v_lshlrev_b32_e32 v126, 16, v112
	v_lshlrev_b32_e32 v127, 16, v116
	v_and_b32_e32 v112, 0xffff0000, v112
	v_and_b32_e32 v116, 0xffff0000, v116
	v_lshlrev_b32_e32 v128, 16, v113
	v_lshlrev_b32_e32 v129, 16, v117
	v_and_b32_e32 v113, 0xffff0000, v113
	v_and_b32_e32 v117, 0xffff0000, v117
	v_fmac_f32_e32 v106, v102, v107
	v_fmac_f32_e32 v108, v103, v109
	v_fmac_f32_e32 v110, v104, v114
	v_fmac_f32_e32 v111, v105, v115
	v_fmac_f32_e32 v126, v98, v127
	v_fmac_f32_e32 v112, v99, v116
	v_fmac_f32_e32 v128, v100, v129
	v_fmac_f32_e32 v113, v101, v117
	v_cvt_pk_bf16_f32 v98, v106, v108
	v_cvt_pk_bf16_f32 v99, v110, v111
	v_cvt_pk_bf16_f32 v100, v126, v112
	v_cvt_pk_bf16_f32 v101, v128, v113
	global_load_dwordx4 v[102:105], v[124:125], off
	global_load_dwordx4 v[106:109], v[122:123], off
	s_waitcnt vmcnt(1)
	v_lshlrev_b32_e32 v110, 16, v104
	global_store_dwordx4 v[120:121], v[98:101], off offset:256
	s_waitcnt vmcnt(1)
	v_lshlrev_b32_e32 v111, 16, v108
	v_and_b32_e32 v104, 0xffff0000, v104
	v_lshlrev_b32_e32 v98, 16, v102
	v_lshlrev_b32_e32 v99, 16, v106
	v_and_b32_e32 v100, 0xffff0000, v102
	v_and_b32_e32 v101, 0xffff0000, v106
	v_lshlrev_b32_e32 v102, 16, v103
	v_lshlrev_b32_e32 v106, 16, v107
	v_and_b32_e32 v103, 0xffff0000, v103
	v_and_b32_e32 v107, 0xffff0000, v107
	v_and_b32_e32 v108, 0xffff0000, v108
	v_lshlrev_b32_e32 v112, 16, v105
	v_lshlrev_b32_e32 v113, 16, v109
	v_and_b32_e32 v105, 0xffff0000, v105
	v_and_b32_e32 v109, 0xffff0000, v109
	v_fmac_f32_e32 v98, v94, v99
	v_fmac_f32_e32 v100, v95, v101
	v_fmac_f32_e32 v102, v96, v106
	v_fmac_f32_e32 v103, v97, v107
	v_fmac_f32_e32 v110, v90, v111
	v_fmac_f32_e32 v104, v91, v108
	v_fmac_f32_e32 v112, v92, v113
	v_fmac_f32_e32 v105, v93, v109
	v_cvt_pk_bf16_f32 v90, v98, v100
	v_cvt_pk_bf16_f32 v91, v102, v103
	v_cvt_pk_bf16_f32 v92, v110, v104
	v_cvt_pk_bf16_f32 v93, v112, v105
	global_load_dwordx4 v[94:97], v[124:125], off offset:256
	global_load_dwordx4 v[98:101], v[122:123], off offset:256
	v_or_b32_e32 v102, 48, v150
	v_ashrrev_i32_e32 v103, 31, v102
	v_lshl_add_u64 v[104:105], s[4:5], 0, v[118:119]
	v_lshlrev_b64 v[102:103], 11, v[102:103]
	v_lshl_add_u64 v[104:105], v[104:105], 0, v[146:147]
	v_lshl_add_u64 v[108:109], s[8:9], 0, v[102:103]
	global_store_dwordx4 v[104:105], v[90:93], off
	v_lshl_add_u64 v[106:107], s[6:7], 0, v[102:103]
	v_lshl_add_u64 v[108:109], v[108:109], 0, v[146:147]
	v_lshl_add_u64 v[106:107], v[106:107], 0, v[146:147]
	s_waitcnt vmcnt(2)
	v_lshlrev_b32_e32 v90, 16, v94
	s_waitcnt vmcnt(1)
; __device__ __forceinline__ unsigned cvt_pk_bf16(float lo, float hi) { unsigned r; asm volatile("v_cvt_pk_bf16_f32 %0, %1, %2" : "=v"(r) : "v"(lo), "v"(hi)); return r; }
; __device__ __forceinline__ float lo_bf(unsigned u) { return __uint_as_float(u << 16); }
; __device__ __forceinline__ float hi_bf(unsigned u) { return __uint_as_float(u & 0xffff0000u); }
;     __device__ __forceinline__ void operator()(const f32x4 (&acc)[2][2][4][2], const pg8::Unit& u, int wr, int wc, int fr, int fq) const {
;     ...
;                         if constexpr (MODE == EP_MIX) {
;                             const u32x4 gv = *(const u32x4*)(G + row * 1024 + col);
;                             const u32x4 tv = *(const u32x4*)(G2 + row * 1024 + col);
;                             r[0] = lo_bf(tv.x) + r[0] * lo_bf(gv.x); r[1] = hi_bf(tv.x) + r[1] * hi_bf(gv.x); r[2] = lo_bf(tv.y) + r[2] * lo_bf(gv.y); r[3] = hi_bf(tv.y) + r[3] * hi_bf(gv.y);
;                             r[4] = lo_bf(tv.z) + r[4] * lo_bf(gv.z); r[5] = hi_bf(tv.z) + r[5] * hi_bf(gv.z); r[6] = lo_bf(tv.w) + r[6] * lo_bf(gv.w); r[7] = hi_bf(tv.w) + r[7] * hi_bf(gv.w);
;     ...
;                         u32x4 w; w.x = cvt_pk_bf16(r[0], r[1]); w.y = cvt_pk_bf16(r[2], r[3]); w.z = cvt_pk_bf16(r[4], r[5]); w.w = cvt_pk_bf16(r[6], r[7]);
;                         *(u32x4*)dst = w;
	v_lshlrev_b32_e32 v91, 16, v98
	v_and_b32_e32 v92, 0xffff0000, v94
	v_and_b32_e32 v93, 0xffff0000, v98
	v_lshlrev_b32_e32 v94, 16, v95
	v_lshlrev_b32_e32 v98, 16, v99
	v_and_b32_e32 v95, 0xffff0000, v95
	v_and_b32_e32 v99, 0xffff0000, v99
	v_lshlrev_b32_e32 v110, 16, v96
	v_lshlrev_b32_e32 v111, 16, v100
	v_and_b32_e32 v96, 0xffff0000, v96
	v_and_b32_e32 v100, 0xffff0000, v100
	v_lshlrev_b32_e32 v112, 16, v97
	v_lshlrev_b32_e32 v113, 16, v101
	v_and_b32_e32 v97, 0xffff0000, v97
	v_and_b32_e32 v101, 0xffff0000, v101
	v_fmac_f32_e32 v90, v86, v91
	v_fmac_f32_e32 v92, v87, v93
	v_fmac_f32_e32 v94, v88, v98
	v_fmac_f32_e32 v95, v89, v99
	v_fmac_f32_e32 v110, v82, v111
	v_fmac_f32_e32 v96, v83, v100
	v_fmac_f32_e32 v112, v84, v113
	v_fmac_f32_e32 v97, v85, v101
	v_cvt_pk_bf16_f32 v82, v90, v92
	v_cvt_pk_bf16_f32 v83, v94, v95
	v_cvt_pk_bf16_f32 v84, v110, v96
	v_cvt_pk_bf16_f32 v85, v112, v97
	global_load_dwordx4 v[86:89], v[108:109], off
	global_load_dwordx4 v[90:93], v[106:107], off
	s_waitcnt vmcnt(1)
	v_lshlrev_b32_e32 v94, 16, v88
	global_store_dwordx4 v[104:105], v[82:85], off offset:256
	s_waitcnt vmcnt(1)
	v_lshlrev_b32_e32 v95, 16, v92
	v_and_b32_e32 v88, 0xffff0000, v88
	v_lshlrev_b32_e32 v82, 16, v86
	v_lshlrev_b32_e32 v83, 16, v90
	v_and_b32_e32 v84, 0xffff0000, v86
	v_and_b32_e32 v85, 0xffff0000, v90
	v_lshlrev_b32_e32 v86, 16, v87
	v_lshlrev_b32_e32 v90, 16, v91
	v_and_b32_e32 v87, 0xffff0000, v87
	v_and_b32_e32 v91, 0xffff0000, v91
	v_and_b32_e32 v92, 0xffff0000, v92
	v_lshlrev_b32_e32 v96, 16, v89
	v_lshlrev_b32_e32 v97, 16, v93
	v_and_b32_e32 v89, 0xffff0000, v89
	v_and_b32_e32 v93, 0xffff0000, v93
	v_fmac_f32_e32 v82, v78, v83
	v_fmac_f32_e32 v84, v79, v85
	v_fmac_f32_e32 v86, v80, v90
	v_fmac_f32_e32 v87, v81, v91
	v_fmac_f32_e32 v94, v74, v95
	v_fmac_f32_e32 v88, v75, v92
	v_fmac_f32_e32 v96, v76, v97
	v_fmac_f32_e32 v89, v77, v93
	v_cvt_pk_bf16_f32 v74, v82, v84
	v_cvt_pk_bf16_f32 v75, v86, v87
	v_cvt_pk_bf16_f32 v76, v94, v88
	v_cvt_pk_bf16_f32 v77, v96, v89
	global_load_dwordx4 v[78:81], v[108:109], off offset:256
	global_load_dwordx4 v[82:85], v[106:107], off offset:256
	v_lshl_add_u64 v[88:89], s[4:5], 0, v[102:103]
	v_lshl_add_u64 v[86:87], v[148:149], 0, s[14:15]
	v_lshl_add_u64 v[88:89], v[88:89], 0, v[146:147]
	v_lshl_add_u64 v[92:93], s[8:9], 0, v[86:87]
	global_store_dwordx4 v[88:89], v[74:77], off
	v_lshl_add_u64 v[90:91], s[6:7], 0, v[86:87]
	v_lshl_add_u64 v[92:93], v[92:93], 0, v[146:147]
	v_lshl_add_u64 v[90:91], v[90:91], 0, v[146:147]
	s_waitcnt vmcnt(2)
	v_lshlrev_b32_e32 v74, 16, v78
	s_waitcnt vmcnt(1)
	v_lshlrev_b32_e32 v75, 16, v82
	v_and_b32_e32 v76, 0xffff0000, v78
	v_and_b32_e32 v77, 0xffff0000, v82
	v_lshlrev_b32_e32 v78, 16, v79
	v_lshlrev_b32_e32 v82, 16, v83
	v_and_b32_e32 v79, 0xffff0000, v79
	v_and_b32_e32 v83, 0xffff0000, v83
	v_lshlrev_b32_e32 v94, 16, v80
	v_lshlrev_b32_e32 v95, 16, v84
	v_and_b32_e32 v80, 0xffff0000, v80
	v_and_b32_e32 v84, 0xffff0000, v84
	v_lshlrev_b32_e32 v96, 16, v81
	v_lshlrev_b32_e32 v97, 16, v85
	v_and_b32_e32 v81, 0xffff0000, v81
	v_and_b32_e32 v85, 0xffff0000, v85
	v_fmac_f32_e32 v74, v70, v75
	v_fmac_f32_e32 v76, v71, v77
	v_fmac_f32_e32 v78, v72, v82
	v_fmac_f32_e32 v79, v73, v83
	v_fmac_f32_e32 v94, v66, v95
	v_fmac_f32_e32 v80, v67, v84
	v_fmac_f32_e32 v96, v68, v97
	v_fmac_f32_e32 v81, v69, v85
	v_cvt_pk_bf16_f32 v66, v74, v76
	v_cvt_pk_bf16_f32 v67, v78, v79
	v_cvt_pk_bf16_f32 v68, v94, v80
	v_cvt_pk_bf16_f32 v69, v96, v81
	global_load_dwordx4 v[70:73], v[92:93], off
	global_load_dwordx4 v[74:77], v[90:91], off
	s_waitcnt vmcnt(1)
	v_lshlrev_b32_e32 v78, 16, v72
	global_store_dwordx4 v[88:89], v[66:69], off offset:256
	s_waitcnt vmcnt(1)
	v_lshlrev_b32_e32 v79, 16, v76
	v_and_b32_e32 v72, 0xffff0000, v72
	v_lshlrev_b32_e32 v66, 16, v70
	v_lshlrev_b32_e32 v67, 16, v74
	v_and_b32_e32 v68, 0xffff0000, v70
	v_and_b32_e32 v69, 0xffff0000, v74
	v_lshlrev_b32_e32 v70, 16, v71
	v_lshlrev_b32_e32 v74, 16, v75
	v_and_b32_e32 v71, 0xffff0000, v71
	v_and_b32_e32 v75, 0xffff0000, v75
	v_and_b32_e32 v76, 0xffff0000, v76
	v_lshlrev_b32_e32 v80, 16, v73
	v_lshlrev_b32_e32 v81, 16, v77
	v_and_b32_e32 v73, 0xffff0000, v73
	v_and_b32_e32 v77, 0xffff0000, v77
	v_fmac_f32_e32 v66, v62, v67
	v_fmac_f32_e32 v68, v63, v69
	v_fmac_f32_e32 v70, v64, v74
	v_fmac_f32_e32 v71, v65, v75
	v_fmac_f32_e32 v78, v58, v79
	v_fmac_f32_e32 v72, v59, v76
	v_fmac_f32_e32 v80, v60, v81
	v_fmac_f32_e32 v73, v61, v77
	v_cvt_pk_bf16_f32 v58, v66, v68
	v_cvt_pk_bf16_f32 v59, v70, v71
	v_cvt_pk_bf16_f32 v60, v78, v72
	v_cvt_pk_bf16_f32 v61, v80, v73
	global_load_dwordx4 v[62:65], v[92:93], off offset:256
	global_load_dwordx4 v[66:69], v[90:91], off offset:256
	v_lshl_add_u64 v[72:73], s[4:5], 0, v[86:87]
	v_lshl_add_u64 v[70:71], v[148:149], 0, s[16:17]
	v_lshl_add_u64 v[72:73], v[72:73], 0, v[146:147]
	v_lshl_add_u64 v[76:77], s[8:9], 0, v[70:71]
	global_store_dwordx4 v[72:73], v[58:61], off
	v_lshl_add_u64 v[74:75], s[6:7], 0, v[70:71]
	v_lshl_add_u64 v[76:77], v[76:77], 0, v[146:147]
	v_lshl_add_u64 v[74:75], v[74:75], 0, v[146:147]
	s_waitcnt vmcnt(2)
	v_lshlrev_b32_e32 v58, 16, v62
	s_waitcnt vmcnt(1)
	v_lshlrev_b32_e32 v59, 16, v66
	v_and_b32_e32 v60, 0xffff0000, v62
	v_and_b32_e32 v61, 0xffff0000, v66
	v_lshlrev_b32_e32 v62, 16, v63
	v_lshlrev_b32_e32 v66, 16, v67
	v_and_b32_e32 v63, 0xffff0000, v63
	v_and_b32_e32 v67, 0xffff0000, v67
	v_lshlrev_b32_e32 v78, 16, v64
	v_lshlrev_b32_e32 v79, 16, v68
	v_and_b32_e32 v64, 0xffff0000, v64
	v_and_b32_e32 v68, 0xffff0000, v68
	v_lshlrev_b32_e32 v80, 16, v65
	v_lshlrev_b32_e32 v81, 16, v69
	v_and_b32_e32 v65, 0xffff0000, v65
	v_and_b32_e32 v69, 0xffff0000, v69
	v_fmac_f32_e32 v58, v54, v59
	v_fmac_f32_e32 v60, v55, v61
	v_fmac_f32_e32 v62, v56, v66
	v_fmac_f32_e32 v63, v57, v67
	v_fmac_f32_e32 v78, v50, v79
	v_fmac_f32_e32 v64, v51, v68
	v_fmac_f32_e32 v80, v52, v81
	v_fmac_f32_e32 v65, v53, v69
	v_cvt_pk_bf16_f32 v50, v58, v60
	v_cvt_pk_bf16_f32 v51, v62, v63
	v_cvt_pk_bf16_f32 v52, v78, v64
	v_cvt_pk_bf16_f32 v53, v80, v65
	global_load_dwordx4 v[54:57], v[76:77], off
	global_load_dwordx4 v[58:61], v[74:75], off
	s_waitcnt vmcnt(1)
; __device__ __forceinline__ unsigned cvt_pk_bf16(float lo, float hi) { unsigned r; asm volatile("v_cvt_pk_bf16_f32 %0, %1, %2" : "=v"(r) : "v"(lo), "v"(hi)); return r; }
; __device__ __forceinline__ float lo_bf(unsigned u) { return __uint_as_float(u << 16); }
; __device__ __forceinline__ float hi_bf(unsigned u) { return __uint_as_float(u & 0xffff0000u); }
;     __device__ __forceinline__ void operator()(const f32x4 (&acc)[2][2][4][2], const pg8::Unit& u, int wr, int wc, int fr, int fq) const {
;     ...
;                         if constexpr (MODE == EP_MIX) {
;                             const u32x4 gv = *(const u32x4*)(G + row * 1024 + col);
;                             const u32x4 tv = *(const u32x4*)(G2 + row * 1024 + col);
;                             r[0] = lo_bf(tv.x) + r[0] * lo_bf(gv.x); r[1] = hi_bf(tv.x) + r[1] * hi_bf(gv.x); r[2] = lo_bf(tv.y) + r[2] * lo_bf(gv.y); r[3] = hi_bf(tv.y) + r[3] * hi_bf(gv.y);
;                             r[4] = lo_bf(tv.z) + r[4] * lo_bf(gv.z); r[5] = hi_bf(tv.z) + r[5] * hi_bf(gv.z); r[6] = lo_bf(tv.w) + r[6] * lo_bf(gv.w); r[7] = hi_bf(tv.w) + r[7] * hi_bf(gv.w);
;     ...
;                         u32x4 w; w.x = cvt_pk_bf16(r[0], r[1]); w.y = cvt_pk_bf16(r[2], r[3]); w.z = cvt_pk_bf16(r[4], r[5]); w.w = cvt_pk_bf16(r[6], r[7]);
;                         *(u32x4*)dst = w;
	v_lshlrev_b32_e32 v62, 16, v56
	global_store_dwordx4 v[72:73], v[50:53], off offset:256
	s_waitcnt vmcnt(1)
	v_lshlrev_b32_e32 v63, 16, v60
	v_and_b32_e32 v56, 0xffff0000, v56
	v_lshlrev_b32_e32 v50, 16, v54
	v_lshlrev_b32_e32 v51, 16, v58
	v_and_b32_e32 v52, 0xffff0000, v54
	v_and_b32_e32 v53, 0xffff0000, v58
	v_lshlrev_b32_e32 v54, 16, v55
	v_lshlrev_b32_e32 v58, 16, v59
	v_and_b32_e32 v55, 0xffff0000, v55
	v_and_b32_e32 v59, 0xffff0000, v59
	v_and_b32_e32 v60, 0xffff0000, v60
	v_lshlrev_b32_e32 v64, 16, v57
	v_lshlrev_b32_e32 v65, 16, v61
	v_and_b32_e32 v57, 0xffff0000, v57
	v_and_b32_e32 v61, 0xffff0000, v61
	v_fmac_f32_e32 v50, v46, v51
	v_fmac_f32_e32 v52, v47, v53
	v_fmac_f32_e32 v54, v48, v58
	v_fmac_f32_e32 v55, v49, v59
	v_fmac_f32_e32 v62, v42, v63
	v_fmac_f32_e32 v56, v43, v60
	v_fmac_f32_e32 v64, v44, v65
	v_fmac_f32_e32 v57, v45, v61
	v_cvt_pk_bf16_f32 v42, v50, v52
	v_cvt_pk_bf16_f32 v43, v54, v55
	v_cvt_pk_bf16_f32 v44, v62, v56
	v_cvt_pk_bf16_f32 v45, v64, v57
	global_load_dwordx4 v[46:49], v[76:77], off offset:256
	global_load_dwordx4 v[50:53], v[74:75], off offset:256
	v_lshl_add_u64 v[56:57], s[4:5], 0, v[70:71]
	v_lshl_add_u64 v[54:55], v[148:149], 0, s[18:19]
	v_lshl_add_u64 v[56:57], v[56:57], 0, v[146:147]
	v_lshl_add_u64 v[60:61], s[8:9], 0, v[54:55]
	global_store_dwordx4 v[56:57], v[42:45], off
	v_lshl_add_u64 v[58:59], s[6:7], 0, v[54:55]
	v_lshl_add_u64 v[60:61], v[60:61], 0, v[146:147]
	v_lshl_add_u64 v[58:59], v[58:59], 0, v[146:147]
	s_waitcnt vmcnt(2)
	v_lshlrev_b32_e32 v42, 16, v46
	s_waitcnt vmcnt(1)
	v_lshlrev_b32_e32 v43, 16, v50
	v_and_b32_e32 v44, 0xffff0000, v46
	v_and_b32_e32 v45, 0xffff0000, v50
	v_lshlrev_b32_e32 v46, 16, v47
	v_lshlrev_b32_e32 v50, 16, v51
	v_and_b32_e32 v47, 0xffff0000, v47
	v_and_b32_e32 v51, 0xffff0000, v51
	v_lshlrev_b32_e32 v62, 16, v48
	v_lshlrev_b32_e32 v63, 16, v52
	v_and_b32_e32 v48, 0xffff0000, v48
	v_and_b32_e32 v52, 0xffff0000, v52
	v_lshlrev_b32_e32 v64, 16, v49
	v_lshlrev_b32_e32 v65, 16, v53
	v_and_b32_e32 v49, 0xffff0000, v49
	v_and_b32_e32 v53, 0xffff0000, v53
	v_fmac_f32_e32 v42, v38, v43
	v_fmac_f32_e32 v44, v39, v45
	v_fmac_f32_e32 v46, v40, v50
	v_fmac_f32_e32 v47, v41, v51
	v_fmac_f32_e32 v62, v34, v63
	v_fmac_f32_e32 v48, v35, v52
	v_fmac_f32_e32 v64, v36, v65
	v_fmac_f32_e32 v49, v37, v53
	v_cvt_pk_bf16_f32 v34, v42, v44
	v_cvt_pk_bf16_f32 v35, v46, v47
	v_cvt_pk_bf16_f32 v36, v62, v48
	v_cvt_pk_bf16_f32 v37, v64, v49
	global_load_dwordx4 v[38:41], v[60:61], off
	global_load_dwordx4 v[42:45], v[58:59], off
	s_waitcnt vmcnt(1)
	v_lshlrev_b32_e32 v46, 16, v40
	global_store_dwordx4 v[56:57], v[34:37], off offset:256
	s_waitcnt vmcnt(1)
	v_lshlrev_b32_e32 v47, 16, v44
	v_and_b32_e32 v40, 0xffff0000, v40
	v_lshlrev_b32_e32 v34, 16, v38
	v_lshlrev_b32_e32 v35, 16, v42
	v_and_b32_e32 v36, 0xffff0000, v38
	v_and_b32_e32 v37, 0xffff0000, v42
	v_lshlrev_b32_e32 v38, 16, v39
	v_lshlrev_b32_e32 v42, 16, v43
	v_and_b32_e32 v39, 0xffff0000, v39
	v_and_b32_e32 v43, 0xffff0000, v43
	v_and_b32_e32 v44, 0xffff0000, v44
	v_lshlrev_b32_e32 v48, 16, v41
	v_lshlrev_b32_e32 v49, 16, v45
	v_and_b32_e32 v41, 0xffff0000, v41
	v_and_b32_e32 v45, 0xffff0000, v45
	v_fmac_f32_e32 v34, v30, v35
	v_fmac_f32_e32 v36, v31, v37
	v_fmac_f32_e32 v38, v32, v42
	v_fmac_f32_e32 v39, v33, v43
	v_fmac_f32_e32 v46, v26, v47
	v_fmac_f32_e32 v40, v27, v44
	v_fmac_f32_e32 v48, v28, v49
	v_fmac_f32_e32 v41, v29, v45
	v_cvt_pk_bf16_f32 v26, v34, v36
	v_cvt_pk_bf16_f32 v27, v38, v39
	v_cvt_pk_bf16_f32 v28, v46, v40
	v_cvt_pk_bf16_f32 v29, v48, v41
	global_load_dwordx4 v[30:33], v[60:61], off offset:256
	global_load_dwordx4 v[34:37], v[58:59], off offset:256
	v_lshl_add_u64 v[40:41], s[4:5], 0, v[54:55]
	v_lshl_add_u64 v[38:39], v[148:149], 0, s[20:21]
	v_lshl_add_u64 v[40:41], v[40:41], 0, v[146:147]
	v_lshl_add_u64 v[44:45], s[8:9], 0, v[38:39]
	global_store_dwordx4 v[40:41], v[26:29], off
	v_lshl_add_u64 v[42:43], s[6:7], 0, v[38:39]
	v_lshl_add_u64 v[44:45], v[44:45], 0, v[146:147]
	v_lshl_add_u64 v[42:43], v[42:43], 0, v[146:147]
	s_waitcnt vmcnt(2)
; #define PG8_BAR __builtin_amdgcn_s_barrier()
; __device__ __forceinline__ float lo_bf(unsigned u) { return __uint_as_float(u << 16); }
; __device__ __forceinline__ float hi_bf(unsigned u) { return __uint_as_float(u & 0xffff0000u); }
; template <class Epi, class Sched, bool ALIGN_EPI = false, bool SP2 = false>
; __device__ __forceinline__ void gemm_phase(PG8_LAS unsigned char* lds, const Gemm g, const Sched& S, const Epi& E) {
;     ...
;         if constexpr (ALIGN_EPI) { if (wr == 0) PG8_BAR; }
;         if constexpr (!Epi::AFTER_DRAIN) { E(acc, cur, wr, wc, fr, fq); S.done(cur); }
;         if (!has_next) break;
; #pragma unroll
;         for (int a = 0; a < 2; ++a)
; #pragma unroll
;             for (int b = 0; b < 2; ++b)
; #pragma unroll
;                 for (int m = 0; m < 4; ++m)
; #pragma unroll
;                     for (int n = 0; n < 2; ++n) acc[a][b][m][n] = (f32x4){0.f, 0.f, 0.f, 0.f};
;         cur = nxt; cA = nA; cB = nB; ++ui;
;         if constexpr (ALIGN_EPI) { if (wr == 1) PG8_BAR; }
;     __device__ __forceinline__ void operator()(const f32x4 (&acc)[2][2][4][2], const pg8::Unit& u, int wr, int wc, int fr, int fq) const {
;     ...
;                         if constexpr (MODE == EP_MIX) {
;                             const u32x4 gv = *(const u32x4*)(G + row * 1024 + col);
;                             const u32x4 tv = *(const u32x4*)(G2 + row * 1024 + col);
;                             r[0] = lo_bf(tv.x) + r[0] * lo_bf(gv.x); r[1] = hi_bf(tv.x) + r[1] * hi_bf(gv.x); r[2] = lo_bf(tv.y) + r[2] * lo_bf(gv.y); r[3] = hi_bf(tv.y) + r[3] * hi_bf(gv.y);
;                             r[4] = lo_bf(tv.z) + r[4] * lo_bf(gv.z); r[5] = hi_bf(tv.z) + r[5] * hi_bf(gv.z); r[6] = lo_bf(tv.w) + r[6] * lo_bf(gv.w); r[7] = hi_bf(tv.w) + r[7] * hi_bf(gv.w);
	v_lshlrev_b32_e32 v26, 16, v30
	s_waitcnt vmcnt(1)
	v_lshlrev_b32_e32 v27, 16, v34
	v_and_b32_e32 v28, 0xffff0000, v30
	v_and_b32_e32 v29, 0xffff0000, v34
	v_lshlrev_b32_e32 v30, 16, v31
	v_lshlrev_b32_e32 v34, 16, v35
	v_and_b32_e32 v31, 0xffff0000, v31
	v_and_b32_e32 v35, 0xffff0000, v35
	v_lshlrev_b32_e32 v46, 16, v32
	v_lshlrev_b32_e32 v47, 16, v36
	v_and_b32_e32 v32, 0xffff0000, v32
	v_and_b32_e32 v36, 0xffff0000, v36
	v_lshlrev_b32_e32 v48, 16, v33
	v_lshlrev_b32_e32 v49, 16, v37
	v_and_b32_e32 v33, 0xffff0000, v33
	v_and_b32_e32 v37, 0xffff0000, v37
	v_fmac_f32_e32 v26, v22, v27
	v_fmac_f32_e32 v28, v23, v29
	v_fmac_f32_e32 v30, v24, v34
	v_fmac_f32_e32 v31, v25, v35
	v_fmac_f32_e32 v46, v18, v47
	v_fmac_f32_e32 v32, v19, v36
	v_fmac_f32_e32 v48, v20, v49
	v_fmac_f32_e32 v33, v21, v37
	v_cvt_pk_bf16_f32 v18, v26, v28
	v_cvt_pk_bf16_f32 v19, v30, v31
	v_cvt_pk_bf16_f32 v20, v46, v32
	v_cvt_pk_bf16_f32 v21, v48, v33
	global_load_dwordx4 v[22:25], v[44:45], off
	global_load_dwordx4 v[26:29], v[42:43], off
	s_waitcnt vmcnt(1)
	v_lshlrev_b32_e32 v30, 16, v24
	global_store_dwordx4 v[40:41], v[18:21], off offset:256
	s_waitcnt vmcnt(1)
	v_lshlrev_b32_e32 v31, 16, v28
	v_and_b32_e32 v24, 0xffff0000, v24
	v_lshlrev_b32_e32 v18, 16, v22
	v_lshlrev_b32_e32 v19, 16, v26
	v_and_b32_e32 v20, 0xffff0000, v22
	v_and_b32_e32 v21, 0xffff0000, v26
	v_lshlrev_b32_e32 v22, 16, v23
	v_lshlrev_b32_e32 v26, 16, v27
	v_and_b32_e32 v23, 0xffff0000, v23
	v_and_b32_e32 v27, 0xffff0000, v27
	v_and_b32_e32 v28, 0xffff0000, v28
	v_lshlrev_b32_e32 v32, 16, v25
	v_lshlrev_b32_e32 v33, 16, v29
	v_and_b32_e32 v25, 0xffff0000, v25
	v_and_b32_e32 v29, 0xffff0000, v29
	v_fmac_f32_e32 v18, v14, v19
	v_fmac_f32_e32 v20, v15, v21
	v_fmac_f32_e32 v22, v16, v26
	v_fmac_f32_e32 v23, v17, v27
	v_fmac_f32_e32 v30, v10, v31
	v_fmac_f32_e32 v24, v11, v28
	v_fmac_f32_e32 v32, v12, v33
	v_fmac_f32_e32 v25, v13, v29
	v_cvt_pk_bf16_f32 v10, v18, v20
	v_cvt_pk_bf16_f32 v11, v22, v23
	v_cvt_pk_bf16_f32 v12, v30, v24
	v_cvt_pk_bf16_f32 v13, v32, v25
	global_load_dwordx4 v[14:17], v[44:45], off offset:256
	global_load_dwordx4 v[18:21], v[42:43], off offset:256
	v_lshl_add_u64 v[22:23], s[4:5], 0, v[38:39]
	v_lshl_add_u64 v[22:23], v[22:23], 0, v[146:147]
	global_store_dwordx4 v[22:23], v[10:13], off
	s_waitcnt vmcnt(2)
	v_lshlrev_b32_e32 v24, 16, v16
	v_lshlrev_b32_e32 v10, 16, v14
	s_waitcnt vmcnt(1)
	v_lshlrev_b32_e32 v11, 16, v18
	v_and_b32_e32 v12, 0xffff0000, v14
	v_and_b32_e32 v13, 0xffff0000, v18
	v_lshlrev_b32_e32 v14, 16, v15
	v_lshlrev_b32_e32 v18, 16, v19
	v_and_b32_e32 v15, 0xffff0000, v15
	v_and_b32_e32 v19, 0xffff0000, v19
	v_lshlrev_b32_e32 v25, 16, v20
	v_and_b32_e32 v16, 0xffff0000, v16
	v_and_b32_e32 v20, 0xffff0000, v20
	v_lshlrev_b32_e32 v26, 16, v17
	v_lshlrev_b32_e32 v27, 16, v21
	v_and_b32_e32 v17, 0xffff0000, v17
	v_and_b32_e32 v21, 0xffff0000, v21
	v_fmac_f32_e32 v10, v6, v11
	v_fmac_f32_e32 v12, v7, v13
	v_fmac_f32_e32 v14, v8, v18
	v_fmac_f32_e32 v15, v9, v19
	v_fmac_f32_e32 v24, v2, v25
	v_fmac_f32_e32 v16, v3, v20
	v_fmac_f32_e32 v26, v4, v27
	v_fmac_f32_e32 v17, v5, v21
	v_cvt_pk_bf16_f32 v2, v10, v12
	v_cvt_pk_bf16_f32 v3, v14, v15
	v_cvt_pk_bf16_f32 v4, v24, v16
	v_cvt_pk_bf16_f32 v5, v26, v17
	global_store_dwordx4 v[22:23], v[2:5], off offset:256
	s_cbranch_vccnz .LBB0_1331
	s_andn2_b64 vcc, exec, s[0:1]
	s_cbranch_vccnz .LBB0_1330
	s_branch .LBB0_1330

; #define PG8_STAGE(bufoff, gbase, voff) do { _Pragma("unroll") for (int _i = 0; _i < 2; ++_i) \
;         __builtin_amdgcn_global_load_lds((const unsigned*)((const char*)(gbase) + (voff)[_i]), (PG8_LAS unsigned*)(lds + (bufoff) + ldsw + _i * 8192), 16, 0, 0); } while (0)
; #define PG8_LDA(dst, b, h) do { _Pragma("unroll") for (int m = 0; m < 4; ++m) _Pragma("unroll") for (int k = 0; k < 2; ++k) dst[m][k] = *(const PG8_LAS bf16x8*)(lds + PG8_SA(b, h) + aoff + m * 2048 + k * 1024); } while (0)
; #define PG8_LDB(dst, b, h) do { _Pragma("unroll") for (int n = 0; n < 2; ++n) _Pragma("unroll") for (int k = 0; k < 2; ++k) dst[n][k] = *(const PG8_LAS bf16x8*)(lds + PG8_SB(b, h) + boff + n * 2048 + k * 1024); } while (0)
; #define PG8_MMA(ai, bj, At, Bt) do { __builtin_amdgcn_s_setprio(1); _Pragma("unroll") for (int m = 0; m < 4; ++m) _Pragma("unroll") for (int n = 0; n < 2; ++n) _Pragma("unroll") for (int k = 0; k < 2; ++k) \
;         acc[ai][bj][m][n] = __builtin_amdgcn_mfma_f32_16x16x32_bf16(Bt[n][k], At[m][k], acc[ai][bj][m][n], 0, 0, 0); __builtin_amdgcn_s_setprio(0); } while (0)
; #define PG8_WAIT_V(n) asm volatile("s_waitcnt vmcnt(" #n ")" ::: "memory")
; template <class Epi, class Sched, bool ALIGN_EPI = false, bool SP2 = false>
; __device__ __forceinline__ void gemm_phase(PG8_LAS unsigned char* lds, const Gemm g, const Sched& S, const Epi& E) {
;     ...
;             PG8_LDB(B0, 0, 0); PG8_LDB(B1, 0, 1); PG8_SCHED; PG8_LDA(At, 0, 0); PG8_STAGE(PG8_SA(1, 1), a1 + hstep, voffA);
;             PG8_WAIT_V(8); PG8_WAIT_L(0); PG8_BAR; PG8_MMA(0, 0, At, B0); PG8_MMA(0, 1, At, B1); PG8_BAR; PG8_SCHED;
;             PG8_LDA(At, 0, 1); PG8_STAGE(PG8_SB(0, 0), b2, voffB); PG8_STAGE(PG8_SB(0, 1), b2 + hstep, voffB); PG8_STAGE(PG8_SA(0, 0), a2, voffA);
;             PG8_WAIT_V(8); PG8_WAIT_L(0); PG8_BAR; PG8_MMA(1, 0, At, B0); PG8_MMA(1, 1, At, B1); PG8_BAR; PG8_SCHED;
;             PG8_LDB(B0, 1, 0); PG8_LDB(B1, 1, 1); PG8_SCHED; PG8_LDA(At, 1, 0); PG8_STAGE(PG8_SA(0, 1), a2 + hstep, voffA);
;             PG8_WAIT_V(8); PG8_WAIT_L(0); PG8_BAR; PG8_MMA(0, 0, At, B0); PG8_MMA(0, 1, At, B1); PG8_BAR; PG8_SCHED;
;             PG8_LDA(At, 1, 1); PG8_STAGE(PG8_SB(1, 0), b3, voffB); PG8_STAGE(PG8_SB(1, 1), b3 + hstep, voffB); PG8_STAGE(PG8_SA(1, 0), a3, voffA);
;             PG8_WAIT_V(8); PG8_WAIT_L(0); PG8_BAR; PG8_MMA(1, 0, At, B0); PG8_MMA(1, 1, At, B1); PG8_BAR; PG8_SCHED;
.LBB0_1432:
	ds_read_b128 v[154:157], v150
	ds_read_b128 v[158:161], v150 offset:1024
	ds_read_b128 v[162:165], v150 offset:2048
	ds_read_b128 v[166:169], v150 offset:3072
	ds_read_b128 v[174:177], v151
	ds_read_b128 v[178:181], v151 offset:1024
	ds_read_b128 v[182:185], v151 offset:2048
	ds_read_b128 v[186:189], v151 offset:3072
	s_add_u32 s30, s28, 0xfffc0080
	s_addc_u32 s31, s29, -1
	s_cmp_eq_u32 s68, 12
	s_cselect_b32 s35, s21, s31
	s_cselect_b32 s34, s64, s30
	s_cselect_b32 s31, s19, s67
	s_cselect_b32 s30, s65, s66
	v_lshl_add_u64 v[146:147], s[28:29], 0, v[138:139]
	s_add_i32 m0, s27, 0xc000
	ds_read_b128 v[190:193], v152
	ds_read_b128 v[194:197], v152 offset:1024
	ds_read_b128 v[198:201], v152 offset:2048
	ds_read_b128 v[202:205], v152 offset:3072
	ds_read_b128 v[206:209], v152 offset:4096
	ds_read_b128 v[210:213], v152 offset:5120
	ds_read_b128 v[214:217], v152 offset:6144
	ds_read_b128 v[218:221], v152 offset:7168
	global_load_lds_dwordx4 v[146:147], off
	v_lshl_add_u64 v[146:147], s[28:29], 0, v[140:141]
	s_add_i32 m0, s27, 0xe000
	s_nop 0
	global_load_lds_dwordx4 v[146:147], off
	s_waitcnt vmcnt(8)
	s_waitcnt lgkmcnt(0)
	s_barrier
	s_waitcnt lgkmcnt(0)
	v_mfma_f32_16x16x32_bf16 v[126:129], v[154:157], v[190:193], v[126:129]
	v_mfma_f32_16x16x32_bf16 v[122:125], v[162:165], v[190:193], v[122:125]
	v_mfma_f32_16x16x32_bf16 v[118:121], v[154:157], v[198:201], v[118:121]
	v_mfma_f32_16x16x32_bf16 v[110:113], v[162:165], v[198:201], v[110:113]
	v_mfma_f32_16x16x32_bf16 v[102:105], v[154:157], v[206:209], v[102:105]
	v_mfma_f32_16x16x32_bf16 v[94:97], v[162:165], v[206:209], v[94:97]
	v_mfma_f32_16x16x32_bf16 v[86:89], v[154:157], v[214:217], v[86:89]
	v_mfma_f32_16x16x32_bf16 v[78:81], v[162:165], v[214:217], v[78:81]
	v_mfma_f32_16x16x32_bf16 v[126:129], v[158:161], v[194:197], v[126:129]
	v_mfma_f32_16x16x32_bf16 v[122:125], v[166:169], v[194:197], v[122:125]
	v_mfma_f32_16x16x32_bf16 v[118:121], v[158:161], v[202:205], v[118:121]
	v_mfma_f32_16x16x32_bf16 v[110:113], v[166:169], v[202:205], v[110:113]
	v_mfma_f32_16x16x32_bf16 v[102:105], v[158:161], v[210:213], v[102:105]
	v_mfma_f32_16x16x32_bf16 v[94:97], v[166:169], v[210:213], v[94:97]
	v_mfma_f32_16x16x32_bf16 v[86:89], v[158:161], v[218:221], v[86:89]
	v_mfma_f32_16x16x32_bf16 v[78:81], v[166:169], v[218:221], v[78:81]
	v_mfma_f32_16x16x32_bf16 v[114:117], v[174:177], v[190:193], v[114:117]
	v_mfma_f32_16x16x32_bf16 v[106:109], v[182:185], v[190:193], v[106:109]
	v_mfma_f32_16x16x32_bf16 v[98:101], v[174:177], v[198:201], v[98:101]
	v_mfma_f32_16x16x32_bf16 v[90:93], v[182:185], v[198:201], v[90:93]
	v_mfma_f32_16x16x32_bf16 v[82:85], v[174:177], v[206:209], v[82:85]
	v_mfma_f32_16x16x32_bf16 v[74:77], v[182:185], v[206:209], v[74:77]
	v_mfma_f32_16x16x32_bf16 v[70:73], v[174:177], v[214:217], v[70:73]
	v_mfma_f32_16x16x32_bf16 v[66:69], v[182:185], v[214:217], v[66:69]
	v_mfma_f32_16x16x32_bf16 v[114:117], v[178:181], v[194:197], v[114:117]
	v_mfma_f32_16x16x32_bf16 v[106:109], v[186:189], v[194:197], v[106:109]
	v_mfma_f32_16x16x32_bf16 v[98:101], v[178:181], v[202:205], v[98:101]
	v_mfma_f32_16x16x32_bf16 v[90:93], v[186:189], v[202:205], v[90:93]
	v_mfma_f32_16x16x32_bf16 v[82:85], v[178:181], v[210:213], v[82:85]
	v_mfma_f32_16x16x32_bf16 v[74:77], v[186:189], v[210:213], v[74:77]
	v_mfma_f32_16x16x32_bf16 v[70:73], v[178:181], v[218:221], v[70:73]
	v_mfma_f32_16x16x32_bf16 v[66:69], v[186:189], v[218:221], v[66:69]
	s_barrier
	s_add_i32 s69, s57, s42
	v_lshl_add_u64 v[146:147], s[30:31], 0, v[132:133]
	s_mov_b32 m0, s69
	ds_read_b128 v[190:193], v152 offset:16384
	ds_read_b128 v[194:197], v152 offset:17408
	ds_read_b128 v[198:201], v152 offset:18432
	ds_read_b128 v[202:205], v152 offset:19456
	ds_read_b128 v[206:209], v152 offset:20480
	ds_read_b128 v[210:213], v152 offset:21504
	ds_read_b128 v[214:217], v152 offset:22528
	ds_read_b128 v[218:221], v152 offset:23552
	global_load_lds_dwordx4 v[146:147], off
	s_add_i32 m0, s69, 0x2000
	s_add_u32 s70, s30, 0x40000
	v_lshl_add_u64 v[170:171], s[30:31], 0, v[136:137]
	s_addc_u32 s71, s31, 0
	s_add_i32 s69, s58, s42
	global_load_lds_dwordx4 v[170:171], off
	v_lshl_add_u64 v[222:223], s[70:71], 0, v[132:133]
	s_mov_b32 m0, s69
	v_lshl_add_u64 v[224:225], s[34:35], 0, v[134:135]
	global_load_lds_dwordx4 v[222:223], off
	v_lshl_add_u64 v[222:223], s[70:71], 0, v[136:137]
	s_add_i32 m0, s69, 0x2000
	s_nop 0
	global_load_lds_dwordx4 v[222:223], off
	v_lshl_add_u64 v[222:223], s[34:35], 0, v[130:131]
	s_mov_b32 m0, s27
	s_nop 0
	global_load_lds_dwordx4 v[222:223], off
	s_mov_b32 m0, s43
	s_nop 0
	global_load_lds_dwordx4 v[224:225], off
	s_waitcnt vmcnt(8)
	s_waitcnt lgkmcnt(0)
	s_barrier
; #define PG8_STAGE(bufoff, gbase, voff) do { _Pragma("unroll") for (int _i = 0; _i < 2; ++_i) \
;         __builtin_amdgcn_global_load_lds((const unsigned*)((const char*)(gbase) + (voff)[_i]), (PG8_LAS unsigned*)(lds + (bufoff) + ldsw + _i * 8192), 16, 0, 0); } while (0)
; #define PG8_LDA(dst, b, h) do { _Pragma("unroll") for (int m = 0; m < 4; ++m) _Pragma("unroll") for (int k = 0; k < 2; ++k) dst[m][k] = *(const PG8_LAS bf16x8*)(lds + PG8_SA(b, h) + aoff + m * 2048 + k * 1024); } while (0)
; #define PG8_LDB(dst, b, h) do { _Pragma("unroll") for (int n = 0; n < 2; ++n) _Pragma("unroll") for (int k = 0; k < 2; ++k) dst[n][k] = *(const PG8_LAS bf16x8*)(lds + PG8_SB(b, h) + boff + n * 2048 + k * 1024); } while (0)
; #define PG8_MMA(ai, bj, At, Bt) do { __builtin_amdgcn_s_setprio(1); _Pragma("unroll") for (int m = 0; m < 4; ++m) _Pragma("unroll") for (int n = 0; n < 2; ++n) _Pragma("unroll") for (int k = 0; k < 2; ++k) \
;         acc[ai][bj][m][n] = __builtin_amdgcn_mfma_f32_16x16x32_bf16(Bt[n][k], At[m][k], acc[ai][bj][m][n], 0, 0, 0); __builtin_amdgcn_s_setprio(0); } while (0)
; #define PG8_WAIT_V(n) asm volatile("s_waitcnt vmcnt(" #n ")" ::: "memory")
; template <class Epi, class Sched, bool ALIGN_EPI = false, bool SP2 = false>
; __device__ __forceinline__ void gemm_phase(PG8_LAS unsigned char* lds, const Gemm g, const Sched& S, const Epi& E) {
;     ...
;             PG8_LDB(B0, 0, 0); PG8_LDB(B1, 0, 1); PG8_SCHED; PG8_LDA(At, 0, 0); PG8_STAGE(PG8_SA(1, 1), a1 + hstep, voffA);
;             PG8_WAIT_V(8); PG8_WAIT_L(0); PG8_BAR; PG8_MMA(0, 0, At, B0); PG8_MMA(0, 1, At, B1); PG8_BAR; PG8_SCHED;
;             PG8_LDA(At, 0, 1); PG8_STAGE(PG8_SB(0, 0), b2, voffB); PG8_STAGE(PG8_SB(0, 1), b2 + hstep, voffB); PG8_STAGE(PG8_SA(0, 0), a2, voffA);
;             PG8_WAIT_V(8); PG8_WAIT_L(0); PG8_BAR; PG8_MMA(1, 0, At, B0); PG8_MMA(1, 1, At, B1); PG8_BAR; PG8_SCHED;
;             PG8_LDB(B0, 1, 0); PG8_LDB(B1, 1, 1); PG8_SCHED; PG8_LDA(At, 1, 0); PG8_STAGE(PG8_SA(0, 1), a2 + hstep, voffA);
;             PG8_WAIT_V(8); PG8_WAIT_L(0); PG8_BAR; PG8_MMA(0, 0, At, B0); PG8_MMA(0, 1, At, B1); PG8_BAR; PG8_SCHED;
;             PG8_LDA(At, 1, 1); PG8_STAGE(PG8_SB(1, 0), b3, voffB); PG8_STAGE(PG8_SB(1, 1), b3 + hstep, voffB); PG8_STAGE(PG8_SA(1, 0), a3, voffA);
;             PG8_WAIT_V(8); PG8_WAIT_L(0); PG8_BAR; PG8_MMA(1, 0, At, B0); PG8_MMA(1, 1, At, B1); PG8_BAR; PG8_SCHED;
	s_waitcnt lgkmcnt(0)
	v_mfma_f32_16x16x32_bf16 v[62:65], v[154:157], v[190:193], v[62:65]
	v_mfma_f32_16x16x32_bf16 v[58:61], v[162:165], v[190:193], v[58:61]
	v_mfma_f32_16x16x32_bf16 v[54:57], v[154:157], v[198:201], v[54:57]
	v_mfma_f32_16x16x32_bf16 v[46:49], v[162:165], v[198:201], v[46:49]
	v_mfma_f32_16x16x32_bf16 v[38:41], v[154:157], v[206:209], v[38:41]
	v_mfma_f32_16x16x32_bf16 v[30:33], v[162:165], v[206:209], v[30:33]
	v_mfma_f32_16x16x32_bf16 v[22:25], v[154:157], v[214:217], v[22:25]
	v_mfma_f32_16x16x32_bf16 v[14:17], v[162:165], v[214:217], v[14:17]
	v_mfma_f32_16x16x32_bf16 v[62:65], v[158:161], v[194:197], v[62:65]
	v_mfma_f32_16x16x32_bf16 v[58:61], v[166:169], v[194:197], v[58:61]
	v_mfma_f32_16x16x32_bf16 v[54:57], v[158:161], v[202:205], v[54:57]
	v_mfma_f32_16x16x32_bf16 v[46:49], v[166:169], v[202:205], v[46:49]
	v_mfma_f32_16x16x32_bf16 v[38:41], v[158:161], v[210:213], v[38:41]
	v_mfma_f32_16x16x32_bf16 v[30:33], v[166:169], v[210:213], v[30:33]
	v_mfma_f32_16x16x32_bf16 v[22:25], v[158:161], v[218:221], v[22:25]
	v_mfma_f32_16x16x32_bf16 v[14:17], v[166:169], v[218:221], v[14:17]
	v_mfma_f32_16x16x32_bf16 v[50:53], v[174:177], v[190:193], v[50:53]
	v_mfma_f32_16x16x32_bf16 v[42:45], v[182:185], v[190:193], v[42:45]
	v_mfma_f32_16x16x32_bf16 v[34:37], v[174:177], v[198:201], v[34:37]
	v_mfma_f32_16x16x32_bf16 v[26:29], v[182:185], v[198:201], v[26:29]
	v_mfma_f32_16x16x32_bf16 v[18:21], v[174:177], v[206:209], v[18:21]
	v_mfma_f32_16x16x32_bf16 v[10:13], v[182:185], v[206:209], v[10:13]
	v_mfma_f32_16x16x32_bf16 v[6:9], v[174:177], v[214:217], v[6:9]
	v_mfma_f32_16x16x32_bf16 v[2:5], v[182:185], v[214:217], v[2:5]
	v_mfma_f32_16x16x32_bf16 v[50:53], v[178:181], v[194:197], v[50:53]
	v_mfma_f32_16x16x32_bf16 v[42:45], v[186:189], v[194:197], v[42:45]
	v_mfma_f32_16x16x32_bf16 v[34:37], v[178:181], v[202:205], v[34:37]
	v_mfma_f32_16x16x32_bf16 v[26:29], v[186:189], v[202:205], v[26:29]
	v_mfma_f32_16x16x32_bf16 v[18:21], v[178:181], v[210:213], v[18:21]
	v_mfma_f32_16x16x32_bf16 v[10:13], v[186:189], v[210:213], v[10:13]
	v_mfma_f32_16x16x32_bf16 v[6:9], v[178:181], v[218:221], v[6:9]
	v_mfma_f32_16x16x32_bf16 v[2:5], v[186:189], v[218:221], v[2:5]
	s_barrier
	s_add_i32 s69, 0, 0x18000
	v_add_u32_e32 v153, s69, v148
	s_add_i32 s70, 0, 0x1c000
	ds_read_b128 v[154:157], v153
	ds_read_b128 v[158:161], v153 offset:1024
	ds_read_b128 v[162:165], v153 offset:2048
	ds_read_b128 v[166:169], v153 offset:3072
	v_add_u32_e32 v153, s70, v148
	ds_read_b128 v[174:177], v153
	ds_read_b128 v[178:181], v153 offset:1024
	ds_read_b128 v[182:185], v153 offset:2048
	ds_read_b128 v[186:189], v153 offset:3072
	s_add_u32 s34, s34, 0x40000
	s_addc_u32 s35, s35, 0
	s_mov_b32 m0, s44
	v_lshl_add_u64 v[226:227], s[34:35], 0, v[130:131]
	ds_read_b128 v[190:193], v152 offset:32768
	ds_read_b128 v[194:197], v152 offset:33792
	ds_read_b128 v[198:201], v152 offset:34816
	ds_read_b128 v[202:205], v152 offset:35840
	ds_read_b128 v[206:209], v152 offset:36864
	ds_read_b128 v[210:213], v152 offset:37888
	ds_read_b128 v[214:217], v152 offset:38912
	ds_read_b128 v[218:221], v152 offset:39936
	global_load_lds_dwordx4 v[226:227], off
	v_lshl_add_u64 v[226:227], s[34:35], 0, v[134:135]
	s_mov_b32 m0, s45
	s_nop 0
	global_load_lds_dwordx4 v[226:227], off
	s_waitcnt vmcnt(8)
	s_waitcnt lgkmcnt(0)
	s_barrier
	s_waitcnt lgkmcnt(0)
	v_mfma_f32_16x16x32_bf16 v[126:129], v[154:157], v[190:193], v[126:129]
	v_mfma_f32_16x16x32_bf16 v[122:125], v[162:165], v[190:193], v[122:125]
	v_mfma_f32_16x16x32_bf16 v[118:121], v[154:157], v[198:201], v[118:121]
	v_mfma_f32_16x16x32_bf16 v[110:113], v[162:165], v[198:201], v[110:113]
	v_mfma_f32_16x16x32_bf16 v[102:105], v[154:157], v[206:209], v[102:105]
	v_mfma_f32_16x16x32_bf16 v[94:97], v[162:165], v[206:209], v[94:97]
	v_mfma_f32_16x16x32_bf16 v[86:89], v[154:157], v[214:217], v[86:89]
	v_mfma_f32_16x16x32_bf16 v[78:81], v[162:165], v[214:217], v[78:81]
	v_mfma_f32_16x16x32_bf16 v[126:129], v[158:161], v[194:197], v[126:129]
	v_mfma_f32_16x16x32_bf16 v[122:125], v[166:169], v[194:197], v[122:125]
	v_mfma_f32_16x16x32_bf16 v[118:121], v[158:161], v[202:205], v[118:121]
	v_mfma_f32_16x16x32_bf16 v[110:113], v[166:169], v[202:205], v[110:113]
	v_mfma_f32_16x16x32_bf16 v[102:105], v[158:161], v[210:213], v[102:105]
	v_mfma_f32_16x16x32_bf16 v[94:97], v[166:169], v[210:213], v[94:97]
	v_mfma_f32_16x16x32_bf16 v[86:89], v[158:161], v[218:221], v[86:89]
	v_mfma_f32_16x16x32_bf16 v[78:81], v[166:169], v[218:221], v[78:81]
	v_mfma_f32_16x16x32_bf16 v[114:117], v[174:177], v[190:193], v[114:117]
	v_mfma_f32_16x16x32_bf16 v[106:109], v[182:185], v[190:193], v[106:109]
	v_mfma_f32_16x16x32_bf16 v[98:101], v[174:177], v[198:201], v[98:101]
	v_mfma_f32_16x16x32_bf16 v[90:93], v[182:185], v[198:201], v[90:93]
	v_mfma_f32_16x16x32_bf16 v[82:85], v[174:177], v[206:209], v[82:85]
	v_mfma_f32_16x16x32_bf16 v[74:77], v[182:185], v[206:209], v[74:77]
	v_mfma_f32_16x16x32_bf16 v[70:73], v[174:177], v[214:217], v[70:73]
	v_mfma_f32_16x16x32_bf16 v[66:69], v[182:185], v[214:217], v[66:69]
	v_mfma_f32_16x16x32_bf16 v[114:117], v[178:181], v[194:197], v[114:117]
	v_mfma_f32_16x16x32_bf16 v[106:109], v[186:189], v[194:197], v[106:109]
	v_mfma_f32_16x16x32_bf16 v[98:101], v[178:181], v[202:205], v[98:101]
	v_mfma_f32_16x16x32_bf16 v[90:93], v[186:189], v[202:205], v[90:93]
	v_mfma_f32_16x16x32_bf16 v[82:85], v[178:181], v[210:213], v[82:85]
	v_mfma_f32_16x16x32_bf16 v[74:77], v[186:189], v[210:213], v[74:77]
	v_mfma_f32_16x16x32_bf16 v[70:73], v[178:181], v[218:221], v[70:73]
	v_mfma_f32_16x16x32_bf16 v[66:69], v[186:189], v[218:221], v[66:69]
	s_barrier
; #define PG8_STAGE(bufoff, gbase, voff) do { _Pragma("unroll") for (int _i = 0; _i < 2; ++_i) \
;         __builtin_amdgcn_global_load_lds((const unsigned*)((const char*)(gbase) + (voff)[_i]), (PG8_LAS unsigned*)(lds + (bufoff) + ldsw + _i * 8192), 16, 0, 0); } while (0)
; #define PG8_WAIT_V(n) asm volatile("s_waitcnt vmcnt(" #n ")" ::: "memory")
; #define PG8_WAIT_L(n) asm volatile("s_waitcnt lgkmcnt(" #n ")" ::: "memory")
; template <class Epi, class Sched, bool ALIGN_EPI = false, bool SP2 = false>
; __device__ __forceinline__ void gemm_phase(PG8_LAS unsigned char* lds, const Gemm g, const Sched& S, const Epi& E) {
;     ...
;             PG8_WAIT_V(8); PG8_WAIT_L(0); PG8_BAR; PG8_MMA(0, 0, At, B0); PG8_MMA(0, 1, At, B1); PG8_BAR; PG8_SCHED;
;             PG8_LDA(At, 1, 1); PG8_STAGE(PG8_SB(1, 0), b3, voffB); PG8_STAGE(PG8_SB(1, 1), b3 + hstep, voffB); PG8_STAGE(PG8_SA(1, 0), a3, voffA);
;             PG8_WAIT_V(8); PG8_WAIT_L(0); PG8_BAR; PG8_MMA(1, 0, At, B0); PG8_MMA(1, 1, At, B1); PG8_BAR; PG8_SCHED;
;             } else {
;             PG8_LDB(B0, 0, 0); PG8_SCHED; PG8_LDA(At, 0, 0); PG8_STAGE(PG8_SA(1, 1), a1 + hstep, voffA);
;             PG8_WAIT_L(8); PG8_BAR; PG8_WAIT_L(0); PG8_MMA(0, 0, At, B0); PG8_BAR; PG8_SCHED;
;             PG8_LDB(B1, 0, 1); PG8_STAGE(PG8_SB(0, 0), b2, voffB);
;             PG8_BAR; PG8_WAIT_L(0); PG8_MMA(0, 1, At, B1); PG8_BAR;
;             PG8_LDA(At, 0, 1); PG8_STAGE(PG8_SA(0, 0), a2, voffA);
;             PG8_BAR; PG8_WAIT_L(0); PG8_MMA(1, 0, At, B0); PG8_BAR; PG8_SCHED;
;             PG8_STAGE(PG8_SB(0, 1), b2 + hstep, voffB);
;             PG8_WAIT_V(6); PG8_BAR; PG8_MMA(1, 1, At, B1); PG8_BAR;
;             PG8_LDB(B0, 1, 0); PG8_SCHED; PG8_LDA(At, 1, 0); PG8_STAGE(PG8_SA(0, 1), a2 + hstep, voffA);
;             PG8_WAIT_L(8); PG8_BAR; PG8_WAIT_L(0); PG8_MMA(0, 0, At, B0); PG8_BAR; PG8_SCHED;
;             PG8_LDB(B1, 1, 1); PG8_STAGE(PG8_SB(1, 0), b3, voffB);
;             PG8_BAR; PG8_WAIT_L(0); PG8_MMA(0, 1, At, B1); PG8_BAR;
;             PG8_LDA(At, 1, 1); PG8_STAGE(PG8_SA(1, 0), a3, voffA);
;             PG8_BAR; PG8_WAIT_L(0); PG8_MMA(1, 0, At, B0); PG8_BAR; PG8_SCHED;
;             PG8_STAGE(PG8_SB(1, 1), b3 + hstep, voffB);
;             PG8_WAIT_V(6); PG8_BAR; PG8_MMA(1, 1, At, B1); PG8_BAR;
;             }
;         }
;         if constexpr (ALIGN_EPI) { if (wr == 0) PG8_BAR; }
	s_add_i32 s34, s69, s42
	v_lshl_add_u64 v[146:147], v[146:147], 0, s[8:9]
	s_mov_b32 m0, s34
	ds_read_b128 v[190:193], v152 offset:49152
	ds_read_b128 v[194:197], v152 offset:50176
	ds_read_b128 v[198:201], v152 offset:51200
	ds_read_b128 v[202:205], v152 offset:52224
	ds_read_b128 v[206:209], v152 offset:53248
	ds_read_b128 v[210:213], v152 offset:54272
	ds_read_b128 v[214:217], v152 offset:55296
	ds_read_b128 v[218:221], v152 offset:56320
	global_load_lds_dwordx4 v[146:147], off
	s_add_i32 m0, s34, 0x2000
	s_add_u32 s30, s30, 0x40080
	v_lshl_add_u64 v[146:147], v[170:171], 0, s[8:9]
	s_addc_u32 s31, s31, 0
	s_add_i32 s34, s70, s42
	global_load_lds_dwordx4 v[146:147], off
	v_lshl_add_u64 v[146:147], s[30:31], 0, v[132:133]
	s_mov_b32 m0, s34
	s_nop 0
	global_load_lds_dwordx4 v[146:147], off
	v_lshl_add_u64 v[146:147], s[30:31], 0, v[136:137]
	s_add_i32 m0, s34, 0x2000
	s_nop 0
	global_load_lds_dwordx4 v[146:147], off
	v_lshl_add_u64 v[146:147], v[222:223], 0, s[8:9]
	s_mov_b32 m0, s53
	s_nop 0
	global_load_lds_dwordx4 v[146:147], off
	v_lshl_add_u64 v[146:147], v[224:225], 0, s[8:9]
	s_mov_b32 m0, s54
	s_nop 0
	global_load_lds_dwordx4 v[146:147], off
	s_waitcnt vmcnt(8)
	s_waitcnt lgkmcnt(0)
	s_barrier
	s_waitcnt lgkmcnt(0)
	v_mfma_f32_16x16x32_bf16 v[62:65], v[154:157], v[190:193], v[62:65]
	v_mfma_f32_16x16x32_bf16 v[58:61], v[162:165], v[190:193], v[58:61]
	v_mfma_f32_16x16x32_bf16 v[54:57], v[154:157], v[198:201], v[54:57]
	v_mfma_f32_16x16x32_bf16 v[46:49], v[162:165], v[198:201], v[46:49]
	v_mfma_f32_16x16x32_bf16 v[38:41], v[154:157], v[206:209], v[38:41]
	v_mfma_f32_16x16x32_bf16 v[30:33], v[162:165], v[206:209], v[30:33]
	v_mfma_f32_16x16x32_bf16 v[22:25], v[154:157], v[214:217], v[22:25]
	v_mfma_f32_16x16x32_bf16 v[14:17], v[162:165], v[214:217], v[14:17]
	v_mfma_f32_16x16x32_bf16 v[62:65], v[158:161], v[194:197], v[62:65]
	v_mfma_f32_16x16x32_bf16 v[58:61], v[166:169], v[194:197], v[58:61]
	v_mfma_f32_16x16x32_bf16 v[54:57], v[158:161], v[202:205], v[54:57]
	v_mfma_f32_16x16x32_bf16 v[46:49], v[166:169], v[202:205], v[46:49]
	v_mfma_f32_16x16x32_bf16 v[38:41], v[158:161], v[210:213], v[38:41]
	v_mfma_f32_16x16x32_bf16 v[30:33], v[166:169], v[210:213], v[30:33]
	v_mfma_f32_16x16x32_bf16 v[22:25], v[158:161], v[218:221], v[22:25]
	v_mfma_f32_16x16x32_bf16 v[14:17], v[166:169], v[218:221], v[14:17]
	v_mfma_f32_16x16x32_bf16 v[50:53], v[174:177], v[190:193], v[50:53]
	v_mfma_f32_16x16x32_bf16 v[42:45], v[182:185], v[190:193], v[42:45]
	v_mfma_f32_16x16x32_bf16 v[34:37], v[174:177], v[198:201], v[34:37]
	v_mfma_f32_16x16x32_bf16 v[26:29], v[182:185], v[198:201], v[26:29]
	v_mfma_f32_16x16x32_bf16 v[18:21], v[174:177], v[206:209], v[18:21]
	v_mfma_f32_16x16x32_bf16 v[10:13], v[182:185], v[206:209], v[10:13]
	v_mfma_f32_16x16x32_bf16 v[6:9], v[174:177], v[214:217], v[6:9]
	v_mfma_f32_16x16x32_bf16 v[2:5], v[182:185], v[214:217], v[2:5]
	v_mfma_f32_16x16x32_bf16 v[50:53], v[178:181], v[194:197], v[50:53]
	v_mfma_f32_16x16x32_bf16 v[42:45], v[186:189], v[194:197], v[42:45]
	v_mfma_f32_16x16x32_bf16 v[34:37], v[178:181], v[202:205], v[34:37]
	v_mfma_f32_16x16x32_bf16 v[26:29], v[186:189], v[202:205], v[26:29]
	v_mfma_f32_16x16x32_bf16 v[18:21], v[178:181], v[210:213], v[18:21]
	v_mfma_f32_16x16x32_bf16 v[10:13], v[186:189], v[210:213], v[10:13]
	v_mfma_f32_16x16x32_bf16 v[6:9], v[178:181], v[218:221], v[6:9]
	v_mfma_f32_16x16x32_bf16 v[2:5], v[186:189], v[218:221], v[2:5]
	s_barrier
	s_add_i32 s68, s68, 2
	s_add_u32 s28, s28, 0x100
	s_addc_u32 s29, s29, 0
	s_add_u32 s66, s66, 0x100
	s_addc_u32 s67, s67, 0
	s_cmp_gt_u32 s68, 13
	s_cbranch_scc0 .LBB0_1432
	s_andn2_b64 vcc, s[10:11], s[2:3]
	s_cbranch_vccz .LBB0_1435
	s_barrier
; __device__ __forceinline__ unsigned cvt_pk_bf16(float lo, float hi) { unsigned r; asm volatile("v_cvt_pk_bf16_f32 %0, %1, %2" : "=v"(r) : "v"(lo), "v"(hi)); return r; }
; __device__ __forceinline__ float sigmoidf_(float x) { return __builtin_amdgcn_rcpf(1.0f + __expf(-x)); }
;     __device__ __forceinline__ void operator()(const f32x4 (&acc)[2][2][4][2], const pg8::Unit& u, int wr, int wc, int fr, int fq) const {
;     ...
;                 const size_t row = (size_t)(row0 + ai * 128 + m * 16);
;                 if constexpr (MODE == EP_SWIGLU) {
;                     const f32x4 g0 = acc[ai][0][m][0], g1 = acc[ai][0][m][1], u0 = acc[ai][1][m][0], u1 = acc[ai][1][m][1];
;                     float r[8];
; #pragma unroll
;                     for (int j = 0; j < 4; ++j) { r[j] = g0[j] * sigmoidf_(g0[j]) * u0[j]; r[4 + j] = g1[j] * sigmoidf_(g1[j]) * u1[j]; }
;                     u32x4 w; w.x = cvt_pk_bf16(r[0], r[1]); w.y = cvt_pk_bf16(r[2], r[3]); w.z = cvt_pk_bf16(r[4], r[5]); w.w = cvt_pk_bf16(r[6], r[7]);
;                     *(u32x4*)(O + row * ldc + u.pn * 128 + cin) = w;
;                 } else {
; #pragma unroll
;                     for (int bj = 0; bj < 2; ++bj) {
;                         const int col = u.pn * 256 + bj * 128 + cin;
;                         const f32x4 a0 = acc[ai][bj][m][0], a1 = acc[ai][bj][m][1];
;                         float r[8] = {a0[0], a0[1], a0[2], a0[3], a1[0], a1[1], a1[2], a1[3]};
;                         bf16_t* dst = O + row * ldc + col;
;     ...
;                         u32x4 w; w.x = cvt_pk_bf16(r[0], r[1]); w.y = cvt_pk_bf16(r[2], r[3]); w.z = cvt_pk_bf16(r[4], r[5]); w.w = cvt_pk_bf16(r[6], r[7]);
;                         *(u32x4*)dst = w;
.LBB0_1435:
	v_lshl_add_u32 v154, s26, 8, v1
	v_lshl_or_b32 v146, s63, 8, v149
	v_ashrrev_i32_e32 v155, 31, v154
	v_lshlrev_b64 v[156:157], 11, v[154:155]
	v_ashrrev_i32_e32 v147, 31, v146
	v_lshl_add_u64 v[156:157], s[6:7], 0, v[156:157]
	v_lshlrev_b64 v[158:159], 1, v[146:147]
	v_lshl_add_u64 v[146:147], v[156:157], 0, v[158:159]
	v_cvt_pk_bf16_f32 v126, v126, v127
	v_cvt_pk_bf16_f32 v127, v128, v129
	v_cvt_pk_bf16_f32 v128, v122, v123
	v_cvt_pk_bf16_f32 v129, v124, v125
	global_store_dwordx4 v[146:147], v[126:129], off
	v_cvt_pk_bf16_f32 v114, v114, v115
	v_cvt_pk_bf16_f32 v115, v116, v117
	v_cvt_pk_bf16_f32 v116, v106, v107
	v_or_b32_e32 v106, 16, v154
	v_ashrrev_i32_e32 v107, 31, v106
	v_lshlrev_b64 v[106:107], 11, v[106:107]
	v_lshl_add_u64 v[106:107], s[6:7], 0, v[106:107]
	v_cvt_pk_bf16_f32 v117, v108, v109
	global_store_dwordx4 v[146:147], v[114:117], off offset:256
	s_nop 1
	v_lshl_add_u64 v[114:115], v[106:107], 0, v[158:159]
	v_cvt_pk_bf16_f32 v106, v118, v119
	v_cvt_pk_bf16_f32 v107, v120, v121
	v_cvt_pk_bf16_f32 v108, v110, v111
	v_cvt_pk_bf16_f32 v109, v112, v113
	global_store_dwordx4 v[114:115], v[106:109], off
	v_cvt_pk_bf16_f32 v98, v98, v99
	v_cvt_pk_bf16_f32 v99, v100, v101
	v_cvt_pk_bf16_f32 v100, v90, v91
	v_or_b32_e32 v90, 32, v154
	v_ashrrev_i32_e32 v91, 31, v90
	v_lshlrev_b64 v[90:91], 11, v[90:91]
	v_lshl_add_u64 v[90:91], s[6:7], 0, v[90:91]
	v_cvt_pk_bf16_f32 v101, v92, v93
	global_store_dwordx4 v[114:115], v[98:101], off offset:256
	s_nop 1
	v_lshl_add_u64 v[98:99], v[90:91], 0, v[158:159]
	v_cvt_pk_bf16_f32 v90, v102, v103
	v_cvt_pk_bf16_f32 v91, v104, v105
	v_cvt_pk_bf16_f32 v92, v94, v95
	v_cvt_pk_bf16_f32 v93, v96, v97
	global_store_dwordx4 v[98:99], v[90:93], off
	v_cvt_pk_bf16_f32 v82, v82, v83
	v_cvt_pk_bf16_f32 v83, v84, v85
	v_cvt_pk_bf16_f32 v84, v74, v75
	v_or_b32_e32 v74, 48, v154
	v_ashrrev_i32_e32 v75, 31, v74
	v_lshlrev_b64 v[74:75], 11, v[74:75]
	v_lshl_add_u64 v[74:75], s[6:7], 0, v[74:75]
	v_cvt_pk_bf16_f32 v85, v76, v77
	global_store_dwordx4 v[98:99], v[82:85], off offset:256
	s_nop 1
	v_lshl_add_u64 v[82:83], v[74:75], 0, v[158:159]
	v_cvt_pk_bf16_f32 v74, v86, v87
	v_cvt_pk_bf16_f32 v75, v88, v89
	v_cvt_pk_bf16_f32 v76, v78, v79
	v_cvt_pk_bf16_f32 v77, v80, v81
	global_store_dwordx4 v[82:83], v[74:77], off
	v_cvt_pk_bf16_f32 v70, v70, v71
	v_cvt_pk_bf16_f32 v71, v72, v73
	v_cvt_pk_bf16_f32 v72, v66, v67
	v_cvt_pk_bf16_f32 v73, v68, v69
	global_store_dwordx4 v[82:83], v[70:73], off offset:256
	v_cvt_pk_bf16_f32 v62, v62, v63
	v_cvt_pk_bf16_f32 v63, v64, v65
	v_cvt_pk_bf16_f32 v64, v58, v59
	v_add_co_u32_e32 v58, vcc, s59, v146
	v_lshl_add_u64 v[66:67], v[146:147], 0, s[0:1]
	s_nop 0
	v_addc_co_u32_e32 v59, vcc, 0, v147, vcc
	v_cvt_pk_bf16_f32 v65, v60, v61
	global_store_dwordx4 v[58:59], v[62:65], off
	v_cvt_pk_bf16_f32 v50, v50, v51
	v_cvt_pk_bf16_f32 v51, v52, v53
	v_cvt_pk_bf16_f32 v52, v42, v43
	v_cvt_pk_bf16_f32 v53, v44, v45
	global_store_dwordx4 v[66:67], v[50:53], off offset:256
	v_cvt_pk_bf16_f32 v42, v54, v55
	v_cvt_pk_bf16_f32 v43, v56, v57
	v_cvt_pk_bf16_f32 v44, v46, v47
	v_add_co_u32_e32 v46, vcc, s60, v146
	s_nop 0
	v_lshl_add_u64 v[50:51], v[146:147], 0, s[12:13]
	v_addc_co_u32_e32 v47, vcc, 0, v147, vcc
	v_cvt_pk_bf16_f32 v45, v48, v49
	global_store_dwordx4 v[46:47], v[42:45], off
	v_cvt_pk_bf16_f32 v34, v34, v35
	v_cvt_pk_bf16_f32 v35, v36, v37
	v_cvt_pk_bf16_f32 v36, v26, v27
	v_cvt_pk_bf16_f32 v37, v28, v29
	global_store_dwordx4 v[50:51], v[34:37], off offset:256
	v_cvt_pk_bf16_f32 v26, v38, v39
	v_cvt_pk_bf16_f32 v27, v40, v41
	v_cvt_pk_bf16_f32 v28, v30, v31
	v_add_co_u32_e32 v30, vcc, s61, v146
	s_nop 0
	v_lshl_add_u64 v[34:35], v[146:147], 0, s[14:15]
	v_addc_co_u32_e32 v31, vcc, 0, v147, vcc
	v_cvt_pk_bf16_f32 v29, v32, v33
	global_store_dwordx4 v[30:31], v[26:29], off
	v_cvt_pk_bf16_f32 v18, v18, v19
	v_cvt_pk_bf16_f32 v19, v20, v21
	v_cvt_pk_bf16_f32 v20, v10, v11
	v_cvt_pk_bf16_f32 v21, v12, v13
	global_store_dwordx4 v[34:35], v[18:21], off offset:256
	v_cvt_pk_bf16_f32 v10, v22, v23
	v_cvt_pk_bf16_f32 v11, v24, v25
	v_cvt_pk_bf16_f32 v12, v14, v15
	v_add_co_u32_e32 v14, vcc, s62, v146
	s_nop 0
	v_lshl_add_u64 v[18:19], v[146:147], 0, s[16:17]
	v_addc_co_u32_e32 v15, vcc, 0, v147, vcc
	s_andn2_b64 vcc, exec, s[2:3]
	s_mov_b64 s[2:3], -1
	v_cvt_pk_bf16_f32 v13, v16, v17
	global_store_dwordx4 v[14:15], v[10:13], off
	v_cvt_pk_bf16_f32 v6, v6, v7
	v_cvt_pk_bf16_f32 v7, v8, v9
	v_cvt_pk_bf16_f32 v8, v2, v3
	v_cvt_pk_bf16_f32 v9, v4, v5
	global_store_dwordx4 v[18:19], v[6:9], off offset:256
	s_cbranch_vccnz .LBB0_1424
	s_andn2_b64 vcc, exec, s[4:5]
	s_cbranch_vccnz .LBB0_1423
	s_branch .LBB0_1423

; #define PG8_STAGE(bufoff, gbase, voff) do { _Pragma("unroll") for (int _i = 0; _i < 2; ++_i) \
;         __builtin_amdgcn_global_load_lds((const unsigned*)((const char*)(gbase) + (voff)[_i]), (PG8_LAS unsigned*)(lds + (bufoff) + ldsw + _i * 8192), 16, 0, 0); } while (0)
; #define PG8_LDA(dst, b, h) do { _Pragma("unroll") for (int m = 0; m < 4; ++m) _Pragma("unroll") for (int k = 0; k < 2; ++k) dst[m][k] = *(const PG8_LAS bf16x8*)(lds + PG8_SA(b, h) + aoff + m * 2048 + k * 1024); } while (0)
; #define PG8_LDB(dst, b, h) do { _Pragma("unroll") for (int n = 0; n < 2; ++n) _Pragma("unroll") for (int k = 0; k < 2; ++k) dst[n][k] = *(const PG8_LAS bf16x8*)(lds + PG8_SB(b, h) + boff + n * 2048 + k * 1024); } while (0)
; #define PG8_MMA(ai, bj, At, Bt) do { __builtin_amdgcn_s_setprio(1); _Pragma("unroll") for (int m = 0; m < 4; ++m) _Pragma("unroll") for (int n = 0; n < 2; ++n) _Pragma("unroll") for (int k = 0; k < 2; ++k) \
;         acc[ai][bj][m][n] = __builtin_amdgcn_mfma_f32_16x16x32_bf16(Bt[n][k], At[m][k], acc[ai][bj][m][n], 0, 0, 0); __builtin_amdgcn_s_setprio(0); } while (0)
; #define PG8_WAIT_V(n) asm volatile("s_waitcnt vmcnt(" #n ")" ::: "memory")
; template <class Epi, class Sched, bool ALIGN_EPI = false, bool SP2 = false>
; __device__ __forceinline__ void gemm_phase(PG8_LAS unsigned char* lds, const Gemm g, const Sched& S, const Epi& E) {
;     ...
;             PG8_LDB(B0, 0, 0); PG8_LDB(B1, 0, 1); PG8_SCHED; PG8_LDA(At, 0, 0); PG8_STAGE(PG8_SA(1, 1), a1 + hstep, voffA);
;             PG8_WAIT_V(8); PG8_WAIT_L(0); PG8_BAR; PG8_MMA(0, 0, At, B0); PG8_MMA(0, 1, At, B1); PG8_BAR; PG8_SCHED;
;             PG8_LDA(At, 0, 1); PG8_STAGE(PG8_SB(0, 0), b2, voffB); PG8_STAGE(PG8_SB(0, 1), b2 + hstep, voffB); PG8_STAGE(PG8_SA(0, 0), a2, voffA);
;             PG8_WAIT_V(8); PG8_WAIT_L(0); PG8_BAR; PG8_MMA(1, 0, At, B0); PG8_MMA(1, 1, At, B1); PG8_BAR; PG8_SCHED;
;             PG8_LDB(B0, 1, 0); PG8_LDB(B1, 1, 1); PG8_SCHED; PG8_LDA(At, 1, 0); PG8_STAGE(PG8_SA(0, 1), a2 + hstep, voffA);
;             PG8_WAIT_V(8); PG8_WAIT_L(0); PG8_BAR; PG8_MMA(0, 0, At, B0); PG8_MMA(0, 1, At, B1); PG8_BAR; PG8_SCHED;
;             PG8_LDA(At, 1, 1); PG8_STAGE(PG8_SB(1, 0), b3, voffB); PG8_STAGE(PG8_SB(1, 1), b3 + hstep, voffB); PG8_STAGE(PG8_SA(1, 0), a3, voffA);
;             PG8_WAIT_V(8); PG8_WAIT_L(0); PG8_BAR; PG8_MMA(1, 0, At, B0); PG8_MMA(1, 1, At, B1); PG8_BAR; PG8_SCHED;
.LBB0_1591:
	ds_read_b128 v[152:155], v149
	ds_read_b128 v[156:159], v149 offset:1024
	ds_read_b128 v[160:163], v149 offset:2048
	ds_read_b128 v[164:167], v149 offset:3072
	ds_read_b128 v[168:171], v150
	ds_read_b128 v[174:177], v150 offset:1024
	ds_read_b128 v[178:181], v150 offset:2048
	ds_read_b128 v[182:185], v150 offset:3072
	s_add_u32 s22, s20, 0xfffc0080
	s_addc_u32 s23, s21, -1
	s_cmp_eq_u32 s56, 12
	s_cselect_b32 s25, s13, s23
	s_cselect_b32 s24, s52, s22
	s_cselect_b32 s23, s11, s55
	s_cselect_b32 s22, s53, s54
	v_lshl_add_u64 v[218:219], s[20:21], 0, v[140:141]
	s_add_i32 m0, s34, 0xc000
	ds_read_b128 v[186:189], v151
	ds_read_b128 v[190:193], v151 offset:1024
	ds_read_b128 v[194:197], v151 offset:2048
	ds_read_b128 v[198:201], v151 offset:3072
	ds_read_b128 v[202:205], v151 offset:4096
	ds_read_b128 v[206:209], v151 offset:5120
	ds_read_b128 v[210:213], v151 offset:6144
	ds_read_b128 v[214:217], v151 offset:7168
	global_load_lds_dwordx4 v[218:219], off
	v_lshl_add_u64 v[218:219], s[20:21], 0, v[142:143]
	s_add_i32 m0, s34, 0xe000
	s_nop 0
	global_load_lds_dwordx4 v[218:219], off
	s_waitcnt vmcnt(8)
	s_waitcnt lgkmcnt(0)
	s_barrier
	s_waitcnt lgkmcnt(0)
	v_mfma_f32_16x16x32_bf16 v[126:129], v[152:155], v[186:189], v[126:129]
	v_mfma_f32_16x16x32_bf16 v[122:125], v[160:163], v[186:189], v[122:125]
	v_mfma_f32_16x16x32_bf16 v[110:113], v[152:155], v[194:197], v[110:113]
	v_mfma_f32_16x16x32_bf16 v[106:109], v[160:163], v[194:197], v[106:109]
	v_mfma_f32_16x16x32_bf16 v[94:97], v[152:155], v[202:205], v[94:97]
	v_mfma_f32_16x16x32_bf16 v[90:93], v[160:163], v[202:205], v[90:93]
	v_mfma_f32_16x16x32_bf16 v[78:81], v[152:155], v[210:213], v[78:81]
	v_mfma_f32_16x16x32_bf16 v[74:77], v[160:163], v[210:213], v[74:77]
	v_mfma_f32_16x16x32_bf16 v[126:129], v[156:159], v[190:193], v[126:129]
	v_mfma_f32_16x16x32_bf16 v[122:125], v[164:167], v[190:193], v[122:125]
	v_mfma_f32_16x16x32_bf16 v[110:113], v[156:159], v[198:201], v[110:113]
	v_mfma_f32_16x16x32_bf16 v[106:109], v[164:167], v[198:201], v[106:109]
	v_mfma_f32_16x16x32_bf16 v[94:97], v[156:159], v[206:209], v[94:97]
	v_mfma_f32_16x16x32_bf16 v[90:93], v[164:167], v[206:209], v[90:93]
	v_mfma_f32_16x16x32_bf16 v[78:81], v[156:159], v[214:217], v[78:81]
	v_mfma_f32_16x16x32_bf16 v[74:77], v[164:167], v[214:217], v[74:77]
	v_mfma_f32_16x16x32_bf16 v[118:121], v[168:171], v[186:189], v[118:121]
	v_mfma_f32_16x16x32_bf16 v[114:117], v[178:181], v[186:189], v[114:117]
	v_mfma_f32_16x16x32_bf16 v[102:105], v[168:171], v[194:197], v[102:105]
	v_mfma_f32_16x16x32_bf16 v[98:101], v[178:181], v[194:197], v[98:101]
	v_mfma_f32_16x16x32_bf16 v[86:89], v[168:171], v[202:205], v[86:89]
	v_mfma_f32_16x16x32_bf16 v[82:85], v[178:181], v[202:205], v[82:85]
	v_mfma_f32_16x16x32_bf16 v[70:73], v[168:171], v[210:213], v[70:73]
	v_mfma_f32_16x16x32_bf16 v[66:69], v[178:181], v[210:213], v[66:69]
	v_mfma_f32_16x16x32_bf16 v[118:121], v[174:177], v[190:193], v[118:121]
	v_mfma_f32_16x16x32_bf16 v[114:117], v[182:185], v[190:193], v[114:117]
	v_mfma_f32_16x16x32_bf16 v[102:105], v[174:177], v[198:201], v[102:105]
	v_mfma_f32_16x16x32_bf16 v[98:101], v[182:185], v[198:201], v[98:101]
	v_mfma_f32_16x16x32_bf16 v[86:89], v[174:177], v[206:209], v[86:89]
	v_mfma_f32_16x16x32_bf16 v[82:85], v[182:185], v[206:209], v[82:85]
	v_mfma_f32_16x16x32_bf16 v[70:73], v[174:177], v[214:217], v[70:73]
	v_mfma_f32_16x16x32_bf16 v[66:69], v[182:185], v[214:217], v[66:69]
	s_barrier
	s_add_i32 s57, s45, s30
	v_lshl_add_u64 v[218:219], s[22:23], 0, v[134:135]
	s_mov_b32 m0, s57
	ds_read_b128 v[186:189], v151 offset:16384
	ds_read_b128 v[190:193], v151 offset:17408
	ds_read_b128 v[194:197], v151 offset:18432
	ds_read_b128 v[198:201], v151 offset:19456
	ds_read_b128 v[202:205], v151 offset:20480
	ds_read_b128 v[206:209], v151 offset:21504
	ds_read_b128 v[210:213], v151 offset:22528
	ds_read_b128 v[214:217], v151 offset:23552
	global_load_lds_dwordx4 v[218:219], off
	s_add_i32 m0, s57, 0x2000
	s_add_u32 s58, s22, 0x40000
	v_lshl_add_u64 v[220:221], s[22:23], 0, v[130:131]
	s_addc_u32 s59, s23, 0
	s_add_i32 s57, s48, s30
	global_load_lds_dwordx4 v[220:221], off
	v_lshl_add_u64 v[222:223], s[58:59], 0, v[134:135]
	s_mov_b32 m0, s57
	v_lshl_add_u64 v[224:225], s[24:25], 0, v[132:133]
	global_load_lds_dwordx4 v[222:223], off
	v_lshl_add_u64 v[222:223], s[58:59], 0, v[130:131]
	s_add_i32 m0, s57, 0x2000
	s_nop 0
	global_load_lds_dwordx4 v[222:223], off
	v_lshl_add_u64 v[222:223], s[24:25], 0, v[136:137]
	s_mov_b32 m0, s34
	s_nop 0
	global_load_lds_dwordx4 v[222:223], off
	s_mov_b32 m0, s35
	s_nop 0
	global_load_lds_dwordx4 v[224:225], off
	s_waitcnt vmcnt(8)
	s_waitcnt lgkmcnt(0)
	s_barrier
; #define PG8_STAGE(bufoff, gbase, voff) do { _Pragma("unroll") for (int _i = 0; _i < 2; ++_i) \
;         __builtin_amdgcn_global_load_lds((const unsigned*)((const char*)(gbase) + (voff)[_i]), (PG8_LAS unsigned*)(lds + (bufoff) + ldsw + _i * 8192), 16, 0, 0); } while (0)
; #define PG8_LDA(dst, b, h) do { _Pragma("unroll") for (int m = 0; m < 4; ++m) _Pragma("unroll") for (int k = 0; k < 2; ++k) dst[m][k] = *(const PG8_LAS bf16x8*)(lds + PG8_SA(b, h) + aoff + m * 2048 + k * 1024); } while (0)
; #define PG8_LDB(dst, b, h) do { _Pragma("unroll") for (int n = 0; n < 2; ++n) _Pragma("unroll") for (int k = 0; k < 2; ++k) dst[n][k] = *(const PG8_LAS bf16x8*)(lds + PG8_SB(b, h) + boff + n * 2048 + k * 1024); } while (0)
; #define PG8_MMA(ai, bj, At, Bt) do { __builtin_amdgcn_s_setprio(1); _Pragma("unroll") for (int m = 0; m < 4; ++m) _Pragma("unroll") for (int n = 0; n < 2; ++n) _Pragma("unroll") for (int k = 0; k < 2; ++k) \
;         acc[ai][bj][m][n] = __builtin_amdgcn_mfma_f32_16x16x32_bf16(Bt[n][k], At[m][k], acc[ai][bj][m][n], 0, 0, 0); __builtin_amdgcn_s_setprio(0); } while (0)
; #define PG8_WAIT_V(n) asm volatile("s_waitcnt vmcnt(" #n ")" ::: "memory")
; template <class Epi, class Sched, bool ALIGN_EPI = false, bool SP2 = false>
; __device__ __forceinline__ void gemm_phase(PG8_LAS unsigned char* lds, const Gemm g, const Sched& S, const Epi& E) {
;     ...
;             PG8_LDB(B0, 0, 0); PG8_LDB(B1, 0, 1); PG8_SCHED; PG8_LDA(At, 0, 0); PG8_STAGE(PG8_SA(1, 1), a1 + hstep, voffA);
;             PG8_WAIT_V(8); PG8_WAIT_L(0); PG8_BAR; PG8_MMA(0, 0, At, B0); PG8_MMA(0, 1, At, B1); PG8_BAR; PG8_SCHED;
;             PG8_LDA(At, 0, 1); PG8_STAGE(PG8_SB(0, 0), b2, voffB); PG8_STAGE(PG8_SB(0, 1), b2 + hstep, voffB); PG8_STAGE(PG8_SA(0, 0), a2, voffA);
;             PG8_WAIT_V(8); PG8_WAIT_L(0); PG8_BAR; PG8_MMA(1, 0, At, B0); PG8_MMA(1, 1, At, B1); PG8_BAR; PG8_SCHED;
;             PG8_LDB(B0, 1, 0); PG8_LDB(B1, 1, 1); PG8_SCHED; PG8_LDA(At, 1, 0); PG8_STAGE(PG8_SA(0, 1), a2 + hstep, voffA);
;             PG8_WAIT_V(8); PG8_WAIT_L(0); PG8_BAR; PG8_MMA(0, 0, At, B0); PG8_MMA(0, 1, At, B1); PG8_BAR; PG8_SCHED;
;             PG8_LDA(At, 1, 1); PG8_STAGE(PG8_SB(1, 0), b3, voffB); PG8_STAGE(PG8_SB(1, 1), b3 + hstep, voffB); PG8_STAGE(PG8_SA(1, 0), a3, voffA);
;             PG8_WAIT_V(8); PG8_WAIT_L(0); PG8_BAR; PG8_MMA(1, 0, At, B0); PG8_MMA(1, 1, At, B1); PG8_BAR; PG8_SCHED;
	s_waitcnt lgkmcnt(0)
	v_mfma_f32_16x16x32_bf16 v[62:65], v[152:155], v[186:189], v[62:65]
	v_mfma_f32_16x16x32_bf16 v[58:61], v[160:163], v[186:189], v[58:61]
	v_mfma_f32_16x16x32_bf16 v[46:49], v[152:155], v[194:197], v[46:49]
	v_mfma_f32_16x16x32_bf16 v[42:45], v[160:163], v[194:197], v[42:45]
	v_mfma_f32_16x16x32_bf16 v[30:33], v[152:155], v[202:205], v[30:33]
	v_mfma_f32_16x16x32_bf16 v[26:29], v[160:163], v[202:205], v[26:29]
	v_mfma_f32_16x16x32_bf16 v[14:17], v[152:155], v[210:213], v[14:17]
	v_mfma_f32_16x16x32_bf16 v[10:13], v[160:163], v[210:213], v[10:13]
	v_mfma_f32_16x16x32_bf16 v[62:65], v[156:159], v[190:193], v[62:65]
	v_mfma_f32_16x16x32_bf16 v[58:61], v[164:167], v[190:193], v[58:61]
	v_mfma_f32_16x16x32_bf16 v[46:49], v[156:159], v[198:201], v[46:49]
	v_mfma_f32_16x16x32_bf16 v[42:45], v[164:167], v[198:201], v[42:45]
	v_mfma_f32_16x16x32_bf16 v[30:33], v[156:159], v[206:209], v[30:33]
	v_mfma_f32_16x16x32_bf16 v[26:29], v[164:167], v[206:209], v[26:29]
	v_mfma_f32_16x16x32_bf16 v[14:17], v[156:159], v[214:217], v[14:17]
	v_mfma_f32_16x16x32_bf16 v[10:13], v[164:167], v[214:217], v[10:13]
	v_mfma_f32_16x16x32_bf16 v[54:57], v[168:171], v[186:189], v[54:57]
	v_mfma_f32_16x16x32_bf16 v[50:53], v[178:181], v[186:189], v[50:53]
	v_mfma_f32_16x16x32_bf16 v[38:41], v[168:171], v[194:197], v[38:41]
	v_mfma_f32_16x16x32_bf16 v[34:37], v[178:181], v[194:197], v[34:37]
	v_mfma_f32_16x16x32_bf16 v[22:25], v[168:171], v[202:205], v[22:25]
	v_mfma_f32_16x16x32_bf16 v[18:21], v[178:181], v[202:205], v[18:21]
	v_mfma_f32_16x16x32_bf16 v[6:9], v[168:171], v[210:213], v[6:9]
	v_mfma_f32_16x16x32_bf16 v[2:5], v[178:181], v[210:213], v[2:5]
	v_mfma_f32_16x16x32_bf16 v[54:57], v[174:177], v[190:193], v[54:57]
	v_mfma_f32_16x16x32_bf16 v[50:53], v[182:185], v[190:193], v[50:53]
	v_mfma_f32_16x16x32_bf16 v[38:41], v[174:177], v[198:201], v[38:41]
	v_mfma_f32_16x16x32_bf16 v[34:37], v[182:185], v[198:201], v[34:37]
	v_mfma_f32_16x16x32_bf16 v[22:25], v[174:177], v[206:209], v[22:25]
	v_mfma_f32_16x16x32_bf16 v[18:21], v[182:185], v[206:209], v[18:21]
	v_mfma_f32_16x16x32_bf16 v[6:9], v[174:177], v[214:217], v[6:9]
	v_mfma_f32_16x16x32_bf16 v[2:5], v[182:185], v[214:217], v[2:5]
	s_barrier
	s_add_i32 s57, 0, 0x18000
	s_add_i32 s58, 0, 0x1c000
	v_add_u32_e32 v164, s57, v148
	v_add_u32_e32 v182, s58, v148
	ds_read_b128 v[152:155], v164
	ds_read_b128 v[156:159], v164 offset:1024
	ds_read_b128 v[160:163], v164 offset:2048
	ds_read_b128 v[164:167], v164 offset:3072
	ds_read_b128 v[168:171], v182
	ds_read_b128 v[174:177], v182 offset:1024
	ds_read_b128 v[178:181], v182 offset:2048
	ds_read_b128 v[182:185], v182 offset:3072
	s_add_u32 s24, s24, 0x40000
	s_addc_u32 s25, s25, 0
	s_mov_b32 m0, s38
	v_lshl_add_u64 v[226:227], s[24:25], 0, v[136:137]
	ds_read_b128 v[186:189], v151 offset:32768
	ds_read_b128 v[190:193], v151 offset:33792
	ds_read_b128 v[194:197], v151 offset:34816
	ds_read_b128 v[198:201], v151 offset:35840
	ds_read_b128 v[202:205], v151 offset:36864
	ds_read_b128 v[206:209], v151 offset:37888
	ds_read_b128 v[210:213], v151 offset:38912
	ds_read_b128 v[214:217], v151 offset:39936
	global_load_lds_dwordx4 v[226:227], off
	v_lshl_add_u64 v[226:227], s[24:25], 0, v[132:133]
	s_mov_b32 m0, s39
	s_nop 0
	global_load_lds_dwordx4 v[226:227], off
	s_waitcnt vmcnt(8)
	s_waitcnt lgkmcnt(0)
	s_barrier
	s_waitcnt lgkmcnt(0)
	v_mfma_f32_16x16x32_bf16 v[126:129], v[152:155], v[186:189], v[126:129]
	v_mfma_f32_16x16x32_bf16 v[122:125], v[160:163], v[186:189], v[122:125]
	v_mfma_f32_16x16x32_bf16 v[110:113], v[152:155], v[194:197], v[110:113]
	v_mfma_f32_16x16x32_bf16 v[106:109], v[160:163], v[194:197], v[106:109]
	v_mfma_f32_16x16x32_bf16 v[94:97], v[152:155], v[202:205], v[94:97]
	v_mfma_f32_16x16x32_bf16 v[90:93], v[160:163], v[202:205], v[90:93]
	v_mfma_f32_16x16x32_bf16 v[78:81], v[152:155], v[210:213], v[78:81]
	v_mfma_f32_16x16x32_bf16 v[74:77], v[160:163], v[210:213], v[74:77]
	v_mfma_f32_16x16x32_bf16 v[126:129], v[156:159], v[190:193], v[126:129]
	v_mfma_f32_16x16x32_bf16 v[122:125], v[164:167], v[190:193], v[122:125]
	v_mfma_f32_16x16x32_bf16 v[110:113], v[156:159], v[198:201], v[110:113]
	v_mfma_f32_16x16x32_bf16 v[106:109], v[164:167], v[198:201], v[106:109]
	v_mfma_f32_16x16x32_bf16 v[94:97], v[156:159], v[206:209], v[94:97]
	v_mfma_f32_16x16x32_bf16 v[90:93], v[164:167], v[206:209], v[90:93]
	v_mfma_f32_16x16x32_bf16 v[78:81], v[156:159], v[214:217], v[78:81]
	v_mfma_f32_16x16x32_bf16 v[74:77], v[164:167], v[214:217], v[74:77]
	v_mfma_f32_16x16x32_bf16 v[118:121], v[168:171], v[186:189], v[118:121]
	v_mfma_f32_16x16x32_bf16 v[114:117], v[178:181], v[186:189], v[114:117]
	v_mfma_f32_16x16x32_bf16 v[102:105], v[168:171], v[194:197], v[102:105]
	v_mfma_f32_16x16x32_bf16 v[98:101], v[178:181], v[194:197], v[98:101]
	v_mfma_f32_16x16x32_bf16 v[86:89], v[168:171], v[202:205], v[86:89]
	v_mfma_f32_16x16x32_bf16 v[82:85], v[178:181], v[202:205], v[82:85]
	v_mfma_f32_16x16x32_bf16 v[70:73], v[168:171], v[210:213], v[70:73]
	v_mfma_f32_16x16x32_bf16 v[66:69], v[178:181], v[210:213], v[66:69]
	v_mfma_f32_16x16x32_bf16 v[118:121], v[174:177], v[190:193], v[118:121]
	v_mfma_f32_16x16x32_bf16 v[114:117], v[182:185], v[190:193], v[114:117]
	v_mfma_f32_16x16x32_bf16 v[102:105], v[174:177], v[198:201], v[102:105]
	v_mfma_f32_16x16x32_bf16 v[98:101], v[182:185], v[198:201], v[98:101]
	v_mfma_f32_16x16x32_bf16 v[86:89], v[174:177], v[206:209], v[86:89]
	v_mfma_f32_16x16x32_bf16 v[82:85], v[182:185], v[206:209], v[82:85]
	v_mfma_f32_16x16x32_bf16 v[70:73], v[174:177], v[214:217], v[70:73]
	v_mfma_f32_16x16x32_bf16 v[66:69], v[182:185], v[214:217], v[66:69]
	s_barrier
; #define PG8_WAIT_V(n) asm volatile("s_waitcnt vmcnt(" #n ")" ::: "memory")
; template <class Epi, class Sched, bool ALIGN_EPI = false, bool SP2 = false>
; __device__ __forceinline__ void gemm_phase(PG8_LAS unsigned char* lds, const Gemm g, const Sched& S, const Epi& E) {
;     ...
;             PG8_WAIT_V(8); PG8_WAIT_L(0); PG8_BAR; PG8_MMA(0, 0, At, B0); PG8_MMA(0, 1, At, B1); PG8_BAR; PG8_SCHED;
;             PG8_LDA(At, 1, 1); PG8_STAGE(PG8_SB(1, 0), b3, voffB); PG8_STAGE(PG8_SB(1, 1), b3 + hstep, voffB); PG8_STAGE(PG8_SA(1, 0), a3, voffA);
;             PG8_WAIT_V(8); PG8_WAIT_L(0); PG8_BAR; PG8_MMA(1, 0, At, B0); PG8_MMA(1, 1, At, B1); PG8_BAR; PG8_SCHED;
;             } else {
;             PG8_LDB(B0, 0, 0); PG8_SCHED; PG8_LDA(At, 0, 0); PG8_STAGE(PG8_SA(1, 1), a1 + hstep, voffA);
;             PG8_WAIT_L(8); PG8_BAR; PG8_WAIT_L(0); PG8_MMA(0, 0, At, B0); PG8_BAR; PG8_SCHED;
;             PG8_LDB(B1, 0, 1); PG8_STAGE(PG8_SB(0, 0), b2, voffB);
;             PG8_BAR; PG8_WAIT_L(0); PG8_MMA(0, 1, At, B1); PG8_BAR;
;             PG8_LDA(At, 0, 1); PG8_STAGE(PG8_SA(0, 0), a2, voffA);
;             PG8_BAR; PG8_WAIT_L(0); PG8_MMA(1, 0, At, B0); PG8_BAR; PG8_SCHED;
;             PG8_STAGE(PG8_SB(0, 1), b2 + hstep, voffB);
;             PG8_WAIT_V(6); PG8_BAR; PG8_MMA(1, 1, At, B1); PG8_BAR;
;             PG8_LDB(B0, 1, 0); PG8_SCHED; PG8_LDA(At, 1, 0); PG8_STAGE(PG8_SA(0, 1), a2 + hstep, voffA);
;             PG8_WAIT_L(8); PG8_BAR; PG8_WAIT_L(0); PG8_MMA(0, 0, At, B0); PG8_BAR; PG8_SCHED;
;             PG8_LDB(B1, 1, 1); PG8_STAGE(PG8_SB(1, 0), b3, voffB);
;             PG8_BAR; PG8_WAIT_L(0); PG8_MMA(0, 1, At, B1); PG8_BAR;
;             PG8_LDA(At, 1, 1); PG8_STAGE(PG8_SA(1, 0), a3, voffA);
;             PG8_BAR; PG8_WAIT_L(0); PG8_MMA(1, 0, At, B0); PG8_BAR; PG8_SCHED;
;             PG8_STAGE(PG8_SB(1, 1), b3 + hstep, voffB);
;             PG8_WAIT_V(6); PG8_BAR; PG8_MMA(1, 1, At, B1); PG8_BAR;
;             }
;         }
;         if constexpr (ALIGN_EPI) { if (wr == 0) PG8_BAR; }
;     __device__ __forceinline__ void operator()(const f32x4 (&acc)[2][2][4][2], const pg8::Unit& u, int wr, int wc, int fr, int fq) const {
;     ...
;                 if constexpr (MODE == EP_SWIGLU) {
;                     const f32x4 g0 = acc[ai][0][m][0], g1 = acc[ai][0][m][1], u0 = acc[ai][1][m][0], u1 = acc[ai][1][m][1];
;                     float r[8];
; #pragma unroll
	s_add_i32 s24, s57, s30
	v_lshl_add_u64 v[218:219], v[218:219], 0, s[6:7]
	s_mov_b32 m0, s24
	ds_read_b128 v[186:189], v151 offset:49152
	ds_read_b128 v[190:193], v151 offset:50176
	ds_read_b128 v[194:197], v151 offset:51200
	ds_read_b128 v[198:201], v151 offset:52224
	ds_read_b128 v[202:205], v151 offset:53248
	ds_read_b128 v[206:209], v151 offset:54272
	ds_read_b128 v[210:213], v151 offset:55296
	ds_read_b128 v[214:217], v151 offset:56320
	global_load_lds_dwordx4 v[218:219], off
	s_add_i32 m0, s24, 0x2000
	s_add_u32 s22, s22, 0x40080
	v_lshl_add_u64 v[218:219], v[220:221], 0, s[6:7]
	s_addc_u32 s23, s23, 0
	s_add_i32 s24, s58, s30
	global_load_lds_dwordx4 v[218:219], off
	v_lshl_add_u64 v[218:219], s[22:23], 0, v[134:135]
	s_mov_b32 m0, s24
	s_nop 0
	global_load_lds_dwordx4 v[218:219], off
	v_lshl_add_u64 v[218:219], s[22:23], 0, v[130:131]
	s_add_i32 m0, s24, 0x2000
	s_nop 0
	global_load_lds_dwordx4 v[218:219], off
	v_lshl_add_u64 v[218:219], v[222:223], 0, s[6:7]
	s_mov_b32 m0, s41
	s_nop 0
	global_load_lds_dwordx4 v[218:219], off
	v_lshl_add_u64 v[218:219], v[224:225], 0, s[6:7]
	s_mov_b32 m0, s42
	s_nop 0
	global_load_lds_dwordx4 v[218:219], off
	s_waitcnt vmcnt(8)
	s_waitcnt lgkmcnt(0)
	s_barrier
	s_waitcnt lgkmcnt(0)
	v_mfma_f32_16x16x32_bf16 v[62:65], v[152:155], v[186:189], v[62:65]
	v_mfma_f32_16x16x32_bf16 v[58:61], v[160:163], v[186:189], v[58:61]
	v_mfma_f32_16x16x32_bf16 v[46:49], v[152:155], v[194:197], v[46:49]
	v_mfma_f32_16x16x32_bf16 v[42:45], v[160:163], v[194:197], v[42:45]
	v_mfma_f32_16x16x32_bf16 v[30:33], v[152:155], v[202:205], v[30:33]
	v_mfma_f32_16x16x32_bf16 v[26:29], v[160:163], v[202:205], v[26:29]
	v_mfma_f32_16x16x32_bf16 v[14:17], v[152:155], v[210:213], v[14:17]
	v_mfma_f32_16x16x32_bf16 v[10:13], v[160:163], v[210:213], v[10:13]
	v_mfma_f32_16x16x32_bf16 v[62:65], v[156:159], v[190:193], v[62:65]
	v_mfma_f32_16x16x32_bf16 v[58:61], v[164:167], v[190:193], v[58:61]
	v_mfma_f32_16x16x32_bf16 v[46:49], v[156:159], v[198:201], v[46:49]
	v_mfma_f32_16x16x32_bf16 v[42:45], v[164:167], v[198:201], v[42:45]
	v_mfma_f32_16x16x32_bf16 v[30:33], v[156:159], v[206:209], v[30:33]
	v_mfma_f32_16x16x32_bf16 v[26:29], v[164:167], v[206:209], v[26:29]
	v_mfma_f32_16x16x32_bf16 v[14:17], v[156:159], v[214:217], v[14:17]
	v_mfma_f32_16x16x32_bf16 v[10:13], v[164:167], v[214:217], v[10:13]
	v_mfma_f32_16x16x32_bf16 v[54:57], v[168:171], v[186:189], v[54:57]
	v_mfma_f32_16x16x32_bf16 v[50:53], v[178:181], v[186:189], v[50:53]
	v_mfma_f32_16x16x32_bf16 v[38:41], v[168:171], v[194:197], v[38:41]
	v_mfma_f32_16x16x32_bf16 v[34:37], v[178:181], v[194:197], v[34:37]
	v_mfma_f32_16x16x32_bf16 v[22:25], v[168:171], v[202:205], v[22:25]
	v_mfma_f32_16x16x32_bf16 v[18:21], v[178:181], v[202:205], v[18:21]
	v_mfma_f32_16x16x32_bf16 v[6:9], v[168:171], v[210:213], v[6:9]
	v_mfma_f32_16x16x32_bf16 v[2:5], v[178:181], v[210:213], v[2:5]
	v_mfma_f32_16x16x32_bf16 v[54:57], v[174:177], v[190:193], v[54:57]
	v_mfma_f32_16x16x32_bf16 v[50:53], v[182:185], v[190:193], v[50:53]
	v_mfma_f32_16x16x32_bf16 v[38:41], v[174:177], v[198:201], v[38:41]
	v_mfma_f32_16x16x32_bf16 v[34:37], v[182:185], v[198:201], v[34:37]
	v_mfma_f32_16x16x32_bf16 v[22:25], v[174:177], v[206:209], v[22:25]
	v_mfma_f32_16x16x32_bf16 v[18:21], v[182:185], v[206:209], v[18:21]
	v_mfma_f32_16x16x32_bf16 v[6:9], v[174:177], v[214:217], v[6:9]
	v_mfma_f32_16x16x32_bf16 v[2:5], v[182:185], v[214:217], v[2:5]
	s_barrier
	s_add_i32 s56, s56, 2
	s_add_u32 s20, s20, 0x100
	s_addc_u32 s21, s21, 0
	s_add_u32 s54, s54, 0x100
	s_addc_u32 s55, s55, 0
	s_cmp_gt_u32 s56, 13
	s_cbranch_scc0 .LBB0_1591
	s_andn2_b64 vcc, s[8:9], s[2:3]
	s_cbranch_vccz .LBB0_1594
	s_barrier
.LBB0_1594:
	v_mul_f32_e32 v153, 0xbfb8aa3b, v126
	v_exp_f32_e32 v153, v153
	v_mul_f32_e32 v154, 0xbfb8aa3b, v122
	v_exp_f32_e32 v154, v154
	v_lshl_add_u32 v152, s18, 8, v1
	v_add_f32_e32 v153, 1.0, v153
	v_rcp_f32_e32 v153, v153
	v_add_f32_e32 v154, 1.0, v154
	v_rcp_f32_e32 v154, v154
	s_lshl_b32 s18, s19, 7
	v_mul_f32_e32 v126, v126, v153
	v_mul_f32_e32 v118, v126, v118
	v_mul_f32_e32 v126, 0xbfb8aa3b, v127
	v_exp_f32_e32 v126, v126
	v_mul_f32_e32 v153, 0xbfb8aa3b, v123
	v_exp_f32_e32 v153, v153
	v_mul_f32_e32 v122, v122, v154
	v_mul_f32_e32 v114, v122, v114
	v_add_f32_e32 v122, 1.0, v126
	v_rcp_f32_e32 v122, v122
	v_add_f32_e32 v126, 1.0, v153
	v_mul_f32_e32 v153, 0xbfb8aa3b, v128
	v_rcp_f32_e32 v126, v126
	v_exp_f32_e32 v153, v153
	v_mul_f32_e32 v122, v127, v122
	v_mul_f32_e32 v119, v122, v119
	v_mul_f32_e32 v122, v123, v126
	v_add_f32_e32 v123, 1.0, v153
	v_rcp_f32_e32 v123, v123
	v_mul_f32_e32 v126, 0xbfb8aa3b, v124
	v_exp_f32_e32 v126, v126
	v_mul_f32_e32 v115, v122, v115
	v_mul_f32_e32 v122, v128, v123
	v_mul_f32_e32 v123, 0xbfb8aa3b, v129
	v_mul_f32_e32 v120, v122, v120
	v_add_f32_e32 v122, 1.0, v126
	v_exp_f32_e32 v123, v123
	v_mul_f32_e32 v126, 0xbfb8aa3b, v125
	v_rcp_f32_e32 v122, v122
	v_exp_f32_e32 v126, v126
	v_add_f32_e32 v123, 1.0, v123
	v_rcp_f32_e32 v123, v123
	v_mul_f32_e32 v122, v124, v122
	v_add_f32_e32 v124, 1.0, v126
	v_rcp_f32_e32 v124, v124
	v_mul_f32_e32 v122, v122, v116
	v_mul_f32_e32 v116, v129, v123
	v_mul_f32_e32 v121, v116, v121
	v_mul_f32_e32 v116, v125, v124
	v_mul_f32_e32 v123, v116, v117
	v_cvt_pk_bf16_f32 v116, v118, v119
	v_cvt_pk_bf16_f32 v117, v120, v121
	v_cvt_pk_bf16_f32 v118, v114, v115
	v_cvt_pk_bf16_f32 v119, v122, v123
	v_mul_f32_e32 v122, 0xbfb8aa3b, v110
	s_ashr_i32 s19, s18, 31
	v_mov_b64_e32 v[114:115], s[4:5]
	v_exp_f32_e32 v122, v122
	v_mad_i64_i32 v[120:121], s[20:21], v152, s49, v[114:115]
	s_lshl_b64 s[18:19], s[18:19], 1
	v_lshl_add_u64 v[120:121], v[120:121], 0, s[18:19]
; __device__ __forceinline__ unsigned cvt_pk_bf16(float lo, float hi) { unsigned r; asm volatile("v_cvt_pk_bf16_f32 %0, %1, %2" : "=v"(r) : "v"(lo), "v"(hi)); return r; }
; __device__ __forceinline__ float sigmoidf_(float x) { return __builtin_amdgcn_rcpf(1.0f + __expf(-x)); }
;     __device__ __forceinline__ void operator()(const f32x4 (&acc)[2][2][4][2], const pg8::Unit& u, int wr, int wc, int fr, int fq) const {
;     ...
;                 if constexpr (MODE == EP_SWIGLU) {
;                     const f32x4 g0 = acc[ai][0][m][0], g1 = acc[ai][0][m][1], u0 = acc[ai][1][m][0], u1 = acc[ai][1][m][1];
;                     float r[8];
; #pragma unroll
;                     for (int j = 0; j < 4; ++j) { r[j] = g0[j] * sigmoidf_(g0[j]) * u0[j]; r[4 + j] = g1[j] * sigmoidf_(g1[j]) * u1[j]; }
;                     u32x4 w; w.x = cvt_pk_bf16(r[0], r[1]); w.y = cvt_pk_bf16(r[2], r[3]); w.z = cvt_pk_bf16(r[4], r[5]); w.w = cvt_pk_bf16(r[6], r[7]);
;                     *(u32x4*)(O + row * ldc + u.pn * 128 + cin) = w;
	v_lshl_add_u64 v[120:121], v[120:121], 0, v[138:139]
	v_mul_f32_e32 v123, 0xbfb8aa3b, v106
	global_store_dwordx4 v[120:121], v[116:119], off
	v_exp_f32_e32 v123, v123
	s_andn2_b64 vcc, exec, s[2:3]
	v_add_f32_e32 v116, 1.0, v122
	v_rcp_f32_e32 v116, v116
	v_add_f32_e32 v117, 1.0, v123
	v_rcp_f32_e32 v117, v117
	v_or_b32_e32 v118, 16, v152
	v_mul_f32_e32 v110, v110, v116
	v_mul_f32_e32 v102, v110, v102
	v_mul_f32_e32 v110, 0xbfb8aa3b, v111
	v_exp_f32_e32 v110, v110
	v_mul_f32_e32 v116, 0xbfb8aa3b, v107
	v_exp_f32_e32 v116, v116
	v_mul_f32_e32 v106, v106, v117
	v_mul_f32_e32 v106, v106, v98
	v_add_f32_e32 v98, 1.0, v110
	v_rcp_f32_e32 v98, v98
	v_add_f32_e32 v110, 1.0, v116
	v_mul_f32_e32 v116, 0xbfb8aa3b, v112
	v_rcp_f32_e32 v110, v110
	v_exp_f32_e32 v116, v116
	v_mul_f32_e32 v98, v111, v98
	v_mul_f32_e32 v98, v98, v103
	v_mul_f32_e32 v103, v107, v110
	v_add_f32_e32 v107, 1.0, v116
	v_rcp_f32_e32 v107, v107
	v_mul_f32_e32 v110, 0xbfb8aa3b, v108
	v_exp_f32_e32 v110, v110
	v_mul_f32_e32 v103, v103, v99
	v_mul_f32_e32 v99, v112, v107
	v_mul_f32_e32 v107, 0xbfb8aa3b, v113
	v_mul_f32_e32 v99, v99, v104
	v_add_f32_e32 v104, 1.0, v110
	v_exp_f32_e32 v107, v107
	v_mul_f32_e32 v110, 0xbfb8aa3b, v109
	v_rcp_f32_e32 v104, v104
	v_exp_f32_e32 v110, v110
	v_add_f32_e32 v107, 1.0, v107
	v_rcp_f32_e32 v107, v107
	v_mul_f32_e32 v104, v108, v104
	v_add_f32_e32 v108, 1.0, v110
	v_rcp_f32_e32 v108, v108
	v_mul_f32_e32 v104, v104, v100
	v_mul_f32_e32 v100, v113, v107
	v_mul_f32_e32 v100, v100, v105
	v_mul_f32_e32 v105, v109, v108
	v_mul_f32_e32 v101, v105, v101
	v_cvt_pk_bf16_f32 v98, v102, v98
	v_cvt_pk_bf16_f32 v99, v99, v100
	v_cvt_pk_bf16_f32 v100, v106, v103
	v_cvt_pk_bf16_f32 v101, v104, v101
	v_mul_f32_e32 v104, 0xbfb8aa3b, v94
	v_exp_f32_e32 v104, v104
	v_mad_i64_i32 v[102:103], s[20:21], v118, s49, v[114:115]
	v_lshl_add_u64 v[102:103], v[102:103], 0, s[18:19]
	v_lshl_add_u64 v[102:103], v[102:103], 0, v[138:139]
	v_mul_f32_e32 v105, 0xbfb8aa3b, v90
	global_store_dwordx4 v[102:103], v[98:101], off
	v_exp_f32_e32 v105, v105
	s_mov_b64 s[2:3], -1
	v_add_f32_e32 v98, 1.0, v104
	v_rcp_f32_e32 v98, v98
	v_add_f32_e32 v99, 1.0, v105
	v_rcp_f32_e32 v99, v99
	v_or_b32_e32 v100, 32, v152
	v_mul_f32_e32 v94, v94, v98
	v_mul_f32_e32 v86, v94, v86
	v_mul_f32_e32 v94, 0xbfb8aa3b, v95
	v_exp_f32_e32 v94, v94
	v_mul_f32_e32 v98, 0xbfb8aa3b, v91
	v_exp_f32_e32 v98, v98
	v_mul_f32_e32 v90, v90, v99
	v_mul_f32_e32 v90, v90, v82
	v_add_f32_e32 v82, 1.0, v94
	v_rcp_f32_e32 v82, v82
	v_add_f32_e32 v94, 1.0, v98
	v_mul_f32_e32 v98, 0xbfb8aa3b, v96
	v_rcp_f32_e32 v94, v94
	v_exp_f32_e32 v98, v98
	v_mul_f32_e32 v82, v95, v82
	v_mul_f32_e32 v82, v82, v87
	v_mul_f32_e32 v87, v91, v94
	v_add_f32_e32 v91, 1.0, v98
	v_rcp_f32_e32 v91, v91
	v_mul_f32_e32 v94, 0xbfb8aa3b, v92
	v_exp_f32_e32 v94, v94
	v_mul_f32_e32 v87, v87, v83
	v_mul_f32_e32 v83, v96, v91
	v_mul_f32_e32 v91, 0xbfb8aa3b, v97
	v_mul_f32_e32 v83, v83, v88
	v_add_f32_e32 v88, 1.0, v94
	v_exp_f32_e32 v91, v91
	v_mul_f32_e32 v94, 0xbfb8aa3b, v93
	v_rcp_f32_e32 v88, v88
	v_exp_f32_e32 v94, v94
	v_add_f32_e32 v91, 1.0, v91
	v_rcp_f32_e32 v91, v91
	v_mul_f32_e32 v88, v92, v88
	v_add_f32_e32 v92, 1.0, v94
	v_rcp_f32_e32 v92, v92
	v_mul_f32_e32 v88, v88, v84
	v_mul_f32_e32 v84, v97, v91
	v_mul_f32_e32 v84, v84, v89
	v_mul_f32_e32 v89, v93, v92
	v_mul_f32_e32 v85, v89, v85
	v_cvt_pk_bf16_f32 v82, v86, v82
	v_cvt_pk_bf16_f32 v83, v83, v84
	v_cvt_pk_bf16_f32 v84, v90, v87
	v_cvt_pk_bf16_f32 v85, v88, v85
	v_mul_f32_e32 v88, 0xbfb8aa3b, v78
	v_exp_f32_e32 v88, v88
	v_mad_i64_i32 v[86:87], s[20:21], v100, s49, v[114:115]
	v_lshl_add_u64 v[86:87], v[86:87], 0, s[18:19]
	v_lshl_add_u64 v[86:87], v[86:87], 0, v[138:139]
	v_mul_f32_e32 v89, 0xbfb8aa3b, v74
	global_store_dwordx4 v[86:87], v[82:85], off
	v_exp_f32_e32 v89, v89
	s_nop 0
	v_add_f32_e32 v82, 1.0, v88
	v_rcp_f32_e32 v82, v82
	v_add_f32_e32 v83, 1.0, v89
	v_rcp_f32_e32 v83, v83
	v_or_b32_e32 v84, 48, v152
	v_mul_f32_e32 v78, v78, v82
	v_mul_f32_e32 v70, v78, v70
	v_mul_f32_e32 v78, 0xbfb8aa3b, v79
	v_exp_f32_e32 v78, v78
	v_mul_f32_e32 v82, 0xbfb8aa3b, v75
	v_exp_f32_e32 v82, v82
	v_mul_f32_e32 v74, v74, v83
	v_mul_f32_e32 v74, v74, v66
	v_add_f32_e32 v66, 1.0, v78
	v_rcp_f32_e32 v66, v66
	v_add_f32_e32 v78, 1.0, v82
	v_mul_f32_e32 v82, 0xbfb8aa3b, v80
	v_rcp_f32_e32 v78, v78
	v_exp_f32_e32 v82, v82
	v_mul_f32_e32 v66, v79, v66
	v_mul_f32_e32 v66, v66, v71
	v_mul_f32_e32 v71, v75, v78
	v_add_f32_e32 v75, 1.0, v82
	v_rcp_f32_e32 v75, v75
	v_mul_f32_e32 v78, 0xbfb8aa3b, v76
	v_exp_f32_e32 v78, v78
	v_mul_f32_e32 v71, v71, v67
	v_mul_f32_e32 v67, v80, v75
	v_mul_f32_e32 v75, 0xbfb8aa3b, v81
	v_mul_f32_e32 v67, v67, v72
	v_add_f32_e32 v72, 1.0, v78
	v_exp_f32_e32 v75, v75
	v_mul_f32_e32 v78, 0xbfb8aa3b, v77
	v_rcp_f32_e32 v72, v72
	v_exp_f32_e32 v78, v78
	v_add_f32_e32 v75, 1.0, v75
	v_rcp_f32_e32 v75, v75
	v_mul_f32_e32 v72, v76, v72
	v_add_f32_e32 v76, 1.0, v78
	v_rcp_f32_e32 v76, v76
	v_mul_f32_e32 v72, v72, v68
	v_mul_f32_e32 v68, v81, v75
	v_mul_f32_e32 v68, v68, v73
	v_mul_f32_e32 v73, v77, v76
	v_mul_f32_e32 v69, v73, v69
	v_cvt_pk_bf16_f32 v66, v70, v66
	v_cvt_pk_bf16_f32 v67, v67, v68
	v_cvt_pk_bf16_f32 v68, v74, v71
	v_cvt_pk_bf16_f32 v69, v72, v69
	v_mul_f32_e32 v72, 0xbfb8aa3b, v62
	v_exp_f32_e32 v72, v72
	v_mad_i64_i32 v[70:71], s[20:21], v84, s49, v[114:115]
	v_lshl_add_u64 v[70:71], v[70:71], 0, s[18:19]
	v_lshl_add_u64 v[70:71], v[70:71], 0, v[138:139]
	v_mul_f32_e32 v73, 0xbfb8aa3b, v58
	global_store_dwordx4 v[70:71], v[66:69], off
	v_exp_f32_e32 v73, v73
	s_nop 0
	v_add_f32_e32 v66, 1.0, v72
	v_rcp_f32_e32 v66, v66
	v_add_f32_e32 v67, 1.0, v73
; __device__ __forceinline__ unsigned cvt_pk_bf16(float lo, float hi) { unsigned r; asm volatile("v_cvt_pk_bf16_f32 %0, %1, %2" : "=v"(r) : "v"(lo), "v"(hi)); return r; }
; #define PG8_BAR __builtin_amdgcn_s_barrier()
; __device__ __forceinline__ float sigmoidf_(float x) { return __builtin_amdgcn_rcpf(1.0f + __expf(-x)); }
; template <class Epi, class Sched, bool ALIGN_EPI = false, bool SP2 = false>
; __device__ __forceinline__ void gemm_phase(PG8_LAS unsigned char* lds, const Gemm g, const Sched& S, const Epi& E) {
;     ...
;         cur = nxt; cA = nA; cB = nB; ++ui;
;         if constexpr (ALIGN_EPI) { if (wr == 1) PG8_BAR; }
;     __device__ __forceinline__ void operator()(const f32x4 (&acc)[2][2][4][2], const pg8::Unit& u, int wr, int wc, int fr, int fq) const {
;     ...
;                 if constexpr (MODE == EP_SWIGLU) {
;                     const f32x4 g0 = acc[ai][0][m][0], g1 = acc[ai][0][m][1], u0 = acc[ai][1][m][0], u1 = acc[ai][1][m][1];
;                     float r[8];
; #pragma unroll
;                     for (int j = 0; j < 4; ++j) { r[j] = g0[j] * sigmoidf_(g0[j]) * u0[j]; r[4 + j] = g1[j] * sigmoidf_(g1[j]) * u1[j]; }
;                     u32x4 w; w.x = cvt_pk_bf16(r[0], r[1]); w.y = cvt_pk_bf16(r[2], r[3]); w.z = cvt_pk_bf16(r[4], r[5]); w.w = cvt_pk_bf16(r[6], r[7]);
;                     *(u32x4*)(O + row * ldc + u.pn * 128 + cin) = w;
	v_rcp_f32_e32 v67, v67
	v_add_u32_e32 v68, 0x80, v152
	v_mul_f32_e32 v62, v62, v66
	v_mul_f32_e32 v54, v62, v54
	v_mul_f32_e32 v62, 0xbfb8aa3b, v63
	v_exp_f32_e32 v62, v62
	v_mul_f32_e32 v66, 0xbfb8aa3b, v59
	v_exp_f32_e32 v66, v66
	v_mul_f32_e32 v58, v58, v67
	v_mul_f32_e32 v58, v58, v50
	v_add_f32_e32 v50, 1.0, v62
	v_rcp_f32_e32 v50, v50
	v_add_f32_e32 v62, 1.0, v66
	v_mul_f32_e32 v66, 0xbfb8aa3b, v64
	v_rcp_f32_e32 v62, v62
	v_exp_f32_e32 v66, v66
	v_mul_f32_e32 v50, v63, v50
	v_mul_f32_e32 v50, v50, v55
	v_mul_f32_e32 v55, v59, v62
	v_add_f32_e32 v59, 1.0, v66
	v_rcp_f32_e32 v59, v59
	v_mul_f32_e32 v62, 0xbfb8aa3b, v60
	v_exp_f32_e32 v62, v62
	v_mul_f32_e32 v55, v55, v51
	v_mul_f32_e32 v51, v64, v59
	v_mul_f32_e32 v59, 0xbfb8aa3b, v65
	v_mul_f32_e32 v51, v51, v56
	v_add_f32_e32 v56, 1.0, v62
	v_exp_f32_e32 v59, v59
	v_mul_f32_e32 v62, 0xbfb8aa3b, v61
	v_rcp_f32_e32 v56, v56
	v_exp_f32_e32 v62, v62
	v_add_f32_e32 v59, 1.0, v59
	v_rcp_f32_e32 v59, v59
	v_mul_f32_e32 v56, v60, v56
	v_add_f32_e32 v60, 1.0, v62
	v_rcp_f32_e32 v60, v60
	v_mul_f32_e32 v56, v56, v52
	v_mul_f32_e32 v52, v65, v59
	v_mul_f32_e32 v52, v52, v57
	v_mul_f32_e32 v57, v61, v60
	v_mul_f32_e32 v53, v57, v53
	v_cvt_pk_bf16_f32 v50, v54, v50
	v_cvt_pk_bf16_f32 v51, v51, v52
	v_cvt_pk_bf16_f32 v52, v58, v55
	v_cvt_pk_bf16_f32 v53, v56, v53
	v_mul_f32_e32 v56, 0xbfb8aa3b, v46
	v_exp_f32_e32 v56, v56
	v_mad_i64_i32 v[54:55], s[20:21], v68, s49, v[114:115]
	v_lshl_add_u64 v[54:55], v[54:55], 0, s[18:19]
	v_lshl_add_u64 v[54:55], v[54:55], 0, v[138:139]
	v_mul_f32_e32 v57, 0xbfb8aa3b, v42
	global_store_dwordx4 v[54:55], v[50:53], off
	v_exp_f32_e32 v57, v57
	s_nop 0
	v_add_f32_e32 v50, 1.0, v56
	v_rcp_f32_e32 v50, v50
	v_add_f32_e32 v51, 1.0, v57
	v_rcp_f32_e32 v51, v51
	v_add_u32_e32 v52, 0x90, v152
	v_mul_f32_e32 v46, v46, v50
	v_mul_f32_e32 v38, v46, v38
	v_mul_f32_e32 v46, 0xbfb8aa3b, v47
	v_exp_f32_e32 v46, v46
	v_mul_f32_e32 v50, 0xbfb8aa3b, v43
	v_exp_f32_e32 v50, v50
	v_mul_f32_e32 v42, v42, v51
	v_mul_f32_e32 v42, v42, v34
	v_add_f32_e32 v34, 1.0, v46
	v_rcp_f32_e32 v34, v34
	v_add_f32_e32 v46, 1.0, v50
	v_mul_f32_e32 v50, 0xbfb8aa3b, v48
	v_rcp_f32_e32 v46, v46
	v_exp_f32_e32 v50, v50
	v_mul_f32_e32 v34, v47, v34
	v_mul_f32_e32 v34, v34, v39
	v_mul_f32_e32 v39, v43, v46
	v_add_f32_e32 v43, 1.0, v50
	v_rcp_f32_e32 v43, v43
	v_mul_f32_e32 v46, 0xbfb8aa3b, v44
	v_exp_f32_e32 v46, v46
	v_mul_f32_e32 v39, v39, v35
	v_mul_f32_e32 v35, v48, v43
	v_mul_f32_e32 v43, 0xbfb8aa3b, v49
	v_mul_f32_e32 v35, v35, v40
	v_add_f32_e32 v40, 1.0, v46
	v_exp_f32_e32 v43, v43
	v_mul_f32_e32 v46, 0xbfb8aa3b, v45
	v_rcp_f32_e32 v40, v40
	v_exp_f32_e32 v46, v46
	v_add_f32_e32 v43, 1.0, v43
	v_rcp_f32_e32 v43, v43
	v_mul_f32_e32 v40, v44, v40
	v_add_f32_e32 v44, 1.0, v46
	v_rcp_f32_e32 v44, v44
	v_mul_f32_e32 v40, v40, v36
	v_mul_f32_e32 v36, v49, v43
	v_mul_f32_e32 v36, v36, v41
	v_mul_f32_e32 v41, v45, v44
	v_mul_f32_e32 v37, v41, v37
	v_cvt_pk_bf16_f32 v34, v38, v34
	v_cvt_pk_bf16_f32 v35, v35, v36
	v_cvt_pk_bf16_f32 v36, v42, v39
	v_cvt_pk_bf16_f32 v37, v40, v37
	v_mul_f32_e32 v40, 0xbfb8aa3b, v30
	v_exp_f32_e32 v40, v40
	v_mad_i64_i32 v[38:39], s[20:21], v52, s49, v[114:115]
	v_lshl_add_u64 v[38:39], v[38:39], 0, s[18:19]
	v_lshl_add_u64 v[38:39], v[38:39], 0, v[138:139]
	v_mul_f32_e32 v41, 0xbfb8aa3b, v26
	global_store_dwordx4 v[38:39], v[34:37], off
	v_exp_f32_e32 v41, v41
	s_nop 0
	v_add_f32_e32 v34, 1.0, v40
	v_rcp_f32_e32 v34, v34
	v_add_f32_e32 v35, 1.0, v41
	v_rcp_f32_e32 v35, v35
	v_add_u32_e32 v36, 0xa0, v152
	v_mul_f32_e32 v30, v30, v34
	v_mul_f32_e32 v22, v30, v22
	v_mul_f32_e32 v30, 0xbfb8aa3b, v31
	v_exp_f32_e32 v30, v30
	v_mul_f32_e32 v34, 0xbfb8aa3b, v27
	v_exp_f32_e32 v34, v34
	v_mul_f32_e32 v26, v26, v35
	v_mul_f32_e32 v26, v26, v18
	v_add_f32_e32 v18, 1.0, v30
	v_rcp_f32_e32 v18, v18
	v_add_f32_e32 v30, 1.0, v34
	v_mul_f32_e32 v34, 0xbfb8aa3b, v32
	v_rcp_f32_e32 v30, v30
	v_exp_f32_e32 v34, v34
	v_mul_f32_e32 v18, v31, v18
	v_mul_f32_e32 v18, v18, v23
	v_mul_f32_e32 v23, v27, v30
	v_add_f32_e32 v27, 1.0, v34
	v_rcp_f32_e32 v27, v27
	v_mul_f32_e32 v30, 0xbfb8aa3b, v28
	v_exp_f32_e32 v30, v30
	v_mul_f32_e32 v23, v23, v19
	v_mul_f32_e32 v19, v32, v27
	v_mul_f32_e32 v27, 0xbfb8aa3b, v33
	v_mul_f32_e32 v19, v19, v24
	v_add_f32_e32 v24, 1.0, v30
	v_exp_f32_e32 v27, v27
	v_mul_f32_e32 v30, 0xbfb8aa3b, v29
	v_rcp_f32_e32 v24, v24
	v_exp_f32_e32 v30, v30
	v_add_f32_e32 v27, 1.0, v27
	v_rcp_f32_e32 v27, v27
	v_mul_f32_e32 v24, v28, v24
	v_add_f32_e32 v28, 1.0, v30
	v_rcp_f32_e32 v28, v28
	v_mul_f32_e32 v24, v24, v20
	v_mul_f32_e32 v20, v33, v27
	v_mul_f32_e32 v20, v20, v25
	v_mul_f32_e32 v25, v29, v28
	v_mul_f32_e32 v21, v25, v21
	v_cvt_pk_bf16_f32 v18, v22, v18
	v_cvt_pk_bf16_f32 v19, v19, v20
	v_cvt_pk_bf16_f32 v20, v26, v23
	v_cvt_pk_bf16_f32 v21, v24, v21
	v_mul_f32_e32 v24, 0xbfb8aa3b, v14
	v_exp_f32_e32 v24, v24
	v_mad_i64_i32 v[22:23], s[20:21], v36, s49, v[114:115]
	v_lshl_add_u64 v[22:23], v[22:23], 0, s[18:19]
	v_lshl_add_u64 v[22:23], v[22:23], 0, v[138:139]
	v_mul_f32_e32 v25, 0xbfb8aa3b, v10
	global_store_dwordx4 v[22:23], v[18:21], off
	v_exp_f32_e32 v25, v25
	s_nop 0
	v_add_f32_e32 v18, 1.0, v24
	v_rcp_f32_e32 v18, v18
	v_add_f32_e32 v19, 1.0, v25
	v_rcp_f32_e32 v19, v19
	v_add_u32_e32 v20, 0xb0, v152
	v_mul_f32_e32 v14, v14, v18
	v_mul_f32_e32 v6, v14, v6
	v_mul_f32_e32 v14, 0xbfb8aa3b, v15
	v_exp_f32_e32 v14, v14
	v_mul_f32_e32 v18, 0xbfb8aa3b, v11
	v_exp_f32_e32 v18, v18
	v_mul_f32_e32 v10, v10, v19
	v_mul_f32_e32 v10, v10, v2
	v_add_f32_e32 v2, 1.0, v14
	v_rcp_f32_e32 v2, v2
	v_add_f32_e32 v14, 1.0, v18
	v_mul_f32_e32 v18, 0xbfb8aa3b, v16
	v_rcp_f32_e32 v14, v14
	v_exp_f32_e32 v18, v18
	v_mul_f32_e32 v2, v15, v2
	v_mul_f32_e32 v2, v2, v7
	v_mul_f32_e32 v7, v11, v14
	v_add_f32_e32 v11, 1.0, v18
	v_rcp_f32_e32 v11, v11
	v_mul_f32_e32 v14, 0xbfb8aa3b, v12
	v_exp_f32_e32 v14, v14
	v_mul_f32_e32 v7, v7, v3
	v_mul_f32_e32 v3, v16, v11
	v_mul_f32_e32 v11, 0xbfb8aa3b, v17
	v_exp_f32_e32 v11, v11
	v_mul_f32_e32 v3, v3, v8
	v_add_f32_e32 v8, 1.0, v14
	v_mul_f32_e32 v14, 0xbfb8aa3b, v13
	v_rcp_f32_e32 v8, v8
	v_exp_f32_e32 v14, v14
	v_add_f32_e32 v11, 1.0, v11
	v_rcp_f32_e32 v11, v11
	v_mul_f32_e32 v8, v12, v8
	v_add_f32_e32 v12, 1.0, v14
	v_rcp_f32_e32 v12, v12
	v_mul_f32_e32 v8, v8, v4
	v_mul_f32_e32 v4, v17, v11
	v_mul_f32_e32 v4, v4, v9
	v_cvt_pk_bf16_f32 v2, v6, v2
	v_cvt_pk_bf16_f32 v3, v3, v4
	v_cvt_pk_bf16_f32 v4, v10, v7
	v_mad_i64_i32 v[6:7], s[20:21], v20, s49, v[114:115]
	v_mul_f32_e32 v9, v13, v12
	v_lshl_add_u64 v[6:7], v[6:7], 0, s[18:19]
	v_mul_f32_e32 v5, v9, v5
	v_lshl_add_u64 v[6:7], v[6:7], 0, v[138:139]
	v_cvt_pk_bf16_f32 v5, v8, v5
	global_store_dwordx4 v[6:7], v[2:5], off
	s_cbranch_vccnz .LBB0_1587
	s_andn2_b64 vcc, exec, s[0:1]
	s_cbranch_vccnz .LBB0_1586
	s_branch .LBB0_1586

; #define PG8_STAGE(bufoff, gbase, voff) do { _Pragma("unroll") for (int _i = 0; _i < 2; ++_i) \
;         __builtin_amdgcn_global_load_lds((const unsigned*)((const char*)(gbase) + (voff)[_i]), (PG8_LAS unsigned*)(lds + (bufoff) + ldsw + _i * 8192), 16, 0, 0); } while (0)
; #define PG8_LDA(dst, b, h) do { _Pragma("unroll") for (int m = 0; m < 4; ++m) _Pragma("unroll") for (int k = 0; k < 2; ++k) dst[m][k] = *(const PG8_LAS bf16x8*)(lds + PG8_SA(b, h) + aoff + m * 2048 + k * 1024); } while (0)
; #define PG8_LDB(dst, b, h) do { _Pragma("unroll") for (int n = 0; n < 2; ++n) _Pragma("unroll") for (int k = 0; k < 2; ++k) dst[n][k] = *(const PG8_LAS bf16x8*)(lds + PG8_SB(b, h) + boff + n * 2048 + k * 1024); } while (0)
; #define PG8_MMA(ai, bj, At, Bt) do { __builtin_amdgcn_s_setprio(1); _Pragma("unroll") for (int m = 0; m < 4; ++m) _Pragma("unroll") for (int n = 0; n < 2; ++n) _Pragma("unroll") for (int k = 0; k < 2; ++k) \
;         acc[ai][bj][m][n] = __builtin_amdgcn_mfma_f32_16x16x32_bf16(Bt[n][k], At[m][k], acc[ai][bj][m][n], 0, 0, 0); __builtin_amdgcn_s_setprio(0); } while (0)
; #define PG8_WAIT_V(n) asm volatile("s_waitcnt vmcnt(" #n ")" ::: "memory")
; template <class Epi, class Sched, bool ALIGN_EPI = false, bool SP2 = false>
; __device__ __forceinline__ void gemm_phase(PG8_LAS unsigned char* lds, const Gemm g, const Sched& S, const Epi& E) {
;     ...
;             PG8_LDB(B0, 0, 0); PG8_LDB(B1, 0, 1); PG8_SCHED; PG8_LDA(At, 0, 0); PG8_STAGE(PG8_SA(1, 1), a1 + hstep, voffA);
;             PG8_WAIT_V(8); PG8_WAIT_L(0); PG8_BAR; PG8_MMA(0, 0, At, B0); PG8_MMA(0, 1, At, B1); PG8_BAR; PG8_SCHED;
;             PG8_LDA(At, 0, 1); PG8_STAGE(PG8_SB(0, 0), b2, voffB); PG8_STAGE(PG8_SB(0, 1), b2 + hstep, voffB); PG8_STAGE(PG8_SA(0, 0), a2, voffA);
;             PG8_WAIT_V(8); PG8_WAIT_L(0); PG8_BAR; PG8_MMA(1, 0, At, B0); PG8_MMA(1, 1, At, B1); PG8_BAR; PG8_SCHED;
;             PG8_LDB(B0, 1, 0); PG8_LDB(B1, 1, 1); PG8_SCHED; PG8_LDA(At, 1, 0); PG8_STAGE(PG8_SA(0, 1), a2 + hstep, voffA);
;             PG8_WAIT_V(8); PG8_WAIT_L(0); PG8_BAR; PG8_MMA(0, 0, At, B0); PG8_MMA(0, 1, At, B1); PG8_BAR; PG8_SCHED;
;             PG8_LDA(At, 1, 1); PG8_STAGE(PG8_SB(1, 0), b3, voffB); PG8_STAGE(PG8_SB(1, 1), b3 + hstep, voffB); PG8_STAGE(PG8_SA(1, 0), a3, voffA);
;             PG8_WAIT_V(8); PG8_WAIT_L(0); PG8_BAR; PG8_MMA(1, 0, At, B0); PG8_MMA(1, 1, At, B1); PG8_BAR; PG8_SCHED;
.LBB0_1688:
	ds_read_b128 v[154:157], v150
	ds_read_b128 v[158:161], v150 offset:1024
	ds_read_b128 v[162:165], v150 offset:2048
	ds_read_b128 v[166:169], v150 offset:3072
	ds_read_b128 v[174:177], v151
	ds_read_b128 v[178:181], v151 offset:1024
	ds_read_b128 v[182:185], v151 offset:2048
	ds_read_b128 v[186:189], v151 offset:3072
	s_add_u32 s24, s22, 0xfff50080
	s_addc_u32 s25, s23, -1
	s_cmp_eq_u32 s62, 40
	s_cselect_b32 s27, s5, s25
	s_cselect_b32 s26, s4, s24
	s_cselect_b32 s25, s21, s61
	s_cselect_b32 s24, s20, s60
	v_lshl_add_u64 v[146:147], s[22:23], 0, v[138:139]
	s_add_i32 m0, s35, 0xc000
	ds_read_b128 v[190:193], v152
	ds_read_b128 v[194:197], v152 offset:1024
	ds_read_b128 v[198:201], v152 offset:2048
	ds_read_b128 v[202:205], v152 offset:3072
	ds_read_b128 v[206:209], v152 offset:4096
	ds_read_b128 v[210:213], v152 offset:5120
	ds_read_b128 v[214:217], v152 offset:6144
	ds_read_b128 v[218:221], v152 offset:7168
	global_load_lds_dwordx4 v[146:147], off
	v_lshl_add_u64 v[146:147], s[22:23], 0, v[140:141]
	s_add_i32 m0, s35, 0xe000
	s_nop 0
	global_load_lds_dwordx4 v[146:147], off
	s_waitcnt vmcnt(8)
	s_waitcnt lgkmcnt(0)
	s_barrier
	s_waitcnt lgkmcnt(0)
	v_mfma_f32_16x16x32_bf16 v[126:129], v[154:157], v[190:193], v[126:129]
	v_mfma_f32_16x16x32_bf16 v[122:125], v[162:165], v[190:193], v[122:125]
	v_mfma_f32_16x16x32_bf16 v[118:121], v[154:157], v[198:201], v[118:121]
	v_mfma_f32_16x16x32_bf16 v[110:113], v[162:165], v[198:201], v[110:113]
	v_mfma_f32_16x16x32_bf16 v[102:105], v[154:157], v[206:209], v[102:105]
	v_mfma_f32_16x16x32_bf16 v[94:97], v[162:165], v[206:209], v[94:97]
	v_mfma_f32_16x16x32_bf16 v[86:89], v[154:157], v[214:217], v[86:89]
	v_mfma_f32_16x16x32_bf16 v[78:81], v[162:165], v[214:217], v[78:81]
	v_mfma_f32_16x16x32_bf16 v[126:129], v[158:161], v[194:197], v[126:129]
	v_mfma_f32_16x16x32_bf16 v[122:125], v[166:169], v[194:197], v[122:125]
	v_mfma_f32_16x16x32_bf16 v[118:121], v[158:161], v[202:205], v[118:121]
	v_mfma_f32_16x16x32_bf16 v[110:113], v[166:169], v[202:205], v[110:113]
	v_mfma_f32_16x16x32_bf16 v[102:105], v[158:161], v[210:213], v[102:105]
	v_mfma_f32_16x16x32_bf16 v[94:97], v[166:169], v[210:213], v[94:97]
	v_mfma_f32_16x16x32_bf16 v[86:89], v[158:161], v[218:221], v[86:89]
	v_mfma_f32_16x16x32_bf16 v[78:81], v[166:169], v[218:221], v[78:81]
	v_mfma_f32_16x16x32_bf16 v[114:117], v[174:177], v[190:193], v[114:117]
	v_mfma_f32_16x16x32_bf16 v[106:109], v[182:185], v[190:193], v[106:109]
	v_mfma_f32_16x16x32_bf16 v[98:101], v[174:177], v[198:201], v[98:101]
	v_mfma_f32_16x16x32_bf16 v[90:93], v[182:185], v[198:201], v[90:93]
	v_mfma_f32_16x16x32_bf16 v[82:85], v[174:177], v[206:209], v[82:85]
	v_mfma_f32_16x16x32_bf16 v[74:77], v[182:185], v[206:209], v[74:77]
	v_mfma_f32_16x16x32_bf16 v[70:73], v[174:177], v[214:217], v[70:73]
	v_mfma_f32_16x16x32_bf16 v[66:69], v[182:185], v[214:217], v[66:69]
	v_mfma_f32_16x16x32_bf16 v[114:117], v[178:181], v[194:197], v[114:117]
	v_mfma_f32_16x16x32_bf16 v[106:109], v[186:189], v[194:197], v[106:109]
	v_mfma_f32_16x16x32_bf16 v[98:101], v[178:181], v[202:205], v[98:101]
	v_mfma_f32_16x16x32_bf16 v[90:93], v[186:189], v[202:205], v[90:93]
	v_mfma_f32_16x16x32_bf16 v[82:85], v[178:181], v[210:213], v[82:85]
	v_mfma_f32_16x16x32_bf16 v[74:77], v[186:189], v[210:213], v[74:77]
	v_mfma_f32_16x16x32_bf16 v[70:73], v[178:181], v[218:221], v[70:73]
	v_mfma_f32_16x16x32_bf16 v[66:69], v[186:189], v[218:221], v[66:69]
	s_barrier
	s_add_i32 s63, s48, s34
	v_lshl_add_u64 v[146:147], s[24:25], 0, v[132:133]
	s_mov_b32 m0, s63
	ds_read_b128 v[190:193], v152 offset:16384
	ds_read_b128 v[194:197], v152 offset:17408
	ds_read_b128 v[198:201], v152 offset:18432
	ds_read_b128 v[202:205], v152 offset:19456
	ds_read_b128 v[206:209], v152 offset:20480
	ds_read_b128 v[210:213], v152 offset:21504
	ds_read_b128 v[214:217], v152 offset:22528
	ds_read_b128 v[218:221], v152 offset:23552
	global_load_lds_dwordx4 v[146:147], off
	s_add_i32 m0, s63, 0x2000
	s_add_u32 s64, s24, 0xb0000
	v_lshl_add_u64 v[170:171], s[24:25], 0, v[136:137]
	s_addc_u32 s65, s25, 0
	s_add_i32 s63, s49, s34
	global_load_lds_dwordx4 v[170:171], off
	v_lshl_add_u64 v[222:223], s[64:65], 0, v[132:133]
	s_mov_b32 m0, s63
	v_lshl_add_u64 v[224:225], s[26:27], 0, v[134:135]
	global_load_lds_dwordx4 v[222:223], off
	v_lshl_add_u64 v[222:223], s[64:65], 0, v[136:137]
	s_add_i32 m0, s63, 0x2000
	s_nop 0
	global_load_lds_dwordx4 v[222:223], off
	v_lshl_add_u64 v[222:223], s[26:27], 0, v[130:131]
	s_mov_b32 m0, s35
	s_nop 0
	global_load_lds_dwordx4 v[222:223], off
	s_mov_b32 m0, s38
	s_nop 0
	global_load_lds_dwordx4 v[224:225], off
	s_waitcnt vmcnt(8)
	s_waitcnt lgkmcnt(0)
	s_barrier
; #define PG8_STAGE(bufoff, gbase, voff) do { _Pragma("unroll") for (int _i = 0; _i < 2; ++_i) \
;         __builtin_amdgcn_global_load_lds((const unsigned*)((const char*)(gbase) + (voff)[_i]), (PG8_LAS unsigned*)(lds + (bufoff) + ldsw + _i * 8192), 16, 0, 0); } while (0)
; #define PG8_LDA(dst, b, h) do { _Pragma("unroll") for (int m = 0; m < 4; ++m) _Pragma("unroll") for (int k = 0; k < 2; ++k) dst[m][k] = *(const PG8_LAS bf16x8*)(lds + PG8_SA(b, h) + aoff + m * 2048 + k * 1024); } while (0)
; #define PG8_LDB(dst, b, h) do { _Pragma("unroll") for (int n = 0; n < 2; ++n) _Pragma("unroll") for (int k = 0; k < 2; ++k) dst[n][k] = *(const PG8_LAS bf16x8*)(lds + PG8_SB(b, h) + boff + n * 2048 + k * 1024); } while (0)
; #define PG8_MMA(ai, bj, At, Bt) do { __builtin_amdgcn_s_setprio(1); _Pragma("unroll") for (int m = 0; m < 4; ++m) _Pragma("unroll") for (int n = 0; n < 2; ++n) _Pragma("unroll") for (int k = 0; k < 2; ++k) \
;         acc[ai][bj][m][n] = __builtin_amdgcn_mfma_f32_16x16x32_bf16(Bt[n][k], At[m][k], acc[ai][bj][m][n], 0, 0, 0); __builtin_amdgcn_s_setprio(0); } while (0)
; #define PG8_WAIT_V(n) asm volatile("s_waitcnt vmcnt(" #n ")" ::: "memory")
; template <class Epi, class Sched, bool ALIGN_EPI = false, bool SP2 = false>
; __device__ __forceinline__ void gemm_phase(PG8_LAS unsigned char* lds, const Gemm g, const Sched& S, const Epi& E) {
;     ...
;             PG8_LDB(B0, 0, 0); PG8_LDB(B1, 0, 1); PG8_SCHED; PG8_LDA(At, 0, 0); PG8_STAGE(PG8_SA(1, 1), a1 + hstep, voffA);
;             PG8_WAIT_V(8); PG8_WAIT_L(0); PG8_BAR; PG8_MMA(0, 0, At, B0); PG8_MMA(0, 1, At, B1); PG8_BAR; PG8_SCHED;
;             PG8_LDA(At, 0, 1); PG8_STAGE(PG8_SB(0, 0), b2, voffB); PG8_STAGE(PG8_SB(0, 1), b2 + hstep, voffB); PG8_STAGE(PG8_SA(0, 0), a2, voffA);
;             PG8_WAIT_V(8); PG8_WAIT_L(0); PG8_BAR; PG8_MMA(1, 0, At, B0); PG8_MMA(1, 1, At, B1); PG8_BAR; PG8_SCHED;
;             PG8_LDB(B0, 1, 0); PG8_LDB(B1, 1, 1); PG8_SCHED; PG8_LDA(At, 1, 0); PG8_STAGE(PG8_SA(0, 1), a2 + hstep, voffA);
;             PG8_WAIT_V(8); PG8_WAIT_L(0); PG8_BAR; PG8_MMA(0, 0, At, B0); PG8_MMA(0, 1, At, B1); PG8_BAR; PG8_SCHED;
;             PG8_LDA(At, 1, 1); PG8_STAGE(PG8_SB(1, 0), b3, voffB); PG8_STAGE(PG8_SB(1, 1), b3 + hstep, voffB); PG8_STAGE(PG8_SA(1, 0), a3, voffA);
;             PG8_WAIT_V(8); PG8_WAIT_L(0); PG8_BAR; PG8_MMA(1, 0, At, B0); PG8_MMA(1, 1, At, B1); PG8_BAR; PG8_SCHED;
	s_waitcnt lgkmcnt(0)
	v_mfma_f32_16x16x32_bf16 v[62:65], v[154:157], v[190:193], v[62:65]
	v_mfma_f32_16x16x32_bf16 v[58:61], v[162:165], v[190:193], v[58:61]
	v_mfma_f32_16x16x32_bf16 v[54:57], v[154:157], v[198:201], v[54:57]
	v_mfma_f32_16x16x32_bf16 v[46:49], v[162:165], v[198:201], v[46:49]
	v_mfma_f32_16x16x32_bf16 v[38:41], v[154:157], v[206:209], v[38:41]
	v_mfma_f32_16x16x32_bf16 v[30:33], v[162:165], v[206:209], v[30:33]
	v_mfma_f32_16x16x32_bf16 v[22:25], v[154:157], v[214:217], v[22:25]
	v_mfma_f32_16x16x32_bf16 v[14:17], v[162:165], v[214:217], v[14:17]
	v_mfma_f32_16x16x32_bf16 v[62:65], v[158:161], v[194:197], v[62:65]
	v_mfma_f32_16x16x32_bf16 v[58:61], v[166:169], v[194:197], v[58:61]
	v_mfma_f32_16x16x32_bf16 v[54:57], v[158:161], v[202:205], v[54:57]
	v_mfma_f32_16x16x32_bf16 v[46:49], v[166:169], v[202:205], v[46:49]
	v_mfma_f32_16x16x32_bf16 v[38:41], v[158:161], v[210:213], v[38:41]
	v_mfma_f32_16x16x32_bf16 v[30:33], v[166:169], v[210:213], v[30:33]
	v_mfma_f32_16x16x32_bf16 v[22:25], v[158:161], v[218:221], v[22:25]
	v_mfma_f32_16x16x32_bf16 v[14:17], v[166:169], v[218:221], v[14:17]
	v_mfma_f32_16x16x32_bf16 v[50:53], v[174:177], v[190:193], v[50:53]
	v_mfma_f32_16x16x32_bf16 v[42:45], v[182:185], v[190:193], v[42:45]
	v_mfma_f32_16x16x32_bf16 v[34:37], v[174:177], v[198:201], v[34:37]
	v_mfma_f32_16x16x32_bf16 v[26:29], v[182:185], v[198:201], v[26:29]
	v_mfma_f32_16x16x32_bf16 v[18:21], v[174:177], v[206:209], v[18:21]
	v_mfma_f32_16x16x32_bf16 v[10:13], v[182:185], v[206:209], v[10:13]
	v_mfma_f32_16x16x32_bf16 v[6:9], v[174:177], v[214:217], v[6:9]
	v_mfma_f32_16x16x32_bf16 v[2:5], v[182:185], v[214:217], v[2:5]
	v_mfma_f32_16x16x32_bf16 v[50:53], v[178:181], v[194:197], v[50:53]
	v_mfma_f32_16x16x32_bf16 v[42:45], v[186:189], v[194:197], v[42:45]
	v_mfma_f32_16x16x32_bf16 v[34:37], v[178:181], v[202:205], v[34:37]
	v_mfma_f32_16x16x32_bf16 v[26:29], v[186:189], v[202:205], v[26:29]
	v_mfma_f32_16x16x32_bf16 v[18:21], v[178:181], v[210:213], v[18:21]
	v_mfma_f32_16x16x32_bf16 v[10:13], v[186:189], v[210:213], v[10:13]
	v_mfma_f32_16x16x32_bf16 v[6:9], v[178:181], v[218:221], v[6:9]
	v_mfma_f32_16x16x32_bf16 v[2:5], v[186:189], v[218:221], v[2:5]
	s_barrier
	s_add_i32 s63, 0, 0x18000
	v_add_u32_e32 v153, s63, v148
	s_add_i32 s64, 0, 0x1c000
	ds_read_b128 v[154:157], v153
	ds_read_b128 v[158:161], v153 offset:1024
	ds_read_b128 v[162:165], v153 offset:2048
	ds_read_b128 v[166:169], v153 offset:3072
	v_add_u32_e32 v153, s64, v148
	ds_read_b128 v[174:177], v153
	ds_read_b128 v[178:181], v153 offset:1024
	ds_read_b128 v[182:185], v153 offset:2048
	ds_read_b128 v[186:189], v153 offset:3072
	s_add_u32 s26, s26, 0xb0000
	s_addc_u32 s27, s27, 0
	s_mov_b32 m0, s39
	v_lshl_add_u64 v[226:227], s[26:27], 0, v[130:131]
	ds_read_b128 v[190:193], v152 offset:32768
	ds_read_b128 v[194:197], v152 offset:33792
	ds_read_b128 v[198:201], v152 offset:34816
	ds_read_b128 v[202:205], v152 offset:35840
	ds_read_b128 v[206:209], v152 offset:36864
	ds_read_b128 v[210:213], v152 offset:37888
	ds_read_b128 v[214:217], v152 offset:38912
	ds_read_b128 v[218:221], v152 offset:39936
	global_load_lds_dwordx4 v[226:227], off
	v_lshl_add_u64 v[226:227], s[26:27], 0, v[134:135]
	s_mov_b32 m0, s40
	s_nop 0
	global_load_lds_dwordx4 v[226:227], off
	s_waitcnt vmcnt(8)
	s_waitcnt lgkmcnt(0)
	s_barrier
	s_waitcnt lgkmcnt(0)
	v_mfma_f32_16x16x32_bf16 v[126:129], v[154:157], v[190:193], v[126:129]
	v_mfma_f32_16x16x32_bf16 v[122:125], v[162:165], v[190:193], v[122:125]
	v_mfma_f32_16x16x32_bf16 v[118:121], v[154:157], v[198:201], v[118:121]
	v_mfma_f32_16x16x32_bf16 v[110:113], v[162:165], v[198:201], v[110:113]
	v_mfma_f32_16x16x32_bf16 v[102:105], v[154:157], v[206:209], v[102:105]
	v_mfma_f32_16x16x32_bf16 v[94:97], v[162:165], v[206:209], v[94:97]
	v_mfma_f32_16x16x32_bf16 v[86:89], v[154:157], v[214:217], v[86:89]
	v_mfma_f32_16x16x32_bf16 v[78:81], v[162:165], v[214:217], v[78:81]
	v_mfma_f32_16x16x32_bf16 v[126:129], v[158:161], v[194:197], v[126:129]
	v_mfma_f32_16x16x32_bf16 v[122:125], v[166:169], v[194:197], v[122:125]
	v_mfma_f32_16x16x32_bf16 v[118:121], v[158:161], v[202:205], v[118:121]
	v_mfma_f32_16x16x32_bf16 v[110:113], v[166:169], v[202:205], v[110:113]
	v_mfma_f32_16x16x32_bf16 v[102:105], v[158:161], v[210:213], v[102:105]
	v_mfma_f32_16x16x32_bf16 v[94:97], v[166:169], v[210:213], v[94:97]
	v_mfma_f32_16x16x32_bf16 v[86:89], v[158:161], v[218:221], v[86:89]
	v_mfma_f32_16x16x32_bf16 v[78:81], v[166:169], v[218:221], v[78:81]
	v_mfma_f32_16x16x32_bf16 v[114:117], v[174:177], v[190:193], v[114:117]
	v_mfma_f32_16x16x32_bf16 v[106:109], v[182:185], v[190:193], v[106:109]
	v_mfma_f32_16x16x32_bf16 v[98:101], v[174:177], v[198:201], v[98:101]
	v_mfma_f32_16x16x32_bf16 v[90:93], v[182:185], v[198:201], v[90:93]
	v_mfma_f32_16x16x32_bf16 v[82:85], v[174:177], v[206:209], v[82:85]
	v_mfma_f32_16x16x32_bf16 v[74:77], v[182:185], v[206:209], v[74:77]
	v_mfma_f32_16x16x32_bf16 v[70:73], v[174:177], v[214:217], v[70:73]
	v_mfma_f32_16x16x32_bf16 v[66:69], v[182:185], v[214:217], v[66:69]
	v_mfma_f32_16x16x32_bf16 v[114:117], v[178:181], v[194:197], v[114:117]
	v_mfma_f32_16x16x32_bf16 v[106:109], v[186:189], v[194:197], v[106:109]
	v_mfma_f32_16x16x32_bf16 v[98:101], v[178:181], v[202:205], v[98:101]
	v_mfma_f32_16x16x32_bf16 v[90:93], v[186:189], v[202:205], v[90:93]
	v_mfma_f32_16x16x32_bf16 v[82:85], v[178:181], v[210:213], v[82:85]
	v_mfma_f32_16x16x32_bf16 v[74:77], v[186:189], v[210:213], v[74:77]
	v_mfma_f32_16x16x32_bf16 v[70:73], v[178:181], v[218:221], v[70:73]
	v_mfma_f32_16x16x32_bf16 v[66:69], v[186:189], v[218:221], v[66:69]
	s_barrier
; #define PG8_STAGE(bufoff, gbase, voff) do { _Pragma("unroll") for (int _i = 0; _i < 2; ++_i) \
;         __builtin_amdgcn_global_load_lds((const unsigned*)((const char*)(gbase) + (voff)[_i]), (PG8_LAS unsigned*)(lds + (bufoff) + ldsw + _i * 8192), 16, 0, 0); } while (0)
; #define PG8_WAIT_V(n) asm volatile("s_waitcnt vmcnt(" #n ")" ::: "memory")
; #define PG8_WAIT_L(n) asm volatile("s_waitcnt lgkmcnt(" #n ")" ::: "memory")
; template <class Epi, class Sched, bool ALIGN_EPI = false, bool SP2 = false>
; __device__ __forceinline__ void gemm_phase(PG8_LAS unsigned char* lds, const Gemm g, const Sched& S, const Epi& E) {
;     ...
;             PG8_WAIT_V(8); PG8_WAIT_L(0); PG8_BAR; PG8_MMA(0, 0, At, B0); PG8_MMA(0, 1, At, B1); PG8_BAR; PG8_SCHED;
;             PG8_LDA(At, 1, 1); PG8_STAGE(PG8_SB(1, 0), b3, voffB); PG8_STAGE(PG8_SB(1, 1), b3 + hstep, voffB); PG8_STAGE(PG8_SA(1, 0), a3, voffA);
;             PG8_WAIT_V(8); PG8_WAIT_L(0); PG8_BAR; PG8_MMA(1, 0, At, B0); PG8_MMA(1, 1, At, B1); PG8_BAR; PG8_SCHED;
;             } else {
;             PG8_LDB(B0, 0, 0); PG8_SCHED; PG8_LDA(At, 0, 0); PG8_STAGE(PG8_SA(1, 1), a1 + hstep, voffA);
;             PG8_WAIT_L(8); PG8_BAR; PG8_WAIT_L(0); PG8_MMA(0, 0, At, B0); PG8_BAR; PG8_SCHED;
;             PG8_LDB(B1, 0, 1); PG8_STAGE(PG8_SB(0, 0), b2, voffB);
;             PG8_BAR; PG8_WAIT_L(0); PG8_MMA(0, 1, At, B1); PG8_BAR;
;             PG8_LDA(At, 0, 1); PG8_STAGE(PG8_SA(0, 0), a2, voffA);
;             PG8_BAR; PG8_WAIT_L(0); PG8_MMA(1, 0, At, B0); PG8_BAR; PG8_SCHED;
;             PG8_STAGE(PG8_SB(0, 1), b2 + hstep, voffB);
;             PG8_WAIT_V(6); PG8_BAR; PG8_MMA(1, 1, At, B1); PG8_BAR;
;             PG8_LDB(B0, 1, 0); PG8_SCHED; PG8_LDA(At, 1, 0); PG8_STAGE(PG8_SA(0, 1), a2 + hstep, voffA);
;             PG8_WAIT_L(8); PG8_BAR; PG8_WAIT_L(0); PG8_MMA(0, 0, At, B0); PG8_BAR; PG8_SCHED;
;             PG8_LDB(B1, 1, 1); PG8_STAGE(PG8_SB(1, 0), b3, voffB);
;             PG8_BAR; PG8_WAIT_L(0); PG8_MMA(0, 1, At, B1); PG8_BAR;
;             PG8_LDA(At, 1, 1); PG8_STAGE(PG8_SA(1, 0), a3, voffA);
;             PG8_BAR; PG8_WAIT_L(0); PG8_MMA(1, 0, At, B0); PG8_BAR; PG8_SCHED;
;             PG8_STAGE(PG8_SB(1, 1), b3 + hstep, voffB);
;             PG8_WAIT_V(6); PG8_BAR; PG8_MMA(1, 1, At, B1); PG8_BAR;
;             }
;         }
;         if constexpr (ALIGN_EPI) { if (wr == 0) PG8_BAR; }
	s_add_i32 s26, s63, s34
	v_lshl_add_u64 v[146:147], v[146:147], 0, s[8:9]
	s_mov_b32 m0, s26
	ds_read_b128 v[190:193], v152 offset:49152
	ds_read_b128 v[194:197], v152 offset:50176
	ds_read_b128 v[198:201], v152 offset:51200
	ds_read_b128 v[202:205], v152 offset:52224
	ds_read_b128 v[206:209], v152 offset:53248
	ds_read_b128 v[210:213], v152 offset:54272
	ds_read_b128 v[214:217], v152 offset:55296
	ds_read_b128 v[218:221], v152 offset:56320
	global_load_lds_dwordx4 v[146:147], off
	s_add_i32 m0, s26, 0x2000
	s_add_u32 s24, s24, 0xb0080
	v_lshl_add_u64 v[146:147], v[170:171], 0, s[8:9]
	s_addc_u32 s25, s25, 0
	s_add_i32 s26, s64, s34
	global_load_lds_dwordx4 v[146:147], off
	v_lshl_add_u64 v[146:147], s[24:25], 0, v[132:133]
	s_mov_b32 m0, s26
	s_nop 0
	global_load_lds_dwordx4 v[146:147], off
	v_lshl_add_u64 v[146:147], s[24:25], 0, v[136:137]
	s_add_i32 m0, s26, 0x2000
	s_nop 0
	global_load_lds_dwordx4 v[146:147], off
	v_lshl_add_u64 v[146:147], v[222:223], 0, s[8:9]
	s_mov_b32 m0, s42
	s_nop 0
	global_load_lds_dwordx4 v[146:147], off
	v_lshl_add_u64 v[146:147], v[224:225], 0, s[8:9]
	s_mov_b32 m0, s43
	s_nop 0
	global_load_lds_dwordx4 v[146:147], off
	s_waitcnt vmcnt(8)
	s_waitcnt lgkmcnt(0)
	s_barrier
	s_waitcnt lgkmcnt(0)
	v_mfma_f32_16x16x32_bf16 v[62:65], v[154:157], v[190:193], v[62:65]
	v_mfma_f32_16x16x32_bf16 v[58:61], v[162:165], v[190:193], v[58:61]
	v_mfma_f32_16x16x32_bf16 v[54:57], v[154:157], v[198:201], v[54:57]
	v_mfma_f32_16x16x32_bf16 v[46:49], v[162:165], v[198:201], v[46:49]
	v_mfma_f32_16x16x32_bf16 v[38:41], v[154:157], v[206:209], v[38:41]
	v_mfma_f32_16x16x32_bf16 v[30:33], v[162:165], v[206:209], v[30:33]
	v_mfma_f32_16x16x32_bf16 v[22:25], v[154:157], v[214:217], v[22:25]
	v_mfma_f32_16x16x32_bf16 v[14:17], v[162:165], v[214:217], v[14:17]
	v_mfma_f32_16x16x32_bf16 v[62:65], v[158:161], v[194:197], v[62:65]
	v_mfma_f32_16x16x32_bf16 v[58:61], v[166:169], v[194:197], v[58:61]
	v_mfma_f32_16x16x32_bf16 v[54:57], v[158:161], v[202:205], v[54:57]
	v_mfma_f32_16x16x32_bf16 v[46:49], v[166:169], v[202:205], v[46:49]
	v_mfma_f32_16x16x32_bf16 v[38:41], v[158:161], v[210:213], v[38:41]
	v_mfma_f32_16x16x32_bf16 v[30:33], v[166:169], v[210:213], v[30:33]
	v_mfma_f32_16x16x32_bf16 v[22:25], v[158:161], v[218:221], v[22:25]
	v_mfma_f32_16x16x32_bf16 v[14:17], v[166:169], v[218:221], v[14:17]
	v_mfma_f32_16x16x32_bf16 v[50:53], v[174:177], v[190:193], v[50:53]
	v_mfma_f32_16x16x32_bf16 v[42:45], v[182:185], v[190:193], v[42:45]
	v_mfma_f32_16x16x32_bf16 v[34:37], v[174:177], v[198:201], v[34:37]
	v_mfma_f32_16x16x32_bf16 v[26:29], v[182:185], v[198:201], v[26:29]
	v_mfma_f32_16x16x32_bf16 v[18:21], v[174:177], v[206:209], v[18:21]
	v_mfma_f32_16x16x32_bf16 v[10:13], v[182:185], v[206:209], v[10:13]
	v_mfma_f32_16x16x32_bf16 v[6:9], v[174:177], v[214:217], v[6:9]
	v_mfma_f32_16x16x32_bf16 v[2:5], v[182:185], v[214:217], v[2:5]
	v_mfma_f32_16x16x32_bf16 v[50:53], v[178:181], v[194:197], v[50:53]
	v_mfma_f32_16x16x32_bf16 v[42:45], v[186:189], v[194:197], v[42:45]
	v_mfma_f32_16x16x32_bf16 v[34:37], v[178:181], v[202:205], v[34:37]
	v_mfma_f32_16x16x32_bf16 v[26:29], v[186:189], v[202:205], v[26:29]
	v_mfma_f32_16x16x32_bf16 v[18:21], v[178:181], v[210:213], v[18:21]
	v_mfma_f32_16x16x32_bf16 v[10:13], v[186:189], v[210:213], v[10:13]
	v_mfma_f32_16x16x32_bf16 v[6:9], v[178:181], v[218:221], v[6:9]
	v_mfma_f32_16x16x32_bf16 v[2:5], v[186:189], v[218:221], v[2:5]
	s_barrier
	s_add_i32 s62, s62, 2
	s_add_u32 s22, s22, 0x100
	s_addc_u32 s23, s23, 0
	s_add_u32 s60, s60, 0x100
	s_addc_u32 s61, s61, 0
	s_cmp_gt_u32 s62, 41
	s_cbranch_scc0 .LBB0_1688
	s_and_b64 vcc, s[10:11], s[2:3]
	s_cbranch_vccz .LBB0_1691
	s_barrier
; __device__ __forceinline__ unsigned cvt_pk_bf16(float lo, float hi) { unsigned r; asm volatile("v_cvt_pk_bf16_f32 %0, %1, %2" : "=v"(r) : "v"(lo), "v"(hi)); return r; }
; __device__ __forceinline__ float sigmoidf_(float x) { return __builtin_amdgcn_rcpf(1.0f + __expf(-x)); }
;     __device__ __forceinline__ void operator()(const f32x4 (&acc)[2][2][4][2], const pg8::Unit& u, int wr, int wc, int fr, int fq) const {
;     ...
;                 const size_t row = (size_t)(row0 + ai * 128 + m * 16);
;                 if constexpr (MODE == EP_SWIGLU) {
;                     const f32x4 g0 = acc[ai][0][m][0], g1 = acc[ai][0][m][1], u0 = acc[ai][1][m][0], u1 = acc[ai][1][m][1];
;                     float r[8];
; #pragma unroll
;                     for (int j = 0; j < 4; ++j) { r[j] = g0[j] * sigmoidf_(g0[j]) * u0[j]; r[4 + j] = g1[j] * sigmoidf_(g1[j]) * u1[j]; }
;                     u32x4 w; w.x = cvt_pk_bf16(r[0], r[1]); w.y = cvt_pk_bf16(r[2], r[3]); w.z = cvt_pk_bf16(r[4], r[5]); w.w = cvt_pk_bf16(r[6], r[7]);
;                     *(u32x4*)(O + row * ldc + u.pn * 128 + cin) = w;
;                 } else {
; #pragma unroll
;                     for (int bj = 0; bj < 2; ++bj) {
;                         const int col = u.pn * 256 + bj * 128 + cin;
;                         const f32x4 a0 = acc[ai][bj][m][0], a1 = acc[ai][bj][m][1];
;                         float r[8] = {a0[0], a0[1], a0[2], a0[3], a1[0], a1[1], a1[2], a1[3]};
;                         bf16_t* dst = O + row * ldc + col;
;     ...
;                         u32x4 w; w.x = cvt_pk_bf16(r[0], r[1]); w.y = cvt_pk_bf16(r[2], r[3]); w.z = cvt_pk_bf16(r[4], r[5]); w.w = cvt_pk_bf16(r[6], r[7]);
;                         *(u32x4*)dst = w;
.LBB0_1691:
	v_lshl_add_u32 v154, s58, 8, v1
	v_lshl_or_b32 v146, s59, 8, v149
	v_ashrrev_i32_e32 v155, 31, v154
	v_lshlrev_b64 v[156:157], 11, v[154:155]
	v_ashrrev_i32_e32 v147, 31, v146
	v_lshl_add_u64 v[156:157], s[6:7], 0, v[156:157]
	v_lshlrev_b64 v[158:159], 1, v[146:147]
	v_lshl_add_u64 v[146:147], v[156:157], 0, v[158:159]
	v_cvt_pk_bf16_f32 v126, v126, v127
	v_cvt_pk_bf16_f32 v127, v128, v129
	v_cvt_pk_bf16_f32 v128, v122, v123
	v_cvt_pk_bf16_f32 v129, v124, v125
	global_store_dwordx4 v[146:147], v[126:129], off
	v_cvt_pk_bf16_f32 v114, v114, v115
	v_cvt_pk_bf16_f32 v115, v116, v117
	v_cvt_pk_bf16_f32 v116, v106, v107
	v_or_b32_e32 v106, 16, v154
	v_ashrrev_i32_e32 v107, 31, v106
	v_lshlrev_b64 v[106:107], 11, v[106:107]
	v_lshl_add_u64 v[106:107], s[6:7], 0, v[106:107]
	v_cvt_pk_bf16_f32 v117, v108, v109
	global_store_dwordx4 v[146:147], v[114:117], off offset:256
	s_nop 1
	v_lshl_add_u64 v[114:115], v[106:107], 0, v[158:159]
	v_cvt_pk_bf16_f32 v106, v118, v119
	v_cvt_pk_bf16_f32 v107, v120, v121
	v_cvt_pk_bf16_f32 v108, v110, v111
	v_cvt_pk_bf16_f32 v109, v112, v113
	global_store_dwordx4 v[114:115], v[106:109], off
	v_cvt_pk_bf16_f32 v98, v98, v99
	v_cvt_pk_bf16_f32 v99, v100, v101
	v_cvt_pk_bf16_f32 v100, v90, v91
	v_or_b32_e32 v90, 32, v154
	v_ashrrev_i32_e32 v91, 31, v90
	v_lshlrev_b64 v[90:91], 11, v[90:91]
	v_lshl_add_u64 v[90:91], s[6:7], 0, v[90:91]
	v_cvt_pk_bf16_f32 v101, v92, v93
	global_store_dwordx4 v[114:115], v[98:101], off offset:256
	s_nop 1
	v_lshl_add_u64 v[98:99], v[90:91], 0, v[158:159]
	v_cvt_pk_bf16_f32 v90, v102, v103
	v_cvt_pk_bf16_f32 v91, v104, v105
	v_cvt_pk_bf16_f32 v92, v94, v95
	v_cvt_pk_bf16_f32 v93, v96, v97
	global_store_dwordx4 v[98:99], v[90:93], off
	v_cvt_pk_bf16_f32 v82, v82, v83
	v_cvt_pk_bf16_f32 v83, v84, v85
	v_cvt_pk_bf16_f32 v84, v74, v75
	v_or_b32_e32 v74, 48, v154
	v_ashrrev_i32_e32 v75, 31, v74
	v_lshlrev_b64 v[74:75], 11, v[74:75]
	v_lshl_add_u64 v[74:75], s[6:7], 0, v[74:75]
	v_cvt_pk_bf16_f32 v85, v76, v77
	global_store_dwordx4 v[98:99], v[82:85], off offset:256
	s_nop 1
	v_lshl_add_u64 v[82:83], v[74:75], 0, v[158:159]
	v_cvt_pk_bf16_f32 v74, v86, v87
	v_cvt_pk_bf16_f32 v75, v88, v89
	v_cvt_pk_bf16_f32 v76, v78, v79
	v_cvt_pk_bf16_f32 v77, v80, v81
	global_store_dwordx4 v[82:83], v[74:77], off
	v_cvt_pk_bf16_f32 v70, v70, v71
	v_cvt_pk_bf16_f32 v71, v72, v73
	v_cvt_pk_bf16_f32 v72, v66, v67
	v_cvt_pk_bf16_f32 v73, v68, v69
	global_store_dwordx4 v[82:83], v[70:73], off offset:256
	v_cvt_pk_bf16_f32 v62, v62, v63
	v_cvt_pk_bf16_f32 v63, v64, v65
	v_cvt_pk_bf16_f32 v64, v58, v59
	v_add_co_u32_e32 v58, vcc, s52, v146
	v_lshl_add_u64 v[66:67], v[146:147], 0, s[12:13]
	s_nop 0
	v_addc_co_u32_e32 v59, vcc, 0, v147, vcc
	v_cvt_pk_bf16_f32 v65, v60, v61
	global_store_dwordx4 v[58:59], v[62:65], off
	v_cvt_pk_bf16_f32 v50, v50, v51
	v_cvt_pk_bf16_f32 v51, v52, v53
	v_cvt_pk_bf16_f32 v52, v42, v43
	v_cvt_pk_bf16_f32 v53, v44, v45
	global_store_dwordx4 v[66:67], v[50:53], off offset:256
	v_cvt_pk_bf16_f32 v42, v54, v55
	v_cvt_pk_bf16_f32 v43, v56, v57
	v_cvt_pk_bf16_f32 v44, v46, v47
	v_add_co_u32_e32 v46, vcc, s53, v146
	s_nop 0
	v_lshl_add_u64 v[50:51], v[146:147], 0, s[14:15]
	v_addc_co_u32_e32 v47, vcc, 0, v147, vcc
	v_cvt_pk_bf16_f32 v45, v48, v49
	global_store_dwordx4 v[46:47], v[42:45], off
	v_cvt_pk_bf16_f32 v34, v34, v35
	v_cvt_pk_bf16_f32 v35, v36, v37
	v_cvt_pk_bf16_f32 v36, v26, v27
	v_cvt_pk_bf16_f32 v37, v28, v29
	global_store_dwordx4 v[50:51], v[34:37], off offset:256
	v_cvt_pk_bf16_f32 v26, v38, v39
	v_cvt_pk_bf16_f32 v27, v40, v41
	v_cvt_pk_bf16_f32 v28, v30, v31
	v_add_co_u32_e32 v30, vcc, s54, v146
	s_nop 0
	v_lshl_add_u64 v[34:35], v[146:147], 0, s[16:17]
	v_addc_co_u32_e32 v31, vcc, 0, v147, vcc
	v_cvt_pk_bf16_f32 v29, v32, v33
	global_store_dwordx4 v[30:31], v[26:29], off
	v_cvt_pk_bf16_f32 v18, v18, v19
	v_cvt_pk_bf16_f32 v19, v20, v21
	v_cvt_pk_bf16_f32 v20, v10, v11
	v_cvt_pk_bf16_f32 v21, v12, v13
	global_store_dwordx4 v[34:35], v[18:21], off offset:256
	v_cvt_pk_bf16_f32 v10, v22, v23
	v_cvt_pk_bf16_f32 v11, v24, v25
	v_cvt_pk_bf16_f32 v12, v14, v15
	v_add_co_u32_e32 v14, vcc, s55, v146
	s_nop 0
	v_lshl_add_u64 v[18:19], v[146:147], 0, s[18:19]
	v_addc_co_u32_e32 v15, vcc, 0, v147, vcc
	s_and_b64 vcc, exec, s[2:3]
	s_mov_b64 s[2:3], -1
	v_cvt_pk_bf16_f32 v13, v16, v17
	global_store_dwordx4 v[14:15], v[10:13], off
	v_cvt_pk_bf16_f32 v6, v6, v7
	v_cvt_pk_bf16_f32 v7, v8, v9
	v_cvt_pk_bf16_f32 v8, v2, v3
	v_cvt_pk_bf16_f32 v9, v4, v5
	global_store_dwordx4 v[18:19], v[6:9], off offset:256
	s_cbranch_vccnz .LBB0_1676
	s_andn2_b64 vcc, exec, s[0:1]
	s_cbranch_vccnz .LBB0_1675
	s_branch .LBB0_1675
